# nt on more read-once streams: weight-copy (transpose) loads in P1/P4/P6 and the P5 pre-conv row loads
# speedup vs baseline: 1.0400x; 1.0069x over previous
; #define LAS __attribute__((address_space(3)))
; __device__ __forceinline__ void p0_transpose_item(const float* W0, const float* W1, int K, int Nsrc, int Nd, int mode, bf16* WT, LAS float* scr, int item, int lane) {
;     const int nblk = Nd / 32, kb = item / nblk, nb = item % nblk, k0 = 64 * kb, n0 = 32 * nb;
;     const float* src = W0; int c0 = n0;
;     if (mode == 1) { const int t = n0 / 256, w = n0 % 256; src = (w < 128) ? W0 : W1; c0 = t * 128 + (w & 127); }
;     const bool okc = (c0 + (lane & 31)) < Nsrc; const int cc = okc ? c0 + (lane & 31) : Nsrc - 1;
;     float tv[32];
; #pragma unroll
;     for (int i = 0; i < 32; ++i) { const int kk = 2 * i + (lane >> 5); tv[i] = src[(size_t)(k0 + kk) * Nsrc + cc]; }
; #pragma unroll
;     for (int i = 0; i < 32; ++i) { const int kk = 2 * i + (lane >> 5); scr[kk * 33 + (lane & 31)] = okc ? tv[i] : 0.f; }
.LBB0_112:
	s_ashr_i32 s0, s6, 31
	s_lshr_b32 s0, s0, 27
	s_add_i32 s0, s6, s0
	s_ashr_i32 s1, s0, 5
	s_lshl_b32 s0, s1, 6
	s_lshl_b32 s7, s1, 10
	v_or_b32_e32 v16, s0, v169
	v_subrev_u32_e32 v14, s7, v5
	v_or_b32_e32 v24, 8, v16
	v_or_b32_e32 v26, 10, v16
	v_or_b32_e32 v28, 12, v16
	v_or_b32_e32 v38, 22, v16
	v_or_b32_e32 v40, 24, v16
	v_or_b32_e32 v42, 26, v16
	v_or_b32_e32 v44, 28, v16
	v_or_b32_e32 v46, 30, v16
	v_or_b32_e32 v48, 32, v16
	v_or_b32_e32 v50, 34, v16
	v_or_b32_e32 v52, 36, v16
	v_or_b32_e32 v54, 38, v16
	v_or_b32_e32 v56, 40, v16
	v_or_b32_e32 v58, 42, v16
	v_ashrrev_i32_e32 v15, 31, v14
	v_ashrrev_i32_e32 v17, 31, v16
	v_or_b32_e32 v18, 2, v16
	v_or_b32_e32 v20, 4, v16
	v_or_b32_e32 v22, 6, v16
	v_or_b32_e32 v30, 14, v16
	v_or_b32_e32 v32, 16, v16
	v_or_b32_e32 v34, 18, v16
	v_or_b32_e32 v36, 20, v16
	v_or_b32_e32 v60, 44, v16
	v_or_b32_e32 v62, 46, v16
	v_or_b32_e32 v64, 48, v16
	v_or_b32_e32 v66, 50, v16
	v_or_b32_e32 v68, 52, v16
	v_or_b32_e32 v70, 54, v16
	v_or_b32_e32 v72, 56, v16
	v_or_b32_e32 v74, 58, v16
	v_or_b32_e32 v76, 60, v16
	v_or_b32_e32 v78, 62, v16
	v_ashrrev_i32_e32 v25, 31, v24
	v_ashrrev_i32_e32 v27, 31, v26
	v_ashrrev_i32_e32 v29, 31, v28
	v_ashrrev_i32_e32 v39, 31, v38
	v_ashrrev_i32_e32 v41, 31, v40
	v_ashrrev_i32_e32 v43, 31, v42
	v_ashrrev_i32_e32 v45, 31, v44
	v_ashrrev_i32_e32 v47, 31, v46
	v_ashrrev_i32_e32 v49, 31, v48
	v_ashrrev_i32_e32 v51, 31, v50
	v_ashrrev_i32_e32 v53, 31, v52
	v_ashrrev_i32_e32 v55, 31, v54
	v_ashrrev_i32_e32 v57, 31, v56
	v_ashrrev_i32_e32 v59, 31, v58
	v_lshl_add_u64 v[14:15], v[14:15], 2, s[10:11]
	v_lshlrev_b64 v[16:17], 12, v[16:17]
	v_ashrrev_i32_e32 v19, 31, v18
	v_ashrrev_i32_e32 v21, 31, v20
	v_ashrrev_i32_e32 v23, 31, v22
	v_ashrrev_i32_e32 v31, 31, v30
	v_ashrrev_i32_e32 v33, 31, v32
	v_ashrrev_i32_e32 v35, 31, v34
	v_ashrrev_i32_e32 v37, 31, v36
	v_ashrrev_i32_e32 v61, 31, v60
	v_ashrrev_i32_e32 v63, 31, v62
	v_ashrrev_i32_e32 v65, 31, v64
	v_ashrrev_i32_e32 v67, 31, v66
	v_ashrrev_i32_e32 v69, 31, v68
	v_ashrrev_i32_e32 v71, 31, v70
	v_ashrrev_i32_e32 v73, 31, v72
	v_ashrrev_i32_e32 v75, 31, v74
	v_ashrrev_i32_e32 v77, 31, v76
	v_ashrrev_i32_e32 v79, 31, v78
	v_lshlrev_b64 v[24:25], 12, v[24:25]
	v_lshlrev_b64 v[26:27], 12, v[26:27]
	v_lshlrev_b64 v[28:29], 12, v[28:29]
	v_lshlrev_b64 v[38:39], 12, v[38:39]
	v_lshlrev_b64 v[40:41], 12, v[40:41]
	v_lshlrev_b64 v[42:43], 12, v[42:43]
	v_lshlrev_b64 v[44:45], 12, v[44:45]
	v_lshlrev_b64 v[46:47], 12, v[46:47]
	v_lshlrev_b64 v[48:49], 12, v[48:49]
	v_lshlrev_b64 v[50:51], 12, v[50:51]
	v_lshlrev_b64 v[52:53], 12, v[52:53]
	v_lshlrev_b64 v[54:55], 12, v[54:55]
	v_lshlrev_b64 v[56:57], 12, v[56:57]
	v_lshlrev_b64 v[58:59], 12, v[58:59]
	v_lshl_add_u64 v[16:17], v[14:15], 0, v[16:17]
	v_lshlrev_b64 v[18:19], 12, v[18:19]
	v_lshlrev_b64 v[20:21], 12, v[20:21]
	v_lshlrev_b64 v[22:23], 12, v[22:23]
	v_lshlrev_b64 v[30:31], 12, v[30:31]
	v_lshlrev_b64 v[32:33], 12, v[32:33]
	v_lshlrev_b64 v[34:35], 12, v[34:35]
	v_lshlrev_b64 v[36:37], 12, v[36:37]
	v_lshlrev_b64 v[60:61], 12, v[60:61]
	v_lshlrev_b64 v[62:63], 12, v[62:63]
	v_lshlrev_b64 v[64:65], 12, v[64:65]
	v_lshlrev_b64 v[66:67], 12, v[66:67]
	v_lshlrev_b64 v[68:69], 12, v[68:69]
	v_lshlrev_b64 v[70:71], 12, v[70:71]
	v_lshlrev_b64 v[72:73], 12, v[72:73]
	v_lshlrev_b64 v[74:75], 12, v[74:75]
	v_lshlrev_b64 v[76:77], 12, v[76:77]
	v_lshlrev_b64 v[78:79], 12, v[78:79]
	v_lshl_add_u64 v[24:25], v[14:15], 0, v[24:25]
	v_lshl_add_u64 v[26:27], v[14:15], 0, v[26:27]
	v_lshl_add_u64 v[28:29], v[14:15], 0, v[28:29]
	v_lshl_add_u64 v[38:39], v[14:15], 0, v[38:39]
	v_lshl_add_u64 v[40:41], v[14:15], 0, v[40:41]
	v_lshl_add_u64 v[42:43], v[14:15], 0, v[42:43]
	v_lshl_add_u64 v[44:45], v[14:15], 0, v[44:45]
	v_lshl_add_u64 v[46:47], v[14:15], 0, v[46:47]
	v_lshl_add_u64 v[48:49], v[14:15], 0, v[48:49]
	v_lshl_add_u64 v[50:51], v[14:15], 0, v[50:51]
	v_lshl_add_u64 v[52:53], v[14:15], 0, v[52:53]
	v_lshl_add_u64 v[54:55], v[14:15], 0, v[54:55]
	v_lshl_add_u64 v[56:57], v[14:15], 0, v[56:57]
	v_lshl_add_u64 v[58:59], v[14:15], 0, v[58:59]
	v_lshl_add_u64 v[18:19], v[14:15], 0, v[18:19]
	v_lshl_add_u64 v[20:21], v[14:15], 0, v[20:21]
	v_lshl_add_u64 v[22:23], v[14:15], 0, v[22:23]
	v_lshl_add_u64 v[30:31], v[14:15], 0, v[30:31]
	v_lshl_add_u64 v[32:33], v[14:15], 0, v[32:33]
	v_lshl_add_u64 v[34:35], v[14:15], 0, v[34:35]
	v_lshl_add_u64 v[36:37], v[14:15], 0, v[36:37]
	v_lshl_add_u64 v[60:61], v[14:15], 0, v[60:61]
	v_lshl_add_u64 v[62:63], v[14:15], 0, v[62:63]
	v_lshl_add_u64 v[64:65], v[14:15], 0, v[64:65]
	v_lshl_add_u64 v[66:67], v[14:15], 0, v[66:67]
	v_lshl_add_u64 v[68:69], v[14:15], 0, v[68:69]
	v_lshl_add_u64 v[70:71], v[14:15], 0, v[70:71]
	v_lshl_add_u64 v[72:73], v[14:15], 0, v[72:73]
	v_lshl_add_u64 v[74:75], v[14:15], 0, v[74:75]
	v_lshl_add_u64 v[76:77], v[14:15], 0, v[76:77]
	v_lshl_add_u64 v[14:15], v[14:15], 0, v[78:79]
	global_load_dword v78, v[16:17], off nt
	global_load_dword v79, v[18:19], off nt
	global_load_dword v80, v[20:21], off nt
	global_load_dword v81, v[22:23], off nt
	s_nop 0
	global_load_dword v24, v[24:25], off nt
	s_nop 0
	global_load_dword v25, v[26:27], off nt
	s_nop 0
	global_load_dword v26, v[28:29], off nt
	global_load_dword v27, v[30:31], off nt
	s_nop 0
	global_load_dword v28, v[32:33], off nt
	global_load_dword v29, v[34:35], off nt
	global_load_dword v82, v[36:37], off nt
	s_nop 0
	global_load_dword v38, v[38:39], off nt
	s_nop 0
	global_load_dword v39, v[40:41], off nt
	s_nop 0
	global_load_dword v40, v[42:43], off nt
	global_load_dword v41, v[44:45], off nt
	s_nop 0
	global_load_dword v42, v[46:47], off nt
	global_load_dword v43, v[48:49], off nt
	global_load_dword v44, v[50:51], off nt
	global_load_dword v45, v[52:53], off nt
	s_nop 0
	global_load_dword v46, v[54:55], off nt
	global_load_dword v47, v[56:57], off nt
	global_load_dword v48, v[58:59], off nt
	global_load_dword v49, v[60:61], off nt
	global_load_dword v50, v[62:63], off nt
	global_load_dword v51, v[64:65], off nt
	global_load_dword v52, v[66:67], off nt
	global_load_dword v53, v[68:69], off nt
	global_load_dword v54, v[70:71], off nt
	global_load_dword v55, v[72:73], off nt
	global_load_dword v56, v[74:75], off nt
	global_load_dword v57, v[76:77], off nt
	global_load_dword v58, v[14:15], off nt
	s_mul_i32 s7, s1, 0xffd40000
	v_add_u32_e32 v14, s7, v4
	s_waitcnt vmcnt(30)
; #define GAS __attribute__((address_space(1)))
; #define LAS __attribute__((address_space(3)))
; #define LDS_WAIT() asm volatile("s_waitcnt lgkmcnt(0)" ::: "memory")
; __device__ __forceinline__ unsigned pk2(float lo, float hi) { f32x2_p v = {lo, hi}; bf16x2_p b = __builtin_convertvector(v, bf16x2_p); return __builtin_bit_cast(unsigned, b); }
; __device__ __forceinline__ void p0_transpose_item(const float* W0, const float* W1, int K, int Nsrc, int Nd, int mode, bf16* WT, LAS float* scr, int item, int lane) {
;     ...
;     for (int i = 0; i < 32; ++i) { const int kk = 2 * i + (lane >> 5); scr[kk * 33 + (lane & 31)] = okc ? tv[i] : 0.f; }
;     LDS_WAIT(); asm volatile("" ::: "memory");
;     const int c = lane & 7;
; #pragma unroll
;     for (int j = 0; j < 4; ++j) { const int n = (lane >> 3) + 8 * j; const LAS float* s = scr + (8 * c) * 33 + n;
;         v4u o; o.x = pk2(s[0 * 33], s[1 * 33]); o.y = pk2(s[2 * 33], s[3 * 33]); o.z = pk2(s[4 * 33], s[5 * 33]); o.w = pk2(s[6 * 33], s[7 * 33]);
;         *(GAS v4u*)(WT + (size_t)(n0 + n) * K + k0 + 8 * c) = o; }
;     LDS_WAIT(); asm volatile("" ::: "memory");
; }
; __device__ __forceinline__ void p_transpose(const float* W0, const float* W1, int K, int Nsrc, int Nd, int mode, bf16* WT, LAS float* scr, int gw, int NGW, int lane) {
;     const int nitems = (K / 64) * (Nd / 32);
;     for (int it = gw; it < nitems; it += NGW) p0_transpose_item(W0, W1, K, Nsrc, Nd, mode, WT, scr, it, lane);
	ds_write2_b32 v6, v78, v79 offset1:66
	s_waitcnt vmcnt(28)
	ds_write2_b32 v6, v80, v81 offset0:132 offset1:198
	s_waitcnt vmcnt(26)
	ds_write2_b32 v7, v24, v25 offset0:8 offset1:74
	s_waitcnt vmcnt(24)
	ds_write2_b32 v7, v26, v27 offset0:140 offset1:206
	s_waitcnt vmcnt(22)
	ds_write2_b32 v8, v28, v29 offset0:16 offset1:82
	s_waitcnt vmcnt(20)
	ds_write2_b32 v8, v82, v38 offset0:148 offset1:214
	s_waitcnt vmcnt(18)
	ds_write2_b32 v9, v39, v40 offset0:24 offset1:90
	s_waitcnt vmcnt(16)
	ds_write2_b32 v9, v41, v42 offset0:156 offset1:222
	s_waitcnt vmcnt(14)
	ds_write2_b32 v10, v43, v44 offset0:32 offset1:98
	s_waitcnt vmcnt(12)
	ds_write2_b32 v10, v45, v46 offset0:164 offset1:230
	s_waitcnt vmcnt(10)
	ds_write2_b32 v11, v47, v48 offset0:40 offset1:106
	s_waitcnt vmcnt(8)
	ds_write2_b32 v11, v49, v50 offset0:172 offset1:238
	s_waitcnt vmcnt(6)
	ds_write2_b32 v12, v51, v52 offset0:48 offset1:114
	s_waitcnt vmcnt(4)
	ds_write2_b32 v12, v53, v54 offset0:180 offset1:246
	s_waitcnt vmcnt(2)
	ds_write2_b32 v13, v55, v56 offset0:56 offset1:122
	s_waitcnt vmcnt(0)
	ds_write2_b32 v13, v57, v58 offset0:188 offset1:254
	s_ashr_i32 s1, s0, 31
	v_add_u32_e32 v18, 0x5800, v14
	v_add_u32_e32 v20, 0xb000, v14
	v_add_u32_e32 v22, 0x10800, v14
	s_waitcnt lgkmcnt(0)
	v_lshl_add_u64 v[16:17], s[0:1], 1, v[2:3]
	v_ashrrev_i32_e32 v19, 31, v18
	v_ashrrev_i32_e32 v21, 31, v20
	v_ashrrev_i32_e32 v23, 31, v22
	v_lshl_add_u64 v[32:33], v[18:19], 1, v[16:17]
	v_lshl_add_u64 v[34:35], v[20:21], 1, v[16:17]
	v_lshl_add_u64 v[36:37], v[22:23], 1, v[16:17]
	ds_read2_b32 v[18:19], v1 offset0:33 offset1:41
	ds_read2_b32 v[20:21], v1 offset1:8
	ds_read2_b32 v[22:23], v1 offset0:66 offset1:74
	ds_read2_b32 v[24:25], v1 offset0:99 offset1:107
	ds_read2_b32 v[26:27], v1 offset0:132 offset1:140
	ds_read2_b32 v[28:29], v1 offset0:165 offset1:173
	ds_read2_b32 v[38:39], v1 offset0:198 offset1:206
	ds_read2_b32 v[40:41], v1 offset0:231 offset1:239
	ds_read2_b32 v[42:43], v1 offset0:49 offset1:57
	ds_read2_b32 v[44:45], v1 offset0:16 offset1:24
	ds_read2_b32 v[46:47], v1 offset0:82 offset1:90
	ds_read2_b32 v[48:49], v1 offset0:115 offset1:123
	ds_read2_b32 v[50:51], v1 offset0:148 offset1:156
	ds_read2_b32 v[52:53], v1 offset0:181 offset1:189
	ds_read2_b32 v[54:55], v1 offset0:214 offset1:222
	ds_read2_b32 v[56:57], v1 offset0:247 offset1:255
	v_ashrrev_i32_e32 v15, 31, v14
	v_lshl_add_u64 v[30:31], v[14:15], 1, v[16:17]
	s_waitcnt lgkmcnt(14)
	v_cvt_pk_bf16_f32 v14, v20, v18
	s_waitcnt lgkmcnt(12)
	v_cvt_pk_bf16_f32 v15, v22, v24
	s_waitcnt lgkmcnt(10)
	v_cvt_pk_bf16_f32 v16, v26, v28
	s_waitcnt lgkmcnt(8)
	v_cvt_pk_bf16_f32 v17, v38, v40
	v_cvt_pk_bf16_f32 v18, v21, v19
	v_cvt_pk_bf16_f32 v19, v23, v25
	v_cvt_pk_bf16_f32 v20, v27, v29
	v_cvt_pk_bf16_f32 v21, v39, v41
	s_waitcnt lgkmcnt(6)
	v_cvt_pk_bf16_f32 v22, v44, v42
	s_waitcnt lgkmcnt(4)
	v_cvt_pk_bf16_f32 v23, v46, v48
	s_waitcnt lgkmcnt(2)
	v_cvt_pk_bf16_f32 v24, v50, v52
	s_waitcnt lgkmcnt(0)
	v_cvt_pk_bf16_f32 v25, v54, v56
	v_cvt_pk_bf16_f32 v26, v45, v43
	v_cvt_pk_bf16_f32 v27, v47, v49
	v_cvt_pk_bf16_f32 v28, v51, v53
	v_cvt_pk_bf16_f32 v29, v55, v57
	global_store_dwordx4 v[30:31], v[14:17], off
	global_store_dwordx4 v[32:33], v[18:21], off
	global_store_dwordx4 v[34:35], v[22:25], off
	global_store_dwordx4 v[36:37], v[26:29], off
	s_waitcnt lgkmcnt(0)
	s_add_i32 s6, s6, s3
	v_add_u32_e32 v4, s4, v4
	s_cmpk_lt_i32 s6, 0x580
	v_add_u32_e32 v5, s5, v5
	s_cbranch_scc1 .LBB0_112

; #define LAS __attribute__((address_space(3)))
; __device__ __forceinline__ void p0_transpose_item(const float* W0, const float* W1, int K, int Nsrc, int Nd, int mode, bf16* WT, LAS float* scr, int item, int lane) {
;     const int nblk = Nd / 32, kb = item / nblk, nb = item % nblk, k0 = 64 * kb, n0 = 32 * nb;
;     const float* src = W0; int c0 = n0;
;     if (mode == 1) { const int t = n0 / 256, w = n0 % 256; src = (w < 128) ? W0 : W1; c0 = t * 128 + (w & 127); }
;     const bool okc = (c0 + (lane & 31)) < Nsrc; const int cc = okc ? c0 + (lane & 31) : Nsrc - 1;
;     float tv[32];
; #pragma unroll
;     for (int i = 0; i < 32; ++i) { const int kk = 2 * i + (lane >> 5); tv[i] = src[(size_t)(k0 + kk) * Nsrc + cc]; }
; #pragma unroll
;     for (int i = 0; i < 32; ++i) { const int kk = 2 * i + (lane >> 5); scr[kk * 33 + (lane & 31)] = okc ? tv[i] : 0.f; }
.LBB0_115:
	s_mul_hi_i32 s6, s2, 0x88888889
	s_add_i32 s6, s6, s2
	s_lshr_b32 s7, s6, 31
	s_ashr_i32 s6, s6, 6
	s_add_i32 s7, s6, s7
	s_lshl_b32 s6, s7, 6
	s_mulk_i32 s7, 0xf100
	s_add_i32 s10, s7, s0
	v_add_u32_e32 v86, s10, v168
	v_add_u32_e32 v14, s10, v170
	v_min_i32_e32 v16, 0xe0f, v86
	v_or_b32_e32 v24, s6, v169
	s_ashr_i32 s7, s6, 31
	v_ashrrev_i32_e32 v15, 31, v14
	v_add_u32_e32 v18, 8, v14
	v_add_u32_e32 v20, 16, v14
	v_add_u32_e32 v22, 24, v14
	v_ashrrev_i32_e32 v17, 31, v16
	v_or_b32_e32 v25, 2, v24
	v_or_b32_e32 v26, 4, v24
	v_or_b32_e32 v30, 6, v24
	v_or_b32_e32 v32, 8, v24
	v_or_b32_e32 v34, 10, v24
	v_or_b32_e32 v36, 12, v24
	v_or_b32_e32 v38, 14, v24
	v_or_b32_e32 v40, 16, v24
	v_or_b32_e32 v42, 18, v24
	v_or_b32_e32 v44, 20, v24
	v_or_b32_e32 v46, 22, v24
	v_or_b32_e32 v48, 24, v24
	v_or_b32_e32 v50, 26, v24
	v_or_b32_e32 v52, 28, v24
	v_or_b32_e32 v54, 30, v24
	v_or_b32_e32 v56, 32, v24
	v_or_b32_e32 v58, 34, v24
	v_or_b32_e32 v60, 36, v24
	v_or_b32_e32 v62, 38, v24
	v_or_b32_e32 v64, 40, v24
	v_or_b32_e32 v66, 42, v24
	v_or_b32_e32 v68, 44, v24
	v_or_b32_e32 v70, 46, v24
	v_or_b32_e32 v72, 48, v24
	v_or_b32_e32 v74, 50, v24
	v_or_b32_e32 v76, 52, v24
	v_or_b32_e32 v78, 54, v24
	v_or_b32_e32 v80, 56, v24
	v_or_b32_e32 v82, 58, v24
	v_or_b32_e32 v84, 60, v24
	v_or_b32_e32 v87, 62, v24
	v_lshl_add_u64 v[12:13], s[6:7], 1, v[2:3]
	v_lshlrev_b64 v[14:15], 11, v[14:15]
	v_ashrrev_i32_e32 v19, 31, v18
	v_ashrrev_i32_e32 v21, 31, v20
	v_ashrrev_i32_e32 v23, 31, v22
	v_lshl_add_u64 v[16:17], v[16:17], 2, s[20:21]
	v_lshl_add_u64 v[28:29], v[12:13], 0, v[14:15]
	v_lshlrev_b64 v[14:15], 11, v[18:19]
	v_lshlrev_b64 v[18:19], 11, v[20:21]
	v_lshlrev_b64 v[20:21], 11, v[22:23]
	v_mad_i64_i32 v[22:23], s[6:7], v24, s4, v[16:17]
	v_mad_i64_i32 v[24:25], s[6:7], v25, s4, v[16:17]
	v_mad_i64_i32 v[26:27], s[6:7], v26, s4, v[16:17]
	v_mad_i64_i32 v[30:31], s[6:7], v30, s4, v[16:17]
	v_mad_i64_i32 v[32:33], s[6:7], v32, s4, v[16:17]
	v_mad_i64_i32 v[34:35], s[6:7], v34, s4, v[16:17]
	v_mad_i64_i32 v[36:37], s[6:7], v36, s4, v[16:17]
	v_mad_i64_i32 v[38:39], s[6:7], v38, s4, v[16:17]
	v_mad_i64_i32 v[40:41], s[6:7], v40, s4, v[16:17]
	v_mad_i64_i32 v[42:43], s[6:7], v42, s4, v[16:17]
	v_mad_i64_i32 v[44:45], s[6:7], v44, s4, v[16:17]
	v_mad_i64_i32 v[46:47], s[6:7], v46, s4, v[16:17]
	v_mad_i64_i32 v[48:49], s[6:7], v48, s4, v[16:17]
	v_mad_i64_i32 v[50:51], s[6:7], v50, s4, v[16:17]
	v_mad_i64_i32 v[52:53], s[6:7], v52, s4, v[16:17]
	v_mad_i64_i32 v[54:55], s[6:7], v54, s4, v[16:17]
	v_mad_i64_i32 v[56:57], s[6:7], v56, s4, v[16:17]
	v_mad_i64_i32 v[58:59], s[6:7], v58, s4, v[16:17]
	v_mad_i64_i32 v[60:61], s[6:7], v60, s4, v[16:17]
	v_mad_i64_i32 v[62:63], s[6:7], v62, s4, v[16:17]
	v_mad_i64_i32 v[64:65], s[6:7], v64, s4, v[16:17]
	v_mad_i64_i32 v[66:67], s[6:7], v66, s4, v[16:17]
	v_mad_i64_i32 v[68:69], s[6:7], v68, s4, v[16:17]
	v_mad_i64_i32 v[70:71], s[6:7], v70, s4, v[16:17]
	v_mad_i64_i32 v[72:73], s[6:7], v72, s4, v[16:17]
	v_mad_i64_i32 v[74:75], s[6:7], v74, s4, v[16:17]
	v_mad_i64_i32 v[76:77], s[6:7], v76, s4, v[16:17]
	v_mad_i64_i32 v[78:79], s[6:7], v78, s4, v[16:17]
	v_mad_i64_i32 v[80:81], s[6:7], v80, s4, v[16:17]
	v_mad_i64_i32 v[82:83], s[6:7], v82, s4, v[16:17]
	v_mad_i64_i32 v[84:85], s[6:7], v84, s4, v[16:17]
	v_mad_i64_i32 v[16:17], s[6:7], v87, s4, v[16:17]
	global_load_dword v22, v[22:23], off nt
	s_nop 0
	global_load_dword v23, v[24:25], off nt
	s_nop 0
	global_load_dword v24, v[26:27], off nt
	global_load_dword v25, v[30:31], off nt
	s_nop 0
	global_load_dword v26, v[32:33], off nt
	global_load_dword v27, v[34:35], off nt
	s_nop 0
	global_load_dword v36, v[36:37], off nt
	s_nop 0
	global_load_dword v37, v[38:39], off nt
	s_nop 0
	global_load_dword v38, v[40:41], off nt
	global_load_dword v39, v[42:43], off nt
	s_nop 0
	global_load_dword v40, v[44:45], off nt
	global_load_dword v41, v[46:47], off nt
	global_load_dword v42, v[48:49], off nt
	global_load_dword v43, v[50:51], off nt
	s_nop 0
	global_load_dword v44, v[52:53], off nt
	global_load_dword v45, v[54:55], off nt
	global_load_dword v46, v[56:57], off nt
	global_load_dword v47, v[58:59], off nt
	global_load_dword v48, v[60:61], off nt
	global_load_dword v49, v[62:63], off nt
	global_load_dword v50, v[64:65], off nt
	global_load_dword v51, v[66:67], off nt
	global_load_dword v52, v[68:69], off nt
	global_load_dword v53, v[70:71], off nt
	global_load_dword v54, v[72:73], off nt
	global_load_dword v55, v[74:75], off nt
	global_load_dword v56, v[76:77], off nt
	global_load_dword v57, v[78:79], off nt
	global_load_dword v58, v[80:81], off nt
	global_load_dword v59, v[82:83], off nt
	global_load_dword v60, v[84:85], off nt
	s_nop 0
	global_load_dword v16, v[16:17], off nt
	v_cmp_gt_i32_e32 vcc, s5, v86
	v_lshl_add_u64 v[30:31], v[12:13], 0, v[14:15]
	v_lshl_add_u64 v[32:33], v[12:13], 0, v[18:19]
	v_lshl_add_u64 v[34:35], v[12:13], 0, v[20:21]
	s_add_i32 s2, s2, s3
	s_add_i32 s0, s0, s1
	s_cmpk_lt_i32 s2, 0x780
	s_waitcnt vmcnt(31)
; #define GAS __attribute__((address_space(1)))
; #define LAS __attribute__((address_space(3)))
; #define LDS_WAIT() asm volatile("s_waitcnt lgkmcnt(0)" ::: "memory")
; __device__ __forceinline__ unsigned pk2(float lo, float hi) { f32x2_p v = {lo, hi}; bf16x2_p b = __builtin_convertvector(v, bf16x2_p); return __builtin_bit_cast(unsigned, b); }
; __device__ __forceinline__ void p0_transpose_item(const float* W0, const float* W1, int K, int Nsrc, int Nd, int mode, bf16* WT, LAS float* scr, int item, int lane) {
;     ...
;     for (int i = 0; i < 32; ++i) { const int kk = 2 * i + (lane >> 5); tv[i] = src[(size_t)(k0 + kk) * Nsrc + cc]; }
; #pragma unroll
;     for (int i = 0; i < 32; ++i) { const int kk = 2 * i + (lane >> 5); scr[kk * 33 + (lane & 31)] = okc ? tv[i] : 0.f; }
;     LDS_WAIT(); asm volatile("" ::: "memory");
;     const int c = lane & 7;
; #pragma unroll
;     for (int j = 0; j < 4; ++j) { const int n = (lane >> 3) + 8 * j; const LAS float* s = scr + (8 * c) * 33 + n;
;         v4u o; o.x = pk2(s[0 * 33], s[1 * 33]); o.y = pk2(s[2 * 33], s[3 * 33]); o.z = pk2(s[4 * 33], s[5 * 33]); o.w = pk2(s[6 * 33], s[7 * 33]);
;         *(GAS v4u*)(WT + (size_t)(n0 + n) * K + k0 + 8 * c) = o; }
;     LDS_WAIT(); asm volatile("" ::: "memory");
	v_cndmask_b32_e32 v12, 0, v22, vcc
	s_waitcnt vmcnt(30)
	v_cndmask_b32_e32 v13, 0, v23, vcc
	s_waitcnt vmcnt(29)
	v_cndmask_b32_e32 v14, 0, v24, vcc
	s_waitcnt vmcnt(28)
	v_cndmask_b32_e32 v15, 0, v25, vcc
	s_waitcnt vmcnt(27)
	v_cndmask_b32_e32 v17, 0, v26, vcc
	s_waitcnt vmcnt(26)
	v_cndmask_b32_e32 v18, 0, v27, vcc
	s_waitcnt vmcnt(25)
	v_cndmask_b32_e32 v19, 0, v36, vcc
	s_waitcnt vmcnt(24)
	v_cndmask_b32_e32 v20, 0, v37, vcc
	s_waitcnt vmcnt(23)
	v_cndmask_b32_e32 v21, 0, v38, vcc
	s_waitcnt vmcnt(22)
	v_cndmask_b32_e32 v22, 0, v39, vcc
	s_waitcnt vmcnt(21)
	v_cndmask_b32_e32 v23, 0, v40, vcc
	s_waitcnt vmcnt(20)
	v_cndmask_b32_e32 v24, 0, v41, vcc
	s_waitcnt vmcnt(19)
	v_cndmask_b32_e32 v25, 0, v42, vcc
	s_waitcnt vmcnt(18)
	v_cndmask_b32_e32 v26, 0, v43, vcc
	s_waitcnt vmcnt(17)
	v_cndmask_b32_e32 v27, 0, v44, vcc
	s_waitcnt vmcnt(16)
	v_cndmask_b32_e32 v36, 0, v45, vcc
	s_waitcnt vmcnt(15)
	v_cndmask_b32_e32 v37, 0, v46, vcc
	s_waitcnt vmcnt(14)
	v_cndmask_b32_e32 v38, 0, v47, vcc
	s_waitcnt vmcnt(13)
	v_cndmask_b32_e32 v39, 0, v48, vcc
	s_waitcnt vmcnt(12)
	v_cndmask_b32_e32 v40, 0, v49, vcc
	s_waitcnt vmcnt(11)
	v_cndmask_b32_e32 v41, 0, v50, vcc
	s_waitcnt vmcnt(10)
	v_cndmask_b32_e32 v42, 0, v51, vcc
	s_waitcnt vmcnt(9)
	v_cndmask_b32_e32 v43, 0, v52, vcc
	s_waitcnt vmcnt(8)
	v_cndmask_b32_e32 v44, 0, v53, vcc
	s_waitcnt vmcnt(7)
	v_cndmask_b32_e32 v45, 0, v54, vcc
	s_waitcnt vmcnt(6)
	v_cndmask_b32_e32 v46, 0, v55, vcc
	s_waitcnt vmcnt(5)
	v_cndmask_b32_e32 v47, 0, v56, vcc
	s_waitcnt vmcnt(4)
	v_cndmask_b32_e32 v48, 0, v57, vcc
	s_waitcnt vmcnt(3)
	v_cndmask_b32_e32 v49, 0, v58, vcc
	s_waitcnt vmcnt(2)
	v_cndmask_b32_e32 v50, 0, v59, vcc
	s_waitcnt vmcnt(1)
	v_cndmask_b32_e32 v51, 0, v60, vcc
	s_waitcnt vmcnt(0)
	v_cndmask_b32_e32 v16, 0, v16, vcc
	ds_write2_b32 v4, v12, v13 offset1:66
	ds_write2_b32 v4, v14, v15 offset0:132 offset1:198
	ds_write2_b32 v5, v17, v18 offset0:8 offset1:74
	ds_write2_b32 v5, v19, v20 offset0:140 offset1:206
	ds_write2_b32 v6, v21, v22 offset0:16 offset1:82
	ds_write2_b32 v6, v23, v24 offset0:148 offset1:214
	ds_write2_b32 v7, v25, v26 offset0:24 offset1:90
	ds_write2_b32 v7, v27, v36 offset0:156 offset1:222
	ds_write2_b32 v8, v37, v38 offset0:32 offset1:98
	ds_write2_b32 v8, v39, v40 offset0:164 offset1:230
	ds_write2_b32 v9, v41, v42 offset0:40 offset1:106
	ds_write2_b32 v9, v43, v44 offset0:172 offset1:238
	ds_write2_b32 v10, v45, v46 offset0:48 offset1:114
	ds_write2_b32 v10, v47, v48 offset0:180 offset1:246
	ds_write2_b32 v11, v49, v50 offset0:56 offset1:122
	ds_write2_b32 v11, v51, v16 offset0:188 offset1:254
	s_waitcnt lgkmcnt(0)
	ds_read2_b32 v[16:17], v1 offset0:33 offset1:41
	ds_read2_b32 v[18:19], v1 offset1:8
	ds_read2_b32 v[20:21], v1 offset0:66 offset1:74
	ds_read2_b32 v[22:23], v1 offset0:99 offset1:107
	ds_read2_b32 v[24:25], v1 offset0:132 offset1:140
	ds_read2_b32 v[26:27], v1 offset0:165 offset1:173
	ds_read2_b32 v[36:37], v1 offset0:198 offset1:206
	ds_read2_b32 v[38:39], v1 offset0:231 offset1:239
	ds_read2_b32 v[40:41], v1 offset0:49 offset1:57
	ds_read2_b32 v[42:43], v1 offset0:16 offset1:24
	ds_read2_b32 v[44:45], v1 offset0:82 offset1:90
	ds_read2_b32 v[46:47], v1 offset0:115 offset1:123
	ds_read2_b32 v[48:49], v1 offset0:148 offset1:156
	ds_read2_b32 v[50:51], v1 offset0:181 offset1:189
	ds_read2_b32 v[52:53], v1 offset0:214 offset1:222
	ds_read2_b32 v[54:55], v1 offset0:247 offset1:255
	s_waitcnt lgkmcnt(14)
	v_cvt_pk_bf16_f32 v12, v18, v16
	s_waitcnt lgkmcnt(12)
	v_cvt_pk_bf16_f32 v13, v20, v22
	s_waitcnt lgkmcnt(10)
	v_cvt_pk_bf16_f32 v14, v24, v26
	s_waitcnt lgkmcnt(8)
	v_cvt_pk_bf16_f32 v15, v36, v38
	v_cvt_pk_bf16_f32 v16, v19, v17
	v_cvt_pk_bf16_f32 v17, v21, v23
	v_cvt_pk_bf16_f32 v18, v25, v27
	v_cvt_pk_bf16_f32 v19, v37, v39
	s_waitcnt lgkmcnt(6)
	v_cvt_pk_bf16_f32 v20, v42, v40
	s_waitcnt lgkmcnt(4)
	v_cvt_pk_bf16_f32 v21, v44, v46
	s_waitcnt lgkmcnt(2)
	v_cvt_pk_bf16_f32 v22, v48, v50
	s_waitcnt lgkmcnt(0)
	v_cvt_pk_bf16_f32 v23, v52, v54
	v_cvt_pk_bf16_f32 v24, v43, v41
	v_cvt_pk_bf16_f32 v25, v45, v47
	v_cvt_pk_bf16_f32 v26, v49, v51
	v_cvt_pk_bf16_f32 v27, v53, v55
	global_store_dwordx4 v[28:29], v[12:15], off
	global_store_dwordx4 v[30:31], v[16:19], off
	global_store_dwordx4 v[32:33], v[20:23], off
	global_store_dwordx4 v[34:35], v[24:27], off
	s_waitcnt lgkmcnt(0)
	s_cbranch_scc1 .LBB0_115

; __device__ __forceinline__ void p0_transpose_item(const float* W0, const float* W1, int K, int Nsrc, int Nd, int mode, bf16* WT, LAS float* scr, int item, int lane) {
;     const int nblk = Nd / 32, kb = item / nblk, nb = item % nblk, k0 = 64 * kb, n0 = 32 * nb;
;     const float* src = W0; int c0 = n0;
;     if (mode == 1) { const int t = n0 / 256, w = n0 % 256; src = (w < 128) ? W0 : W1; c0 = t * 128 + (w & 127); }
;     const bool okc = (c0 + (lane & 31)) < Nsrc; const int cc = okc ? c0 + (lane & 31) : Nsrc - 1;
;     float tv[32];
; #pragma unroll
;     for (int i = 0; i < 32; ++i) { const int kk = 2 * i + (lane >> 5); tv[i] = src[(size_t)(k0 + kk) * Nsrc + cc]; }
.LBB0_952:
	s_ashr_i32 s0, s2, 31
	s_lshr_b32 s0, s0, 27
	s_add_i32 s0, s2, s0
	s_ashr_i32 s1, s0, 5
	s_lshl_b32 s0, s1, 6
	s_lshl_b32 s6, s1, 10
	v_or_b32_e32 v16, s0, v169
	v_subrev_u32_e32 v14, s6, v5
	v_or_b32_e32 v24, 8, v16
	v_or_b32_e32 v26, 10, v16
	v_or_b32_e32 v28, 12, v16
	v_or_b32_e32 v38, 22, v16
	v_or_b32_e32 v40, 24, v16
	v_or_b32_e32 v42, 26, v16
	v_or_b32_e32 v44, 28, v16
	v_or_b32_e32 v46, 30, v16
	v_or_b32_e32 v48, 32, v16
	v_or_b32_e32 v50, 34, v16
	v_or_b32_e32 v52, 36, v16
	v_or_b32_e32 v54, 38, v16
	v_or_b32_e32 v56, 40, v16
	v_or_b32_e32 v58, 42, v16
	v_ashrrev_i32_e32 v15, 31, v14
	v_ashrrev_i32_e32 v17, 31, v16
	v_or_b32_e32 v18, 2, v16
	v_or_b32_e32 v20, 4, v16
	v_or_b32_e32 v22, 6, v16
	v_or_b32_e32 v30, 14, v16
	v_or_b32_e32 v32, 16, v16
	v_or_b32_e32 v34, 18, v16
	v_or_b32_e32 v36, 20, v16
	v_or_b32_e32 v60, 44, v16
	v_or_b32_e32 v62, 46, v16
	v_or_b32_e32 v64, 48, v16
	v_or_b32_e32 v66, 50, v16
	v_or_b32_e32 v68, 52, v16
	v_or_b32_e32 v70, 54, v16
	v_or_b32_e32 v72, 56, v16
	v_or_b32_e32 v74, 58, v16
	v_or_b32_e32 v76, 60, v16
	v_or_b32_e32 v78, 62, v16
	v_ashrrev_i32_e32 v25, 31, v24
	v_ashrrev_i32_e32 v27, 31, v26
	v_ashrrev_i32_e32 v29, 31, v28
	v_ashrrev_i32_e32 v39, 31, v38
	v_ashrrev_i32_e32 v41, 31, v40
	v_ashrrev_i32_e32 v43, 31, v42
	v_ashrrev_i32_e32 v45, 31, v44
	v_ashrrev_i32_e32 v47, 31, v46
	v_ashrrev_i32_e32 v49, 31, v48
	v_ashrrev_i32_e32 v51, 31, v50
	v_ashrrev_i32_e32 v53, 31, v52
	v_ashrrev_i32_e32 v55, 31, v54
	v_ashrrev_i32_e32 v57, 31, v56
	v_ashrrev_i32_e32 v59, 31, v58
	v_lshl_add_u64 v[14:15], v[14:15], 2, s[20:21]
	v_lshlrev_b64 v[16:17], 12, v[16:17]
	v_ashrrev_i32_e32 v19, 31, v18
	v_ashrrev_i32_e32 v21, 31, v20
	v_ashrrev_i32_e32 v23, 31, v22
	v_ashrrev_i32_e32 v31, 31, v30
	v_ashrrev_i32_e32 v33, 31, v32
	v_ashrrev_i32_e32 v35, 31, v34
	v_ashrrev_i32_e32 v37, 31, v36
	v_ashrrev_i32_e32 v61, 31, v60
	v_ashrrev_i32_e32 v63, 31, v62
	v_ashrrev_i32_e32 v65, 31, v64
	v_ashrrev_i32_e32 v67, 31, v66
	v_ashrrev_i32_e32 v69, 31, v68
	v_ashrrev_i32_e32 v71, 31, v70
	v_ashrrev_i32_e32 v73, 31, v72
	v_ashrrev_i32_e32 v75, 31, v74
	v_ashrrev_i32_e32 v77, 31, v76
	v_ashrrev_i32_e32 v79, 31, v78
	v_lshlrev_b64 v[24:25], 12, v[24:25]
	v_lshlrev_b64 v[26:27], 12, v[26:27]
	v_lshlrev_b64 v[28:29], 12, v[28:29]
	v_lshlrev_b64 v[38:39], 12, v[38:39]
	v_lshlrev_b64 v[40:41], 12, v[40:41]
	v_lshlrev_b64 v[42:43], 12, v[42:43]
	v_lshlrev_b64 v[44:45], 12, v[44:45]
	v_lshlrev_b64 v[46:47], 12, v[46:47]
	v_lshlrev_b64 v[48:49], 12, v[48:49]
	v_lshlrev_b64 v[50:51], 12, v[50:51]
	v_lshlrev_b64 v[52:53], 12, v[52:53]
	v_lshlrev_b64 v[54:55], 12, v[54:55]
	v_lshlrev_b64 v[56:57], 12, v[56:57]
	v_lshlrev_b64 v[58:59], 12, v[58:59]
	v_lshl_add_u64 v[16:17], v[14:15], 0, v[16:17]
	v_lshlrev_b64 v[18:19], 12, v[18:19]
	v_lshlrev_b64 v[20:21], 12, v[20:21]
	v_lshlrev_b64 v[22:23], 12, v[22:23]
	v_lshlrev_b64 v[30:31], 12, v[30:31]
	v_lshlrev_b64 v[32:33], 12, v[32:33]
	v_lshlrev_b64 v[34:35], 12, v[34:35]
	v_lshlrev_b64 v[36:37], 12, v[36:37]
	v_lshlrev_b64 v[60:61], 12, v[60:61]
	v_lshlrev_b64 v[62:63], 12, v[62:63]
	v_lshlrev_b64 v[64:65], 12, v[64:65]
	v_lshlrev_b64 v[66:67], 12, v[66:67]
	v_lshlrev_b64 v[68:69], 12, v[68:69]
	v_lshlrev_b64 v[70:71], 12, v[70:71]
	v_lshlrev_b64 v[72:73], 12, v[72:73]
	v_lshlrev_b64 v[74:75], 12, v[74:75]
	v_lshlrev_b64 v[76:77], 12, v[76:77]
	v_lshlrev_b64 v[78:79], 12, v[78:79]
	v_lshl_add_u64 v[24:25], v[14:15], 0, v[24:25]
	v_lshl_add_u64 v[26:27], v[14:15], 0, v[26:27]
	v_lshl_add_u64 v[28:29], v[14:15], 0, v[28:29]
	v_lshl_add_u64 v[38:39], v[14:15], 0, v[38:39]
	v_lshl_add_u64 v[40:41], v[14:15], 0, v[40:41]
	v_lshl_add_u64 v[42:43], v[14:15], 0, v[42:43]
	v_lshl_add_u64 v[44:45], v[14:15], 0, v[44:45]
	v_lshl_add_u64 v[46:47], v[14:15], 0, v[46:47]
	v_lshl_add_u64 v[48:49], v[14:15], 0, v[48:49]
	v_lshl_add_u64 v[50:51], v[14:15], 0, v[50:51]
	v_lshl_add_u64 v[52:53], v[14:15], 0, v[52:53]
	v_lshl_add_u64 v[54:55], v[14:15], 0, v[54:55]
	v_lshl_add_u64 v[56:57], v[14:15], 0, v[56:57]
	v_lshl_add_u64 v[58:59], v[14:15], 0, v[58:59]
	v_lshl_add_u64 v[18:19], v[14:15], 0, v[18:19]
	v_lshl_add_u64 v[20:21], v[14:15], 0, v[20:21]
	v_lshl_add_u64 v[22:23], v[14:15], 0, v[22:23]
	v_lshl_add_u64 v[30:31], v[14:15], 0, v[30:31]
	v_lshl_add_u64 v[32:33], v[14:15], 0, v[32:33]
	v_lshl_add_u64 v[34:35], v[14:15], 0, v[34:35]
	v_lshl_add_u64 v[36:37], v[14:15], 0, v[36:37]
	v_lshl_add_u64 v[60:61], v[14:15], 0, v[60:61]
	v_lshl_add_u64 v[62:63], v[14:15], 0, v[62:63]
	v_lshl_add_u64 v[64:65], v[14:15], 0, v[64:65]
	v_lshl_add_u64 v[66:67], v[14:15], 0, v[66:67]
	v_lshl_add_u64 v[68:69], v[14:15], 0, v[68:69]
	v_lshl_add_u64 v[70:71], v[14:15], 0, v[70:71]
	v_lshl_add_u64 v[72:73], v[14:15], 0, v[72:73]
	v_lshl_add_u64 v[74:75], v[14:15], 0, v[74:75]
	v_lshl_add_u64 v[76:77], v[14:15], 0, v[76:77]
	v_lshl_add_u64 v[14:15], v[14:15], 0, v[78:79]
	global_load_dword v78, v[16:17], off nt
	global_load_dword v79, v[18:19], off nt
	global_load_dword v80, v[20:21], off nt
	global_load_dword v81, v[22:23], off nt
	s_nop 0
	global_load_dword v24, v[24:25], off nt
	s_nop 0
	global_load_dword v25, v[26:27], off nt
	s_nop 0
	global_load_dword v26, v[28:29], off nt
	global_load_dword v27, v[30:31], off nt
	s_nop 0
	global_load_dword v28, v[32:33], off nt
	global_load_dword v29, v[34:35], off nt
	global_load_dword v82, v[36:37], off nt
	s_nop 0
	global_load_dword v38, v[38:39], off nt
	s_nop 0
	global_load_dword v39, v[40:41], off nt
	s_nop 0
	global_load_dword v40, v[42:43], off nt
	global_load_dword v41, v[44:45], off nt
	s_nop 0
	global_load_dword v42, v[46:47], off nt
	global_load_dword v43, v[48:49], off nt
	global_load_dword v44, v[50:51], off nt
	global_load_dword v45, v[52:53], off nt
	s_nop 0
	global_load_dword v46, v[54:55], off nt
	global_load_dword v47, v[56:57], off nt
	global_load_dword v48, v[58:59], off nt
	global_load_dword v49, v[60:61], off nt
	global_load_dword v50, v[62:63], off nt
	global_load_dword v51, v[64:65], off nt
	global_load_dword v52, v[66:67], off nt
	global_load_dword v53, v[68:69], off nt
	global_load_dword v54, v[70:71], off nt
	global_load_dword v55, v[72:73], off nt
	global_load_dword v56, v[74:75], off nt
	global_load_dword v57, v[76:77], off nt
	global_load_dword v58, v[14:15], off nt
	s_mul_i32 s6, s1, 0xffd40000
	v_add_u32_e32 v14, s6, v4
	s_waitcnt vmcnt(0)
; #define GAS __attribute__((address_space(1)))
; #define LAS __attribute__((address_space(3)))
; #define LDS_WAIT() asm volatile("s_waitcnt lgkmcnt(0)" ::: "memory")
; __device__ __forceinline__ unsigned pk2(float lo, float hi) { f32x2_p v = {lo, hi}; bf16x2_p b = __builtin_convertvector(v, bf16x2_p); return __builtin_bit_cast(unsigned, b); }
; __device__ __forceinline__ void p0_transpose_item(const float* W0, const float* W1, int K, int Nsrc, int Nd, int mode, bf16* WT, LAS float* scr, int item, int lane) {
;     ...
;     for (int i = 0; i < 32; ++i) { const int kk = 2 * i + (lane >> 5); scr[kk * 33 + (lane & 31)] = okc ? tv[i] : 0.f; }
;     LDS_WAIT(); asm volatile("" ::: "memory");
;     const int c = lane & 7;
; #pragma unroll
;     for (int j = 0; j < 4; ++j) { const int n = (lane >> 3) + 8 * j; const LAS float* s = scr + (8 * c) * 33 + n;
;         v4u o; o.x = pk2(s[0 * 33], s[1 * 33]); o.y = pk2(s[2 * 33], s[3 * 33]); o.z = pk2(s[4 * 33], s[5 * 33]); o.w = pk2(s[6 * 33], s[7 * 33]);
;         *(GAS v4u*)(WT + (size_t)(n0 + n) * K + k0 + 8 * c) = o; }
;     LDS_WAIT(); asm volatile("" ::: "memory");
; }
; __device__ __forceinline__ void p_transpose(const float* W0, const float* W1, int K, int Nsrc, int Nd, int mode, bf16* WT, LAS float* scr, int gw, int NGW, int lane) {
;     const int nitems = (K / 64) * (Nd / 32);
;     for (int it = gw; it < nitems; it += NGW) p0_transpose_item(W0, W1, K, Nsrc, Nd, mode, WT, scr, it, lane);
	ds_write2_b32 v6, v78, v79 offset1:66
	ds_write2_b32 v6, v80, v81 offset0:132 offset1:198
	ds_write2_b32 v7, v24, v25 offset0:8 offset1:74
	ds_write2_b32 v7, v26, v27 offset0:140 offset1:206
	ds_write2_b32 v8, v28, v29 offset0:16 offset1:82
	ds_write2_b32 v8, v82, v38 offset0:148 offset1:214
	ds_write2_b32 v9, v39, v40 offset0:24 offset1:90
	ds_write2_b32 v9, v41, v42 offset0:156 offset1:222
	ds_write2_b32 v10, v43, v44 offset0:32 offset1:98
	ds_write2_b32 v10, v45, v46 offset0:164 offset1:230
	ds_write2_b32 v11, v47, v48 offset0:40 offset1:106
	ds_write2_b32 v11, v49, v50 offset0:172 offset1:238
	ds_write2_b32 v12, v51, v52 offset0:48 offset1:114
	ds_write2_b32 v12, v53, v54 offset0:180 offset1:246
	ds_write2_b32 v13, v55, v56 offset0:56 offset1:122
	ds_write2_b32 v13, v57, v58 offset0:188 offset1:254
	s_ashr_i32 s1, s0, 31
	v_add_u32_e32 v18, 0x5800, v14
	v_add_u32_e32 v20, 0xb000, v14
	v_add_u32_e32 v22, 0x10800, v14
	s_waitcnt lgkmcnt(0)
	v_lshl_add_u64 v[16:17], s[0:1], 1, v[2:3]
	v_ashrrev_i32_e32 v19, 31, v18
	v_ashrrev_i32_e32 v21, 31, v20
	v_ashrrev_i32_e32 v23, 31, v22
	v_lshl_add_u64 v[32:33], v[18:19], 1, v[16:17]
	v_lshl_add_u64 v[34:35], v[20:21], 1, v[16:17]
	v_lshl_add_u64 v[36:37], v[22:23], 1, v[16:17]
	ds_read2_b32 v[18:19], v1 offset0:33 offset1:41
	ds_read2_b32 v[20:21], v1 offset1:8
	ds_read2_b32 v[22:23], v1 offset0:66 offset1:74
	ds_read2_b32 v[24:25], v1 offset0:99 offset1:107
	ds_read2_b32 v[26:27], v1 offset0:132 offset1:140
	ds_read2_b32 v[28:29], v1 offset0:165 offset1:173
	ds_read2_b32 v[38:39], v1 offset0:198 offset1:206
	ds_read2_b32 v[40:41], v1 offset0:231 offset1:239
	ds_read2_b32 v[42:43], v1 offset0:49 offset1:57
	ds_read2_b32 v[44:45], v1 offset0:16 offset1:24
	ds_read2_b32 v[46:47], v1 offset0:82 offset1:90
	ds_read2_b32 v[48:49], v1 offset0:115 offset1:123
	ds_read2_b32 v[50:51], v1 offset0:148 offset1:156
	ds_read2_b32 v[52:53], v1 offset0:181 offset1:189
	ds_read2_b32 v[54:55], v1 offset0:214 offset1:222
	ds_read2_b32 v[56:57], v1 offset0:247 offset1:255
	v_ashrrev_i32_e32 v15, 31, v14
	v_lshl_add_u64 v[30:31], v[14:15], 1, v[16:17]
	s_waitcnt lgkmcnt(14)
	v_cvt_pk_bf16_f32 v14, v20, v18
	s_waitcnt lgkmcnt(12)
	v_cvt_pk_bf16_f32 v15, v22, v24
	s_waitcnt lgkmcnt(10)
	v_cvt_pk_bf16_f32 v16, v26, v28
	s_waitcnt lgkmcnt(8)
	v_cvt_pk_bf16_f32 v17, v38, v40
	v_cvt_pk_bf16_f32 v18, v21, v19
	v_cvt_pk_bf16_f32 v19, v23, v25
	v_cvt_pk_bf16_f32 v20, v27, v29
	v_cvt_pk_bf16_f32 v21, v39, v41
	s_waitcnt lgkmcnt(6)
	v_cvt_pk_bf16_f32 v22, v44, v42
	s_waitcnt lgkmcnt(4)
	v_cvt_pk_bf16_f32 v23, v46, v48
	s_waitcnt lgkmcnt(2)
	v_cvt_pk_bf16_f32 v24, v50, v52
	s_waitcnt lgkmcnt(0)
	v_cvt_pk_bf16_f32 v25, v54, v56
	v_cvt_pk_bf16_f32 v26, v45, v43
	v_cvt_pk_bf16_f32 v27, v47, v49
	v_cvt_pk_bf16_f32 v28, v51, v53
	v_cvt_pk_bf16_f32 v29, v55, v57
	global_store_dwordx4 v[30:31], v[14:17], off
	global_store_dwordx4 v[32:33], v[18:21], off
	global_store_dwordx4 v[34:35], v[22:25], off
	global_store_dwordx4 v[36:37], v[26:29], off
	s_waitcnt lgkmcnt(0)
	s_add_i32 s2, s2, s3
	v_add_u32_e32 v4, s4, v4
	s_cmpk_lt_i32 s2, 0x580
	v_add_u32_e32 v5, s5, v5
	s_cbranch_scc1 .LBB0_952

; __device__ __forceinline__ void p_gdn_prep(const float* P, const float* sconv, const float* convw, const float* alog, const float* dtb, float* GQ, float* GK, float* GV, float* GG, float* GB, int m0, int vcu, int G, int h, int lane) {
;     ...
;             const float sp = (aa > 20.f) ? aa : log1pf(__expf(aa));
;             GG[(size_t)m * NH + h] = -__expf(alog[h]) * sp; }
.LBB0_1007:
	global_load_dword v40, v48, s[34:35] nt
	v_readlane_b32 s0, v244, 35
	s_add_u32 s0, s0, s2
	v_readlane_b32 s1, v244, 36
	s_addc_u32 s1, s1, s3
	s_waitcnt vmcnt(0)
	v_mul_f32_e32 v40, 0x3fb8aa3b, v40
	v_exp_f32_e32 v40, v40
	s_nop 0
	v_mul_f32_e64 v39, v39, -v40
	global_store_dword v48, v39, s[0:1]

; __device__ __forceinline__ void p_gdn_prep(const float* P, const float* sconv, const float* convw, const float* alog, const float* dtb, float* GQ, float* GK, float* GV, float* GG, float* GB, int m0, int vcu, int G, int h, int lane) {
;     ...
;         for (int part = 0; part < 3; ++part) {
;             const int c = part * 512 + h * 64 + lane; float acc = 0.f;
; #pragma unroll
;             for (int j = 0; j < 4; ++j) { const int tt = t - 3 + j;
;                 const float* src = (tt >= 0) ? P + (size_t)(m - t + tt) * NINP + C_GQKV + c : sconv + ((size_t)b * 3 + (tt + 3)) * 1536 + c;
;                 acc += *src * convw[j * 1536 + c]; }
.LBB0_1017:
	global_load_dword v39, v[40:41], off nt
	global_load_dword v56, v[8:9], off nt
	s_cmp_lt_i32 s13, 2
	s_cselect_b64 s[8:9], -1, 0
	s_cmp_gt_i32 s13, 1
	s_mov_b64 s[0:1], -1
	s_cbranch_scc1 .LBB0_1019
	s_add_i32 s0, s13, 1
	s_ashr_i32 s1, s0, 31
	s_add_u32 s0, s24, s0
	s_addc_u32 s1, s23, s1
	s_mul_i32 s6, s1, 0x1800
	v_mad_u64_u32 v[40:41], s[0:1], s0, v52, v[6:7]
	v_add_u32_e32 v41, s6, v41
	s_mov_b64 s[0:1], 0

; __device__ __forceinline__ void p_gdn_prep(const float* P, const float* sconv, const float* convw, const float* alog, const float* dtb, float* GQ, float* GK, float* GV, float* GG, float* GB, int m0, int vcu, int G, int h, int lane) {
;     ...
;         for (int part = 0; part < 3; ++part) {
;             const int c = part * 512 + h * 64 + lane; float acc = 0.f;
; #pragma unroll
;             for (int j = 0; j < 4; ++j) { const int tt = t - 3 + j;
;                 const float* src = (tt >= 0) ? P + (size_t)(m - t + tt) * NINP + C_GQKV + c : sconv + ((size_t)b * 3 + (tt + 3)) * 1536 + c;
;                 acc += *src * convw[j * 1536 + c]; }
.LBB0_1021:
	global_load_dword v57, v[40:41], off nt
	global_load_dword v58, v[10:11], off nt
	s_cmp_lt_i32 s13, 1
	s_cselect_b64 s[10:11], -1, 0
	s_cmp_gt_i32 s13, 0
	s_mov_b64 s[0:1], -1
	s_cbranch_scc1 .LBB0_1023
	s_add_i32 s0, s13, 2
	s_ashr_i32 s1, s0, 31
	s_add_u32 s0, s24, s0
	s_addc_u32 s1, s23, s1
	s_mul_i32 s6, s1, 0x1800
	v_mad_u64_u32 v[40:41], s[0:1], s0, v52, v[6:7]
	v_add_u32_e32 v41, s6, v41
	s_mov_b64 s[0:1], 0

; __device__ __forceinline__ void p_gdn_prep(const float* P, const float* sconv, const float* convw, const float* alog, const float* dtb, float* GQ, float* GK, float* GV, float* GG, float* GB, int m0, int vcu, int G, int h, int lane) {
;     ...
;         for (int part = 0; part < 3; ++part) {
;             const int c = part * 512 + h * 64 + lane; float acc = 0.f;
; #pragma unroll
;             for (int j = 0; j < 4; ++j) { const int tt = t - 3 + j;
;                 const float* src = (tt >= 0) ? P + (size_t)(m - t + tt) * NINP + C_GQKV + c : sconv + ((size_t)b * 3 + (tt + 3)) * 1536 + c;
;                 acc += *src * convw[j * 1536 + c]; }
.LBB0_1025:
	global_load_dword v59, v[40:41], off nt
	global_load_dword v60, v[12:13], off nt
	s_cmp_lt_i32 s13, 0
	s_cselect_b64 s[16:17], -1, 0
	s_cmp_gt_i32 s13, -1
	s_mov_b64 s[0:1], -1
	s_cbranch_scc1 .LBB0_1027
	s_add_i32 s0, s13, 3
	s_ashr_i32 s1, s0, 31
	s_add_u32 s0, s24, s0
	s_addc_u32 s1, s23, s1
	s_mul_i32 s6, s1, 0x1800
	v_mad_u64_u32 v[40:41], s[0:1], s0, v52, v[6:7]
	v_add_u32_e32 v41, s6, v41
	s_mov_b64 s[0:1], 0

; __device__ __forceinline__ void p_gdn_prep(const float* P, const float* sconv, const float* convw, const float* alog, const float* dtb, float* GQ, float* GK, float* GV, float* GG, float* GB, int m0, int vcu, int G, int h, int lane) {
;     ...
;         for (int part = 0; part < 3; ++part) {
;             const int c = part * 512 + h * 64 + lane; float acc = 0.f;
; #pragma unroll
;             for (int j = 0; j < 4; ++j) { const int tt = t - 3 + j;
;                 const float* src = (tt >= 0) ? P + (size_t)(m - t + tt) * NINP + C_GQKV + c : sconv + ((size_t)b * 3 + (tt + 3)) * 1536 + c;
;                 acc += *src * convw[j * 1536 + c]; }
.LBB0_1029:
	global_load_dword v63, v[40:41], off nt
	global_load_dword v64, v[14:15], off nt
	v_cndmask_b32_e64 v40, 0, 1, s[2:3]
	v_cmp_ne_u32_e64 s[0:1], 1, v40
	s_andn2_b64 vcc, exec, s[2:3]
	s_mov_b64 s[2:3], -1
	s_cbranch_vccnz .LBB0_1031
	s_ashr_i32 s2, s13, 31
	s_add_u32 s3, s24, s13
	s_addc_u32 s2, s23, s2
	s_mul_i32 s6, s2, 0x1800
	v_mad_u64_u32 v[40:41], s[2:3], s3, v52, v[18:19]
	v_add_u32_e32 v41, s6, v41
	s_mov_b64 s[2:3], 0

; __device__ __forceinline__ void p_gdn_prep(const float* P, const float* sconv, const float* convw, const float* alog, const float* dtb, float* GQ, float* GK, float* GV, float* GG, float* GB, int m0, int vcu, int G, int h, int lane) {
;     ...
;         for (int part = 0; part < 3; ++part) {
;             const int c = part * 512 + h * 64 + lane; float acc = 0.f;
; #pragma unroll
;             for (int j = 0; j < 4; ++j) { const int tt = t - 3 + j;
;                 const float* src = (tt >= 0) ? P + (size_t)(m - t + tt) * NINP + C_GQKV + c : sconv + ((size_t)b * 3 + (tt + 3)) * 1536 + c;
;                 acc += *src * convw[j * 1536 + c]; }
.LBB0_1033:
	global_load_dword v69, v[40:41], off nt
	global_load_dword v70, v[8:9], off offset:2048 nt
	v_cndmask_b32_e64 v40, 0, 1, s[8:9]
	v_cmp_ne_u32_e64 s[6:7], 1, v40
	s_andn2_b64 vcc, exec, s[8:9]
	s_mov_b64 s[2:3], -1
	s_cbranch_vccnz .LBB0_1035
	s_add_i32 s2, s13, 1
	s_ashr_i32 s3, s2, 31
	s_add_u32 s2, s24, s2
	s_addc_u32 s3, s23, s3
	s_mul_i32 s8, s3, 0x1800
	v_mad_u64_u32 v[40:41], s[2:3], s2, v52, v[18:19]
	v_add_u32_e32 v41, s8, v41
	s_mov_b64 s[2:3], 0

; __device__ __forceinline__ void p_gdn_prep(const float* P, const float* sconv, const float* convw, const float* alog, const float* dtb, float* GQ, float* GK, float* GV, float* GG, float* GB, int m0, int vcu, int G, int h, int lane) {
;     ...
;         for (int part = 0; part < 3; ++part) {
;             const int c = part * 512 + h * 64 + lane; float acc = 0.f;
; #pragma unroll
;             for (int j = 0; j < 4; ++j) { const int tt = t - 3 + j;
;                 const float* src = (tt >= 0) ? P + (size_t)(m - t + tt) * NINP + C_GQKV + c : sconv + ((size_t)b * 3 + (tt + 3)) * 1536 + c;
;                 acc += *src * convw[j * 1536 + c]; }
.LBB0_1037:
	global_load_dword v71, v[40:41], off nt
	global_load_dword v72, v[20:21], off nt
	v_cndmask_b32_e64 v40, 0, 1, s[10:11]
	v_cmp_ne_u32_e64 s[8:9], 1, v40
	s_andn2_b64 vcc, exec, s[10:11]
	s_mov_b64 s[2:3], -1
	s_cbranch_vccnz .LBB0_1039
	s_add_i32 s2, s13, 2
	s_ashr_i32 s3, s2, 31
	s_add_u32 s2, s24, s2
	s_addc_u32 s3, s23, s3
	s_mul_i32 s10, s3, 0x1800
	v_mad_u64_u32 v[40:41], s[2:3], s2, v52, v[18:19]
	v_add_u32_e32 v41, s10, v41
	s_mov_b64 s[2:3], 0

; __device__ __forceinline__ void p_gdn_prep(const float* P, const float* sconv, const float* convw, const float* alog, const float* dtb, float* GQ, float* GK, float* GV, float* GG, float* GB, int m0, int vcu, int G, int h, int lane) {
;     ...
;         for (int part = 0; part < 3; ++part) {
;             const int c = part * 512 + h * 64 + lane; float acc = 0.f;
; #pragma unroll
;             for (int j = 0; j < 4; ++j) { const int tt = t - 3 + j;
;                 const float* src = (tt >= 0) ? P + (size_t)(m - t + tt) * NINP + C_GQKV + c : sconv + ((size_t)b * 3 + (tt + 3)) * 1536 + c;
;                 acc += *src * convw[j * 1536 + c]; }
.LBB0_1041:
	global_load_dword v73, v[40:41], off nt
	global_load_dword v74, v[22:23], off nt
	v_cndmask_b32_e64 v40, 0, 1, s[16:17]
	v_cmp_ne_u32_e64 s[10:11], 1, v40
	s_andn2_b64 vcc, exec, s[16:17]
	s_mov_b64 s[2:3], -1
	s_cbranch_vccnz .LBB0_1043
	s_add_i32 s2, s13, 3
	s_ashr_i32 s3, s2, 31
	s_add_u32 s2, s24, s2
	s_addc_u32 s3, s23, s3
	s_mul_i32 s16, s3, 0x1800
	v_mad_u64_u32 v[40:41], s[2:3], s2, v52, v[18:19]
	v_add_u32_e32 v41, s16, v41
	s_mov_b64 s[2:3], 0

; __device__ __forceinline__ void p_gdn_prep(const float* P, const float* sconv, const float* convw, const float* alog, const float* dtb, float* GQ, float* GK, float* GV, float* GG, float* GB, int m0, int vcu, int G, int h, int lane) {
;     ...
;         for (int part = 0; part < 3; ++part) {
;             const int c = part * 512 + h * 64 + lane; float acc = 0.f;
; #pragma unroll
;             for (int j = 0; j < 4; ++j) { const int tt = t - 3 + j;
;                 const float* src = (tt >= 0) ? P + (size_t)(m - t + tt) * NINP + C_GQKV + c : sconv + ((size_t)b * 3 + (tt + 3)) * 1536 + c;
;                 acc += *src * convw[j * 1536 + c]; }
.LBB0_1045:
	global_load_dword v75, v[40:41], off nt
	global_load_dword v76, v[24:25], off nt
	s_and_b64 vcc, exec, s[0:1]
	s_mov_b64 s[0:1], -1
	s_cbranch_vccnz .LBB0_1047
	s_ashr_i32 s0, s13, 31
	s_add_u32 s1, s24, s13
	s_addc_u32 s0, s23, s0
	s_mul_i32 s2, s0, 0x1800
	v_mad_u64_u32 v[40:41], s[0:1], s1, v52, v[28:29]
	v_add_u32_e32 v41, s2, v41
	s_mov_b64 s[0:1], 0

; __device__ __forceinline__ void p_gdn_prep(const float* P, const float* sconv, const float* convw, const float* alog, const float* dtb, float* GQ, float* GK, float* GV, float* GG, float* GB, int m0, int vcu, int G, int h, int lane) {
;     ...
;         for (int part = 0; part < 3; ++part) {
;             const int c = part * 512 + h * 64 + lane; float acc = 0.f;
; #pragma unroll
;             for (int j = 0; j < 4; ++j) { const int tt = t - 3 + j;
;                 const float* src = (tt >= 0) ? P + (size_t)(m - t + tt) * NINP + C_GQKV + c : sconv + ((size_t)b * 3 + (tt + 3)) * 1536 + c;
;                 acc += *src * convw[j * 1536 + c]; }
.LBB0_1049:
	global_load_dword v61, v[40:41], off nt
	global_load_dword v62, v[30:31], off nt
	s_and_b64 vcc, exec, s[6:7]
	s_mov_b64 s[0:1], -1
	s_cbranch_vccnz .LBB0_1051
	s_add_i32 s0, s13, 1
	s_ashr_i32 s1, s0, 31
	s_add_u32 s0, s24, s0
	s_addc_u32 s1, s23, s1
	s_mul_i32 s2, s1, 0x1800
	v_mad_u64_u32 v[40:41], s[0:1], s0, v52, v[28:29]
	v_add_u32_e32 v41, s2, v41
	s_mov_b64 s[0:1], 0

; __device__ __forceinline__ void p_gdn_prep(const float* P, const float* sconv, const float* convw, const float* alog, const float* dtb, float* GQ, float* GK, float* GV, float* GG, float* GB, int m0, int vcu, int G, int h, int lane) {
;     ...
;         for (int part = 0; part < 3; ++part) {
;             const int c = part * 512 + h * 64 + lane; float acc = 0.f;
; #pragma unroll
;             for (int j = 0; j < 4; ++j) { const int tt = t - 3 + j;
;                 const float* src = (tt >= 0) ? P + (size_t)(m - t + tt) * NINP + C_GQKV + c : sconv + ((size_t)b * 3 + (tt + 3)) * 1536 + c;
;                 acc += *src * convw[j * 1536 + c]; }
.LBB0_1053:
	global_load_dword v65, v[40:41], off nt
	global_load_dword v66, v[32:33], off nt
	s_and_b64 vcc, exec, s[8:9]
	s_mov_b64 s[0:1], -1
	s_cbranch_vccnz .LBB0_1055
	s_add_i32 s0, s13, 2
	s_ashr_i32 s1, s0, 31
	s_add_u32 s0, s24, s0
	s_addc_u32 s1, s23, s1
	s_mul_i32 s2, s1, 0x1800
	v_mad_u64_u32 v[40:41], s[0:1], s0, v52, v[28:29]
	v_add_u32_e32 v41, s2, v41
	s_mov_b64 s[0:1], 0

; __device__ __forceinline__ void p_gdn_prep(const float* P, const float* sconv, const float* convw, const float* alog, const float* dtb, float* GQ, float* GK, float* GV, float* GG, float* GB, int m0, int vcu, int G, int h, int lane) {
;     ...
;         for (int part = 0; part < 3; ++part) {
;             const int c = part * 512 + h * 64 + lane; float acc = 0.f;
; #pragma unroll
;             for (int j = 0; j < 4; ++j) { const int tt = t - 3 + j;
;                 const float* src = (tt >= 0) ? P + (size_t)(m - t + tt) * NINP + C_GQKV + c : sconv + ((size_t)b * 3 + (tt + 3)) * 1536 + c;
;                 acc += *src * convw[j * 1536 + c]; }
.LBB0_1057:
	global_load_dword v67, v[40:41], off nt
	global_load_dword v68, v[34:35], off nt
	s_and_b64 vcc, exec, s[10:11]
	s_mov_b64 s[0:1], -1
	s_cbranch_vccnz .LBB0_1059
	s_add_i32 s0, s13, 3
	s_ashr_i32 s1, s0, 31
	s_add_u32 s0, s24, s0
	s_addc_u32 s1, s23, s1
	s_mul_i32 s2, s1, 0x1800
	v_mad_u64_u32 v[40:41], s[0:1], s0, v52, v[28:29]
	v_add_u32_e32 v41, s2, v41
	s_ashr_i32 s13, s12, 31
	s_mov_b64 s[0:1], 0

; __device__ __forceinline__ void p_gdn_prep(const float* P, const float* sconv, const float* convw, const float* alog, const float* dtb, float* GQ, float* GK, float* GV, float* GG, float* GB, int m0, int vcu, int G, int h, int lane) {
;     ...
;         for (int part = 0; part < 3; ++part) {
;             const int c = part * 512 + h * 64 + lane; float acc = 0.f;
; #pragma unroll
;             for (int j = 0; j < 4; ++j) { const int tt = t - 3 + j;
;                 const float* src = (tt >= 0) ? P + (size_t)(m - t + tt) * NINP + C_GQKV + c : sconv + ((size_t)b * 3 + (tt + 3)) * 1536 + c;
;                 acc += *src * convw[j * 1536 + c]; }
;             r[part] = acc / (1.0f + __expf(-acc)); }
;         const float qn = wave_sum(r[0] * r[0]), kn = wave_sum(r[1] * r[1]);
;         GQ[(size_t)m * GW + h * 64 + lane] = r[0] * (1.0f / sqrtf(qn + RMS_EPS)) * 0.125f;
;         GK[(size_t)m * GW + h * 64 + lane] = r[1] * (1.0f / sqrtf(kn + RMS_EPS));
;         GV[(size_t)m * GW + h * 64 + lane] = r[2];
.LBB0_1061:
	global_load_dword v40, v[40:41], off nt
	s_nop 0
	global_load_dword v41, v[36:37], off nt
	s_waitcnt vmcnt(14)
	v_fma_f32 v69, v69, v70, 0
	s_waitcnt vmcnt(12)
	v_fmac_f32_e32 v69, v71, v72
	s_waitcnt vmcnt(10)
	v_fmac_f32_e32 v69, v73, v74
	s_waitcnt vmcnt(8)
	v_fmac_f32_e32 v69, v75, v76
	v_mul_f32_e32 v70, 0xbfb8aa3b, v69
	v_exp_f32_e32 v70, v70
	v_fma_f32 v39, v39, v56, 0
	v_fmac_f32_e32 v39, v57, v58
	v_fmac_f32_e32 v39, v59, v60
	v_add_f32_e32 v70, 1.0, v70
	v_div_scale_f32 v71, s[0:1], v70, v70, v69
	v_rcp_f32_e32 v72, v71
	v_fmac_f32_e32 v39, v63, v64
	v_mul_f32_e32 v57, 0xbfb8aa3b, v39
	v_exp_f32_e32 v57, v57
	v_fma_f32 v73, -v71, v72, 1.0
	v_div_scale_f32 v56, vcc, v69, v70, v69
	v_fmac_f32_e32 v72, v73, v72
	v_mul_f32_e32 v58, v56, v72
	v_fma_f32 v59, -v71, v58, v56
	v_add_f32_e32 v57, 1.0, v57
	v_fmac_f32_e32 v58, v59, v72
	v_div_scale_f32 v59, s[0:1], v57, v57, v39
	v_rcp_f32_e32 v60, v59
	v_fma_f32 v56, -v71, v58, v56
	v_div_fmas_f32 v56, v56, v72, v58
	s_waitcnt vmcnt(6)
	v_fma_f32 v61, v61, v62, 0
	v_fma_f32 v58, -v59, v60, 1.0
	v_fmac_f32_e32 v60, v58, v60
	v_div_scale_f32 v58, vcc, v39, v57, v39
	v_mul_f32_e32 v63, v58, v60
	v_fma_f32 v64, -v59, v63, v58
	v_fmac_f32_e32 v63, v64, v60
	v_fma_f32 v58, -v59, v63, v58
	v_div_fmas_f32 v58, v58, v60, v63
	v_div_fixup_f32 v39, v58, v57, v39
	v_mul_f32_e32 v57, v39, v39
	ds_bpermute_b32 v57, v42, v57
	v_div_fixup_f32 v59, v56, v70, v69
	v_mul_f32_e32 v56, v59, v59
	ds_bpermute_b32 v56, v42, v56
	s_waitcnt vmcnt(4)
	v_fmac_f32_e32 v61, v65, v66
	s_waitcnt lgkmcnt(1)
	v_fmac_f32_e32 v57, v39, v39
	ds_bpermute_b32 v58, v43, v57
	s_waitcnt vmcnt(2)
	v_fmac_f32_e32 v61, v67, v68
	s_waitcnt lgkmcnt(1)
	v_fmac_f32_e32 v56, v59, v59
	ds_bpermute_b32 v60, v43, v56
	s_waitcnt lgkmcnt(1)
	v_add_f32_e32 v57, v57, v58
	ds_bpermute_b32 v58, v44, v57
	s_waitcnt lgkmcnt(1)
	v_add_f32_e32 v56, v56, v60
	ds_bpermute_b32 v60, v44, v56
	s_waitcnt lgkmcnt(1)
	v_add_f32_e32 v57, v57, v58
	ds_bpermute_b32 v58, v45, v57
	s_waitcnt lgkmcnt(1)
	v_add_f32_e32 v56, v56, v60
	ds_bpermute_b32 v60, v45, v56
	s_waitcnt lgkmcnt(1)
	v_add_f32_e32 v57, v57, v58
	ds_bpermute_b32 v58, v46, v57
	s_waitcnt lgkmcnt(1)
	v_add_f32_e32 v56, v56, v60
	ds_bpermute_b32 v60, v46, v56
	s_waitcnt lgkmcnt(1)
	v_add_f32_e32 v57, v57, v58
	ds_bpermute_b32 v58, v47, v57
	s_waitcnt lgkmcnt(1)
	v_add_f32_e32 v56, v56, v60
	ds_bpermute_b32 v60, v47, v56
	s_waitcnt lgkmcnt(1)
	v_add_f32_e32 v57, v57, v58
	v_add_f32_e32 v57, 0x358637bd, v57
	v_mul_f32_e32 v58, 0x4f800000, v57
	v_cmp_gt_f32_e32 vcc, s22, v57
	s_waitcnt vmcnt(0)
	v_fmac_f32_e32 v61, v40, v41
	v_mul_f32_e32 v40, 0xbfb8aa3b, v61
	v_cndmask_b32_e32 v57, v57, v58, vcc
	v_sqrt_f32_e32 v58, v57
	v_exp_f32_e32 v40, v40
	v_add_u32_e32 v62, -1, v58
	v_add_f32_e32 v40, 1.0, v40
	v_add_u32_e32 v41, 1, v58
	v_fma_f32 v63, -v62, v58, v57
	v_div_scale_f32 v65, s[0:1], v40, v40, v61
	v_fma_f32 v64, -v41, v58, v57
	v_rcp_f32_e32 v66, v65
	v_cmp_ge_f32_e64 s[0:1], 0, v63
	v_cmp_lt_f32_e64 s[6:7], 0, v64
	v_fma_f32 v63, -v65, v66, 1.0
	v_cndmask_b32_e64 v58, v58, v62, s[0:1]
	v_cndmask_b32_e64 v41, v58, v41, s[6:7]
	v_mul_f32_e32 v58, 0x37800000, v41
	v_cndmask_b32_e32 v41, v41, v58, vcc
	v_cmp_class_f32_e32 vcc, v57, v49
	v_div_scale_f32 v62, s[0:1], v61, v40, v61
	v_fmac_f32_e32 v66, v63, v66
	v_cndmask_b32_e32 v41, v41, v57, vcc
	v_mul_f32_e32 v63, v62, v66
	v_div_scale_f32 v57, s[2:3], v41, v41, 1.0
	v_fma_f32 v67, -v65, v63, v62
	v_rcp_f32_e32 v58, v57
	v_fmac_f32_e32 v63, v67, v66
	v_fma_f32 v62, -v65, v63, v62
	s_mov_b64 vcc, s[0:1]
	v_div_fmas_f32 v62, v62, v66, v63
	v_div_fixup_f32 v61, v62, v40, v61
	s_waitcnt lgkmcnt(0)
	v_add_f32_e32 v40, v56, v60
	v_fma_f32 v56, -v57, v58, 1.0
	v_fmac_f32_e32 v58, v56, v58
	v_div_scale_f32 v56, vcc, 1.0, v41, 1.0
	v_mul_f32_e32 v60, v56, v58
	v_fma_f32 v62, -v57, v60, v56
	v_fmac_f32_e32 v60, v62, v58
	v_fma_f32 v56, -v57, v60, v56
	v_div_fmas_f32 v56, v56, v58, v60
	v_div_fixup_f32 v41, v56, v41, 1.0
	v_add_f32_e32 v40, 0x358637bd, v40
	v_mul_f32_e32 v39, v39, v41
	v_mul_f32_e32 v41, 0x4f800000, v40
	v_cmp_gt_f32_e32 vcc, s22, v40
	s_lshl_b64 s[0:1], s[12:13], 9
	v_mul_f32_e32 v39, 0x3e000000, v39
	v_cndmask_b32_e32 v56, v40, v41, vcc
	v_sqrt_f32_e32 v57, v56
	v_lshl_add_u64 v[40:41], s[0:1], 0, v[2:3]
	v_lshlrev_b64 v[40:41], 2, v[40:41]
	v_add_u32_e32 v58, -1, v57
	v_fma_f32 v60, -v58, v57, v56
	v_cmp_ge_f32_e64 s[0:1], 0, v60
	v_add_u32_e32 v60, 1, v57
	s_nop 0
	v_cndmask_b32_e64 v58, v57, v58, s[0:1]
	v_fma_f32 v57, -v60, v57, v56
	v_cmp_lt_f32_e64 s[0:1], 0, v57
	s_nop 1
	v_cndmask_b32_e64 v57, v58, v60, s[0:1]
	v_mul_f32_e32 v58, 0x37800000, v57
	v_cndmask_b32_e32 v57, v57, v58, vcc
	v_cmp_class_f32_e32 vcc, v56, v49
	s_nop 1
	v_cndmask_b32_e32 v58, v57, v56, vcc
	v_div_scale_f32 v60, s[0:1], v58, v58, 1.0
	v_rcp_f32_e32 v62, v60
	v_readlane_b32 s0, v244, 31
	v_readlane_b32 s1, v244, 32
	s_nop 1
	v_lshl_add_u64 v[56:57], s[0:1], 0, v[40:41]
	global_store_dword v[56:57], v39, off
	v_fma_f32 v39, -v60, v62, 1.0
	v_fmac_f32_e32 v62, v39, v62
	v_div_scale_f32 v39, vcc, 1.0, v58, 1.0
	v_mul_f32_e32 v56, v39, v62
	v_fma_f32 v57, -v60, v56, v39
	v_fmac_f32_e32 v56, v57, v62
	v_fma_f32 v39, -v60, v56, v39
	v_div_fmas_f32 v39, v39, v62, v56
	v_readlane_b32 s0, v244, 33
	v_div_fixup_f32 v39, v39, v58, 1.0
	v_readlane_b32 s1, v244, 34
	v_mul_f32_e32 v39, v59, v39
	s_nop 0
	v_lshl_add_u64 v[56:57], s[0:1], 0, v[40:41]
	v_lshl_add_u64 v[40:41], s[68:69], 0, v[40:41]
	global_store_dword v[56:57], v39, off
	global_store_dword v[40:41], v61, off
	s_and_saveexec_b64 s[6:7], s[4:5]
	s_cbranch_execz .LBB0_1008
; __device__ __forceinline__ void p_gdn_prep(const float* P, const float* sconv, const float* convw, const float* alog, const float* dtb, float* GQ, float* GK, float* GV, float* GG, float* GB, int m0, int vcu, int G, int h, int lane) {
;     ...
;         if (lane == 0) { const float bb = P[(size_t)m * NINP + C_B + h], aa = P[(size_t)m * NINP + C_A + h] + dtb[h];
;             GB[(size_t)m * NH + h] = 1.0f / (1.0f + __expf(-bb));
;             const float sp = (aa > 20.f) ? aa : log1pf(__expf(aa));
;             GG[(size_t)m * NH + h] = -__expf(alog[h]) * sp; }
	s_mul_i32 s0, s13, 0x3c00
	s_mul_hi_u32 s1, s12, 0x3c00
	s_add_i32 s1, s1, s0
	s_mul_i32 s0, s12, 0x3c00
	s_add_u32 s0, s88, s0
	s_addc_u32 s1, s89, s1
	s_lshl_b32 s2, s50, 2
	s_add_u32 s0, s0, s2
	s_addc_u32 s1, s1, 0
	global_load_dword v39, v50, s[0:1] offset:2048 nt
	global_load_dword v40, v48, s[14:15] nt
	global_load_dword v41, v50, s[0:1] offset:2080 nt
	s_lshl_b64 s[0:1], s[12:13], 3
	s_add_u32 s0, s0, s50
	s_addc_u32 s1, s1, 0
	s_lshl_b64 s[2:3], s[0:1], 2
	v_readlane_b32 s0, v244, 37
	s_add_u32 s8, s0, s2
	v_readlane_b32 s0, v244, 38
	s_addc_u32 s9, s0, s3
	s_mov_b32 s10, 0x41a00000
	s_waitcnt vmcnt(2)
	v_mul_f32_e32 v39, 0xbfb8aa3b, v39
	v_exp_f32_e32 v56, v39
	s_waitcnt vmcnt(0)
	v_add_f32_e32 v39, v41, v40
	v_cmp_lt_f32_e32 vcc, s10, v39
	v_add_f32_e32 v40, 1.0, v56
	v_div_scale_f32 v41, s[0:1], v40, v40, 1.0
	v_rcp_f32_e32 v56, v41
	s_and_b64 s[0:1], exec, vcc
	v_div_scale_f32 v57, vcc, 1.0, v40, 1.0
	v_fma_f32 v58, -v41, v56, 1.0
	v_fmac_f32_e32 v56, v58, v56
	v_mul_f32_e32 v58, v57, v56
	v_fma_f32 v59, -v41, v58, v57
	v_fmac_f32_e32 v58, v59, v56
	v_fma_f32 v41, -v41, v58, v57
	v_div_fmas_f32 v41, v41, v56, v58
	v_div_fixup_f32 v40, v41, v40, 1.0
	s_mov_b64 vcc, s[0:1]
	global_store_dword v48, v40, s[8:9]
	s_cbranch_vccnz .LBB0_1007
	v_mul_f32_e32 v39, 0x3fb8aa3b, v39
	v_exp_f32_e32 v70, v39
	s_mov_b32 s0, 0x3f2aaaab
	v_add_f32_e32 v39, 1.0, v70
	v_frexp_mant_f32_e32 v57, v39
	v_cvt_f64_f32_e32 v[40:41], v39
	v_add_f32_e32 v56, -1.0, v39
	v_frexp_exp_i32_f64_e32 v40, v[40:41]
	v_cmp_gt_f32_e32 vcc, s0, v57
	v_sub_f32_e32 v58, v56, v39
	v_sub_f32_e32 v56, v70, v56
	v_subbrev_co_u32_e32 v62, vcc, 0, v40, vcc
	v_add_f32_e32 v58, 1.0, v58
	v_sub_u32_e32 v40, 0, v62
	v_add_f32_e32 v56, v56, v58
	v_ldexp_f32 v39, v39, v40
	v_ldexp_f32 v40, v56, v40
	v_add_f32_e32 v56, -1.0, v39
	v_add_f32_e32 v41, 1.0, v56
	v_sub_f32_e32 v41, v39, v41
	v_add_f32_e32 v57, v40, v41
	v_add_f32_e32 v41, 1.0, v39
	v_add_f32_e32 v58, -1.0, v41
	v_sub_f32_e32 v39, v39, v58
	v_add_f32_e32 v39, v40, v39
	v_add_f32_e32 v63, v41, v39
	v_rcp_f32_e32 v64, v63
	v_sub_f32_e32 v40, v63, v41
	v_add_f32_e32 v41, v56, v57
	v_sub_f32_e32 v39, v39, v40
	v_mul_f32_e32 v66, v41, v64
	v_sub_f32_e32 v40, v41, v56
	v_mul_f32_e32 v56, v63, v66
	v_fma_f32 v58, v66, v63, -v56
	v_fmac_f32_e32 v58, v66, v39
	v_sub_f32_e32 v65, v57, v40
	v_add_f32_e32 v40, v56, v58
	v_sub_f32_e32 v57, v41, v40
	v_pk_add_f32 v[60:61], v[40:41], v[56:57] neg_lo:[0,1] neg_hi:[0,1]
	v_mov_b32_e32 v59, v40
	v_pk_add_f32 v[40:41], v[60:61], v[58:59] neg_lo:[0,1] neg_hi:[0,1]
	s_mov_b32 s0, 0x3f317218
	v_add_f32_e32 v41, v65, v41
	v_add_f32_e32 v40, v40, v41
	v_add_f32_e32 v41, v57, v40
	v_mul_f32_e32 v65, v64, v41
	v_mul_f32_e32 v56, v63, v65
	v_fma_f32 v58, v65, v63, -v56
	v_fmac_f32_e32 v58, v65, v39
	v_sub_f32_e32 v39, v57, v41
	v_add_f32_e32 v39, v40, v39
	v_add_f32_e32 v40, v56, v58
	v_sub_f32_e32 v57, v41, v40
	v_pk_add_f32 v[60:61], v[40:41], v[56:57] neg_lo:[0,1] neg_hi:[0,1]
	v_mov_b32_e32 v59, v40
	v_pk_add_f32 v[40:41], v[60:61], v[58:59] neg_lo:[0,1] neg_hi:[0,1]
	s_nop 0
	v_add_f32_e32 v39, v39, v41
	v_add_f32_e32 v39, v40, v39
	v_add_f32_e32 v41, v66, v65
	v_add_f32_e32 v39, v57, v39
	v_sub_f32_e32 v40, v41, v66
	v_mul_f32_e32 v39, v64, v39
	v_sub_f32_e32 v40, v65, v40
	v_add_f32_e32 v56, v40, v39
	v_add_f32_e32 v58, v41, v56
	v_cvt_f32_i32_e32 v40, v62
	v_mul_f32_e32 v59, v58, v58
	v_sub_f32_e32 v41, v58, v41
	v_fmamk_f32 v39, v59, 0x3e9b6dac, v51
	v_sub_f32_e32 v41, v56, v41
	v_fmaak_f32 v39, v59, v39, 0x3f2aaada
	v_ldexp_f32 v60, v41, 1
	v_mul_f32_e32 v41, v58, v59
	v_ldexp_f32 v57, v58, 1
	v_pk_mul_f32 v[58:59], v[40:41], v[38:39]
	s_nop 0
	v_fma_f32 v56, v40, s0, -v58
	v_fmac_f32_e32 v56, 0xb102e308, v40
	v_pk_add_f32 v[40:41], v[58:59], v[56:57]
	s_mov_b32 s0, 0x7f800000
	v_sub_f32_e32 v39, v41, v57
	v_sub_f32_e32 v39, v59, v39
	v_add_f32_e32 v61, v60, v39
	v_mov_b32_e32 v60, v58
	v_pk_add_f32 v[58:59], v[40:41], v[58:59] neg_lo:[0,1] neg_hi:[0,1]
	v_pk_add_f32 v[62:63], v[40:41], v[60:61]
	v_mov_b32_e32 v57, v40
	v_mov_b32_e32 v59, v63
	v_pk_add_f32 v[64:65], v[56:57], v[58:59] neg_lo:[0,1] neg_hi:[0,1]
	v_pk_add_f32 v[56:57], v[56:57], v[58:59]
	v_mov_b32_e32 v68, v41
	v_pk_add_f32 v[58:59], v[56:57], v[40:41] op_sel:[1,0] op_sel_hi:[0,1] neg_lo:[0,1] neg_hi:[0,1]
	v_pk_add_f32 v[66:67], v[62:63], v[58:59] op_sel_hi:[1,0] neg_lo:[0,1] neg_hi:[0,1]
	v_mov_b32_e32 v62, v63
	v_mov_b32_e32 v63, v57
	v_mov_b32_e32 v69, v58
	v_pk_add_f32 v[58:59], v[62:63], v[68:69] neg_lo:[0,1] neg_hi:[0,1]
	v_mov_b32_e32 v60, v61
	v_mov_b32_e32 v61, v40
	v_pk_add_f32 v[40:41], v[60:61], v[58:59] neg_lo:[0,1] neg_hi:[0,1]
	v_mov_b32_e32 v66, v64
	v_pk_add_f32 v[58:59], v[66:67], v[40:41]
	v_mov_b32_e32 v65, v57
	v_pk_add_f32 v[60:61], v[58:59], v[58:59] op_sel:[0,1] op_sel_hi:[1,0]
	v_cmp_neq_f32_e32 vcc, s0, v70
	v_pk_add_f32 v[56:57], v[56:57], v[60:61] op_sel:[1,0] op_sel_hi:[0,1]
	v_mov_b32_e32 v59, v56
	v_pk_add_f32 v[62:63], v[58:59], v[64:65] neg_lo:[0,1] neg_hi:[0,1]
	v_mov_b32_e32 v41, v60
	v_sub_f32_e32 v39, v58, v62
	v_pk_add_f32 v[40:41], v[40:41], v[62:63] neg_lo:[0,1] neg_hi:[0,1]
	v_sub_f32_e32 v39, v64, v39
	v_add_f32_e32 v39, v40, v39
	v_add_f32_e32 v39, v39, v41
	v_add_f32_e32 v39, v56, v39
	v_cndmask_b32_e32 v39, v53, v39, vcc
	v_cmp_ngt_f32_e32 vcc, -1.0, v70
	s_mov_b32 s0, 0x33800000
	s_nop 0
	v_cndmask_b32_e32 v39, v54, v39, vcc
	v_cmp_neq_f32_e32 vcc, -1.0, v70
	s_nop 1
	v_cndmask_b32_e32 v39, v55, v39, vcc
	v_cmp_lt_f32_e64 vcc, |v70|, s0
	s_nop 1
	v_cndmask_b32_e32 v39, v39, v70, vcc
	s_branch .LBB0_1007

.LBB0_1066:
	v_lshl_add_u64 v[44:45], v[22:23], 1, s[6:7]
	s_movk_i32 s2, 0xfc00
	v_add_co_u32_e32 v30, vcc, s2, v44
	s_movk_i32 s4, 0x1000
	s_nop 0
	v_addc_co_u32_e32 v31, vcc, -1, v45, vcc
	flat_load_ushort v17, v[30:31] nt
	v_add_co_u32_e32 v30, vcc, s4, v44
	s_waitcnt vmcnt(0)
	v_mul_f32_e32 v16, v5, v16
	v_addc_co_u32_e32 v31, vcc, 0, v45, vcc
	v_add_co_u32_e32 v48, vcc, s14, v44
	v_fmac_f32_e32 v16, v9, v70
	s_nop 0
	v_addc_co_u32_e32 v49, vcc, 0, v45, vcc
	flat_load_ushort v54, v[30:31] offset:3072 nt
	flat_load_ushort v71, v[30:31] nt
	flat_load_ushort v47, v[48:49] nt
	flat_load_ushort v50, v[30:31] offset:1024 nt
	flat_load_ushort v52, v[44:45] offset:3072 nt
	flat_load_ushort v55, v[48:49] offset:3072 nt
	flat_load_ushort v72, v[44:45] nt
	v_fmac_f32_e32 v16, v7, v46
	v_mov_b32_e32 v57, 0
	v_mul_f32_e32 v32, 0xbfb8aa3b, v14
	v_exp_f32_e32 v62, v32
	v_mov_b32_e32 v60, 0
	v_add_co_u32_e32 v58, vcc, s12, v44
	s_mov_b64 s[2:3], 0x4000
	s_nop 0
	v_addc_co_u32_e32 v59, vcc, 0, v45, vcc
	flat_load_ushort v56, v[44:45] offset:1024 nt
	flat_load_ushort v69, v[58:59] nt
	flat_load_ushort v53, v[58:59] offset:1024 nt
	flat_load_ushort v51, v[48:49] offset:1024 nt
	v_add_f32_e32 v48, 1.0, v62
	v_mov_b32_e32 v61, 0
	v_lshl_add_u64 v[32:33], v[44:45], 0, s[2:3]
	v_add_co_u32_e32 v36, vcc, s13, v44
	v_div_scale_f32 v49, s[2:3], v48, v48, 1.0
	s_movk_i32 s4, 0x5000
	v_addc_co_u32_e32 v37, vcc, 0, v45, vcc
	v_rcp_f32_e32 v62, v49
	v_add_co_u32_e32 v42, vcc, s4, v44
	s_movk_i32 s18, 0x6000
	s_nop 0
	v_addc_co_u32_e32 v43, vcc, 0, v45, vcc
	v_add_co_u32_e32 v38, vcc, s18, v44
	v_fma_f32 v67, -v49, v62, 1.0
	s_nop 0
	v_addc_co_u32_e32 v39, vcc, 0, v45, vcc
	v_div_scale_f32 v66, vcc, 1.0, v48, 1.0
	v_fmac_f32_e32 v62, v67, v62
	v_mul_f32_e32 v67, v66, v62
	v_fma_f32 v73, -v49, v67, v66
	v_lshrrev_b32_e32 v21, 3, v22
	v_lshlrev_b32_e32 v87, 1, v22
	v_fmac_f32_e32 v67, v73, v62
	s_mov_b64 s[6:7], 0x5000
	v_and_b32_e32 v64, 14, v87
	v_lshlrev_b32_e32 v65, 4, v21
	v_fma_f32 v49, -v49, v67, v66
	s_mov_b64 s[8:9], 0x6000
	s_mov_b64 s[16:17], 0x7000
	v_lshl_add_u64 v[34:35], v[44:45], 0, s[6:7]
	v_or_b32_e32 v63, v65, v64
	v_div_fmas_f32 v49, v49, v62, v67
	v_mov_b32_e32 v14, v28
	v_lshl_add_u64 v[40:41], v[44:45], 0, s[8:9]
	v_lshl_add_u64 v[30:31], v[44:45], 0, s[16:17]
	v_div_fixup_f32 v102, v49, v48, 1.0
	v_add_u32_e32 v114, s51, v63
	v_pk_mul_f32 v[14:15], v[12:13], v[14:15]
	v_readlane_b32 s6, v102, 0
	v_add_f32_e32 v14, v14, v15
	v_mov_b32_e32 v15, v12
	v_readlane_b32 s7, v102, 1
	v_readlane_b32 s8, v102, 2
	v_readlane_b32 s9, v102, 3
	v_pk_mul_f32 v[26:27], v[2:3], v[26:27] op_sel_hi:[0,1]
	v_pk_fma_f32 v[26:27], v[4:5], v[24:25], v[26:27] op_sel_hi:[0,1,1]
	v_ashrrev_i32_e32 v109, 5, v22
	v_lshlrev_b32_e32 v108, 4, v96
	s_waitcnt lgkmcnt(0)
	v_lshlrev_b32_e32 v68, 16, v17
	v_fmac_f32_e32 v16, v105, v68
	v_mul_f32_e32 v17, 0xbfb8aa3b, v16
	v_exp_f32_e32 v17, v17
	s_waitcnt vmcnt(0)
	v_lshlrev_b32_e32 v54, 16, v54
	v_add_f32_e32 v17, 1.0, v17
	v_rcp_f32_e32 v17, v17
	v_lshlrev_b32_e32 v52, 16, v52
	v_mul_f32_e32 v16, v16, v17
	v_mul_f32_e32 v17, v16, v16
	v_lshlrev_b32_e32 v56, 16, v56
	s_nop 0
	v_mov_b32_dpp v57, v17 quad_perm:[1,0,3,2] row_mask:0xf bank_mask:0xf
	v_fmac_f32_e32 v57, v16, v16
	s_nop 1
	v_add_f32_dpp v17, v57, v57 quad_perm:[2,3,0,1] row_mask:0xf bank_mask:0xf bound_ctrl:1
	s_nop 1
	v_add_f32_dpp v17, v17, v17 row_half_mirror row_mask:0xf bank_mask:0xf bound_ctrl:1
	s_nop 1
	v_add_f32_dpp v17, v17, v17 row_mirror row_mask:0xf bank_mask:0xf bound_ctrl:1
	s_nop 1
	v_mov_b32_dpp v60, v17 row_bcast:15 row_mask:0xa bank_mask:0xf
	v_add_f32_e32 v17, v17, v60
	v_lshlrev_b32_e32 v60, 16, v55
	s_nop 0
	v_mov_b32_dpp v61, v17 row_bcast:31 row_mask:0xc bank_mask:0xf
	v_add_f32_e32 v17, v17, v61
	s_nop 0
	v_readlane_b32 s2, v17, 63
	s_nop 1
	v_add_f32_e32 v17, s2, v86
	v_rsq_f32_e32 v17, v17
	s_movk_i32 s2, 0x7000
	v_mul_f32_e32 v16, v16, v17
	v_mul_f32_e32 v16, 0x3e000000, v16
	v_cvt_pk_bf16_f32 v73, v16, s0
	v_add_co_u32_e32 v16, vcc, s2, v44
	v_readlane_b32 s2, v3, 0
	s_nop 0
	v_addc_co_u32_e32 v17, vcc, 0, v45, vcc
	flat_load_ushort v48, v[58:59] offset:3072 nt
	flat_load_ushort v49, v[36:37] offset:3072 nt
	flat_load_ushort v57, v[42:43] offset:3072 nt
	s_nop 0
	flat_load_ushort v59, v[42:43] nt
	flat_load_ushort v66, v[40:41] offset:1024 nt
	flat_load_ushort v63, v[36:37] nt
	flat_load_ushort v58, v[32:33] offset:1024 nt
	flat_load_ushort v55, v[34:35] offset:1024 nt
	s_nop 0
	flat_load_ushort v34, v[38:39] offset:3072 nt
	flat_load_ushort v61, v[16:17] nt
	flat_load_ushort v62, v[38:39] nt
	flat_load_ushort v67, v[30:31] offset:1024 nt
	v_lshlrev_b32_e32 v33, 16, v71
	v_lshlrev_b32_e32 v32, 16, v72
	v_pk_mov_b32 v[30:31], v[28:29], v[32:33] op_sel:[1,0]
	v_mov_b32_e32 v38, 0
	v_pk_mul_f32 v[36:37], v[10:11], v[30:31]
	v_mul_f32_e32 v35, v5, v70
	v_add_f32_e32 v14, v36, v14
	v_add_f32_e32 v36, v14, v37
	v_mul_f32_e32 v14, 0xbfb8aa3b, v36
	v_exp_f32_e32 v14, v14
	v_fmac_f32_e32 v35, v9, v46
	v_fmac_f32_e32 v35, v7, v68
	v_pk_mul_f32 v[40:41], v[10:11], v[32:33]
	v_add_f32_e32 v14, 1.0, v14
	v_rcp_f32_e32 v37, v14
	v_mov_b32_e32 v14, v13
	v_pk_mul_f32 v[28:29], v[14:15], v[28:29]
	v_fmac_f32_e32 v35, v105, v52
	v_mul_f32_e32 v36, v36, v37
	v_mul_f32_e32 v37, v36, v36
	v_add_f32_e32 v28, v29, v28
	v_add_f32_e32 v28, v28, v40
	v_mov_b32_dpp v38, v37 quad_perm:[1,0,3,2] row_mask:0xf bank_mask:0xf
	v_fmac_f32_e32 v38, v36, v36
	v_add_f32_e32 v28, v28, v41
	v_mul_f32_e32 v29, 0xbfb8aa3b, v35
	v_add_f32_dpp v37, v38, v38 quad_perm:[2,3,0,1] row_mask:0xf bank_mask:0xf bound_ctrl:1
	v_mov_b32_e32 v38, 0
	v_exp_f32_e32 v29, v29
	v_add_f32_dpp v37, v37, v37 row_half_mirror row_mask:0xf bank_mask:0xf bound_ctrl:1
	v_mul_f32_e32 v40, 0xbfb8aa3b, v28
	v_exp_f32_e32 v40, v40
	v_add_f32_dpp v37, v37, v37 row_mirror row_mask:0xf bank_mask:0xf bound_ctrl:1
	v_mov_b32_e32 v39, s2
	v_add_f32_e32 v29, 1.0, v29
	v_mov_b32_dpp v38, v37 row_bcast:15 row_mask:0xa bank_mask:0xf
	v_add_f32_e32 v37, v37, v38
	v_mov_b32_e32 v38, 0
	v_rcp_f32_e32 v29, v29
	ds_write_b16 v114, v73
	v_mov_b32_dpp v38, v37 row_bcast:31 row_mask:0xc bank_mask:0xf
	v_add_f32_e32 v37, v37, v38
	v_mul_f32_e32 v29, v35, v29
	v_readlane_b32 s3, v37, 63
	v_mul_f32_e32 v35, v29, v29
	s_waitcnt vmcnt(0) lgkmcnt(0)
	v_lshlrev_b32_e32 v103, 16, v57
	v_add_f32_e32 v37, s3, v86
	v_rsq_f32_e32 v38, v37
	v_mov_b32_e32 v37, s6
	v_lshlrev_b32_e32 v57, 16, v50
	v_pk_mov_b32 v[24:25], v[24:25], v[56:57] op_sel:[1,0]
	v_pk_mul_f32 v[36:37], v[36:37], v[38:39]
	v_add_f32_e32 v38, 1.0, v40
	v_rcp_f32_e32 v38, v38
	v_cvt_pk_bf16_f32 v39, v36, s0
	ds_write_b16 v114, v39 offset:4096
	v_pk_fma_f32 v[26:27], v[6:7], v[24:25], v[26:27] op_sel_hi:[0,1,1]
	v_mul_f32_e32 v28, v28, v38
	v_mov_b32_e32 v38, 0
	v_pk_fma_f32 v[26:27], v[8:9], v[56:57], v[26:27] op_sel_hi:[0,1,1]
	v_lshlrev_b32_e32 v98, 16, v34
	v_mov_b32_dpp v38, v35 quad_perm:[1,0,3,2] row_mask:0xf bank_mask:0xf
	v_fmac_f32_e32 v38, v29, v29
	v_mul_f32_e32 v34, 0xbfb8aa3b, v26
	v_exp_f32_e32 v34, v34
	v_add_f32_dpp v35, v38, v38 quad_perm:[2,3,0,1] row_mask:0xf bank_mask:0xf bound_ctrl:1
	v_mov_b32_e32 v38, 0
	v_mul_f32_e32 v88, v36, v37
	v_add_f32_dpp v35, v35, v35 row_half_mirror row_mask:0xf bank_mask:0xf bound_ctrl:1
	v_add_f32_e32 v34, 1.0, v34
	v_rcp_f32_e32 v74, v34
	v_add_f32_dpp v35, v35, v35 row_mirror row_mask:0xf bank_mask:0xf bound_ctrl:1
	v_lshlrev_b32_e32 v55, 16, v55
	v_lshlrev_b32_e32 v61, 16, v61
	v_mov_b32_dpp v38, v35 row_bcast:15 row_mask:0xa bank_mask:0xf
	v_add_f32_e32 v35, v35, v38
	v_mov_b32_e32 v38, 0
	v_mul_f32_e32 v123, v9, v98
	v_fmac_f32_e32 v123, v5, v103
	v_mov_b32_dpp v38, v35 row_bcast:31 row_mask:0xc bank_mask:0xf
	v_add_f32_e32 v35, v35, v38
	v_mov_b32_e32 v38, 0
	v_readlane_b32 s2, v35, 63
	v_mul_f32_e32 v35, v28, v28
	s_nop 0
	v_add_f32_e32 v39, s2, v86
	v_mov_b32_dpp v38, v35 quad_perm:[1,0,3,2] row_mask:0xf bank_mask:0xf
	v_fmac_f32_e32 v38, v28, v28
	v_rsq_f32_e32 v39, v39
	s_nop 0
	v_add_f32_dpp v35, v38, v38 quad_perm:[2,3,0,1] row_mask:0xf bank_mask:0xf bound_ctrl:1
	v_mov_b32_e32 v38, 0
	v_mul_f32_e32 v29, v29, v39
	v_add_f32_dpp v35, v35, v35 row_half_mirror row_mask:0xf bank_mask:0xf bound_ctrl:1
	v_mul_f32_e32 v29, 0x3e000000, v29
	v_cvt_pk_bf16_f32 v29, v29, s0
	v_add_f32_dpp v35, v35, v35 row_mirror row_mask:0xf bank_mask:0xf bound_ctrl:1
	s_nop 1
	v_mov_b32_dpp v38, v35 row_bcast:15 row_mask:0xa bank_mask:0xf
	v_add_f32_e32 v35, v35, v38
	v_mov_b32_e32 v38, 0
	s_nop 1
	v_mov_b32_dpp v38, v35 row_bcast:31 row_mask:0xc bank_mask:0xf
	v_add_f32_e32 v35, v35, v38
	s_nop 0
	v_readlane_b32 s2, v35, 63
	s_nop 1
	v_add_f32_e32 v35, s2, v86
	v_rsq_f32_e32 v38, v35
	v_xor_b32_e32 v35, 16, v65
	v_or_b32_e32 v35, v35, v64
	v_add_u32_e32 v116, s51, v35
	v_mul_f32_e32 v35, v9, v68
	v_fmac_f32_e32 v35, v5, v46
	v_fmac_f32_e32 v35, v7, v52
	v_fmac_f32_e32 v35, v105, v54
	v_mul_f32_e32 v39, 0xbfb8aa3b, v35
	v_exp_f32_e32 v39, v39
	ds_write_b16 v116, v29 offset:128
	v_readlane_b32 s2, v3, 1
	v_add_f32_e32 v29, 1.0, v39
	v_rcp_f32_e32 v40, v29
	v_mov_b32_e32 v29, s7
	v_mov_b32_e32 v39, s2
	v_pk_mul_f32 v[38:39], v[28:29], v[38:39]
	v_mul_f32_e32 v28, v35, v40
	v_mul_f32_e32 v29, v28, v28
	v_mov_b32_e32 v35, 0
	v_pk_mul_f32 v[40:41], v[14:15], v[30:31]
	v_mul_f32_e32 v90, v38, v39
	v_mov_b32_dpp v35, v29 quad_perm:[1,0,3,2] row_mask:0xf bank_mask:0xf
	v_fmac_f32_e32 v35, v28, v28
	v_cvt_pk_bf16_f32 v36, v36, v38
	s_nop 0
	v_add_f32_dpp v29, v35, v35 quad_perm:[2,3,0,1] row_mask:0xf bank_mask:0xf bound_ctrl:1
	v_mov_b32_e32 v35, 0
	s_nop 0
	v_add_f32_dpp v29, v29, v29 row_half_mirror row_mask:0xf bank_mask:0xf bound_ctrl:1
	s_nop 1
	v_add_f32_dpp v29, v29, v29 row_mirror row_mask:0xf bank_mask:0xf bound_ctrl:1
	s_nop 1
	v_mov_b32_dpp v35, v29 row_bcast:15 row_mask:0xa bank_mask:0xf
	v_add_f32_e32 v29, v29, v35
	v_mov_b32_e32 v35, 0
	s_nop 1
	v_mov_b32_dpp v35, v29 row_bcast:31 row_mask:0xc bank_mask:0xf
	v_add_f32_e32 v29, v29, v35
	v_cvt_pk_bf16_f32 v35, v38, s0
	v_readlane_b32 s2, v29, 63
	ds_write_b16 v116, v35 offset:4224
	v_add_f32_e32 v35, v40, v41
	v_add_f32_e32 v29, s2, v86
	v_rsq_f32_e32 v29, v29
	v_mov_b32_e32 v41, 0
	v_readlane_b32 s2, v3, 2
	v_mul_f32_e32 v28, v28, v29
	v_xor_b32_e32 v29, 32, v65
	v_mul_f32_e32 v28, 0x3e000000, v28
	v_or_b32_e32 v29, v29, v64
	v_cvt_pk_bf16_f32 v28, v28, s0
	v_add_u32_e32 v115, s51, v29
	ds_write_b16 v115, v28 offset:256
	v_lshlrev_b32_e32 v29, 16, v69
	v_lshlrev_b32_e32 v28, 16, v47
	v_pk_mov_b32 v[30:31], v[32:33], v[28:29] op_sel:[1,0]
	v_mul_f32_e32 v69, v9, v52
	v_pk_mul_f32 v[42:43], v[10:11], v[30:31]
	v_fmac_f32_e32 v69, v5, v68
	v_add_f32_e32 v35, v35, v42
	v_add_f32_e32 v35, v35, v43
	v_mul_f32_e32 v40, 0xbfb8aa3b, v35
	v_exp_f32_e32 v40, v40
	v_pk_mul_f32 v[32:33], v[14:15], v[32:33]
	v_fmac_f32_e32 v69, v7, v54
	v_pk_mul_f32 v[46:47], v[10:11], v[28:29]
	v_add_f32_e32 v40, 1.0, v40
	v_rcp_f32_e32 v40, v40
	v_add_f32_e32 v32, v32, v33
	v_fmac_f32_e32 v69, v105, v60
	v_add_f32_e32 v32, v32, v46
	v_mul_f32_e32 v40, v35, v40
	v_mul_f32_e32 v35, v40, v40
	v_add_f32_e32 v32, v32, v47
	v_mul_f32_e32 v33, 0xbfb8aa3b, v69
	v_mov_b32_dpp v41, v35 quad_perm:[1,0,3,2] row_mask:0xf bank_mask:0xf
	v_fmac_f32_e32 v41, v40, v40
	v_exp_f32_e32 v33, v33
	v_mov_b32_e32 v43, s2
	v_add_f32_dpp v35, v41, v41 quad_perm:[2,3,0,1] row_mask:0xf bank_mask:0xf bound_ctrl:1
	v_mov_b32_e32 v41, 0
	v_add_f32_e32 v33, 1.0, v33
	v_add_f32_dpp v35, v35, v35 row_half_mirror row_mask:0xf bank_mask:0xf bound_ctrl:1
	v_rcp_f32_e32 v33, v33
	v_lshlrev_b32_e32 v68, 16, v48
	v_add_f32_dpp v35, v35, v35 row_mirror row_mask:0xf bank_mask:0xf bound_ctrl:1
	v_mul_f32_e32 v33, v69, v33
	s_nop 0
	v_mov_b32_dpp v41, v35 row_bcast:15 row_mask:0xa bank_mask:0xf
	v_add_f32_e32 v35, v35, v41
	v_mov_b32_e32 v41, 0
	s_nop 1
	v_mov_b32_dpp v41, v35 row_bcast:31 row_mask:0xc bank_mask:0xf
	v_add_f32_e32 v35, v35, v41
	v_mov_b32_e32 v41, s8
	v_readlane_b32 s3, v35, 63
	s_nop 1
	v_add_f32_e32 v35, s3, v86
	v_rsq_f32_e32 v42, v35
	v_mul_f32_e32 v35, 0xbfb8aa3b, v32
	v_exp_f32_e32 v35, v35
	v_pk_mul_f32 v[40:41], v[40:41], v[42:43]
	s_nop 0
	v_cvt_pk_bf16_f32 v42, v40, s0
	v_add_f32_e32 v35, 1.0, v35
	v_rcp_f32_e32 v35, v35
	ds_write_b16 v115, v42 offset:4352
	v_mov_b32_e32 v42, 0
	v_mul_f32_e32 v89, v40, v41
	v_mul_f32_e32 v32, v32, v35
	v_mul_f32_e32 v35, v33, v33
	s_nop 1
	v_mov_b32_dpp v42, v35 quad_perm:[1,0,3,2] row_mask:0xf bank_mask:0xf
	v_fmac_f32_e32 v42, v33, v33
	s_nop 1
	v_add_f32_dpp v35, v42, v42 quad_perm:[2,3,0,1] row_mask:0xf bank_mask:0xf bound_ctrl:1
	v_mov_b32_e32 v42, 0
	s_nop 0
	v_add_f32_dpp v35, v35, v35 row_half_mirror row_mask:0xf bank_mask:0xf bound_ctrl:1
	s_nop 1
	v_add_f32_dpp v35, v35, v35 row_mirror row_mask:0xf bank_mask:0xf bound_ctrl:1
	s_nop 1
	v_mov_b32_dpp v42, v35 row_bcast:15 row_mask:0xa bank_mask:0xf
	v_add_f32_e32 v35, v35, v42
	v_mov_b32_e32 v42, 0
	s_nop 1
	v_mov_b32_dpp v42, v35 row_bcast:31 row_mask:0xc bank_mask:0xf
	v_add_f32_e32 v35, v35, v42
	v_mov_b32_e32 v42, 0
	v_readlane_b32 s2, v35, 63
	v_mul_f32_e32 v35, v32, v32
	s_nop 0
	v_add_f32_e32 v43, s2, v86
	v_mov_b32_dpp v42, v35 quad_perm:[1,0,3,2] row_mask:0xf bank_mask:0xf
	v_fmac_f32_e32 v42, v32, v32
	v_rsq_f32_e32 v43, v43
	s_nop 0
	v_add_f32_dpp v35, v42, v42 quad_perm:[2,3,0,1] row_mask:0xf bank_mask:0xf bound_ctrl:1
	v_mov_b32_e32 v42, 0
	v_mul_f32_e32 v33, v33, v43
	v_add_f32_dpp v35, v35, v35 row_half_mirror row_mask:0xf bank_mask:0xf bound_ctrl:1
	v_mul_f32_e32 v33, 0x3e000000, v33
	v_cvt_pk_bf16_f32 v33, v33, s0
	v_add_f32_dpp v35, v35, v35 row_mirror row_mask:0xf bank_mask:0xf bound_ctrl:1
	s_nop 1
	v_mov_b32_dpp v42, v35 row_bcast:15 row_mask:0xa bank_mask:0xf
	v_add_f32_e32 v35, v35, v42
	v_mov_b32_e32 v42, 0
	s_nop 1
	v_mov_b32_dpp v42, v35 row_bcast:31 row_mask:0xc bank_mask:0xf
	v_add_f32_e32 v35, v35, v42
	s_nop 0
	v_readlane_b32 s2, v35, 63
	s_nop 1
	v_add_f32_e32 v35, s2, v86
	v_rsq_f32_e32 v42, v35
	v_xor_b32_e32 v35, 48, v65
	v_or_b32_e32 v35, v35, v64
	v_add_u32_e32 v117, s51, v35
	v_readlane_b32 s2, v3, 3
	ds_write_b16 v117, v33 offset:384
	v_mov_b32_e32 v33, s9
	v_mov_b32_e32 v43, s2
	v_pk_mul_f32 v[46:47], v[32:33], v[42:43]
	v_mul_f32_e32 v35, 0xbfb8aa3b, v27
	v_cvt_pk_bf16_f32 v32, v46, s0
	ds_write_b16 v117, v32 offset:4480
	flat_load_ushort v33, v[16:17] offset:3072 nt
	v_exp_f32_e32 v35, v35
	s_mov_b32 s2, 0x8000
	v_add_co_u32_e32 v70, vcc, s2, v44
	v_add_f32_e32 v34, 1.0, v35
	v_rcp_f32_e32 v75, v34
	v_lshlrev_b32_e32 v35, 16, v53
	v_lshlrev_b32_e32 v34, 16, v51
	v_pk_mul_f32 v[50:51], v[4:5], v[56:57] op_sel_hi:[0,1]
	v_pk_fma_f32 v[24:25], v[2:3], v[24:25], v[50:51] op_sel_hi:[0,1,1]
	v_pk_mov_b32 v[50:51], v[56:57], v[34:35] op_sel:[1,0]
	v_lshl_or_b32 v16, v109, 11, v108
	v_pk_fma_f32 v[24:25], v[6:7], v[50:51], v[24:25] op_sel_hi:[0,1,1]
	v_addc_co_u32_e32 v71, vcc, 0, v45, vcc
	s_mov_b32 s2, 0x9000
	v_ashrrev_i32_e32 v17, 31, v16
	v_pk_fma_f32 v[56:57], v[8:9], v[34:35], v[24:25] op_sel_hi:[0,1,1]
	v_add_co_u32_e32 v72, vcc, s2, v44
	v_lshl_add_u64 v[42:43], s[0:1], 0, v[16:17]
	s_mov_b64 s[2:3], 0x2800
	v_mul_f32_e32 v24, 0xbfb8aa3b, v56
	v_addc_co_u32_e32 v73, vcc, 0, v45, vcc
	v_lshl_add_u64 v[16:17], v[42:43], 0, s[2:3]
	s_mov_b32 s2, 0xa000
	v_exp_f32_e32 v37, v24
	v_add_co_u32_e32 v48, vcc, s2, v44
	v_lshlrev_b32_e32 v32, 16, v49
	s_nop 0
	v_addc_co_u32_e32 v49, vcc, 0, v45, vcc
	flat_load_ushort v69, v[70:71] nt
	flat_load_ushort v76, v[70:71] offset:3072 nt
	flat_load_ushort v77, v[72:73] offset:3072 nt
	flat_load_ushort v92, v[48:49] offset:3072 nt
	v_mul_f32_e32 v24, 0xbfb8aa3b, v57
	v_exp_f32_e32 v53, v24
	v_pk_mul_f32 v[24:25], v[26:27], v[74:75]
	v_add_f32_e32 v26, 1.0, v37
	v_mul_f32_e32 v37, v9, v54
	v_fmac_f32_e32 v37, v5, v52
	v_fmac_f32_e32 v37, v7, v60
	v_fmac_f32_e32 v37, v105, v68
	v_mul_f32_e32 v39, 0xbfb8aa3b, v37
	v_exp_f32_e32 v39, v39
	v_add_f32_e32 v27, 1.0, v53
	v_mov_b32_e32 v53, 0
	v_rcp_f32_e32 v26, v26
	v_rcp_f32_e32 v27, v27
	v_mul_f32_e32 v91, v46, v47
	flat_load_ushort v104, v[48:49] nt
	flat_load_ushort v47, v[72:73] offset:1024 nt
	flat_load_ushort v107, v[72:73] nt
	flat_load_ushort v78, v[70:71] offset:1024 nt
	v_pk_mul_f32 v[24:25], v[24:25], s[6:7]
	v_pk_mul_f32 v[26:27], v[56:57], v[26:27]
	v_readlane_b32 s6, v102, 4
	v_readlane_b32 s7, v102, 5
	v_pk_mul_f32 v[26:27], v[26:27], s[8:9]
	s_waitcnt vmcnt(0) lgkmcnt(0)
	v_lshlrev_b32_e32 v100, 16, v33
	v_add_f32_e32 v33, 1.0, v39
	v_rcp_f32_e32 v52, v33
	v_fmac_f32_e32 v123, v7, v100
	v_mul_f32_e32 v52, v37, v52
	v_mul_f32_e32 v37, v52, v52
	v_lshlrev_b32_e32 v33, 16, v69
	s_nop 0
	v_mov_b32_dpp v53, v37 quad_perm:[1,0,3,2] row_mask:0xf bank_mask:0xf
	v_fmac_f32_e32 v53, v52, v52
	v_lshlrev_b32_e32 v41, 16, v76
	v_fmac_f32_e32 v123, v105, v41
	v_add_f32_dpp v37, v53, v53 quad_perm:[2,3,0,1] row_mask:0xf bank_mask:0xf bound_ctrl:1
	v_mov_b32_e32 v53, 0
	v_lshlrev_b32_e32 v39, 16, v77
	v_add_f32_dpp v37, v37, v37 row_half_mirror row_mask:0xf bank_mask:0xf bound_ctrl:1
	v_mul_f32_e32 v132, v9, v39
	v_fmac_f32_e32 v132, v5, v41
	v_add_f32_dpp v37, v37, v37 row_mirror row_mask:0xf bank_mask:0xf bound_ctrl:1
	s_nop 1
	v_mov_b32_dpp v53, v37 row_bcast:15 row_mask:0xa bank_mask:0xf
	v_add_f32_e32 v37, v37, v53
	v_mov_b32_e32 v53, 0
	s_nop 1
	v_mov_b32_dpp v53, v37 row_bcast:31 row_mask:0xc bank_mask:0xf
	v_add_f32_e32 v37, v37, v53
	s_nop 0
	v_readlane_b32 s2, v37, 63
	s_nop 1
	v_add_f32_e32 v37, s2, v86
	v_rsq_f32_e32 v53, v37
	s_mov_b32 s2, 0xb000
	v_add_co_u32_e32 v56, vcc, s2, v44
	v_readlane_b32 s2, v3, 4
	s_nop 0
	v_addc_co_u32_e32 v57, vcc, 0, v45, vcc
	flat_load_ushort v79, v[56:57] offset:1024 nt
	flat_load_ushort v97, v[56:57] nt
	flat_load_ushort v99, v[48:49] offset:1024 nt
	v_pk_mul_f32 v[48:49], v[14:15], v[30:31]
	v_mul_f32_e32 v30, v52, v53
	v_xor_b32_e32 v31, 64, v65
	v_mul_f32_e32 v30, 0x3e000000, v30
	v_or_b32_e32 v31, v31, v64
	v_cvt_pk_bf16_f32 v30, v30, s0
	v_add_u32_e32 v118, s51, v31
	ds_write_b16 v118, v30 offset:512
	v_lshlrev_b32_e32 v31, 16, v59
	v_lshlrev_b32_e32 v30, 16, v63
	v_pk_mov_b32 v[52:53], v[28:29], v[30:31] op_sel:[1,0]
	v_add_f32_e32 v48, v48, v49
	v_pk_mul_f32 v[70:71], v[10:11], v[52:53]
	v_mul_f32_e32 v59, v9, v60
	v_add_f32_e32 v48, v48, v70
	v_add_f32_e32 v48, v48, v71
	v_mul_f32_e32 v49, 0xbfb8aa3b, v48
	v_exp_f32_e32 v49, v49
	v_fmac_f32_e32 v59, v5, v54
	v_mov_b32_e32 v54, 0
	v_pk_mul_f32 v[28:29], v[14:15], v[28:29]
	v_add_f32_e32 v49, 1.0, v49
	v_rcp_f32_e32 v49, v49
	v_mov_b32_e32 v71, s2
	v_fmac_f32_e32 v59, v7, v68
	v_add_f32_e32 v28, v28, v29
	v_mul_f32_e32 v48, v48, v49
	v_mul_f32_e32 v49, v48, v48
	v_fmac_f32_e32 v59, v105, v32
	v_mul_f32_e32 v29, 0xbfb8aa3b, v59
	v_mov_b32_dpp v54, v49 quad_perm:[1,0,3,2] row_mask:0xf bank_mask:0xf
	v_fmac_f32_e32 v54, v48, v48
	v_exp_f32_e32 v29, v29
	v_lshlrev_b32_e32 v37, 16, v92
	v_add_f32_dpp v49, v54, v54 quad_perm:[2,3,0,1] row_mask:0xf bank_mask:0xf bound_ctrl:1
	v_mov_b32_e32 v54, 0
	v_add_f32_e32 v29, 1.0, v29
	v_add_f32_dpp v49, v49, v49 row_half_mirror row_mask:0xf bank_mask:0xf bound_ctrl:1
	v_rcp_f32_e32 v29, v29
	v_fmac_f32_e32 v132, v7, v37
	v_add_f32_dpp v49, v49, v49 row_mirror row_mask:0xf bank_mask:0xf bound_ctrl:1
	v_mul_f32_e32 v29, v59, v29
	s_nop 0
	v_mov_b32_dpp v54, v49 row_bcast:15 row_mask:0xa bank_mask:0xf
	v_add_f32_e32 v49, v49, v54
	v_mov_b32_e32 v54, 0
	s_nop 1
	v_mov_b32_dpp v54, v49 row_bcast:31 row_mask:0xc bank_mask:0xf
	v_add_f32_e32 v49, v49, v54
	s_nop 0
	v_readlane_b32 s3, v49, 63
	s_nop 1
	v_add_f32_e32 v49, s3, v86
	v_rsq_f32_e32 v70, v49
	v_mov_b32_e32 v49, s6
	v_readlane_b32 s3, v3, 6
	v_pk_mul_f32 v[48:49], v[48:49], v[70:71]
	v_pk_mul_f32 v[70:71], v[10:11], v[30:31]
	v_mul_f32_e32 v92, v48, v49
	v_add_f32_e32 v28, v28, v70
	v_add_f32_e32 v28, v28, v71
	v_mul_f32_e32 v54, 0xbfb8aa3b, v28
	v_exp_f32_e32 v54, v54
	v_mov_b32_e32 v49, 0
	v_cvt_pk_bf16_f32 v63, v48, s0
	ds_write_b16 v118, v63 offset:4608
	v_add_f32_e32 v54, 1.0, v54
	v_rcp_f32_e32 v54, v54
	v_mov_b32_e32 v71, s7
	v_mul_f32_e32 v70, v28, v54
	v_mul_f32_e32 v28, v29, v29
	s_nop 1
	v_mov_b32_dpp v49, v28 quad_perm:[1,0,3,2] row_mask:0xf bank_mask:0xf
	v_fmac_f32_e32 v49, v29, v29
	s_nop 1
	v_add_f32_dpp v28, v49, v49 quad_perm:[2,3,0,1] row_mask:0xf bank_mask:0xf bound_ctrl:1
	v_mov_b32_e32 v49, 0
	s_nop 0
	v_add_f32_dpp v28, v28, v28 row_half_mirror row_mask:0xf bank_mask:0xf bound_ctrl:1
	s_nop 1
	v_add_f32_dpp v28, v28, v28 row_mirror row_mask:0xf bank_mask:0xf bound_ctrl:1
	s_nop 1
	v_mov_b32_dpp v49, v28 row_bcast:15 row_mask:0xa bank_mask:0xf
	v_add_f32_e32 v28, v28, v49
	v_mov_b32_e32 v49, 0
	s_nop 1
	v_mov_b32_dpp v49, v28 row_bcast:31 row_mask:0xc bank_mask:0xf
	v_add_f32_e32 v28, v28, v49
	v_mov_b32_e32 v49, 0
	v_readlane_b32 s2, v28, 63
	v_mul_f32_e32 v28, v70, v70
	s_nop 0
	v_add_f32_e32 v54, s2, v86
	v_mov_b32_dpp v49, v28 quad_perm:[1,0,3,2] row_mask:0xf bank_mask:0xf
	v_fmac_f32_e32 v49, v70, v70
	v_rsq_f32_e32 v54, v54
	s_nop 0
	v_add_f32_dpp v28, v49, v49 quad_perm:[2,3,0,1] row_mask:0xf bank_mask:0xf bound_ctrl:1
	v_mov_b32_e32 v49, 0
	s_nop 0
	v_add_f32_dpp v28, v28, v28 row_half_mirror row_mask:0xf bank_mask:0xf bound_ctrl:1
	s_nop 1
	v_add_f32_dpp v28, v28, v28 row_mirror row_mask:0xf bank_mask:0xf bound_ctrl:1
	s_nop 1
	v_mov_b32_dpp v49, v28 row_bcast:15 row_mask:0xa bank_mask:0xf
	v_add_f32_e32 v28, v28, v49
	v_mov_b32_e32 v49, 0
	s_nop 1
	v_mov_b32_dpp v49, v28 row_bcast:31 row_mask:0xc bank_mask:0xf
	v_add_f32_e32 v28, v28, v49
	v_mul_f32_e32 v49, v9, v68
	v_readlane_b32 s2, v28, 63
	v_mul_f32_e32 v28, v29, v54
	v_mul_f32_e32 v28, 0x3e000000, v28
	v_add_f32_e32 v29, s2, v86
	v_rsq_f32_e32 v72, v29
	v_xor_b32_e32 v29, 0x50, v65
	v_or_b32_e32 v29, v29, v64
	v_cvt_pk_bf16_f32 v28, v28, s0
	v_add_u32_e32 v119, s51, v29
	ds_write_b16 v119, v28 offset:640
	v_lshlrev_b32_e32 v54, 16, v58
	v_pk_mul_f32 v[28:29], v[4:5], v[34:35] op_sel_hi:[0,1]
	v_pk_fma_f32 v[28:29], v[2:3], v[50:51], v[28:29] op_sel_hi:[0,1,1]
	v_pk_mov_b32 v[58:59], v[34:35], v[54:55] op_sel:[1,0]
	v_fmac_f32_e32 v49, v5, v60
	v_pk_fma_f32 v[28:29], v[6:7], v[58:59], v[28:29] op_sel_hi:[0,1,1]
	v_pk_fma_f32 v[28:29], v[8:9], v[54:55], v[28:29] op_sel_hi:[0,1,1]
	v_mul_f32_e32 v34, 0xbfb8aa3b, v28
	v_mul_f32_e32 v35, 0xbfb8aa3b, v29
	v_exp_f32_e32 v34, v34
	v_exp_f32_e32 v35, v35
	v_fmac_f32_e32 v49, v7, v32
	v_fmac_f32_e32 v49, v105, v103
	v_add_f32_e32 v34, 1.0, v34
	v_add_f32_e32 v35, 1.0, v35
	v_mul_f32_e32 v50, 0xbfb8aa3b, v49
	v_rcp_f32_e32 v34, v34
	v_rcp_f32_e32 v35, v35
	v_exp_f32_e32 v50, v50
	v_mov_b32_e32 v60, 0
	v_readlane_b32 s2, v3, 5
	v_pk_mul_f32 v[28:29], v[28:29], v[34:35]
	v_add_f32_e32 v34, 1.0, v50
	v_rcp_f32_e32 v34, v34
	v_mov_b32_e32 v73, s2
	v_pk_mul_f32 v[50:51], v[70:71], v[72:73]
	v_pk_mul_f32 v[28:29], v[28:29], s[6:7]
	v_mul_f32_e32 v49, v49, v34
	v_mul_f32_e32 v34, v49, v49
	v_cvt_pk_bf16_f32 v35, v50, s0
	ds_write_b16 v119, v35 offset:4736
	v_mov_b32_dpp v60, v34 quad_perm:[1,0,3,2] row_mask:0xf bank_mask:0xf
	v_fmac_f32_e32 v60, v49, v49
	v_mul_f32_e32 v93, v50, v51
	v_xor_b32_e32 v51, 0x60, v65
	v_add_f32_dpp v34, v60, v60 quad_perm:[2,3,0,1] row_mask:0xf bank_mask:0xf bound_ctrl:1
	v_mov_b32_e32 v60, 0
	v_or_b32_e32 v51, v51, v64
	v_add_f32_dpp v34, v34, v34 row_half_mirror row_mask:0xf bank_mask:0xf bound_ctrl:1
	v_add_u32_e32 v124, s51, v51
	v_mov_b32_e32 v51, 0
	v_add_f32_dpp v34, v34, v34 row_mirror row_mask:0xf bank_mask:0xf bound_ctrl:1
	v_readlane_b32 s6, v102, 12
	v_readlane_b32 s7, v102, 13
	v_mov_b32_dpp v60, v34 row_bcast:15 row_mask:0xa bank_mask:0xf
	v_add_f32_e32 v34, v34, v60
	v_mov_b32_e32 v60, 0
	s_nop 1
	v_mov_b32_dpp v60, v34 row_bcast:31 row_mask:0xc bank_mask:0xf
	v_add_f32_e32 v34, v34, v60
	s_nop 0
	v_readlane_b32 s2, v34, 63
	s_nop 1
	v_add_f32_e32 v34, s2, v86
	v_rsq_f32_e32 v60, v34
	v_pk_mul_f32 v[34:35], v[14:15], v[52:53]
	v_readlane_b32 s2, v102, 6
	v_add_f32_e32 v34, v34, v35
	v_mul_f32_e32 v49, v49, v60
	v_lshlrev_b32_e32 v60, 16, v62
	v_pk_mov_b32 v[62:63], v[30:31], v[60:61] op_sel:[1,0]
	v_mul_f32_e32 v49, 0x3e000000, v49
	v_pk_mul_f32 v[52:53], v[10:11], v[62:63]
	v_cvt_pk_bf16_f32 v49, v49, s0
	v_add_f32_e32 v34, v34, v52
	v_add_f32_e32 v34, v34, v53
	v_mul_f32_e32 v35, 0xbfb8aa3b, v34
	v_exp_f32_e32 v35, v35
	ds_write_b16 v124, v49 offset:768
	v_mul_f32_e32 v49, v9, v32
	v_fmac_f32_e32 v49, v5, v68
	v_add_f32_e32 v35, 1.0, v35
	v_rcp_f32_e32 v35, v35
	v_pk_mul_f32 v[30:31], v[14:15], v[30:31]
	v_mov_b32_e32 v53, s3
	v_fmac_f32_e32 v49, v7, v103
	v_mul_f32_e32 v34, v34, v35
	v_mul_f32_e32 v35, v34, v34
	v_add_f32_e32 v30, v30, v31
	v_fmac_f32_e32 v49, v105, v98
	v_mov_b32_dpp v51, v35 quad_perm:[1,0,3,2] row_mask:0xf bank_mask:0xf
	v_fmac_f32_e32 v51, v34, v34
	v_mul_f32_e32 v31, 0xbfb8aa3b, v49
	v_exp_f32_e32 v31, v31
	v_add_f32_dpp v35, v51, v51 quad_perm:[2,3,0,1] row_mask:0xf bank_mask:0xf bound_ctrl:1
	v_mov_b32_e32 v51, 0
	v_pk_mul_f32 v[76:77], v[14:15], v[62:63]
	v_add_f32_dpp v35, v35, v35 row_half_mirror row_mask:0xf bank_mask:0xf bound_ctrl:1
	v_add_f32_e32 v31, 1.0, v31
	v_rcp_f32_e32 v31, v31
	v_add_f32_dpp v35, v35, v35 row_mirror row_mask:0xf bank_mask:0xf bound_ctrl:1
	v_mul_f32_e32 v31, v49, v31
	s_nop 0
	v_mov_b32_dpp v51, v35 row_bcast:15 row_mask:0xa bank_mask:0xf
	v_add_f32_e32 v35, v35, v51
	v_mov_b32_e32 v51, 0
	s_nop 1
	v_mov_b32_dpp v51, v35 row_bcast:31 row_mask:0xc bank_mask:0xf
	v_add_f32_e32 v35, v35, v51
	s_nop 0
	v_readlane_b32 s4, v35, 63
	s_nop 1
	v_add_f32_e32 v35, s4, v86
	v_rsq_f32_e32 v52, v35
	v_mov_b32_e32 v35, s2
	v_readlane_b32 s4, v3, 7
	v_pk_mul_f32 v[52:53], v[34:35], v[52:53]
	v_pk_mul_f32 v[34:35], v[10:11], v[60:61]
	v_mul_f32_e32 v94, v52, v53
	v_add_f32_e32 v30, v30, v34
	v_add_f32_e32 v30, v30, v35
	v_mul_f32_e32 v34, 0xbfb8aa3b, v30
	v_exp_f32_e32 v34, v34
	v_cvt_pk_bf16_f32 v35, v52, s0
	ds_write_b16 v124, v35 offset:4864
	v_mov_b32_e32 v71, s4
	v_add_f32_e32 v34, 1.0, v34
	v_rcp_f32_e32 v34, v34
	v_readlane_b32 s4, v3, 9
	v_mul_f32_e32 v68, v30, v34
	v_mul_f32_e32 v30, v31, v31
	v_mov_b32_e32 v34, 0
	s_nop 1
	v_mov_b32_dpp v34, v30 quad_perm:[1,0,3,2] row_mask:0xf bank_mask:0xf
	v_fmac_f32_e32 v34, v31, v31
	s_nop 1
	v_add_f32_dpp v30, v34, v34 quad_perm:[2,3,0,1] row_mask:0xf bank_mask:0xf bound_ctrl:1
	v_mov_b32_e32 v34, 0
	s_nop 0
	v_add_f32_dpp v30, v30, v30 row_half_mirror row_mask:0xf bank_mask:0xf bound_ctrl:1
	s_nop 1
	v_add_f32_dpp v30, v30, v30 row_mirror row_mask:0xf bank_mask:0xf bound_ctrl:1
	s_nop 1
	v_mov_b32_dpp v34, v30 row_bcast:15 row_mask:0xa bank_mask:0xf
	v_add_f32_e32 v30, v30, v34
	v_mov_b32_e32 v34, 0
	s_nop 1
	v_mov_b32_dpp v34, v30 row_bcast:31 row_mask:0xc bank_mask:0xf
	v_add_f32_e32 v30, v30, v34
	v_mov_b32_e32 v34, 0
	v_readlane_b32 s3, v30, 63
	v_mul_f32_e32 v30, v68, v68
	s_nop 0
	v_add_f32_e32 v35, s3, v86
	v_mov_b32_dpp v34, v30 quad_perm:[1,0,3,2] row_mask:0xf bank_mask:0xf
	v_fmac_f32_e32 v34, v68, v68
	v_rsq_f32_e32 v35, v35
	s_nop 0
	v_add_f32_dpp v30, v34, v34 quad_perm:[2,3,0,1] row_mask:0xf bank_mask:0xf bound_ctrl:1
	v_mov_b32_e32 v34, 0
	s_nop 0
	v_add_f32_dpp v30, v30, v30 row_half_mirror row_mask:0xf bank_mask:0xf bound_ctrl:1
	s_nop 1
	v_add_f32_dpp v30, v30, v30 row_mirror row_mask:0xf bank_mask:0xf bound_ctrl:1
	s_nop 1
	v_mov_b32_dpp v34, v30 row_bcast:15 row_mask:0xa bank_mask:0xf
	v_add_f32_e32 v30, v30, v34
	v_mov_b32_e32 v34, 0
	s_nop 1
	v_mov_b32_dpp v34, v30 row_bcast:31 row_mask:0xc bank_mask:0xf
	v_add_f32_e32 v30, v30, v34
	v_lshlrev_b32_e32 v34, 16, v66
	v_readlane_b32 s3, v30, 63
	v_mul_f32_e32 v30, v31, v35
	v_mul_f32_e32 v30, 0x3e000000, v30
	v_add_f32_e32 v31, s3, v86
	v_cvt_pk_bf16_f32 v49, v30, s0
	v_xor_b32_e32 v30, 0x70, v65
	v_rsq_f32_e32 v70, v31
	v_or_b32_e32 v51, v30, v64
	v_lshlrev_b32_e32 v35, 16, v67
	v_pk_mul_f32 v[30:31], v[4:5], v[54:55] op_sel_hi:[0,1]
	v_pk_fma_f32 v[30:31], v[2:3], v[58:59], v[30:31] op_sel_hi:[0,1,1]
	v_pk_mov_b32 v[58:59], v[54:55], v[34:35] op_sel:[1,0]
	v_add_u32_e32 v125, s51, v51
	v_pk_fma_f32 v[30:31], v[6:7], v[58:59], v[30:31] op_sel_hi:[0,1,1]
	v_pk_fma_f32 v[30:31], v[8:9], v[34:35], v[30:31] op_sel_hi:[0,1,1]
	v_mul_f32_e32 v53, 0xbfb8aa3b, v30
	v_exp_f32_e32 v53, v53
	v_mul_f32_e32 v54, 0xbfb8aa3b, v31
	v_exp_f32_e32 v55, v54
	v_readlane_b32 s3, v102, 7
	v_add_f32_e32 v51, 1.0, v53
	v_rcp_f32_e32 v54, v51
	v_add_f32_e32 v51, 1.0, v55
	v_rcp_f32_e32 v55, v51
	v_mov_b32_e32 v69, s3
	ds_write_b16 v125, v49 offset:896
	v_mov_b32_e32 v51, 0
	v_pk_mul_f32 v[30:31], v[30:31], v[54:55]
	v_pk_mul_f32 v[54:55], v[68:69], v[70:71]
	v_pk_mul_f32 v[30:31], v[30:31], s[2:3]
	v_cvt_pk_bf16_f32 v49, v54, s0
	ds_write_b16 v125, v49 offset:4992
	v_mul_f32_e32 v49, v9, v103
	v_fmac_f32_e32 v49, v5, v32
	v_fmac_f32_e32 v49, v7, v98
	v_fmac_f32_e32 v49, v105, v100
	v_mul_f32_e32 v32, 0xbfb8aa3b, v49
	v_exp_f32_e32 v32, v32
	s_mov_b64 s[2:3], 0xc000
	v_lshl_add_u64 v[64:65], v[44:45], 0, s[2:3]
	s_mov_b64 s[2:3], 0xd000
	v_add_f32_e32 v32, 1.0, v32
	v_rcp_f32_e32 v32, v32
	v_lshl_add_u64 v[68:69], v[44:45], 0, s[2:3]
	s_mov_b32 s2, 0xc000
	v_add_co_u32_e32 v70, vcc, s2, v44
	v_mul_f32_e32 v49, v49, v32
	v_mul_f32_e32 v32, v49, v49
	s_mov_b64 s[2:3], 0xe000
	v_addc_co_u32_e32 v71, vcc, 0, v45, vcc
	v_mov_b32_dpp v51, v32 quad_perm:[1,0,3,2] row_mask:0xf bank_mask:0xf
	v_fmac_f32_e32 v51, v49, v49
	v_lshl_add_u64 v[72:73], v[44:45], 0, s[2:3]
	s_mov_b32 s2, 0xd000
	v_add_f32_dpp v32, v51, v51 quad_perm:[2,3,0,1] row_mask:0xf bank_mask:0xf bound_ctrl:1
	v_mov_b32_e32 v51, 0
	v_add_co_u32_e32 v74, vcc, s2, v44
	v_add_f32_dpp v32, v32, v32 row_half_mirror row_mask:0xf bank_mask:0xf bound_ctrl:1
	s_mov_b64 s[2:3], 0xf000
	v_addc_co_u32_e32 v75, vcc, 0, v45, vcc
	v_add_f32_dpp v32, v32, v32 row_mirror row_mask:0xf bank_mask:0xf bound_ctrl:1
	v_lshl_add_u64 v[120:121], v[44:45], 0, s[2:3]
	s_mov_b32 s2, 0xe000
	v_mov_b32_dpp v51, v32 row_bcast:15 row_mask:0xa bank_mask:0xf
	v_add_f32_e32 v32, v32, v51
	v_mov_b32_e32 v51, 0
	v_add_co_u32_e32 v128, vcc, s2, v44
	s_nop 0
	v_mov_b32_dpp v51, v32 row_bcast:31 row_mask:0xc bank_mask:0xf
	v_add_f32_e32 v32, v32, v51
	v_addc_co_u32_e32 v129, vcc, 0, v45, vcc
	v_readlane_b32 s2, v32, 63
	v_mul_f32_e32 v95, v54, v55
	s_mov_b32 s3, 0x12000
	v_add_f32_e32 v32, s2, v86
	v_rsq_f32_e32 v51, v32
	s_mov_b32 s2, 0xf000
	v_add_co_u32_e32 v66, vcc, s2, v44
	v_mul_f32_e32 v49, v49, v51
	v_mul_f32_e32 v49, 0x3e000000, v49
	v_cvt_pk_bf16_f32 v113, v49, s0
	v_mul_f32_e32 v49, 0xbfb8aa3b, v123
	v_exp_f32_e32 v51, v49
	flat_load_ushort v110, v[56:57] offset:3072 nt
	flat_load_ushort v111, v[70:71] offset:3072 nt
	flat_load_ushort v112, v[74:75] offset:3072 nt
	flat_load_ushort v106, v[74:75] nt
	flat_load_ushort v49, v[72:73] offset:1024 nt
	flat_load_ushort v53, v[70:71] nt
	flat_load_ushort v122, v[64:65] offset:1024 nt
	flat_load_ushort v126, v[68:69] offset:1024 nt
	v_mov_b32_e32 v64, 0
	v_mov_b32_e32 v32, v61
	v_add_f32_e32 v51, 1.0, v51
	v_rcp_f32_e32 v56, v51
	v_pk_mul_f32 v[62:63], v[10:11], v[32:33]
	v_mul_f32_e32 v61, v12, v61
	v_mul_f32_e32 v69, v10, v33
	v_mul_f32_e32 v56, v123, v56
	v_mul_f32_e32 v57, v56, v56
	v_mov_b32_e32 v68, v62
	v_lshlrev_b32_e32 v62, 16, v107
	v_mov_b32_dpp v64, v57 quad_perm:[1,0,3,2] row_mask:0xf bank_mask:0xf
	v_fmac_f32_e32 v64, v56, v56
	v_mul_f32_e32 v70, v9, v100
	v_fmac_f32_e32 v70, v5, v98
	v_add_f32_dpp v57, v64, v64 quad_perm:[2,3,0,1] row_mask:0xf bank_mask:0xf bound_ctrl:1
	v_mov_b32_e32 v64, 0
	v_fmac_f32_e32 v70, v7, v41
	v_add_f32_dpp v57, v57, v57 row_half_mirror row_mask:0xf bank_mask:0xf bound_ctrl:1
	v_fmac_f32_e32 v70, v105, v39
	v_addc_co_u32_e32 v67, vcc, 0, v45, vcc
	v_add_f32_dpp v57, v57, v57 row_mirror row_mask:0xf bank_mask:0xf bound_ctrl:1
	flat_load_ushort v65, v[128:129] offset:3072 nt
	flat_load_ushort v55, v[66:67] nt
	flat_load_ushort v103, v[128:129] nt
	flat_load_ushort v51, v[120:121] offset:1024 nt
	v_mov_b32_dpp v64, v57 row_bcast:15 row_mask:0xa bank_mask:0xf
	v_add_f32_e32 v57, v57, v64
	v_mov_b32_e32 v64, 0
	ds_write_b16 v114, v113 offset:1024
	s_waitcnt vmcnt(0) lgkmcnt(0)
	v_lshlrev_b32_e32 v107, 16, v111
	v_mov_b32_dpp v64, v57 row_bcast:31 row_mask:0xc bank_mask:0xf
	v_add_f32_e32 v57, v57, v64
	v_lshlrev_b32_e32 v121, 16, v112
	v_readlane_b32 s2, v57, 63
	s_nop 1
	v_add_f32_e32 v57, s2, v86
	v_rsq_f32_e32 v64, v57
	v_mul_f32_e32 v57, v13, v60
	v_mov_b32_e32 v60, v77
	v_mul_f32_e32 v56, v56, v64
	v_mul_f32_e32 v64, 0x3e000000, v56
	v_mov_b32_e32 v56, v76
	v_pk_add_f32 v[56:57], v[56:57], v[60:61]
	v_mul_f32_e32 v61, v11, v62
	v_pk_add_f32 v[56:57], v[56:57], v[68:69]
	v_mov_b32_e32 v60, v63
	v_pk_add_f32 v[56:57], v[56:57], v[60:61]
	v_mov_b32_e32 v63, 0
	v_mul_f32_e32 v60, 0xbfb8aa3b, v56
	v_mul_f32_e32 v61, 0xbfb8aa3b, v57
	v_exp_f32_e32 v60, v60
	v_exp_f32_e32 v61, v61
	v_pk_mul_f32 v[68:69], v[14:15], v[32:33]
	v_cvt_pk_bf16_f32 v64, v64, s0
	v_add_f32_e32 v60, 1.0, v60
	v_add_f32_e32 v61, 1.0, v61
	v_rcp_f32_e32 v60, v60
	v_rcp_f32_e32 v61, v61
	v_mul_f32_e32 v33, v13, v33
	v_mov_b32_e32 v76, 0
	v_pk_mul_f32 v[56:57], v[56:57], v[60:61]
	s_nop 0
	v_pk_mul_f32 v[60:61], v[56:57], v[56:57]
	s_nop 1
	v_add_f32_dpp v60, v60, v60 quad_perm:[1,0,3,2] row_mask:0xf bank_mask:0xf bound_ctrl:1
	v_add_f32_dpp v61, v61, v61 quad_perm:[1,0,3,2] row_mask:0xf bank_mask:0xf bound_ctrl:1
	s_nop 0
	v_add_f32_dpp v60, v60, v60 quad_perm:[2,3,0,1] row_mask:0xf bank_mask:0xf bound_ctrl:1
	v_add_f32_dpp v61, v61, v61 quad_perm:[2,3,0,1] row_mask:0xf bank_mask:0xf bound_ctrl:1
	s_nop 0
	v_add_f32_dpp v60, v60, v60 row_half_mirror row_mask:0xf bank_mask:0xf bound_ctrl:1
	v_add_f32_dpp v61, v61, v61 row_half_mirror row_mask:0xf bank_mask:0xf bound_ctrl:1
	s_nop 0
	v_add_f32_dpp v60, v60, v60 row_mirror row_mask:0xf bank_mask:0xf bound_ctrl:1
	v_add_f32_dpp v61, v61, v61 row_mirror row_mask:0xf bank_mask:0xf bound_ctrl:1
	s_nop 0
	v_mov_b32_dpp v63, v60 row_bcast:15 row_mask:0xa bank_mask:0xf
	v_add_f32_e32 v60, v60, v63
	v_mov_b32_e32 v63, 0
	s_nop 1
	v_mov_b32_dpp v63, v60 row_bcast:31 row_mask:0xc bank_mask:0xf
	v_add_f32_e32 v60, v60, v63
	v_mov_b32_e32 v63, 0
	v_readlane_b32 s2, v60, 63
	s_nop 0
	v_mov_b32_dpp v63, v61 row_bcast:15 row_mask:0xa bank_mask:0xf
	v_add_f32_e32 v61, v61, v63
	v_mov_b32_e32 v63, 0
	v_add_f32_e32 v60, s2, v86
	v_rsq_f32_e32 v60, v60
	v_mov_b32_dpp v63, v61 row_bcast:31 row_mask:0xc bank_mask:0xf
	v_add_f32_e32 v61, v61, v63
	v_mul_f32_e32 v63, 0xbfb8aa3b, v70
	v_exp_f32_e32 v71, v63
	v_readlane_b32 s2, v61, 63
	v_lshlrev_b32_e32 v63, 16, v104
	v_mul_f32_e32 v73, v10, v63
	v_add_f32_e32 v61, s2, v86
	v_rsq_f32_e32 v61, v61
	v_add_f32_e32 v32, 1.0, v71
	v_rcp_f32_e32 v32, v32
	v_mul_f32_e32 v71, v12, v62
	v_pk_mul_f32 v[56:57], v[56:57], v[60:61]
	v_mov_b32_e32 v61, 0
	v_cvt_pk_bf16_f32 v60, v56, s0
	v_mul_f32_e32 v32, v70, v32
	ds_write_b16 v114, v60 offset:5120
	ds_write_b16 v116, v64 offset:1152
	v_mul_f32_e32 v60, v32, v32
	v_lshlrev_b32_e32 v104, 16, v110
	v_lshlrev_b32_e32 v110, 16, v65
	v_mov_b32_dpp v61, v60 quad_perm:[1,0,3,2] row_mask:0xf bank_mask:0xf
	v_fmac_f32_e32 v61, v32, v32
	v_fmac_f32_e32 v132, v105, v104
	v_cvt_pk_bf16_f32 v38, v56, v57
	v_add_f32_dpp v60, v61, v61 quad_perm:[2,3,0,1] row_mask:0xf bank_mask:0xf bound_ctrl:1
	v_mov_b32_e32 v61, 0
	s_nop 0
	v_add_f32_dpp v60, v60, v60 row_half_mirror row_mask:0xf bank_mask:0xf bound_ctrl:1
	s_nop 1
	v_add_f32_dpp v60, v60, v60 row_mirror row_mask:0xf bank_mask:0xf bound_ctrl:1
	s_nop 1
	v_mov_b32_dpp v61, v60 row_bcast:15 row_mask:0xa bank_mask:0xf
	v_add_f32_e32 v60, v60, v61
	v_mov_b32_e32 v61, 0
	s_nop 1
	v_mov_b32_dpp v61, v60 row_bcast:31 row_mask:0xc bank_mask:0xf
	v_add_f32_e32 v60, v60, v61
	s_nop 0
	v_readlane_b32 s2, v60, 63
	s_nop 1
	v_add_f32_e32 v60, s2, v86
	v_rsq_f32_e32 v64, v60
	v_cvt_pk_bf16_f32 v60, v57, s0
	ds_write_b16 v116, v60 offset:5248
	v_pk_mul_f32 v[60:61], v[10:11], v[62:63]
	v_mul_f32_e32 v32, v32, v64
	v_mul_f32_e32 v64, v9, v41
	v_fmac_f32_e32 v64, v5, v100
	v_fmac_f32_e32 v64, v7, v39
	v_fmac_f32_e32 v64, v105, v37
	v_mul_f32_e32 v70, 0xbfb8aa3b, v64
	v_exp_f32_e32 v70, v70
	v_mul_f32_e32 v32, 0x3e000000, v32
	v_cvt_pk_bf16_f32 v32, v32, s0
	ds_write_b16 v115, v32 offset:1280
	v_add_f32_e32 v32, 1.0, v70
	v_rcp_f32_e32 v32, v32
	v_mov_b32_e32 v70, v69
	v_mov_b32_e32 v72, v60
	v_mul_f32_e32 v41, 0xbfb8aa3b, v132
	v_mul_f32_e32 v74, v64, v32
	v_mul_f32_e32 v32, v74, v74
	v_mov_b32_e32 v64, 0
	v_exp_f32_e32 v41, v41
	s_nop 0
	v_mov_b32_dpp v64, v32 quad_perm:[1,0,3,2] row_mask:0xf bank_mask:0xf
	v_fmac_f32_e32 v64, v74, v74
	v_add_f32_e32 v41, 1.0, v41
	v_rcp_f32_e32 v41, v41
	v_add_f32_dpp v32, v64, v64 quad_perm:[2,3,0,1] row_mask:0xf bank_mask:0xf bound_ctrl:1
	v_mov_b32_e32 v64, 0
	v_mul_f32_e32 v41, v132, v41
	v_add_f32_dpp v32, v32, v32 row_half_mirror row_mask:0xf bank_mask:0xf bound_ctrl:1
	s_nop 1
	v_add_f32_dpp v32, v32, v32 row_mirror row_mask:0xf bank_mask:0xf bound_ctrl:1
	s_nop 1
	v_mov_b32_dpp v64, v32 row_bcast:15 row_mask:0xa bank_mask:0xf
	v_add_f32_e32 v75, v32, v64
	v_mov_b32_e32 v32, v68
	v_pk_add_f32 v[32:33], v[32:33], v[70:71]
	v_lshlrev_b32_e32 v64, 16, v97
	v_pk_add_f32 v[32:33], v[32:33], v[72:73]
	v_mul_f32_e32 v69, v11, v64
	v_mov_b32_e32 v68, v61
	v_pk_add_f32 v[32:33], v[32:33], v[68:69]
	v_mov_b32_e32 v69, 0
	v_mul_f32_e32 v60, 0xbfb8aa3b, v32
	v_mul_f32_e32 v61, 0xbfb8aa3b, v33
	v_exp_f32_e32 v60, v60
	v_exp_f32_e32 v61, v61
	v_mov_b32_dpp v76, v75 row_bcast:31 row_mask:0xc bank_mask:0xf
	v_add_f32_e32 v68, v75, v76
	v_add_f32_e32 v60, 1.0, v60
	v_add_f32_e32 v61, 1.0, v61
	v_rcp_f32_e32 v60, v60
	v_rcp_f32_e32 v61, v61
	v_readlane_b32 s2, v68, 63
	v_pk_mul_f32 v[32:33], v[32:33], v[60:61]
	s_nop 0
	v_pk_mul_f32 v[60:61], v[32:33], v[32:33]
	v_add_f32_e32 v68, s2, v86
	v_rsq_f32_e32 v68, v68
	v_add_f32_dpp v60, v60, v60 quad_perm:[1,0,3,2] row_mask:0xf bank_mask:0xf bound_ctrl:1
	v_add_f32_dpp v61, v61, v61 quad_perm:[1,0,3,2] row_mask:0xf bank_mask:0xf bound_ctrl:1
	v_mul_f32_e32 v68, v74, v68
	v_add_f32_dpp v60, v60, v60 quad_perm:[2,3,0,1] row_mask:0xf bank_mask:0xf bound_ctrl:1
	v_add_f32_dpp v61, v61, v61 quad_perm:[2,3,0,1] row_mask:0xf bank_mask:0xf bound_ctrl:1
	v_mul_f32_e32 v68, 0x3e000000, v68
	v_add_f32_dpp v60, v60, v60 row_half_mirror row_mask:0xf bank_mask:0xf bound_ctrl:1
	v_add_f32_dpp v61, v61, v61 row_half_mirror row_mask:0xf bank_mask:0xf bound_ctrl:1
	v_cvt_pk_bf16_f32 v68, v68, s0
	v_add_f32_dpp v60, v60, v60 row_mirror row_mask:0xf bank_mask:0xf bound_ctrl:1
	v_add_f32_dpp v61, v61, v61 row_mirror row_mask:0xf bank_mask:0xf bound_ctrl:1
	s_nop 0
	v_mov_b32_dpp v69, v60 row_bcast:15 row_mask:0xa bank_mask:0xf
	v_add_f32_e32 v60, v60, v69
	v_mov_b32_e32 v69, 0
	s_nop 1
	v_mov_b32_dpp v69, v60 row_bcast:31 row_mask:0xc bank_mask:0xf
	v_add_f32_e32 v60, v60, v69
	v_mov_b32_e32 v69, 0
	v_readlane_b32 s2, v60, 63
	s_nop 0
	v_mov_b32_dpp v69, v61 row_bcast:15 row_mask:0xa bank_mask:0xf
	v_add_f32_e32 v61, v61, v69
	v_mov_b32_e32 v69, 0
	v_add_f32_e32 v60, s2, v86
	v_rsq_f32_e32 v60, v60
	v_mov_b32_dpp v69, v61 row_bcast:31 row_mask:0xc bank_mask:0xf
	v_add_f32_e32 v61, v61, v69
	s_nop 0
	v_readlane_b32 s2, v61, 63
	s_nop 1
	v_add_f32_e32 v61, s2, v86
	v_rsq_f32_e32 v61, v61
	s_mov_b32 s2, 0x10000
	v_add_co_u32_e32 v72, vcc, s2, v44
	v_pk_mul_f32 v[60:61], v[32:33], v[60:61]
	s_nop 0
	v_addc_co_u32_e32 v73, vcc, 0, v45, vcc
	v_cvt_pk_bf16_f32 v32, v60, s0
	ds_write_b16 v115, v32 offset:5376
	ds_write_b16 v117, v68 offset:1408
	v_cvt_pk_bf16_f32 v32, v61, s0
	ds_write_b16 v117, v32 offset:5504
	s_mov_b32 s2, 0x11000
	v_add_co_u32_e32 v76, vcc, s2, v44
	v_pk_mul_f32 v[32:33], v[4:5], v[34:35] op_sel_hi:[0,1]
	s_nop 0
	v_addc_co_u32_e32 v77, vcc, 0, v45, vcc
	flat_load_ushort v113, v[66:67] offset:3072 nt
	flat_load_ushort v129, v[72:73] offset:3072 nt
	flat_load_ushort v130, v[76:77] offset:3072 nt
	v_add_co_u32_e32 v74, vcc, s3, v44
	v_lshlrev_b32_e32 v67, 16, v47
	s_nop 0
	v_addc_co_u32_e32 v75, vcc, 0, v45, vcc
	flat_load_ushort v131, v[74:75] offset:3072 nt
	v_lshlrev_b32_e32 v66, 16, v78
	v_pk_fma_f32 v[32:33], v[2:3], v[58:59], v[32:33] op_sel_hi:[0,1,1]
	v_pk_mov_b32 v[34:35], v[34:35], v[66:67] op_sel:[1,0]
	v_readlane_b32 s3, v3, 8
	v_pk_fma_f32 v[32:33], v[6:7], v[34:35], v[32:33] op_sel_hi:[0,1,1]
	v_pk_fma_f32 v[32:33], v[8:9], v[66:67], v[32:33] op_sel_hi:[0,1,1]
	v_mul_f32_e32 v47, 0xbfb8aa3b, v32
	v_exp_f32_e32 v47, v47
	v_mul_f32_e32 v58, 0xbfb8aa3b, v33
	v_exp_f32_e32 v59, v58
	v_mov_b32_e32 v65, s3
	v_add_f32_e32 v47, 1.0, v47
	v_rcp_f32_e32 v58, v47
	v_add_f32_e32 v47, 1.0, v59
	v_rcp_f32_e32 v59, v47
	v_readlane_b32 s3, v102, 9
	v_pk_mul_f32 v[68:69], v[4:5], v[66:67] op_sel_hi:[0,1]
	v_pk_fma_f32 v[34:35], v[2:3], v[34:35], v[68:69] op_sel_hi:[0,1,1]
	v_pk_mul_f32 v[32:33], v[32:33], v[58:59]
	v_mov_b32_e32 v58, s4
	v_mul_f32_e32 v58, s3, v58
	v_mul_f32_e32 v97, v57, v58
	v_lshlrev_b32_e32 v59, 16, v79
	v_lshlrev_b32_e32 v58, 16, v99
	v_pk_mov_b32 v[70:71], v[66:67], v[58:59] op_sel:[1,0]
	v_readlane_b32 s2, v102, 8
	v_pk_fma_f32 v[34:35], v[6:7], v[70:71], v[34:35] op_sel_hi:[0,1,1]
	v_pk_fma_f32 v[34:35], v[8:9], v[58:59], v[34:35] op_sel_hi:[0,1,1]
	v_mul_f32_e32 v47, s2, v65
	v_mul_f32_e32 v98, v56, v47
	v_mul_f32_e32 v47, 0xbfb8aa3b, v34
	v_exp_f32_e32 v47, v47
	v_mul_f32_e32 v65, 0xbfb8aa3b, v35
	v_exp_f32_e32 v65, v65
	v_pk_mul_f32 v[32:33], v[32:33], s[2:3]
	v_readlane_b32 s3, v3, 10
	v_add_f32_e32 v47, 1.0, v47
	v_readlane_b32 s2, v102, 10
	v_mov_b32_e32 v68, s3
	v_rcp_f32_e32 v66, v47
	v_add_f32_e32 v47, 1.0, v65
	v_rcp_f32_e32 v67, v47
	v_mul_f32_e32 v47, s2, v68
	v_pk_mul_f32 v[68:69], v[14:15], v[62:63]
	v_mul_f32_e32 v100, v60, v47
	v_mul_f32_e32 v47, v41, v41
	v_mov_b32_e32 v62, 0
	v_readlane_b32 s4, v3, 11
	v_readlane_b32 s3, v102, 11
	v_mov_b32_dpp v62, v47 quad_perm:[1,0,3,2] row_mask:0xf bank_mask:0xf
	v_fmac_f32_e32 v62, v41, v41
	v_pk_mul_f32 v[34:35], v[34:35], v[66:67]
	v_mov_b32_e32 v65, s4
	v_add_f32_dpp v47, v62, v62 quad_perm:[2,3,0,1] row_mask:0xf bank_mask:0xf bound_ctrl:1
	v_mov_b32_e32 v62, 0
	v_pk_mul_f32 v[34:35], v[34:35], s[2:3]
	v_add_f32_dpp v47, v47, v47 row_half_mirror row_mask:0xf bank_mask:0xf bound_ctrl:1
	v_mul_f32_e32 v66, s3, v65
	s_mov_b32 s2, 0x13000
	v_add_f32_dpp v47, v47, v47 row_mirror row_mask:0xf bank_mask:0xf bound_ctrl:1
	v_mul_f32_e32 v99, v61, v66
	v_add_co_u32_e32 v66, vcc, s2, v44
	v_mov_b32_dpp v62, v47 row_bcast:15 row_mask:0xa bank_mask:0xf
	v_add_f32_e32 v47, v47, v62
	v_mov_b32_e32 v62, 0
	v_addc_co_u32_e32 v67, vcc, 0, v45, vcc
	s_nop 0
	v_mov_b32_dpp v62, v47 row_bcast:31 row_mask:0xc bank_mask:0xf
	v_add_f32_e32 v47, v47, v62
	v_mul_f32_e32 v62, v9, v37
	v_fmac_f32_e32 v62, v5, v39
	v_fmac_f32_e32 v62, v7, v104
	v_fmac_f32_e32 v62, v105, v107
	v_mul_f32_e32 v39, 0xbfb8aa3b, v62
	v_exp_f32_e32 v39, v39
	v_readlane_b32 s2, v47, 63
	v_lshlrev_b32_e32 v65, 16, v53
	flat_load_ushort v128, v[72:73] nt
	flat_load_ushort v123, v[74:75] nt
	flat_load_ushort v53, v[76:77] offset:1024 nt
	flat_load_ushort v127, v[76:77] nt
	flat_load_ushort v79, v[72:73] offset:1024 nt
	v_add_f32_e32 v47, s2, v86
	v_rsq_f32_e32 v47, v47
	v_add_f32_e32 v39, 1.0, v39
	v_rcp_f32_e32 v39, v39
	s_waitcnt vmcnt(0) lgkmcnt(0)
	v_lshlrev_b32_e32 v120, 16, v113
	v_mul_f32_e32 v41, v41, v47
	v_mul_f32_e32 v41, 0x3e000000, v41
	v_cvt_pk_bf16_f32 v41, v41, s0
	v_mul_f32_e32 v39, v62, v39
	flat_load_ushort v112, v[66:67] offset:1024 nt
	flat_load_ushort v111, v[66:67] nt
	flat_load_ushort v113, v[74:75] offset:1024 nt
	ds_write_b16 v118, v41 offset:1536
	v_mul_f32_e32 v41, v39, v39
	v_mov_b32_e32 v47, 0
	v_mul_f32_e32 v63, v13, v63
	v_mul_f32_e32 v73, v12, v64
	v_mov_b32_dpp v47, v41 quad_perm:[1,0,3,2] row_mask:0xf bank_mask:0xf
	v_fmac_f32_e32 v47, v39, v39
	v_mov_b32_e32 v62, v68
	v_mov_b32_e32 v72, v69
	v_add_f32_dpp v41, v47, v47 quad_perm:[2,3,0,1] row_mask:0xf bank_mask:0xf bound_ctrl:1
	v_mov_b32_e32 v47, 0
	v_pk_add_f32 v[62:63], v[62:63], v[72:73]
	v_add_f32_dpp v41, v41, v41 row_half_mirror row_mask:0xf bank_mask:0xf bound_ctrl:1
	v_lshlrev_b32_e32 v69, 16, v126
	v_lshlrev_b32_e32 v68, 16, v122
	v_add_f32_dpp v41, v41, v41 row_mirror row_mask:0xf bank_mask:0xf bound_ctrl:1
	v_pk_mul_f32 v[72:73], v[4:5], v[58:59] op_sel_hi:[0,1]
	v_pk_fma_f32 v[72:73], v[2:3], v[70:71], v[72:73] op_sel_hi:[0,1,1]
	v_mov_b32_dpp v47, v41 row_bcast:15 row_mask:0xa bank_mask:0xf
	v_add_f32_e32 v41, v41, v47
	v_mov_b32_e32 v47, 0
	v_pk_mov_b32 v[70:71], v[58:59], v[68:69] op_sel:[1,0]
	v_pk_mul_f32 v[74:75], v[10:11], v[64:65]
	v_mov_b32_dpp v47, v41 row_bcast:31 row_mask:0xc bank_mask:0xf
	v_pk_fma_f32 v[58:59], v[6:7], v[70:71], v[72:73] op_sel_hi:[0,1,1]
	v_lshlrev_b32_e32 v77, 16, v130
	v_lshlrev_b32_e32 v76, 16, v131
	v_add_f32_e32 v41, v41, v47
	v_mul_f32_e32 v131, v10, v65
	v_mov_b32_e32 v130, v74
	v_pk_fma_f32 v[72:73], v[8:9], v[68:69], v[58:59] op_sel_hi:[0,1,1]
	v_lshlrev_b32_e32 v58, 16, v106
	v_readlane_b32 s3, v41, 63
	v_pk_add_f32 v[62:63], v[62:63], v[130:131]
	v_mul_f32_e32 v131, v11, v58
	v_mov_b32_e32 v130, v75
	v_add_f32_e32 v41, s3, v86
	v_pk_add_f32 v[62:63], v[62:63], v[130:131]
	v_rsq_f32_e32 v41, v41
	v_mul_f32_e32 v47, 0xbfb8aa3b, v62
	v_exp_f32_e32 v47, v47
	v_mul_f32_e32 v59, 0xbfb8aa3b, v63
	v_exp_f32_e32 v59, v59
	v_mul_f32_e32 v39, v39, v41
	v_mul_f32_e32 v41, v9, v104
	v_fmac_f32_e32 v41, v5, v37
	v_add_f32_e32 v37, 1.0, v47
	v_rcp_f32_e32 v74, v37
	v_add_f32_e32 v37, 1.0, v59
	v_rcp_f32_e32 v75, v37
	v_mov_b32_e32 v47, 0
	v_fmac_f32_e32 v41, v7, v107
	v_fmac_f32_e32 v41, v105, v121
	v_pk_mul_f32 v[62:63], v[62:63], v[74:75]
	v_mul_f32_e32 v39, 0x3e000000, v39
	v_pk_mul_f32 v[74:75], v[62:63], v[62:63]
	v_cvt_pk_bf16_f32 v39, v39, s0
	v_pk_mul_f32 v[130:131], v[14:15], v[64:65]
	v_add_f32_dpp v37, v74, v74 quad_perm:[1,0,3,2] row_mask:0xf bank_mask:0xf bound_ctrl:1
	v_lshlrev_b32_e32 v59, 16, v103
	v_mul_f32_e32 v65, v13, v65
	v_add_f32_dpp v37, v37, v37 quad_perm:[2,3,0,1] row_mask:0xf bank_mask:0xf bound_ctrl:1
	v_mul_f32_e32 v133, v12, v58
	v_mov_b32_e32 v132, v131
	v_add_f32_dpp v37, v37, v37 row_half_mirror row_mask:0xf bank_mask:0xf bound_ctrl:1
	v_mul_f32_e32 v135, v10, v59
	v_readlane_b32 s2, v3, 12
	v_add_f32_dpp v37, v37, v37 row_mirror row_mask:0xf bank_mask:0xf bound_ctrl:1
	v_readlane_b32 s4, v3, 15
	v_lshlrev_b32_e32 v78, 16, v129
	v_mov_b32_dpp v47, v37 row_bcast:15 row_mask:0xa bank_mask:0xf
	v_add_f32_e32 v37, v37, v47
	v_mov_b32_e32 v47, 0
	v_lshlrev_b32_e32 v53, 16, v53
	v_mul_f32_e32 v126, v9, v77
	v_mov_b32_dpp v47, v37 row_bcast:31 row_mask:0xc bank_mask:0xf
	v_add_f32_e32 v37, v37, v47
	v_mov_b32_e32 v47, 0
	v_readlane_b32 s3, v37, 63
	v_fmac_f32_e32 v126, v5, v78
	v_fmac_f32_e32 v126, v7, v76
	v_add_f32_e32 v37, s3, v86
	v_rsq_f32_e32 v74, v37
	s_nop 0
	v_add_f32_dpp v37, v75, v75 quad_perm:[1,0,3,2] row_mask:0xf bank_mask:0xf bound_ctrl:1
	s_nop 1
	v_add_f32_dpp v37, v37, v37 quad_perm:[2,3,0,1] row_mask:0xf bank_mask:0xf bound_ctrl:1
	s_nop 1
	v_add_f32_dpp v37, v37, v37 row_half_mirror row_mask:0xf bank_mask:0xf bound_ctrl:1
	s_nop 1
	v_add_f32_dpp v37, v37, v37 row_mirror row_mask:0xf bank_mask:0xf bound_ctrl:1
	s_nop 1
	v_mov_b32_dpp v47, v37 row_bcast:15 row_mask:0xa bank_mask:0xf
	v_add_f32_e32 v37, v37, v47
	v_mov_b32_e32 v47, 0
	s_nop 1
	v_mov_b32_dpp v47, v37 row_bcast:31 row_mask:0xc bank_mask:0xf
	v_add_f32_e32 v37, v37, v47
	s_nop 0
	v_readlane_b32 s3, v37, 63
	s_nop 1
	v_add_f32_e32 v37, s3, v86
	v_rsq_f32_e32 v75, v37
	v_mul_f32_e32 v37, 0xbfb8aa3b, v41
	v_exp_f32_e32 v37, v37
	v_pk_mul_f32 v[74:75], v[62:63], v[74:75]
	s_nop 0
	v_cvt_pk_bf16_f32 v47, v74, s0
	v_add_f32_e32 v37, 1.0, v37
	v_rcp_f32_e32 v37, v37
	ds_write_b16 v118, v47 offset:5632
	ds_write_b16 v119, v39 offset:1664
	v_mov_b32_e32 v47, 0
	v_cvt_pk_bf16_f32 v39, v75, s0
	v_mul_f32_e32 v37, v41, v37
	v_mul_f32_e32 v41, v37, v37
	ds_write_b16 v119, v39 offset:5760
	s_nop 0
	v_mov_b32_dpp v47, v41 quad_perm:[1,0,3,2] row_mask:0xf bank_mask:0xf
	v_fmac_f32_e32 v47, v37, v37
	s_nop 1
	v_add_f32_dpp v41, v47, v47 quad_perm:[2,3,0,1] row_mask:0xf bank_mask:0xf bound_ctrl:1
	v_mov_b32_e32 v47, 0
	s_nop 0
	v_add_f32_dpp v41, v41, v41 row_half_mirror row_mask:0xf bank_mask:0xf bound_ctrl:1
	s_nop 1
	v_add_f32_dpp v41, v41, v41 row_mirror row_mask:0xf bank_mask:0xf bound_ctrl:1
	s_nop 1
	v_mov_b32_dpp v47, v41 row_bcast:15 row_mask:0xa bank_mask:0xf
	v_add_f32_e32 v41, v41, v47
	v_mov_b32_e32 v47, 0
	s_nop 1
	v_mov_b32_dpp v47, v41 row_bcast:31 row_mask:0xc bank_mask:0xf
	v_add_f32_e32 v41, v41, v47
	v_mul_f32_e32 v47, v9, v107
	v_fmac_f32_e32 v47, v5, v104
	v_fmac_f32_e32 v47, v7, v121
	v_fmac_f32_e32 v47, v105, v110
	v_mul_f32_e32 v62, 0xbfb8aa3b, v47
	v_readlane_b32 s3, v41, 63
	v_exp_f32_e32 v64, v62
	v_pk_mul_f32 v[62:63], v[10:11], v[58:59]
	v_add_f32_e32 v41, s3, v86
	v_rsq_f32_e32 v41, v41
	v_add_f32_e32 v39, 1.0, v64
	v_rcp_f32_e32 v39, v39
	v_mov_b32_e32 v64, v130
	v_mul_f32_e32 v37, v37, v41
	v_mul_f32_e32 v37, 0x3e000000, v37
	v_cvt_pk_bf16_f32 v37, v37, s0
	ds_write_b16 v124, v37 offset:1792
	v_mul_f32_e32 v37, v47, v39
	v_mul_f32_e32 v39, v37, v37
	v_mov_b32_e32 v41, 0
	v_pk_add_f32 v[64:65], v[64:65], v[132:133]
	v_mov_b32_e32 v134, v62
	v_mov_b32_dpp v41, v39 quad_perm:[1,0,3,2] row_mask:0xf bank_mask:0xf
	v_fmac_f32_e32 v41, v37, v37
	v_lshlrev_b32_e32 v62, 16, v55
	v_pk_add_f32 v[64:65], v[64:65], v[134:135]
	v_add_f32_dpp v39, v41, v41 quad_perm:[2,3,0,1] row_mask:0xf bank_mask:0xf bound_ctrl:1
	v_mov_b32_e32 v41, 0
	v_mul_f32_e32 v131, v11, v62
	v_add_f32_dpp v39, v39, v39 row_half_mirror row_mask:0xf bank_mask:0xf bound_ctrl:1
	v_mov_b32_e32 v130, v63
	v_pk_add_f32 v[64:65], v[64:65], v[130:131]
	v_add_f32_dpp v39, v39, v39 row_mirror row_mask:0xf bank_mask:0xf bound_ctrl:1
	v_mov_b32_e32 v55, 0
	v_cvt_pk_bf16_f32 v132, v74, v75
	v_mov_b32_dpp v41, v39 row_bcast:15 row_mask:0xa bank_mask:0xf
	v_add_f32_e32 v39, v39, v41
	v_mov_b32_e32 v41, 0
	v_lshlrev_b32_e32 v63, 16, v128
	s_nop 0
	v_mov_b32_dpp v41, v39 row_bcast:31 row_mask:0xc bank_mask:0xf
	v_add_f32_e32 v39, v39, v41
	s_nop 0
	v_readlane_b32 s3, v39, 63
	s_nop 1
	v_add_f32_e32 v39, s3, v86
	v_rsq_f32_e32 v39, v39
	s_nop 0
	v_mul_f32_e32 v37, v37, v39
	v_mul_f32_e32 v37, 0x3e000000, v37
	v_cvt_pk_bf16_f32 v103, v37, s0
	v_mul_f32_e32 v37, 0xbfb8aa3b, v64
	v_exp_f32_e32 v37, v37
	v_mul_f32_e32 v39, 0xbfb8aa3b, v65
	v_exp_f32_e32 v39, v39
	v_add_f32_e32 v37, 1.0, v37
	v_rcp_f32_e32 v130, v37
	v_add_f32_e32 v37, 1.0, v39
	v_rcp_f32_e32 v131, v37
	v_cvt_pk_bf16_f32 v37, v40, v46
	v_cvt_pk_bf16_f32 v39, v60, v61
	v_pk_mul_f32 v[40:41], v[64:65], v[130:131]
	s_nop 0
	v_pk_mul_f32 v[46:47], v[40:41], v[40:41]
	v_cvt_pk_bf16_f32 v131, v52, v54
	v_cvt_pk_bf16_f32 v130, v48, v50
	v_add_f32_dpp v46, v46, v46 quad_perm:[1,0,3,2] row_mask:0xf bank_mask:0xf bound_ctrl:1
	v_add_f32_dpp v47, v47, v47 quad_perm:[1,0,3,2] row_mask:0xf bank_mask:0xf bound_ctrl:1
	s_nop 0
	v_add_f32_dpp v46, v46, v46 quad_perm:[2,3,0,1] row_mask:0xf bank_mask:0xf bound_ctrl:1
	v_add_f32_dpp v47, v47, v47 quad_perm:[2,3,0,1] row_mask:0xf bank_mask:0xf bound_ctrl:1
	s_nop 0
	v_add_f32_dpp v46, v46, v46 row_half_mirror row_mask:0xf bank_mask:0xf bound_ctrl:1
	v_add_f32_dpp v47, v47, v47 row_half_mirror row_mask:0xf bank_mask:0xf bound_ctrl:1
	s_nop 0
	v_add_f32_dpp v46, v46, v46 row_mirror row_mask:0xf bank_mask:0xf bound_ctrl:1
	v_add_f32_dpp v47, v47, v47 row_mirror row_mask:0xf bank_mask:0xf bound_ctrl:1
	s_nop 0
	v_mov_b32_dpp v55, v46 row_bcast:15 row_mask:0xa bank_mask:0xf
	v_add_f32_e32 v46, v46, v55
	v_mov_b32_e32 v55, 0
	s_nop 1
	v_mov_b32_dpp v55, v46 row_bcast:31 row_mask:0xc bank_mask:0xf
	v_add_f32_e32 v46, v46, v55
	v_mov_b32_e32 v55, 0
	v_readlane_b32 s3, v46, 63
	s_nop 0
	v_mov_b32_dpp v55, v47 row_bcast:15 row_mask:0xa bank_mask:0xf
	v_add_f32_e32 v47, v47, v55
	v_mov_b32_e32 v55, 0
	v_add_f32_e32 v46, s3, v86
	v_rsq_f32_e32 v46, v46
	v_mov_b32_dpp v55, v47 row_bcast:31 row_mask:0xc bank_mask:0xf
	v_add_f32_e32 v47, v47, v55
	s_nop 0
	v_readlane_b32 s3, v47, 63
	s_nop 1
	v_add_f32_e32 v47, s3, v86
	v_rsq_f32_e32 v47, v47
	s_mov_b32 s3, 0x14000
	v_pk_mul_f32 v[54:55], v[40:41], v[46:47]
	s_nop 0
	v_cvt_pk_bf16_f32 v40, v54, s0
	ds_write_b16 v124, v40 offset:5888
	ds_write_b16 v125, v103 offset:1920
	v_cvt_pk_bf16_f32 v40, v55, s0
	ds_write_b16 v125, v40 offset:6016
	v_add_co_u32_e32 v40, vcc, s14, v42
	v_cvt_pk_bf16_f32 v133, v54, v55
	s_nop 0
	v_addc_co_u32_e32 v41, vcc, 0, v43, vcc
	flat_store_dwordx4 v[40:41], v[36:39] offset:2048
	flat_store_dwordx4 v[16:17], v[130:133] offset:512
	v_add_co_u32_e32 v56, vcc, s3, v44
	v_mov_b32_e32 v38, s2
	s_nop 0
	v_addc_co_u32_e32 v57, vcc, 0, v45, vcc
	flat_load_ushort v52, v[66:67] offset:3072 nt
	flat_load_ushort v122, v[56:57] offset:3072 nt
	v_readlane_b32 s2, v3, 13
	v_mul_f32_e32 v38, s6, v38
	v_mul_f32_e32 v104, v74, v38
	v_mov_b32_e32 v39, s2
	v_mul_f32_e32 v39, s7, v39
	v_mul_f32_e32 v103, v75, v39
	v_lshlrev_b32_e32 v41, 16, v51
	v_lshlrev_b32_e32 v40, 16, v49
	v_pk_mul_f32 v[38:39], v[4:5], v[68:69] op_sel_hi:[0,1]
	v_pk_fma_f32 v[38:39], v[2:3], v[70:71], v[38:39] op_sel_hi:[0,1,1]
	v_pk_mov_b32 v[42:43], v[68:69], v[40:41] op_sel:[1,0]
	v_mul_f32_e32 v69, v9, v121
	v_pk_fma_f32 v[38:39], v[6:7], v[42:43], v[38:39] op_sel_hi:[0,1,1]
	v_pk_fma_f32 v[38:39], v[8:9], v[40:41], v[38:39] op_sel_hi:[0,1,1]
	v_mul_f32_e32 v46, 0xbfb8aa3b, v38
	v_mul_f32_e32 v47, 0xbfb8aa3b, v39
	v_exp_f32_e32 v46, v46
	v_exp_f32_e32 v47, v47
	v_readlane_b32 s3, v3, 14
	v_fmac_f32_e32 v69, v5, v107
	v_add_f32_e32 v46, 1.0, v46
	v_add_f32_e32 v47, 1.0, v47
	v_rcp_f32_e32 v46, v46
	v_rcp_f32_e32 v47, v47
	v_readlane_b32 s2, v102, 14
	v_mov_b32_e32 v48, s3
	v_fmac_f32_e32 v69, v7, v110
	v_mul_f32_e32 v66, s2, v48
	v_fmac_f32_e32 v69, v105, v120
	v_mul_f32_e32 v36, 0xbfb8aa3b, v72
	v_mul_f32_e32 v37, 0xbfb8aa3b, v73
	v_readlane_b32 s3, v102, 15
	v_pk_mul_f32 v[38:39], v[38:39], v[46:47]
	v_mov_b32_e32 v46, s4
	v_mul_f32_e32 v107, v54, v66
	v_mul_f32_e32 v54, 0xbfb8aa3b, v69
	v_exp_f32_e32 v36, v36
	v_exp_f32_e32 v37, v37
	v_mul_f32_e32 v67, s3, v46
	v_pk_mul_f32 v[46:47], v[14:15], v[58:59]
	v_exp_f32_e32 v58, v54
	v_pk_mul_f32 v[38:39], v[38:39], s[2:3]
	s_mov_b64 s[2:3], 0x14000
	v_lshl_add_u64 v[48:49], v[44:45], 0, s[2:3]
	s_mov_b64 s[2:3], 0x15000
	v_add_f32_e32 v36, 1.0, v36
	v_add_f32_e32 v37, 1.0, v37
	v_lshl_add_u64 v[50:51], v[44:45], 0, s[2:3]
	s_mov_b64 s[2:3], 0x16000
	v_add_f32_e32 v58, 1.0, v58
	v_rcp_f32_e32 v36, v36
	v_rcp_f32_e32 v37, v37
	v_lshl_add_u64 v[60:61], v[44:45], 0, s[2:3]
	s_mov_b64 s[2:3], 0x17000
	v_rcp_f32_e32 v58, v58
	v_lshl_add_u64 v[64:65], v[44:45], 0, s[2:3]
	s_mov_b32 s2, 0x15000
	v_add_co_u32_e32 v54, vcc, s2, v44
	v_mul_f32_e32 v106, v55, v67
	s_nop 0
	v_addc_co_u32_e32 v55, vcc, 0, v45, vcc
	v_pk_mul_f32 v[36:37], v[72:73], v[36:37]
	flat_load_ushort v73, v[54:55] nt
	flat_load_ushort v68, v[56:57] nt
	flat_load_ushort v66, v[48:49] offset:1024 nt
	flat_load_ushort v67, v[50:51] offset:1024 nt
	flat_load_ushort v74, v[60:61] offset:1024 nt
	flat_load_ushort v75, v[64:65] offset:1024 nt
	v_mul_f32_e32 v50, v69, v58
	v_mul_f32_e32 v48, v50, v50
	v_mov_b32_e32 v49, 0
	v_mul_f32_e32 v61, v9, v110
	v_fmac_f32_e32 v61, v5, v121
	v_mov_b32_dpp v49, v48 quad_perm:[1,0,3,2] row_mask:0xf bank_mask:0xf
	v_fmac_f32_e32 v49, v50, v50
	v_fmac_f32_e32 v61, v7, v120
	v_fmac_f32_e32 v61, v105, v78
	v_add_f32_dpp v48, v49, v49 quad_perm:[2,3,0,1] row_mask:0xf bank_mask:0xf bound_ctrl:1
	v_mov_b32_e32 v49, 0
	s_mov_b32 s2, 0x16000
	v_add_f32_dpp v48, v48, v48 row_half_mirror row_mask:0xf bank_mask:0xf bound_ctrl:1
	v_add_co_u32_e32 v56, vcc, s2, v44
	s_nop 0
	v_add_f32_dpp v48, v48, v48 row_mirror row_mask:0xf bank_mask:0xf bound_ctrl:1
	s_waitcnt vmcnt(0) lgkmcnt(0)
	v_lshlrev_b32_e32 v71, 16, v52
	v_addc_co_u32_e32 v57, vcc, 0, v45, vcc
	v_mov_b32_dpp v49, v48 row_bcast:15 row_mask:0xa bank_mask:0xf
	v_add_f32_e32 v48, v48, v49
	v_mov_b32_e32 v49, 0
	s_mov_b32 s2, 0x17000
	v_readlane_b32 s4, v3, 17
	v_mov_b32_dpp v49, v48 row_bcast:31 row_mask:0xc bank_mask:0xf
	v_add_f32_e32 v48, v48, v49
	v_fmac_f32_e32 v126, v105, v71
	v_readlane_b32 s3, v48, 63
	v_lshlrev_b32_e32 v122, 16, v122
	v_pk_mul_f32 v[36:37], v[36:37], s[6:7]
	v_add_f32_e32 v48, s3, v86
	v_rsq_f32_e32 v51, v48
	v_pk_mul_f32 v[48:49], v[10:11], v[62:63]
	v_readlane_b32 s3, v3, 16
	v_readlane_b32 s7, v102, 21
	v_mul_f32_e32 v50, v50, v51
	v_mul_f32_e32 v50, 0x3e000000, v50
	v_cvt_pk_bf16_f32 v58, v50, s0
	v_mul_f32_e32 v50, 0xbfb8aa3b, v61
	v_exp_f32_e32 v52, v50
	v_add_co_u32_e32 v50, vcc, s2, v44
	v_readlane_b32 s6, v102, 20
	v_add_f32_e32 v52, 1.0, v52
	v_rcp_f32_e32 v64, v52
	v_addc_co_u32_e32 v51, vcc, 0, v45, vcc
	flat_load_ushort v52, v[54:55] offset:3072 nt
	flat_load_ushort v60, v[56:57] offset:3072 nt
	flat_load_ushort v70, v[50:51] nt
	flat_load_ushort v72, v[56:57] nt
	v_mul_f32_e32 v54, v61, v64
	v_mul_f32_e32 v55, v54, v54
	v_mov_b32_e32 v56, 0
	v_mul_f32_e32 v57, v12, v62
	ds_write_b16 v114, v58 offset:2048
	v_mov_b32_dpp v56, v55 quad_perm:[1,0,3,2] row_mask:0xf bank_mask:0xf
	v_fmac_f32_e32 v56, v54, v54
	v_mov_b32_e32 v58, v48
	v_mul_f32_e32 v64, v9, v120
	v_add_f32_dpp v55, v56, v56 quad_perm:[2,3,0,1] row_mask:0xf bank_mask:0xf bound_ctrl:1
	v_mov_b32_e32 v56, 0
	v_fmac_f32_e32 v64, v5, v110
	v_add_f32_dpp v55, v55, v55 row_half_mirror row_mask:0xf bank_mask:0xf bound_ctrl:1
	v_fmac_f32_e32 v64, v7, v78
	v_fmac_f32_e32 v64, v105, v77
	v_add_f32_dpp v55, v55, v55 row_mirror row_mask:0xf bank_mask:0xf bound_ctrl:1
	v_mov_b32_e32 v110, 0
	s_waitcnt vmcnt(0) lgkmcnt(0)
	v_lshlrev_b32_e32 v134, 16, v52
	v_mov_b32_dpp v56, v55 row_bcast:15 row_mask:0xa bank_mask:0xf
	v_add_f32_e32 v55, v55, v56
	v_mov_b32_e32 v56, 0
	v_lshlrev_b32_e32 v52, 16, v79
	v_lshlrev_b32_e32 v129, 16, v60
	v_mov_b32_dpp v56, v55 row_bcast:31 row_mask:0xc bank_mask:0xf
	v_add_f32_e32 v55, v55, v56
	v_mul_f32_e32 v149, v9, v134
	v_readlane_b32 s2, v55, 63
	v_fmac_f32_e32 v149, v5, v122
	v_fmac_f32_e32 v149, v7, v129
	v_add_f32_e32 v55, s2, v86
	v_rsq_f32_e32 v56, v55
	v_mul_f32_e32 v55, v13, v59
	v_mul_f32_e32 v59, v10, v63
	v_mul_f32_e32 v54, v54, v56
	v_mul_f32_e32 v61, 0x3e000000, v54
	v_mov_b32_e32 v54, v46
	v_mov_b32_e32 v56, v47
	v_pk_add_f32 v[46:47], v[54:55], v[56:57]
	v_mov_b32_e32 v56, v49
	v_pk_add_f32 v[54:55], v[46:47], v[58:59]
	v_lshlrev_b32_e32 v46, 16, v127
	v_mul_f32_e32 v57, v11, v46
	v_pk_add_f32 v[48:49], v[54:55], v[56:57]
	v_cvt_pk_bf16_f32 v61, v61, s0
	v_mul_f32_e32 v47, 0xbfb8aa3b, v48
	v_exp_f32_e32 v47, v47
	v_mul_f32_e32 v54, 0xbfb8aa3b, v49
	v_exp_f32_e32 v55, v54
	v_pk_mul_f32 v[58:59], v[14:15], v[62:63]
	v_add_f32_e32 v47, 1.0, v47
	v_rcp_f32_e32 v54, v47
	v_add_f32_e32 v47, 1.0, v55
	v_rcp_f32_e32 v55, v47
	v_mov_b32_e32 v62, 0
	v_pk_mul_f32 v[48:49], v[48:49], v[54:55]
	s_nop 0
	v_pk_mul_f32 v[54:55], v[48:49], v[48:49]
	s_nop 1
	v_add_f32_dpp v47, v54, v54 quad_perm:[1,0,3,2] row_mask:0xf bank_mask:0xf bound_ctrl:1
	v_mov_b32_e32 v54, 0
	s_nop 0
	v_add_f32_dpp v47, v47, v47 quad_perm:[2,3,0,1] row_mask:0xf bank_mask:0xf bound_ctrl:1
	s_nop 1
	v_add_f32_dpp v47, v47, v47 row_half_mirror row_mask:0xf bank_mask:0xf bound_ctrl:1
	s_nop 1
	v_add_f32_dpp v47, v47, v47 row_mirror row_mask:0xf bank_mask:0xf bound_ctrl:1
	s_nop 1
	v_mov_b32_dpp v54, v47 row_bcast:15 row_mask:0xa bank_mask:0xf
	v_add_f32_e32 v47, v47, v54
	v_mov_b32_e32 v54, 0
	s_nop 1
	v_mov_b32_dpp v54, v47 row_bcast:31 row_mask:0xc bank_mask:0xf
	v_add_f32_e32 v47, v47, v54
	s_nop 0
	v_readlane_b32 s2, v47, 63
	s_nop 1
	v_add_f32_e32 v47, s2, v86
	v_rsq_f32_e32 v54, v47
	s_nop 0
	v_add_f32_dpp v47, v55, v55 quad_perm:[1,0,3,2] row_mask:0xf bank_mask:0xf bound_ctrl:1
	v_mov_b32_e32 v55, 0
	s_nop 0
	v_add_f32_dpp v47, v47, v47 quad_perm:[2,3,0,1] row_mask:0xf bank_mask:0xf bound_ctrl:1
	s_nop 1
	v_add_f32_dpp v47, v47, v47 row_half_mirror row_mask:0xf bank_mask:0xf bound_ctrl:1
	s_nop 1
	v_add_f32_dpp v47, v47, v47 row_mirror row_mask:0xf bank_mask:0xf bound_ctrl:1
	s_nop 1
	v_mov_b32_dpp v55, v47 row_bcast:15 row_mask:0xa bank_mask:0xf
	v_add_f32_e32 v47, v47, v55
	v_mov_b32_e32 v55, 0
	s_nop 1
	v_mov_b32_dpp v55, v47 row_bcast:31 row_mask:0xc bank_mask:0xf
	v_add_f32_e32 v47, v47, v55
	s_nop 0
	v_readlane_b32 s2, v47, 63
	s_nop 1
	v_add_f32_e32 v47, s2, v86
	v_rsq_f32_e32 v55, v47
	v_mul_f32_e32 v47, 0xbfb8aa3b, v64
	v_exp_f32_e32 v65, v47
	v_lshlrev_b32_e32 v47, 16, v123
	v_pk_mul_f32 v[56:57], v[48:49], v[54:55]
	v_add_f32_e32 v48, 1.0, v65
	v_rcp_f32_e32 v48, v48
	v_cvt_pk_bf16_f32 v49, v56, s0
	ds_write_b16 v114, v49 offset:6144
	ds_write_b16 v116, v61 offset:2176
	v_mov_b32_e32 v49, 0
	v_mul_f32_e32 v54, v64, v48
	v_mul_f32_e32 v48, v54, v54
	v_mul_f32_e32 v61, v9, v78
	v_fmac_f32_e32 v61, v5, v120
	v_mov_b32_dpp v49, v48 quad_perm:[1,0,3,2] row_mask:0xf bank_mask:0xf
	v_fmac_f32_e32 v49, v54, v54
	v_fmac_f32_e32 v61, v7, v77
	v_fmac_f32_e32 v61, v105, v76
	v_add_f32_dpp v48, v49, v49 quad_perm:[2,3,0,1] row_mask:0xf bank_mask:0xf bound_ctrl:1
	v_mov_b32_e32 v49, 0
	v_mul_f32_e32 v65, v10, v47
	v_add_f32_dpp v48, v48, v48 row_half_mirror row_mask:0xf bank_mask:0xf bound_ctrl:1
	s_nop 1
	v_add_f32_dpp v48, v48, v48 row_mirror row_mask:0xf bank_mask:0xf bound_ctrl:1
	s_nop 1
	v_mov_b32_dpp v49, v48 row_bcast:15 row_mask:0xa bank_mask:0xf
	v_add_f32_e32 v48, v48, v49
	v_mov_b32_e32 v49, 0
	s_nop 1
	v_mov_b32_dpp v49, v48 row_bcast:31 row_mask:0xc bank_mask:0xf
	v_add_f32_e32 v48, v48, v49
	s_nop 0
	v_readlane_b32 s2, v48, 63
	s_nop 1
	v_add_f32_e32 v48, s2, v86
	v_rsq_f32_e32 v55, v48
	v_cvt_pk_bf16_f32 v48, v57, s0
	ds_write_b16 v116, v48 offset:6272
	v_pk_mul_f32 v[48:49], v[10:11], v[46:47]
	v_mul_f32_e32 v54, v54, v55
	v_mul_f32_e32 v55, 0xbfb8aa3b, v61
	v_exp_f32_e32 v55, v55
	v_mul_f32_e32 v54, 0x3e000000, v54
	v_cvt_pk_bf16_f32 v54, v54, s0
	ds_write_b16 v115, v54 offset:2304
	v_add_f32_e32 v54, 1.0, v55
	v_rcp_f32_e32 v54, v54
	v_mul_f32_e32 v55, v13, v63
	v_mul_f32_e32 v63, v12, v46
	v_mov_b32_e32 v64, v48
	v_mul_f32_e32 v61, v61, v54
	v_mul_f32_e32 v54, v61, v61
	v_lshlrev_b32_e32 v48, 16, v111
	s_nop 0
	v_mov_b32_dpp v62, v54 quad_perm:[1,0,3,2] row_mask:0xf bank_mask:0xf
	v_fmac_f32_e32 v62, v61, v61
	s_nop 1
	v_add_f32_dpp v54, v62, v62 quad_perm:[2,3,0,1] row_mask:0xf bank_mask:0xf bound_ctrl:1
	v_mov_b32_e32 v62, 0
	s_nop 0
	v_add_f32_dpp v54, v54, v54 row_half_mirror row_mask:0xf bank_mask:0xf bound_ctrl:1
	s_nop 1
	v_add_f32_dpp v54, v54, v54 row_mirror row_mask:0xf bank_mask:0xf bound_ctrl:1
	s_nop 1
	v_mov_b32_dpp v62, v54 row_bcast:15 row_mask:0xa bank_mask:0xf
	v_add_f32_e32 v69, v54, v62
	v_mov_b32_e32 v54, v58
	v_mov_b32_e32 v62, v59
	v_pk_add_f32 v[54:55], v[54:55], v[62:63]
	v_mul_f32_e32 v59, v11, v48
	v_pk_add_f32 v[54:55], v[54:55], v[64:65]
	v_mov_b32_e32 v58, v49
	v_pk_add_f32 v[54:55], v[54:55], v[58:59]
	v_mov_b32_dpp v110, v69 row_bcast:31 row_mask:0xc bank_mask:0xf
	v_mul_f32_e32 v49, 0xbfb8aa3b, v54
	v_exp_f32_e32 v49, v49
	v_mul_f32_e32 v58, 0xbfb8aa3b, v55
	v_exp_f32_e32 v59, v58
	v_add_f32_e32 v62, v69, v110
	v_add_f32_e32 v49, 1.0, v49
	v_rcp_f32_e32 v58, v49
	v_add_f32_e32 v49, 1.0, v59
	v_rcp_f32_e32 v59, v49
	v_readlane_b32 s2, v62, 63
	v_mov_b32_e32 v62, 0
	v_pk_mul_f32 v[54:55], v[54:55], v[58:59]
	s_nop 0
	v_pk_mul_f32 v[58:59], v[54:55], v[54:55]
	v_add_f32_e32 v49, s2, v86
	v_rsq_f32_e32 v49, v49
	v_add_f32_dpp v58, v58, v58 quad_perm:[1,0,3,2] row_mask:0xf bank_mask:0xf bound_ctrl:1
	v_add_f32_dpp v59, v59, v59 quad_perm:[1,0,3,2] row_mask:0xf bank_mask:0xf bound_ctrl:1
	v_mul_f32_e32 v49, v61, v49
	v_add_f32_dpp v58, v58, v58 quad_perm:[2,3,0,1] row_mask:0xf bank_mask:0xf bound_ctrl:1
	v_add_f32_dpp v59, v59, v59 quad_perm:[2,3,0,1] row_mask:0xf bank_mask:0xf bound_ctrl:1
	v_mul_f32_e32 v49, 0x3e000000, v49
	v_add_f32_dpp v58, v58, v58 row_half_mirror row_mask:0xf bank_mask:0xf bound_ctrl:1
	v_add_f32_dpp v59, v59, v59 row_half_mirror row_mask:0xf bank_mask:0xf bound_ctrl:1
	v_cvt_pk_bf16_f32 v49, v49, s0
	v_add_f32_dpp v58, v58, v58 row_mirror row_mask:0xf bank_mask:0xf bound_ctrl:1
	v_add_f32_dpp v59, v59, v59 row_mirror row_mask:0xf bank_mask:0xf bound_ctrl:1
	v_pk_mov_b32 v[60:61], v[40:41], v[52:53] op_sel:[1,0]
	v_mov_b32_dpp v62, v58 row_bcast:15 row_mask:0xa bank_mask:0xf
	v_add_f32_e32 v58, v58, v62
	v_mov_b32_e32 v62, 0
	s_nop 1
	v_mov_b32_dpp v62, v58 row_bcast:31 row_mask:0xc bank_mask:0xf
	v_add_f32_e32 v58, v58, v62
	v_mov_b32_e32 v62, 0
	v_readlane_b32 s2, v58, 63
	s_nop 0
	v_mov_b32_dpp v62, v59 row_bcast:15 row_mask:0xa bank_mask:0xf
	v_add_f32_e32 v59, v59, v62
	v_mov_b32_e32 v62, 0
	v_add_f32_e32 v58, s2, v86
	v_rsq_f32_e32 v58, v58
	v_mov_b32_dpp v62, v59 row_bcast:31 row_mask:0xc bank_mask:0xf
	v_add_f32_e32 v59, v59, v62
	s_nop 0
	v_readlane_b32 s2, v59, 63
	s_nop 1
	v_add_f32_e32 v59, s2, v86
	v_rsq_f32_e32 v59, v59
	s_mov_b32 s2, 0x18000
	v_pk_mul_f32 v[58:59], v[54:55], v[58:59]
	s_nop 0
	v_cvt_pk_bf16_f32 v54, v58, s0
	ds_write_b16 v115, v54 offset:6400
	ds_write_b16 v117, v49 offset:2432
	v_cvt_pk_bf16_f32 v49, v59, s0
	v_add_co_u32_e32 v54, vcc, s2, v44
	ds_write_b16 v117, v49 offset:6528
	s_nop 0
	v_addc_co_u32_e32 v55, vcc, 0, v45, vcc
	s_mov_b32 s2, 0x19000
	v_add_co_u32_e32 v62, vcc, s2, v44
	v_mov_b32_e32 v49, s3
	s_nop 0
	v_addc_co_u32_e32 v63, vcc, 0, v45, vcc
	flat_load_ushort v69, v[50:51] offset:3072 nt
	flat_load_ushort v120, v[54:55] offset:3072 nt
	flat_load_ushort v121, v[62:63] offset:3072 nt
	v_pk_mul_f32 v[50:51], v[4:5], v[40:41] op_sel_hi:[0,1]
	v_pk_fma_f32 v[42:43], v[2:3], v[42:43], v[50:51] op_sel_hi:[0,1,1]
	v_pk_fma_f32 v[40:41], v[6:7], v[60:61], v[42:43] op_sel_hi:[0,1,1]
	v_pk_fma_f32 v[40:41], v[8:9], v[52:53], v[40:41] op_sel_hi:[0,1,1]
	v_mul_f32_e32 v42, 0xbfb8aa3b, v40
	v_mul_f32_e32 v43, 0xbfb8aa3b, v41
	v_exp_f32_e32 v42, v42
	v_exp_f32_e32 v43, v43
	s_mov_b32 s3, 0x1a000
	v_add_co_u32_e32 v64, vcc, s3, v44
	v_add_f32_e32 v42, 1.0, v42
	v_add_f32_e32 v43, 1.0, v43
	v_rcp_f32_e32 v42, v42
	v_rcp_f32_e32 v43, v43
	v_readlane_b32 s3, v102, 17
	v_lshlrev_b32_e32 v51, 16, v112
	v_lshlrev_b32_e32 v50, 16, v113
	v_pk_mul_f32 v[40:41], v[40:41], v[42:43]
	v_mov_b32_e32 v42, s4
	v_mul_f32_e32 v42, s3, v42
	v_mul_f32_e32 v110, v57, v42
	v_pk_mul_f32 v[42:43], v[4:5], v[52:53] op_sel_hi:[0,1]
	v_pk_fma_f32 v[42:43], v[2:3], v[60:61], v[42:43] op_sel_hi:[0,1,1]
	v_pk_mov_b32 v[52:53], v[52:53], v[50:51] op_sel:[1,0]
	v_readlane_b32 s2, v102, 16
	v_pk_fma_f32 v[42:43], v[6:7], v[52:53], v[42:43] op_sel_hi:[0,1,1]
	v_pk_fma_f32 v[42:43], v[8:9], v[50:51], v[42:43] op_sel_hi:[0,1,1]
	v_mul_f32_e32 v49, s2, v49
	v_mul_f32_e32 v111, v56, v49
	v_mul_f32_e32 v49, 0xbfb8aa3b, v42
	v_exp_f32_e32 v49, v49
	v_mul_f32_e32 v60, 0xbfb8aa3b, v43
	v_exp_f32_e32 v61, v60
	v_pk_mul_f32 v[40:41], v[40:41], s[2:3]
	v_add_f32_e32 v49, 1.0, v49
	v_rcp_f32_e32 v60, v49
	v_add_f32_e32 v49, 1.0, v61
	v_rcp_f32_e32 v61, v49
	v_readlane_b32 s3, v3, 18
	v_readlane_b32 s4, v3, 19
	v_readlane_b32 s2, v102, 18
	v_pk_mul_f32 v[42:43], v[42:43], v[60:61]
	v_pk_mul_f32 v[60:61], v[14:15], v[46:47]
	v_mul_f32_e32 v46, 0xbfb8aa3b, v126
	v_exp_f32_e32 v46, v46
	v_mov_b32_e32 v112, s3
	v_readlane_b32 s3, v102, 19
	v_mov_b32_e32 v49, s4
	v_add_f32_e32 v46, 1.0, v46
	v_rcp_f32_e32 v46, v46
	v_addc_co_u32_e32 v65, vcc, 0, v45, vcc
	v_mul_f32_e32 v112, s2, v112
	v_mul_f32_e32 v123, s3, v49
	v_mul_f32_e32 v46, v126, v46
	flat_load_ushort v79, v[64:65] offset:3072 nt
	v_mul_f32_e32 v113, v58, v112
	v_mul_f32_e32 v112, v59, v123
	flat_load_ushort v123, v[54:55] nt
	flat_load_ushort v135, v[64:65] nt
	flat_load_ushort v137, v[62:63] offset:1024 nt
	flat_load_ushort v136, v[62:63] nt
	flat_load_ushort v138, v[54:55] offset:1024 nt
	v_mul_f32_e32 v54, v46, v46
	v_mov_b32_e32 v55, 0
	v_pk_mul_f32 v[42:43], v[42:43], s[2:3]
	v_lshlrev_b32_e32 v49, 16, v68
	v_mov_b32_dpp v55, v54 quad_perm:[1,0,3,2] row_mask:0xf bank_mask:0xf
	v_fmac_f32_e32 v55, v46, v46
	v_pk_mul_f32 v[62:63], v[10:11], v[48:49]
	v_mul_f32_e32 v47, v13, v47
	v_add_f32_dpp v54, v55, v55 quad_perm:[2,3,0,1] row_mask:0xf bank_mask:0xf bound_ctrl:1
	v_mov_b32_e32 v55, 0
	v_readlane_b32 s3, v3, 22
	v_add_f32_dpp v54, v54, v54 row_half_mirror row_mask:0xf bank_mask:0xf bound_ctrl:1
	v_readlane_b32 s4, v3, 23
	s_waitcnt vmcnt(0) lgkmcnt(0)
	v_lshlrev_b32_e32 v133, 16, v69
	v_add_f32_dpp v54, v54, v54 row_mirror row_mask:0xf bank_mask:0xf bound_ctrl:1
	v_mul_f32_e32 v69, v10, v49
	v_lshlrev_b32_e32 v128, 16, v120
	v_mov_b32_dpp v55, v54 row_bcast:15 row_mask:0xa bank_mask:0xf
	v_add_f32_e32 v54, v54, v55
	v_mov_b32_e32 v55, 0
	v_mov_b32_e32 v120, 0
	v_lshlrev_b32_e32 v127, 16, v121
	v_mov_b32_dpp v55, v54 row_bcast:31 row_mask:0xc bank_mask:0xf
	v_add_f32_e32 v54, v54, v55
	v_fmac_f32_e32 v149, v105, v133
	v_readlane_b32 s2, v54, 63
	v_lshlrev_b32_e32 v126, 16, v79
	s_nop 0
	v_add_f32_e32 v54, s2, v86
	s_mov_b32 s2, 0x1b000
	v_rsq_f32_e32 v68, v54
	v_add_co_u32_e32 v54, vcc, s2, v44
	v_readlane_b32 s2, v3, 20
	s_nop 0
	v_addc_co_u32_e32 v55, vcc, 0, v45, vcc
	flat_load_ushort v131, v[54:55] offset:1024 nt
	flat_load_ushort v130, v[54:55] nt
	flat_load_ushort v132, v[64:65] offset:1024 nt
	v_mul_f32_e32 v64, v9, v76
	v_fmac_f32_e32 v64, v5, v77
	v_fmac_f32_e32 v64, v7, v71
	v_fmac_f32_e32 v64, v105, v122
	v_mul_f32_e32 v65, 0xbfb8aa3b, v64
	v_exp_f32_e32 v65, v65
	v_mul_f32_e32 v46, v46, v68
	v_mul_f32_e32 v46, 0x3e000000, v46
	v_cvt_pk_bf16_f32 v46, v46, s0
	ds_write_b16 v118, v46 offset:2560
	v_add_f32_e32 v46, 1.0, v65
	v_rcp_f32_e32 v46, v46
	v_mov_b32_e32 v65, 0
	v_mov_b32_e32 v77, s2
	v_mov_b32_e32 v68, v62
	v_mul_f32_e32 v46, v64, v46
	v_mul_f32_e32 v64, v46, v46
	s_nop 1
	v_mov_b32_dpp v65, v64 quad_perm:[1,0,3,2] row_mask:0xf bank_mask:0xf
	v_fmac_f32_e32 v65, v46, v46
	s_nop 1
	v_add_f32_dpp v64, v65, v65 quad_perm:[2,3,0,1] row_mask:0xf bank_mask:0xf bound_ctrl:1
	v_mov_b32_e32 v65, 0
	s_nop 0
	v_add_f32_dpp v64, v64, v64 row_half_mirror row_mask:0xf bank_mask:0xf bound_ctrl:1
	s_nop 1
	v_add_f32_dpp v64, v64, v64 row_mirror row_mask:0xf bank_mask:0xf bound_ctrl:1
	s_nop 1
	v_mov_b32_dpp v65, v64 row_bcast:15 row_mask:0xa bank_mask:0xf
	v_add_f32_e32 v64, v64, v65
	v_mov_b32_e32 v65, 0
	s_nop 1
	v_mov_b32_dpp v65, v64 row_bcast:31 row_mask:0xc bank_mask:0xf
	v_add_f32_e32 v64, v64, v65
	v_mul_f32_e32 v65, v12, v48
	v_readlane_b32 s2, v64, 63
	s_nop 1
	v_add_f32_e32 v64, s2, v86
	v_rsq_f32_e32 v64, v64
	s_nop 0
	v_mul_f32_e32 v46, v46, v64
	v_mul_f32_e32 v78, 0x3e000000, v46
	v_mov_b32_e32 v46, v60
	v_mov_b32_e32 v64, v61
	v_pk_add_f32 v[46:47], v[46:47], v[64:65]
	v_lshlrev_b32_e32 v65, 16, v67
	v_pk_add_f32 v[60:61], v[46:47], v[68:69]
	v_lshlrev_b32_e32 v64, 16, v66
	v_pk_mul_f32 v[46:47], v[4:5], v[50:51] op_sel_hi:[0,1]
	v_pk_fma_f32 v[46:47], v[2:3], v[52:53], v[46:47] op_sel_hi:[0,1,1]
	v_pk_mov_b32 v[66:67], v[50:51], v[64:65] op_sel:[1,0]
	v_mov_b32_e32 v52, v63
	v_pk_fma_f32 v[46:47], v[6:7], v[66:67], v[46:47] op_sel_hi:[0,1,1]
	v_pk_fma_f32 v[46:47], v[8:9], v[64:65], v[46:47] op_sel_hi:[0,1,1]
	v_mul_f32_e32 v50, 0xbfb8aa3b, v46
	v_exp_f32_e32 v50, v50
	v_mul_f32_e32 v51, 0xbfb8aa3b, v47
	v_exp_f32_e32 v51, v51
	v_pk_mul_f32 v[62:63], v[14:15], v[48:49]
	v_add_f32_e32 v50, 1.0, v50
	v_rcp_f32_e32 v68, v50
	v_add_f32_e32 v50, 1.0, v51
	v_rcp_f32_e32 v69, v50
	v_lshlrev_b32_e32 v50, 16, v73
	v_mul_f32_e32 v53, v11, v50
	v_pk_add_f32 v[52:53], v[60:61], v[52:53]
	v_mul_f32_e32 v73, v9, v71
	v_mul_f32_e32 v51, 0xbfb8aa3b, v52
	v_exp_f32_e32 v51, v51
	v_mul_f32_e32 v60, 0xbfb8aa3b, v53
	v_exp_f32_e32 v61, v60
	v_fmac_f32_e32 v73, v5, v76
	v_add_f32_e32 v51, 1.0, v51
	v_rcp_f32_e32 v60, v51
	v_add_f32_e32 v51, 1.0, v61
	v_rcp_f32_e32 v61, v51
	v_fmac_f32_e32 v73, v7, v122
	v_fmac_f32_e32 v73, v105, v134
	v_cvt_pk_bf16_f32 v78, v78, s0
	v_pk_mul_f32 v[52:53], v[52:53], v[60:61]
	v_mul_f32_e32 v49, v13, v49
	v_pk_mul_f32 v[60:61], v[52:53], v[52:53]
	v_pk_mul_f32 v[46:47], v[46:47], v[68:69]
	v_lshlrev_b32_e32 v69, 16, v75
	v_add_f32_dpp v51, v60, v60 quad_perm:[1,0,3,2] row_mask:0xf bank_mask:0xf bound_ctrl:1
	v_mov_b32_e32 v60, 0
	v_pk_mul_f32 v[46:47], v[46:47], s[6:7]
	v_add_f32_dpp v51, v51, v51 quad_perm:[2,3,0,1] row_mask:0xf bank_mask:0xf bound_ctrl:1
	s_nop 1
	v_add_f32_dpp v51, v51, v51 row_half_mirror row_mask:0xf bank_mask:0xf bound_ctrl:1
	s_nop 1
	v_add_f32_dpp v51, v51, v51 row_mirror row_mask:0xf bank_mask:0xf bound_ctrl:1
	s_nop 1
	v_mov_b32_dpp v60, v51 row_bcast:15 row_mask:0xa bank_mask:0xf
	v_add_f32_e32 v51, v51, v60
	v_mov_b32_e32 v60, 0
	s_nop 1
	v_mov_b32_dpp v60, v51 row_bcast:31 row_mask:0xc bank_mask:0xf
	v_add_f32_e32 v51, v51, v60
	s_nop 0
	v_readlane_b32 s2, v51, 63
	s_nop 1
	v_add_f32_e32 v51, s2, v86
	v_rsq_f32_e32 v60, v51
	s_nop 0
	v_add_f32_dpp v51, v61, v61 quad_perm:[1,0,3,2] row_mask:0xf bank_mask:0xf bound_ctrl:1
	v_mov_b32_e32 v61, 0
	s_nop 0
	v_add_f32_dpp v51, v51, v51 quad_perm:[2,3,0,1] row_mask:0xf bank_mask:0xf bound_ctrl:1
	s_nop 1
	v_add_f32_dpp v51, v51, v51 row_half_mirror row_mask:0xf bank_mask:0xf bound_ctrl:1
	s_nop 1
	v_add_f32_dpp v51, v51, v51 row_mirror row_mask:0xf bank_mask:0xf bound_ctrl:1
	s_nop 1
	v_mov_b32_dpp v61, v51 row_bcast:15 row_mask:0xa bank_mask:0xf
	v_add_f32_e32 v51, v51, v61
	v_mov_b32_e32 v61, 0
	s_nop 1
	v_mov_b32_dpp v61, v51 row_bcast:31 row_mask:0xc bank_mask:0xf
	v_add_f32_e32 v51, v51, v61
	s_nop 0
	v_readlane_b32 s2, v51, 63
	s_nop 1
	v_add_f32_e32 v51, s2, v86
	v_rsq_f32_e32 v61, v51
	v_mul_f32_e32 v51, 0xbfb8aa3b, v73
	v_exp_f32_e32 v76, v51
	v_lshlrev_b32_e32 v51, 16, v72
	v_pk_mul_f32 v[60:61], v[52:53], v[60:61]
	v_mov_b32_e32 v53, 0
	v_add_f32_e32 v48, 1.0, v76
	v_rcp_f32_e32 v48, v48
	v_cvt_pk_bf16_f32 v52, v60, s0
	ds_write_b16 v118, v52 offset:6656
	ds_write_b16 v119, v78 offset:2688
	v_mul_f32_e32 v79, v10, v51
	v_mul_f32_e32 v48, v73, v48
	v_mul_f32_e32 v52, v48, v48
	v_mul_f32_e32 v73, v12, v50
	s_nop 0
	v_mov_b32_dpp v53, v52 quad_perm:[1,0,3,2] row_mask:0xf bank_mask:0xf
	v_fmac_f32_e32 v53, v48, v48
	s_nop 1
	v_add_f32_dpp v52, v53, v53 quad_perm:[2,3,0,1] row_mask:0xf bank_mask:0xf bound_ctrl:1
	v_mov_b32_e32 v53, 0
	s_nop 0
	v_add_f32_dpp v52, v52, v52 row_half_mirror row_mask:0xf bank_mask:0xf bound_ctrl:1
	s_nop 1
	v_add_f32_dpp v52, v52, v52 row_mirror row_mask:0xf bank_mask:0xf bound_ctrl:1
	s_nop 1
	v_mov_b32_dpp v53, v52 row_bcast:15 row_mask:0xa bank_mask:0xf
	v_add_f32_e32 v52, v52, v53
	v_mov_b32_e32 v53, 0
	s_nop 1
	v_mov_b32_dpp v53, v52 row_bcast:31 row_mask:0xc bank_mask:0xf
	v_add_f32_e32 v52, v52, v53
	s_nop 0
	v_readlane_b32 s2, v52, 63
	s_nop 1
	v_add_f32_e32 v52, s2, v86
	v_rsq_f32_e32 v72, v52
	v_cvt_pk_bf16_f32 v52, v61, s0
	ds_write_b16 v119, v52 offset:6784
	v_pk_mul_f32 v[52:53], v[10:11], v[50:51]
	v_mul_f32_e32 v48, v48, v72
	v_mul_f32_e32 v72, v9, v122
	v_fmac_f32_e32 v72, v5, v71
	v_fmac_f32_e32 v72, v7, v134
	v_fmac_f32_e32 v72, v105, v129
	v_mul_f32_e32 v71, 0xbfb8aa3b, v72
	v_exp_f32_e32 v71, v71
	v_mul_f32_e32 v48, 0x3e000000, v48
	v_cvt_pk_bf16_f32 v48, v48, s0
	ds_write_b16 v124, v48 offset:2816
	v_add_f32_e32 v48, 1.0, v71
	v_rcp_f32_e32 v48, v48
	v_mov_b32_e32 v78, v52
	v_lshlrev_b32_e32 v52, 16, v70
	v_mul_f32_e32 v71, v72, v48
	v_mul_f32_e32 v48, v71, v71
	v_mov_b32_e32 v72, 0
	s_nop 1
	v_mov_b32_dpp v72, v48 quad_perm:[1,0,3,2] row_mask:0xf bank_mask:0xf
	v_fmac_f32_e32 v72, v71, v71
	s_nop 1
	v_add_f32_dpp v48, v72, v72 quad_perm:[2,3,0,1] row_mask:0xf bank_mask:0xf bound_ctrl:1
	v_mov_b32_e32 v72, 0
	s_nop 0
	v_add_f32_dpp v48, v48, v48 row_half_mirror row_mask:0xf bank_mask:0xf bound_ctrl:1
	s_nop 1
	v_add_f32_dpp v48, v48, v48 row_mirror row_mask:0xf bank_mask:0xf bound_ctrl:1
	s_nop 1
	v_mov_b32_dpp v72, v48 row_bcast:15 row_mask:0xa bank_mask:0xf
	v_add_f32_e32 v76, v48, v72
	v_mov_b32_e32 v48, v62
	v_mov_b32_e32 v72, v63
	v_pk_add_f32 v[48:49], v[48:49], v[72:73]
	v_mul_f32_e32 v63, v11, v52
	v_pk_add_f32 v[48:49], v[48:49], v[78:79]
	v_mov_b32_e32 v62, v53
	v_pk_add_f32 v[48:49], v[48:49], v[62:63]
	v_mov_b32_dpp v120, v76 row_bcast:31 row_mask:0xc bank_mask:0xf
	v_mul_f32_e32 v53, 0xbfb8aa3b, v48
	v_exp_f32_e32 v53, v53
	v_mul_f32_e32 v62, 0xbfb8aa3b, v49
	v_exp_f32_e32 v63, v62
	v_add_f32_e32 v70, v76, v120
	v_add_f32_e32 v53, 1.0, v53
	v_rcp_f32_e32 v62, v53
	v_add_f32_e32 v53, 1.0, v63
	v_rcp_f32_e32 v63, v53
	v_readlane_b32 s2, v70, 63
	v_mov_b32_e32 v70, 0
	v_pk_mul_f32 v[48:49], v[48:49], v[62:63]
	s_nop 0
	v_pk_mul_f32 v[62:63], v[48:49], v[48:49]
	v_add_f32_e32 v53, s2, v86
	v_rsq_f32_e32 v53, v53
	v_add_f32_dpp v62, v62, v62 quad_perm:[1,0,3,2] row_mask:0xf bank_mask:0xf bound_ctrl:1
	v_add_f32_dpp v63, v63, v63 quad_perm:[1,0,3,2] row_mask:0xf bank_mask:0xf bound_ctrl:1
	v_mul_f32_e32 v53, v71, v53
	v_add_f32_dpp v62, v62, v62 quad_perm:[2,3,0,1] row_mask:0xf bank_mask:0xf bound_ctrl:1
	v_add_f32_dpp v63, v63, v63 quad_perm:[2,3,0,1] row_mask:0xf bank_mask:0xf bound_ctrl:1
	v_mul_f32_e32 v53, 0x3e000000, v53
	v_add_f32_dpp v62, v62, v62 row_half_mirror row_mask:0xf bank_mask:0xf bound_ctrl:1
	v_add_f32_dpp v63, v63, v63 row_half_mirror row_mask:0xf bank_mask:0xf bound_ctrl:1
	v_cvt_pk_bf16_f32 v53, v53, s0
	v_add_f32_dpp v62, v62, v62 row_mirror row_mask:0xf bank_mask:0xf bound_ctrl:1
	v_add_f32_dpp v63, v63, v63 row_mirror row_mask:0xf bank_mask:0xf bound_ctrl:1
	s_nop 0
	v_mov_b32_dpp v70, v62 row_bcast:15 row_mask:0xa bank_mask:0xf
	v_add_f32_e32 v62, v62, v70
	v_mov_b32_e32 v70, 0
	s_nop 1
	v_mov_b32_dpp v70, v62 row_bcast:31 row_mask:0xc bank_mask:0xf
	v_add_f32_e32 v62, v62, v70
	v_mov_b32_e32 v70, 0
	v_readlane_b32 s2, v62, 63
	s_nop 0
	v_mov_b32_dpp v70, v63 row_bcast:15 row_mask:0xa bank_mask:0xf
	v_add_f32_e32 v63, v63, v70
	v_mov_b32_e32 v70, 0
	v_add_f32_e32 v62, s2, v86
	v_rsq_f32_e32 v62, v62
	v_mov_b32_dpp v70, v63 row_bcast:31 row_mask:0xc bank_mask:0xf
	v_add_f32_e32 v63, v63, v70
	s_nop 0
	v_readlane_b32 s2, v63, 63
	s_nop 1
	v_add_f32_e32 v63, s2, v86
	v_rsq_f32_e32 v63, v63
	s_mov_b32 s2, 0x1c000
	v_add_co_u32_e32 v70, vcc, s2, v44
	v_pk_mul_f32 v[62:63], v[48:49], v[62:63]
	s_nop 0
	v_addc_co_u32_e32 v71, vcc, 0, v45, vcc
	v_cvt_pk_bf16_f32 v48, v62, s0
	ds_write_b16 v124, v48 offset:6912
	ds_write_b16 v125, v53 offset:2944
	v_cvt_pk_bf16_f32 v48, v63, s0
	ds_write_b16 v125, v48 offset:7040
	s_mov_b32 s2, 0x1d000
	flat_load_ushort v141, v[54:55] offset:3072 nt
	flat_load_ushort v142, v[70:71] offset:3072 nt
	v_add_co_u32_e32 v54, vcc, s2, v44
	v_readlane_b32 s2, v3, 21
	s_nop 0
	v_addc_co_u32_e32 v55, vcc, 0, v45, vcc
	v_mov_b32_e32 v48, s2
	s_mov_b32 s2, 0x1e000
	v_add_co_u32_e32 v72, vcc, s2, v44
	s_mov_b32 s2, 0x1f000
	s_nop 0
	v_addc_co_u32_e32 v73, vcc, 0, v45, vcc
	v_mul_f32_e32 v68, s7, v48
	v_add_co_u32_e32 v48, vcc, s2, v44
	flat_load_ushort v143, v[54:55] offset:3072 nt
	s_nop 0
	v_addc_co_u32_e32 v49, vcc, 0, v45, vcc
	flat_load_ushort v147, v[72:73] offset:3072 nt
	flat_load_ushort v148, v[48:49] nt
	v_mul_f32_e32 v120, v61, v68
	v_lshlrev_b32_e32 v68, 16, v74
	v_pk_mul_f32 v[48:49], v[4:5], v[64:65] op_sel_hi:[0,1]
	v_pk_fma_f32 v[48:49], v[2:3], v[66:67], v[48:49] op_sel_hi:[0,1,1]
	v_pk_mov_b32 v[64:65], v[64:65], v[68:69] op_sel:[1,0]
	v_mul_f32_e32 v53, s6, v77
	v_pk_fma_f32 v[48:49], v[6:7], v[64:65], v[48:49] op_sel_hi:[0,1,1]
	v_pk_fma_f32 v[48:49], v[8:9], v[68:69], v[48:49] op_sel_hi:[0,1,1]
	v_mul_f32_e32 v121, v60, v53
	v_mul_f32_e32 v53, 0xbfb8aa3b, v48
	v_exp_f32_e32 v53, v53
	v_mul_f32_e32 v66, 0xbfb8aa3b, v49
	v_exp_f32_e32 v67, v66
	v_readlane_b32 s2, v102, 22
	v_add_f32_e32 v53, 1.0, v53
	v_rcp_f32_e32 v66, v53
	v_add_f32_e32 v53, 1.0, v67
	v_rcp_f32_e32 v67, v53
	v_mov_b32_e32 v74, s3
	v_readlane_b32 s3, v102, 23
	v_mov_b32_e32 v53, s4
	v_pk_mul_f32 v[48:49], v[48:49], v[66:67]
	v_mul_f32_e32 v139, s2, v74
	v_pk_mul_f32 v[48:49], v[48:49], s[2:3]
	v_mul_f32_e32 v140, s3, v53
	s_mov_b64 s[2:3], 0x1c000
	v_lshl_add_u64 v[76:77], v[44:45], 0, s[2:3]
	s_mov_b64 s[2:3], 0x1d000
	v_lshl_add_u64 v[78:79], v[44:45], 0, s[2:3]
	s_mov_b64 s[2:3], 0x1e000
	v_lshl_add_u64 v[66:67], v[44:45], 0, s[2:3]
	s_mov_b64 s[2:3], 0x1f000
	v_lshl_add_u64 v[74:75], v[44:45], 0, s[2:3]
	v_pk_mul_f32 v[44:45], v[14:15], v[50:51]
	v_mul_f32_e32 v50, 0xbfb8aa3b, v149
	v_exp_f32_e32 v50, v50
	v_lshlrev_b32_e32 v53, 16, v123
	v_mul_f32_e32 v123, v62, v139
	v_mul_f32_e32 v122, v63, v140
	v_add_f32_e32 v50, 1.0, v50
	v_rcp_f32_e32 v50, v50
	flat_load_ushort v144, v[54:55] nt
	flat_load_ushort v146, v[70:71] nt
	flat_load_ushort v145, v[76:77] offset:1024 nt
	s_nop 0
	flat_load_ushort v79, v[78:79] offset:1024 nt
	s_nop 0
	flat_load_ushort v139, v[74:75] offset:1024 nt
	flat_load_ushort v140, v[66:67] offset:1024 nt
	v_mov_b32_e32 v66, 0
	flat_load_ushort v78, v[72:73] nt
	v_mul_f32_e32 v50, v149, v50
	v_mul_f32_e32 v55, v50, v50
	v_readlane_b32 s3, v3, 24
	v_mul_f32_e32 v51, v13, v51
	v_mov_b32_dpp v66, v55 quad_perm:[1,0,3,2] row_mask:0xf bank_mask:0xf
	v_fmac_f32_e32 v66, v50, v50
	v_pk_mul_f32 v[70:71], v[10:11], v[52:53]
	v_mul_f32_e32 v73, v10, v53
	v_add_f32_dpp v55, v66, v66 quad_perm:[2,3,0,1] row_mask:0xf bank_mask:0xf bound_ctrl:1
	v_mov_b32_e32 v66, 0
	v_mov_b32_e32 v72, v70
	v_add_f32_dpp v55, v55, v55 row_half_mirror row_mask:0xf bank_mask:0xf bound_ctrl:1
	v_readlane_b32 s4, v3, 25
	v_mul_f32_e32 v77, v9, v133
	v_add_f32_dpp v55, v55, v55 row_mirror row_mask:0xf bank_mask:0xf bound_ctrl:1
	v_fmac_f32_e32 v77, v5, v129
	v_fmac_f32_e32 v77, v7, v128
	v_mov_b32_dpp v66, v55 row_bcast:15 row_mask:0xa bank_mask:0xf
	v_add_f32_e32 v55, v55, v66
	v_mov_b32_e32 v66, 0
	v_fmac_f32_e32 v77, v105, v127
	s_waitcnt vmcnt(0) lgkmcnt(0)
	v_lshlrev_b32_e32 v54, 16, v141
	v_mov_b32_dpp v66, v55 row_bcast:31 row_mask:0xc bank_mask:0xf
	v_add_f32_e32 v55, v55, v66
	v_lshlrev_b32_e32 v142, 16, v142
	v_readlane_b32 s2, v55, 63
	v_cmp_gt_u32_e32 vcc, 32, v22
	v_lshlrev_b32_e32 v141, 16, v143
	v_add_f32_e32 v55, s2, v86
	v_rsq_f32_e32 v66, v55
	v_readlane_b32 s2, v102, 24
	v_lshlrev_b32_e32 v55, 16, v148
	v_lshlrev_b32_e32 v143, 16, v147
	v_mul_f32_e32 v50, v50, v66
	v_mul_f32_e32 v66, v9, v129
	v_fmac_f32_e32 v66, v5, v134
	v_fmac_f32_e32 v66, v7, v133
	v_fmac_f32_e32 v66, v105, v128
	v_mul_f32_e32 v67, 0xbfb8aa3b, v66
	v_exp_f32_e32 v67, v67
	v_mul_f32_e32 v50, 0x3e000000, v50
	v_cvt_pk_bf16_f32 v50, v50, s0
	ds_write_b16 v114, v50 offset:3072
	v_add_f32_e32 v50, 1.0, v67
	v_rcp_f32_e32 v50, v50
	v_mov_b32_e32 v67, s3
	v_mul_f32_e32 v74, s2, v67
	v_mov_b32_e32 v67, 0
	v_mul_f32_e32 v50, v66, v50
	v_mul_f32_e32 v66, v50, v50
	s_nop 1
	v_mov_b32_dpp v67, v66 quad_perm:[1,0,3,2] row_mask:0xf bank_mask:0xf
	v_fmac_f32_e32 v67, v50, v50
	s_nop 1
	v_add_f32_dpp v66, v67, v67 quad_perm:[2,3,0,1] row_mask:0xf bank_mask:0xf bound_ctrl:1
	v_mov_b32_e32 v67, 0
	s_nop 0
	v_add_f32_dpp v66, v66, v66 row_half_mirror row_mask:0xf bank_mask:0xf bound_ctrl:1
	s_nop 1
	v_add_f32_dpp v66, v66, v66 row_mirror row_mask:0xf bank_mask:0xf bound_ctrl:1
	s_nop 1
	v_mov_b32_dpp v67, v66 row_bcast:15 row_mask:0xa bank_mask:0xf
	v_add_f32_e32 v66, v66, v67
	v_mov_b32_e32 v67, 0
	s_nop 1
	v_mov_b32_dpp v67, v66 row_bcast:31 row_mask:0xc bank_mask:0xf
	v_add_f32_e32 v66, v66, v67
	v_mul_f32_e32 v67, v12, v52
	v_readlane_b32 s3, v66, 63
	s_nop 1
	v_add_f32_e32 v66, s3, v86
	v_rsq_f32_e32 v66, v66
	v_readlane_b32 s3, v102, 25
	v_mul_f32_e32 v50, v50, v66
	v_mul_f32_e32 v75, 0x3e000000, v50
	v_mov_b32_e32 v50, v44
	v_mov_b32_e32 v66, v45
	v_pk_add_f32 v[44:45], v[50:51], v[66:67]
	v_lshlrev_b32_e32 v51, 16, v137
	v_lshlrev_b32_e32 v50, 16, v138
	v_pk_mul_f32 v[66:67], v[4:5], v[68:69] op_sel_hi:[0,1]
	v_pk_fma_f32 v[64:65], v[2:3], v[64:65], v[66:67] op_sel_hi:[0,1,1]
	v_pk_mov_b32 v[66:67], v[68:69], v[50:51] op_sel:[1,0]
	v_pk_add_f32 v[72:73], v[44:45], v[72:73]
	v_pk_fma_f32 v[64:65], v[6:7], v[66:67], v[64:65] op_sel_hi:[0,1,1]
	v_pk_fma_f32 v[64:65], v[8:9], v[50:51], v[64:65] op_sel_hi:[0,1,1]
	v_mul_f32_e32 v68, 0xbfb8aa3b, v64
	v_mul_f32_e32 v69, 0xbfb8aa3b, v65
	v_exp_f32_e32 v68, v68
	v_exp_f32_e32 v69, v69
	v_cvt_pk_bf16_f32 v75, v75, s0
	v_add_f32_e32 v44, 1.0, v68
	v_add_f32_e32 v45, 1.0, v69
	v_rcp_f32_e32 v44, v44
	v_rcp_f32_e32 v45, v45
	v_lshlrev_b32_e32 v68, 16, v136
	v_pk_mul_f32 v[44:45], v[64:65], v[44:45]
	v_mov_b32_e32 v64, s4
	v_mul_f32_e32 v76, s3, v64
	v_mul_f32_e32 v65, v11, v68
	v_mov_b32_e32 v64, v71
	v_pk_add_f32 v[64:65], v[72:73], v[64:65]
	v_pk_mul_f32 v[72:73], v[14:15], v[52:53]
	v_mul_f32_e32 v69, 0xbfb8aa3b, v64
	v_exp_f32_e32 v69, v69
	v_mul_f32_e32 v70, 0xbfb8aa3b, v65
	v_exp_f32_e32 v71, v70
	v_pk_mul_f32 v[44:45], v[44:45], s[2:3]
	v_add_f32_e32 v69, 1.0, v69
	v_rcp_f32_e32 v70, v69
	v_add_f32_e32 v69, 1.0, v71
	v_rcp_f32_e32 v71, v69
	v_mov_b32_e32 v69, 0
	v_readlane_b32 s3, v3, 26
	v_mul_f32_e32 v53, v13, v53
	v_pk_mul_f32 v[64:65], v[64:65], v[70:71]
	v_readlane_b32 s4, v3, 27
	v_pk_mul_f32 v[70:71], v[64:65], v[64:65]
	s_nop 1
	v_add_f32_dpp v52, v70, v70 quad_perm:[1,0,3,2] row_mask:0xf bank_mask:0xf bound_ctrl:1
	s_nop 1
	v_add_f32_dpp v52, v52, v52 quad_perm:[2,3,0,1] row_mask:0xf bank_mask:0xf bound_ctrl:1
	s_nop 1
	v_add_f32_dpp v52, v52, v52 row_half_mirror row_mask:0xf bank_mask:0xf bound_ctrl:1
	s_nop 1
	v_add_f32_dpp v52, v52, v52 row_mirror row_mask:0xf bank_mask:0xf bound_ctrl:1
	s_nop 1
	v_mov_b32_dpp v69, v52 row_bcast:15 row_mask:0xa bank_mask:0xf
	v_add_f32_e32 v52, v52, v69
	v_mov_b32_e32 v69, 0
	s_nop 1
	v_mov_b32_dpp v69, v52 row_bcast:31 row_mask:0xc bank_mask:0xf
	v_add_f32_e32 v52, v52, v69
	v_mov_b32_e32 v69, 0
	v_readlane_b32 s2, v52, 63
	s_nop 1
	v_add_f32_e32 v52, s2, v86
	v_rsq_f32_e32 v70, v52
	s_nop 0
	v_add_f32_dpp v52, v71, v71 quad_perm:[1,0,3,2] row_mask:0xf bank_mask:0xf bound_ctrl:1
	s_nop 1
	v_add_f32_dpp v52, v52, v52 quad_perm:[2,3,0,1] row_mask:0xf bank_mask:0xf bound_ctrl:1
	s_nop 1
	v_add_f32_dpp v52, v52, v52 row_half_mirror row_mask:0xf bank_mask:0xf bound_ctrl:1
	s_nop 1
	v_add_f32_dpp v52, v52, v52 row_mirror row_mask:0xf bank_mask:0xf bound_ctrl:1
	s_nop 1
	v_mov_b32_dpp v69, v52 row_bcast:15 row_mask:0xa bank_mask:0xf
	v_add_f32_e32 v52, v52, v69
	v_mov_b32_e32 v69, 0
	s_nop 1
	v_mov_b32_dpp v69, v52 row_bcast:31 row_mask:0xc bank_mask:0xf
	v_add_f32_e32 v52, v52, v69
	v_lshlrev_b32_e32 v69, 16, v135
	v_readlane_b32 s2, v52, 63
	v_mul_f32_e32 v135, v10, v69
	v_mul_f32_e32 v13, v13, v69
	v_add_f32_e32 v52, s2, v86
	v_rsq_f32_e32 v71, v52
	v_mul_f32_e32 v52, 0xbfb8aa3b, v77
	v_exp_f32_e32 v52, v52
	v_pk_mul_f32 v[64:65], v[64:65], v[70:71]
	s_nop 0
	v_cvt_pk_bf16_f32 v70, v64, s0
	v_add_f32_e32 v52, 1.0, v52
	v_rcp_f32_e32 v52, v52
	ds_write_b16 v114, v70 offset:7168
	ds_write_b16 v116, v75 offset:3200
	v_mov_b32_e32 v75, 0
	v_mul_f32_e32 v52, v77, v52
	v_mul_f32_e32 v71, v52, v52
	v_cvt_pk_bf16_f32 v70, v65, s0
	ds_write_b16 v116, v70 offset:7296
	v_mov_b32_dpp v75, v71 quad_perm:[1,0,3,2] row_mask:0xf bank_mask:0xf
	v_fmac_f32_e32 v75, v52, v52
	v_mul_f32_e32 v74, v64, v74
	s_nop 0
	v_add_f32_dpp v71, v75, v75 quad_perm:[2,3,0,1] row_mask:0xf bank_mask:0xf bound_ctrl:1
	v_mov_b32_e32 v75, 0
	s_nop 0
	v_add_f32_dpp v71, v71, v71 row_half_mirror row_mask:0xf bank_mask:0xf bound_ctrl:1
	s_nop 1
	v_add_f32_dpp v71, v71, v71 row_mirror row_mask:0xf bank_mask:0xf bound_ctrl:1
	s_nop 1
	v_mov_b32_dpp v75, v71 row_bcast:15 row_mask:0xa bank_mask:0xf
	v_add_f32_e32 v71, v71, v75
	v_mov_b32_e32 v75, 0
	s_nop 1
	v_mov_b32_dpp v75, v71 row_bcast:31 row_mask:0xc bank_mask:0xf
	v_add_f32_e32 v71, v71, v75
	v_mul_f32_e32 v75, v65, v76
	v_readlane_b32 s2, v71, 63
	v_mul_f32_e32 v76, v9, v128
	v_fmac_f32_e32 v76, v5, v133
	v_add_f32_e32 v71, s2, v86
	v_rsq_f32_e32 v77, v71
	v_fmac_f32_e32 v76, v7, v127
	v_fmac_f32_e32 v76, v105, v126
	v_readlane_b32 s2, v102, 26
	v_mul_f32_e32 v52, v52, v77
	v_mul_f32_e32 v77, 0xbfb8aa3b, v76
	v_exp_f32_e32 v77, v77
	v_mul_f32_e32 v52, 0x3e000000, v52
	v_cvt_pk_bf16_f32 v52, v52, s0
	ds_write_b16 v115, v52 offset:3328
	v_add_f32_e32 v52, 1.0, v77
	v_rcp_f32_e32 v52, v52
	v_mov_b32_e32 v77, s3
	v_mul_f32_e32 v114, s2, v77
	v_mov_b32_e32 v77, 0
	v_mul_f32_e32 v52, v76, v52
	v_mul_f32_e32 v76, v52, v52
	v_pk_mul_f32 v[70:71], v[10:11], v[68:69]
	s_nop 0
	v_mov_b32_dpp v77, v76 quad_perm:[1,0,3,2] row_mask:0xf bank_mask:0xf
	v_fmac_f32_e32 v77, v52, v52
	v_mov_b32_e32 v134, v70
	s_nop 0
	v_add_f32_dpp v76, v77, v77 quad_perm:[2,3,0,1] row_mask:0xf bank_mask:0xf bound_ctrl:1
	v_mov_b32_e32 v77, 0
	s_nop 0
	v_add_f32_dpp v76, v76, v76 row_half_mirror row_mask:0xf bank_mask:0xf bound_ctrl:1
	s_nop 1
	v_add_f32_dpp v76, v76, v76 row_mirror row_mask:0xf bank_mask:0xf bound_ctrl:1
	s_nop 1
	v_mov_b32_dpp v77, v76 row_bcast:15 row_mask:0xa bank_mask:0xf
	v_add_f32_e32 v76, v76, v77
	v_mov_b32_e32 v77, 0
	s_nop 1
	v_mov_b32_dpp v77, v76 row_bcast:31 row_mask:0xc bank_mask:0xf
	v_add_f32_e32 v76, v76, v77
	v_mul_f32_e32 v77, v12, v68
	v_readlane_b32 s3, v76, 63
	s_nop 1
	v_add_f32_e32 v76, s3, v86
	v_rsq_f32_e32 v76, v76
	v_readlane_b32 s3, v102, 27
	v_mul_f32_e32 v52, v52, v76
	v_mul_f32_e32 v116, 0x3e000000, v52
	v_mov_b32_e32 v52, v72
	v_mov_b32_e32 v76, v73
	v_pk_add_f32 v[76:77], v[52:53], v[76:77]
	v_lshlrev_b32_e32 v53, 16, v131
	v_lshlrev_b32_e32 v52, 16, v132
	v_pk_mul_f32 v[72:73], v[4:5], v[50:51] op_sel_hi:[0,1]
	v_pk_fma_f32 v[66:67], v[2:3], v[66:67], v[72:73] op_sel_hi:[0,1,1]
	v_pk_mov_b32 v[72:73], v[50:51], v[52:53] op_sel:[1,0]
	v_mul_f32_e32 v131, v9, v127
	v_pk_fma_f32 v[50:51], v[6:7], v[72:73], v[66:67] op_sel_hi:[0,1,1]
	v_pk_fma_f32 v[50:51], v[8:9], v[52:53], v[50:51] op_sel_hi:[0,1,1]
	v_mul_f32_e32 v66, 0xbfb8aa3b, v50
	v_exp_f32_e32 v70, v66
	v_mul_f32_e32 v66, 0xbfb8aa3b, v51
	v_exp_f32_e32 v129, v66
	v_pk_add_f32 v[66:67], v[76:77], v[134:135]
	v_add_f32_e32 v70, 1.0, v70
	v_rcp_f32_e32 v76, v70
	v_add_f32_e32 v70, 1.0, v129
	v_rcp_f32_e32 v77, v70
	v_lshlrev_b32_e32 v70, 16, v130
	v_fmac_f32_e32 v131, v5, v128
	v_fmac_f32_e32 v131, v7, v126
	v_pk_mul_f32 v[50:51], v[50:51], v[76:77]
	v_mul_f32_e32 v77, v11, v70
	v_mov_b32_e32 v76, v71
	v_pk_add_f32 v[66:67], v[66:67], v[76:77]
	v_pk_mul_f32 v[50:51], v[50:51], s[2:3]
	v_mul_f32_e32 v71, 0xbfb8aa3b, v66
	v_exp_f32_e32 v71, v71
	v_mul_f32_e32 v76, 0xbfb8aa3b, v67
	v_exp_f32_e32 v77, v76
	v_mov_b32_e32 v129, s4
	v_add_f32_e32 v71, 1.0, v71
	v_rcp_f32_e32 v76, v71
	v_add_f32_e32 v71, 1.0, v77
	v_rcp_f32_e32 v77, v71
	v_fmac_f32_e32 v131, v105, v54
	v_mul_f32_e32 v130, s3, v129
	v_pk_mul_f32 v[128:129], v[14:15], v[68:69]
	v_pk_mul_f32 v[66:67], v[66:67], v[76:77]
	v_mul_f32_e32 v68, 0xbfb8aa3b, v131
	v_pk_mul_f32 v[76:77], v[66:67], v[66:67]
	v_exp_f32_e32 v68, v68
	v_cvt_pk_bf16_f32 v116, v116, s0
	v_add_f32_dpp v71, v76, v76 quad_perm:[1,0,3,2] row_mask:0xf bank_mask:0xf bound_ctrl:1
	v_mov_b32_e32 v76, 0
	v_add_f32_e32 v68, 1.0, v68
	v_add_f32_dpp v71, v71, v71 quad_perm:[2,3,0,1] row_mask:0xf bank_mask:0xf bound_ctrl:1
	v_rcp_f32_e32 v68, v68
	v_readlane_b32 s3, v3, 28
	v_add_f32_dpp v71, v71, v71 row_half_mirror row_mask:0xf bank_mask:0xf bound_ctrl:1
	v_mul_f32_e32 v69, v12, v70
	v_mul_f32_e32 v68, v131, v68
	v_add_f32_dpp v71, v71, v71 row_mirror row_mask:0xf bank_mask:0xf bound_ctrl:1
	v_readlane_b32 s4, v3, 29
	s_nop 0
	v_mov_b32_dpp v76, v71 row_bcast:15 row_mask:0xa bank_mask:0xf
	v_add_f32_e32 v71, v71, v76
	v_mov_b32_e32 v76, 0
	s_nop 1
	v_mov_b32_dpp v76, v71 row_bcast:31 row_mask:0xc bank_mask:0xf
	v_add_f32_e32 v71, v71, v76
	s_nop 0
	v_readlane_b32 s2, v71, 63
	s_nop 1
	v_add_f32_e32 v71, s2, v86
	v_rsq_f32_e32 v76, v71
	s_nop 0
	v_add_f32_dpp v71, v77, v77 quad_perm:[1,0,3,2] row_mask:0xf bank_mask:0xf bound_ctrl:1
	v_mov_b32_e32 v77, 0
	s_nop 0
	v_add_f32_dpp v71, v71, v71 quad_perm:[2,3,0,1] row_mask:0xf bank_mask:0xf bound_ctrl:1
	s_nop 1
	v_add_f32_dpp v71, v71, v71 row_half_mirror row_mask:0xf bank_mask:0xf bound_ctrl:1
	s_nop 1
	v_add_f32_dpp v71, v71, v71 row_mirror row_mask:0xf bank_mask:0xf bound_ctrl:1
	s_nop 1
	v_mov_b32_dpp v77, v71 row_bcast:15 row_mask:0xa bank_mask:0xf
	v_add_f32_e32 v71, v71, v77
	v_mov_b32_e32 v77, 0
	s_nop 1
	v_mov_b32_dpp v77, v71 row_bcast:31 row_mask:0xc bank_mask:0xf
	v_add_f32_e32 v71, v71, v77
	s_nop 0
	v_readlane_b32 s2, v71, 63
	s_nop 1
	v_add_f32_e32 v71, s2, v86
	v_rsq_f32_e32 v77, v71
	v_lshlrev_b32_e32 v71, 16, v146
	v_pk_mul_f32 v[66:67], v[66:67], v[76:77]
	s_nop 0
	v_cvt_pk_bf16_f32 v76, v66, s0
	v_cvt_pk_bf16_f32 v77, v67, s0
	ds_write_b16 v115, v76 offset:7424
	v_mul_f32_e32 v76, v66, v114
	ds_write_b16 v117, v77 offset:7552
	v_mul_f32_e32 v77, v68, v68
	v_mov_b32_e32 v114, 0
	ds_write_b16 v117, v116 offset:3456
	s_nop 0
	v_mov_b32_dpp v114, v77 quad_perm:[1,0,3,2] row_mask:0xf bank_mask:0xf
	v_fmac_f32_e32 v114, v68, v68
	s_nop 1
	v_add_f32_dpp v77, v114, v114 quad_perm:[2,3,0,1] row_mask:0xf bank_mask:0xf bound_ctrl:1
	v_mov_b32_e32 v114, 0
	s_nop 0
	v_add_f32_dpp v77, v77, v77 row_half_mirror row_mask:0xf bank_mask:0xf bound_ctrl:1
	s_nop 1
	v_add_f32_dpp v77, v77, v77 row_mirror row_mask:0xf bank_mask:0xf bound_ctrl:1
	s_nop 1
	v_mov_b32_dpp v114, v77 row_bcast:15 row_mask:0xa bank_mask:0xf
	v_add_f32_e32 v77, v77, v114
	v_mov_b32_e32 v114, 0
	s_nop 1
	v_mov_b32_dpp v114, v77 row_bcast:31 row_mask:0xc bank_mask:0xf
	v_add_f32_e32 v77, v77, v114
	v_pk_mul_f32 v[114:115], v[10:11], v[70:71]
	v_readlane_b32 s2, v77, 63
	s_nop 1
	v_add_f32_e32 v77, s2, v86
	v_rsq_f32_e32 v116, v77
	v_readlane_b32 s2, v102, 28
	v_mul_f32_e32 v77, v67, v130
	v_mul_f32_e32 v68, v68, v116
	v_mul_f32_e32 v116, v9, v126
	v_fmac_f32_e32 v116, v5, v127
	v_fmac_f32_e32 v116, v7, v54
	v_fmac_f32_e32 v116, v105, v142
	v_mul_f32_e32 v117, 0xbfb8aa3b, v116
	v_exp_f32_e32 v117, v117
	v_mul_f32_e32 v68, 0x3e000000, v68
	v_cvt_pk_bf16_f32 v68, v68, s0
	ds_write_b16 v118, v68 offset:3584
	v_add_f32_e32 v68, 1.0, v117
	v_rcp_f32_e32 v68, v68
	v_mov_b32_e32 v117, s3
	v_mul_f32_e32 v130, s2, v117
	v_mov_b32_e32 v117, 0
	v_mul_f32_e32 v68, v116, v68
	v_mul_f32_e32 v116, v68, v68
	s_nop 1
	v_mov_b32_dpp v117, v116 quad_perm:[1,0,3,2] row_mask:0xf bank_mask:0xf
	v_fmac_f32_e32 v117, v68, v68
	s_nop 1
	v_add_f32_dpp v116, v117, v117 quad_perm:[2,3,0,1] row_mask:0xf bank_mask:0xf bound_ctrl:1
	v_mov_b32_e32 v117, 0
	s_nop 0
	v_add_f32_dpp v116, v116, v116 row_half_mirror row_mask:0xf bank_mask:0xf bound_ctrl:1
	s_nop 1
	v_add_f32_dpp v116, v116, v116 row_mirror row_mask:0xf bank_mask:0xf bound_ctrl:1
	s_nop 1
	v_mov_b32_dpp v117, v116 row_bcast:15 row_mask:0xa bank_mask:0xf
	v_add_f32_e32 v116, v116, v117
	v_mov_b32_e32 v117, 0
	s_nop 1
	v_mov_b32_dpp v117, v116 row_bcast:31 row_mask:0xc bank_mask:0xf
	v_add_f32_e32 v116, v116, v117
	v_mul_f32_e32 v117, v10, v71
	v_readlane_b32 s3, v116, 63
	s_nop 1
	v_add_f32_e32 v116, s3, v86
	v_rsq_f32_e32 v116, v116
	v_readlane_b32 s3, v102, 29
	v_mul_f32_e32 v12, v68, v116
	v_mul_f32_e32 v127, 0x3e000000, v12
	v_mov_b32_e32 v12, v128
	v_mov_b32_e32 v68, v129
	v_pk_add_f32 v[128:129], v[12:13], v[68:69]
	v_lshlrev_b32_e32 v13, 16, v79
	v_lshlrev_b32_e32 v12, 16, v145
	v_pk_mul_f32 v[68:69], v[4:5], v[52:53] op_sel_hi:[0,1]
	v_pk_fma_f32 v[72:73], v[2:3], v[72:73], v[68:69] op_sel_hi:[0,1,1]
	v_pk_mov_b32 v[68:69], v[52:53], v[12:13] op_sel:[1,0]
	v_mov_b32_e32 v116, v114
	v_pk_fma_f32 v[52:53], v[6:7], v[68:69], v[72:73] op_sel_hi:[0,1,1]
	v_pk_fma_f32 v[52:53], v[8:9], v[12:13], v[52:53] op_sel_hi:[0,1,1]
	v_mul_f32_e32 v72, 0xbfb8aa3b, v52
	v_exp_f32_e32 v79, v72
	v_mul_f32_e32 v72, 0xbfb8aa3b, v53
	v_exp_f32_e32 v114, v72
	v_pk_add_f32 v[72:73], v[128:129], v[116:117]
	v_add_f32_e32 v79, 1.0, v79
	v_rcp_f32_e32 v116, v79
	v_add_f32_e32 v79, 1.0, v114
	v_rcp_f32_e32 v117, v79
	v_lshlrev_b32_e32 v114, 16, v144
	v_cvt_pk_bf16_f32 v79, v127, s0
	v_mov_b32_e32 v127, s4
	v_pk_mul_f32 v[52:53], v[52:53], v[116:117]
	v_mul_f32_e32 v117, v11, v114
	v_mov_b32_e32 v116, v115
	v_pk_add_f32 v[72:73], v[72:73], v[116:117]
	v_pk_mul_f32 v[52:53], v[52:53], s[2:3]
	v_mul_f32_e32 v115, 0xbfb8aa3b, v72
	v_exp_f32_e32 v115, v115
	v_mul_f32_e32 v116, 0xbfb8aa3b, v73
	v_exp_f32_e32 v117, v116
	v_mul_f32_e32 v129, v9, v54
	v_add_f32_e32 v115, 1.0, v115
	v_rcp_f32_e32 v116, v115
	v_add_f32_e32 v115, 1.0, v117
	v_rcp_f32_e32 v117, v115
	v_mul_f32_e32 v128, s3, v127
	v_fmac_f32_e32 v129, v5, v126
	v_pk_mul_f32 v[126:127], v[14:15], v[70:71]
	v_pk_mul_f32 v[72:73], v[72:73], v[116:117]
	v_fmac_f32_e32 v129, v7, v142
	v_pk_mul_f32 v[116:117], v[72:73], v[72:73]
	v_fmac_f32_e32 v129, v105, v141
	v_mul_f32_e32 v9, v9, v142
	v_add_f32_dpp v115, v116, v116 quad_perm:[1,0,3,2] row_mask:0xf bank_mask:0xf bound_ctrl:1
	v_mov_b32_e32 v116, 0
	v_fmac_f32_e32 v9, v5, v54
	v_add_f32_dpp v115, v115, v115 quad_perm:[2,3,0,1] row_mask:0xf bank_mask:0xf bound_ctrl:1
	v_fmac_f32_e32 v9, v7, v141
	v_fmac_f32_e32 v9, v105, v143
	v_add_f32_dpp v115, v115, v115 row_half_mirror row_mask:0xf bank_mask:0xf bound_ctrl:1
	v_mul_f32_e32 v7, 0xbfb8aa3b, v9
	v_exp_f32_e32 v7, v7
	v_add_f32_dpp v115, v115, v115 row_mirror row_mask:0xf bank_mask:0xf bound_ctrl:1
	v_readlane_b32 s3, v3, 30
	v_readlane_b32 s4, v3, 31
	v_mov_b32_dpp v116, v115 row_bcast:15 row_mask:0xa bank_mask:0xf
	v_add_f32_e32 v115, v115, v116
	v_mov_b32_e32 v116, 0
	v_add_f32_e32 v7, 1.0, v7
	v_rcp_f32_e32 v7, v7
	v_mov_b32_dpp v116, v115 row_bcast:31 row_mask:0xc bank_mask:0xf
	v_add_f32_e32 v115, v115, v116
	v_mul_f32_e32 v7, v9, v7
	v_readlane_b32 s2, v115, 63
	v_mov_b32_e32 v9, 0
	s_nop 0
	v_add_f32_e32 v115, s2, v86
	v_rsq_f32_e32 v116, v115
	s_nop 0
	v_add_f32_dpp v115, v117, v117 quad_perm:[1,0,3,2] row_mask:0xf bank_mask:0xf bound_ctrl:1
	v_mov_b32_e32 v117, 0
	s_nop 0
	v_add_f32_dpp v115, v115, v115 quad_perm:[2,3,0,1] row_mask:0xf bank_mask:0xf bound_ctrl:1
	s_nop 1
	v_add_f32_dpp v115, v115, v115 row_half_mirror row_mask:0xf bank_mask:0xf bound_ctrl:1
	s_nop 1
	v_add_f32_dpp v115, v115, v115 row_mirror row_mask:0xf bank_mask:0xf bound_ctrl:1
	s_nop 1
	v_mov_b32_dpp v117, v115 row_bcast:15 row_mask:0xa bank_mask:0xf
	v_add_f32_e32 v115, v115, v117
	v_mov_b32_e32 v117, 0
	s_nop 1
	v_mov_b32_dpp v117, v115 row_bcast:31 row_mask:0xc bank_mask:0xf
	v_add_f32_e32 v115, v115, v117
	s_nop 0
	v_readlane_b32 s2, v115, 63
	s_nop 1
	v_add_f32_e32 v115, s2, v86
	v_rsq_f32_e32 v117, v115
	v_lshlrev_b32_e32 v115, 16, v78
	v_mov_b32_e32 v54, v115
	v_pk_mul_f32 v[72:73], v[72:73], v[116:117]
	s_nop 0
	v_cvt_pk_bf16_f32 v70, v72, s0
	ds_write_b16 v118, v70 offset:7680
	v_pk_mul_f32 v[116:117], v[10:11], v[114:115]
	v_add_f32_e32 v70, v126, v127
	v_add_f32_e32 v70, v70, v116
	ds_write_b16 v119, v79 offset:3712
	v_add_f32_e32 v70, v70, v117
	v_mul_f32_e32 v79, 0xbfb8aa3b, v129
	v_exp_f32_e32 v79, v79
	v_mul_f32_e32 v116, 0xbfb8aa3b, v70
	v_exp_f32_e32 v116, v116
	v_cvt_pk_bf16_f32 v117, v73, s0
	v_add_f32_e32 v79, 1.0, v79
	v_rcp_f32_e32 v118, v79
	v_add_f32_e32 v79, 1.0, v116
	v_rcp_f32_e32 v116, v79
	ds_write_b16 v119, v117 offset:7808
	v_mul_f32_e32 v117, v129, v118
	v_mov_b32_e32 v118, 0
	v_mul_f32_e32 v116, v70, v116
	v_mul_f32_e32 v70, v117, v117
	v_pk_mul_f32 v[10:11], v[10:11], v[54:55]
	v_lshlrev_b32_e32 v54, 16, v140
	v_mov_b32_dpp v118, v70 quad_perm:[1,0,3,2] row_mask:0xf bank_mask:0xf
	v_fmac_f32_e32 v118, v117, v117
	v_lshlrev_b32_e32 v55, 16, v139
	v_mul_f32_e32 v78, v72, v130
	v_add_f32_dpp v70, v118, v118 quad_perm:[2,3,0,1] row_mask:0xf bank_mask:0xf bound_ctrl:1
	v_mov_b32_e32 v118, 0
	v_mul_f32_e32 v79, v73, v128
	v_add_f32_dpp v70, v70, v70 row_half_mirror row_mask:0xf bank_mask:0xf bound_ctrl:1
	v_and_b32_e32 v127, 7, v22
	s_nop 0
	v_add_f32_dpp v70, v70, v70 row_mirror row_mask:0xf bank_mask:0xf bound_ctrl:1
	s_nop 1
	v_mov_b32_dpp v118, v70 row_bcast:15 row_mask:0xa bank_mask:0xf
	v_add_f32_e32 v70, v70, v118
	v_mov_b32_e32 v118, 0
	s_nop 1
	v_mov_b32_dpp v118, v70 row_bcast:31 row_mask:0xc bank_mask:0xf
	v_add_f32_e32 v70, v70, v118
	v_mov_b32_e32 v118, 0
	v_readlane_b32 s2, v70, 63
	v_mul_f32_e32 v70, v116, v116
	s_nop 0
	v_add_f32_e32 v119, s2, v86
	v_mov_b32_dpp v118, v70 quad_perm:[1,0,3,2] row_mask:0xf bank_mask:0xf
	v_fmac_f32_e32 v118, v116, v116
	v_rsq_f32_e32 v119, v119
	s_nop 0
	v_add_f32_dpp v70, v118, v118 quad_perm:[2,3,0,1] row_mask:0xf bank_mask:0xf bound_ctrl:1
	v_mov_b32_e32 v118, 0
	s_nop 0
	v_add_f32_dpp v70, v70, v70 row_half_mirror row_mask:0xf bank_mask:0xf bound_ctrl:1
	s_nop 1
	v_add_f32_dpp v70, v70, v70 row_mirror row_mask:0xf bank_mask:0xf bound_ctrl:1
	s_nop 1
	v_mov_b32_dpp v118, v70 row_bcast:15 row_mask:0xa bank_mask:0xf
	v_add_f32_e32 v70, v70, v118
	v_mov_b32_e32 v118, 0
	s_nop 1
	v_mov_b32_dpp v118, v70 row_bcast:31 row_mask:0xc bank_mask:0xf
	v_add_f32_e32 v70, v70, v118
	s_nop 0
	v_readlane_b32 s2, v70, 63
	v_mul_f32_e32 v70, v117, v119
	v_mul_f32_e32 v70, 0x3e000000, v70
	v_cvt_pk_bf16_f32 v70, v70, s0
	ds_write_b16 v124, v70 offset:3840
	v_pk_mov_b32 v[70:71], v[70:71], v[114:115] op_sel:[1,0]
	v_add_f32_e32 v117, s2, v86
	v_pk_mul_f32 v[14:15], v[14:15], v[70:71]
	v_rsq_f32_e32 v118, v117
	v_add_f32_e32 v5, v14, v15
	v_add_f32_e32 v5, v5, v10
	v_add_f32_e32 v5, v5, v11
	v_mul_f32_e32 v10, 0xbfb8aa3b, v5
	v_exp_f32_e32 v10, v10
	v_mov_b32_e32 v119, s3
	v_readlane_b32 s2, v102, 30
	v_mov_b32_e32 v15, s4
	v_add_f32_e32 v10, 1.0, v10
	v_rcp_f32_e32 v10, v10
	v_mov_b32_e32 v117, s2
	v_pk_mul_f32 v[116:117], v[116:117], v[118:119]
	v_add_u32_e32 v119, 4, v109
	v_mul_f32_e32 v10, v5, v10
	v_mul_f32_e32 v5, v7, v7
	v_cvt_pk_bf16_f32 v11, v116, s0
	ds_write_b16 v124, v11 offset:7936
	v_mov_b32_dpp v9, v5 quad_perm:[1,0,3,2] row_mask:0xf bank_mask:0xf
	v_fmac_f32_e32 v9, v7, v7
	v_mul_f32_e32 v105, v116, v117
	v_add_u32_e32 v117, 2, v109
	v_add_f32_dpp v5, v9, v9 quad_perm:[2,3,0,1] row_mask:0xf bank_mask:0xf bound_ctrl:1
	v_mov_b32_e32 v9, 0
	v_lshlrev_b32_e32 v115, 2, v109
	v_add_f32_dpp v5, v5, v5 row_half_mirror row_mask:0xf bank_mask:0xf bound_ctrl:1
	v_sub_u32_e32 v128, v96, v115
	s_movk_i32 s4, 0x50
	v_add_f32_dpp v5, v5, v5 row_mirror row_mask:0xf bank_mask:0xf bound_ctrl:1
	s_nop 1
	v_mov_b32_dpp v9, v5 row_bcast:15 row_mask:0xa bank_mask:0xf
	v_add_f32_e32 v5, v5, v9
	v_mov_b32_e32 v9, 0
	s_nop 1
	v_mov_b32_dpp v9, v5 row_bcast:31 row_mask:0xc bank_mask:0xf
	v_add_f32_e32 v5, v5, v9
	v_mov_b32_e32 v9, 0
	v_readlane_b32 s3, v5, 63
	v_mul_f32_e32 v5, v10, v10
	s_nop 0
	v_add_f32_e32 v11, s3, v86
	v_mov_b32_dpp v9, v5 quad_perm:[1,0,3,2] row_mask:0xf bank_mask:0xf
	v_fmac_f32_e32 v9, v10, v10
	v_rsq_f32_e32 v11, v11
	s_nop 0
	v_add_f32_dpp v5, v9, v9 quad_perm:[2,3,0,1] row_mask:0xf bank_mask:0xf bound_ctrl:1
	v_mov_b32_e32 v9, 0
	s_nop 0
	v_add_f32_dpp v5, v5, v5 row_half_mirror row_mask:0xf bank_mask:0xf bound_ctrl:1
	s_nop 1
	v_add_f32_dpp v5, v5, v5 row_mirror row_mask:0xf bank_mask:0xf bound_ctrl:1
	s_nop 1
	v_mov_b32_dpp v9, v5 row_bcast:15 row_mask:0xa bank_mask:0xf
	v_add_f32_e32 v5, v5, v9
	v_mov_b32_e32 v9, 0
	s_nop 1
	v_mov_b32_dpp v9, v5 row_bcast:31 row_mask:0xc bank_mask:0xf
	v_add_f32_e32 v5, v5, v9
	s_nop 0
	v_readlane_b32 s3, v5, 63
	v_mul_f32_e32 v5, v7, v11
	v_mul_f32_e32 v7, 0x3e000000, v5
	v_add_f32_e32 v5, s3, v86
	v_rsq_f32_e32 v14, v5
	v_pk_mul_f32 v[4:5], v[4:5], v[12:13] op_sel_hi:[0,1]
	v_pk_fma_f32 v[4:5], v[2:3], v[68:69], v[4:5] op_sel_hi:[0,1,1]
	v_pk_mov_b32 v[12:13], v[12:13], v[54:55] op_sel:[1,0]
	v_readlane_b32 s3, v102, 31
	v_pk_fma_f32 v[4:5], v[6:7], v[12:13], v[4:5] op_sel_hi:[0,1,1]
	v_pk_fma_f32 v[4:5], v[8:9], v[54:55], v[4:5] op_sel_hi:[0,1,1]
	v_mul_f32_e32 v2, 0xbfb8aa3b, v4
	v_exp_f32_e32 v2, v2
	v_mul_f32_e32 v6, 0xbfb8aa3b, v5
	v_exp_f32_e32 v8, v6
	v_cvt_pk_bf16_f32 v9, v7, s0
	v_add_f32_e32 v2, 1.0, v2
	v_rcp_f32_e32 v6, v2
	v_add_f32_e32 v2, 1.0, v8
	v_rcp_f32_e32 v7, v2
	v_mov_b32_e32 v11, s3
	v_pk_mul_f32 v[10:11], v[10:11], v[14:15]
	ds_write_b16 v125, v9 offset:3968
	v_pk_mul_f32 v[2:3], v[4:5], v[6:7]
	v_cvt_pk_bf16_f32 v4, v64, v65
	v_pk_mul_f32 v[54:55], v[2:3], s[2:3]
	v_cvt_pk_bf16_f32 v2, v10, s0
	ds_write_b16 v125, v2 offset:8064
	v_cvt_pk_bf16_f32 v2, v56, v57
	v_cvt_pk_bf16_f32 v3, v58, v59
	v_cvt_pk_bf16_f32 v5, v66, v67
	v_cvt_pk_bf16_f32 v6, v60, v61
	v_cvt_pk_bf16_f32 v7, v62, v63
	v_cvt_pk_bf16_f32 v8, v72, v73
	v_cvt_pk_bf16_f32 v9, v116, v10
	flat_store_dwordx4 v[16:17], v[2:5] offset:1024
	flat_store_dwordx4 v[16:17], v[6:9] offset:1536
	v_mul_f32_e32 v114, v10, v11
	v_lshlrev_b32_e32 v2, 7, v22
	v_and_b32_e32 v2, 0xf80, v2
	v_add_u32_e32 v64, s51, v2
	v_bitop3_b32 v2, v109, v22, 7 bitop3:0x78
	s_waitcnt lgkmcnt(0)
	v_lshl_add_u32 v116, v2, 4, v64
	ds_read_b128 v[2:5], v116 offset:4096
	ds_read_b128 v[6:9], v116
	s_waitcnt lgkmcnt(0)
	v_mfma_f32_32x32x16_bf16 v[2:17], v[2:5], v[6:9], 0
	v_bitop3_b32 v56, v117, v22, 7 bitop3:0x78
	v_lshl_add_u32 v118, v56, 4, v64
	ds_read_b128 v[56:59], v118 offset:4096
	ds_read_b128 v[60:63], v118
	v_add_u32_e32 v125, 6, v109
	v_readlane_b32 s2, v101, 0
	v_readlane_b32 s3, v101, 4
	s_waitcnt lgkmcnt(0)
	v_mfma_f32_32x32x16_bf16 v[2:17], v[56:59], v[60:63], v[2:17]
	v_bitop3_b32 v56, v119, v22, 7 bitop3:0x78
	v_lshl_add_u32 v124, v56, 4, v64
	ds_read_b128 v[56:59], v124 offset:4096
	ds_read_b128 v[60:63], v124
	s_waitcnt lgkmcnt(0)
	v_mfma_f32_32x32x16_bf16 v[2:17], v[56:59], v[60:63], v[2:17]
	v_bitop3_b32 v56, v125, v22, 7 bitop3:0x78
	v_lshl_add_u32 v126, v56, 4, v64
	ds_read_b128 v[56:59], v126 offset:4096
	ds_read_b128 v[60:63], v126
	s_waitcnt lgkmcnt(0)
	v_mfma_f32_32x32x16_bf16 v[2:17], v[56:59], v[60:63], v[2:17]
	v_mov_b32_e32 v56, s3
	v_mov_b32_e32 v57, s2
	v_cndmask_b32_e32 v56, v56, v57, vcc
	v_sub_f32_e32 v56, v101, v56
	v_mul_f32_e32 v56, 0x3fb8aa3b, v56
	v_readlane_b32 s2, v101, 1
	v_readlane_b32 s3, v101, 5
	v_exp_f32_e32 v64, v56
	v_mov_b32_e32 v57, s2
	v_mov_b32_e32 v56, s3
	v_cndmask_b32_e32 v56, v56, v57, vcc
	v_sub_f32_e32 v56, v101, v56
	v_mul_f32_e32 v56, 0x3fb8aa3b, v56
	v_readlane_b32 s2, v101, 2
	v_readlane_b32 s3, v101, 6
	v_exp_f32_e32 v65, v56
	v_mov_b32_e32 v57, s2
	v_mov_b32_e32 v56, s3
	v_cndmask_b32_e32 v56, v56, v57, vcc
	v_sub_f32_e32 v56, v101, v56
	v_mul_f32_e32 v56, 0x3fb8aa3b, v56
	v_readlane_b32 s2, v101, 3
	v_readlane_b32 s3, v101, 7
	v_exp_f32_e32 v62, v56
	v_mov_b32_e32 v57, s2
	v_mov_b32_e32 v56, s3
	v_cndmask_b32_e32 v56, v56, v57, vcc
	v_sub_f32_e32 v56, v101, v56
	v_mul_f32_e32 v56, 0x3fb8aa3b, v56
	v_readlane_b32 s2, v101, 8
	v_readlane_b32 s3, v101, 12
	v_exp_f32_e32 v63, v56
	v_mov_b32_e32 v57, s2
	v_mov_b32_e32 v56, s3
	v_cndmask_b32_e32 v56, v56, v57, vcc
	v_sub_f32_e32 v56, v101, v56
	v_mul_f32_e32 v56, 0x3fb8aa3b, v56
	v_readlane_b32 s2, v101, 9
	v_readlane_b32 s3, v101, 13
	v_exp_f32_e32 v60, v56
	v_mov_b32_e32 v57, s2
	v_mov_b32_e32 v56, s3
	v_cndmask_b32_e32 v56, v56, v57, vcc
	v_sub_f32_e32 v56, v101, v56
	v_mul_f32_e32 v56, 0x3fb8aa3b, v56
	v_readlane_b32 s2, v101, 10
	v_readlane_b32 s3, v101, 14
	v_exp_f32_e32 v61, v56
	v_mov_b32_e32 v57, s2
	v_mov_b32_e32 v56, s3
	v_cndmask_b32_e32 v56, v56, v57, vcc
	v_sub_f32_e32 v56, v101, v56
	v_mul_f32_e32 v56, 0x3fb8aa3b, v56
	v_readlane_b32 s2, v101, 11
	v_readlane_b32 s3, v101, 15
	v_exp_f32_e32 v58, v56
	v_mov_b32_e32 v57, s2
	v_mov_b32_e32 v56, s3
	v_cndmask_b32_e32 v56, v56, v57, vcc
	v_sub_f32_e32 v56, v101, v56
	v_mul_f32_e32 v56, 0x3fb8aa3b, v56
	v_readlane_b32 s2, v101, 16
	v_readlane_b32 s3, v101, 20
	v_exp_f32_e32 v59, v56
	v_mov_b32_e32 v57, s2
	v_mov_b32_e32 v56, s3
	v_cndmask_b32_e32 v56, v56, v57, vcc
	v_sub_f32_e32 v56, v101, v56
	v_mul_f32_e32 v56, 0x3fb8aa3b, v56
	v_readlane_b32 s2, v101, 17
	v_readlane_b32 s3, v101, 21
	v_exp_f32_e32 v72, v56
	v_mov_b32_e32 v57, s2
	v_mov_b32_e32 v56, s3
	v_cndmask_b32_e32 v56, v56, v57, vcc
	v_sub_f32_e32 v56, v101, v56
	v_mul_f32_e32 v56, 0x3fb8aa3b, v56
	v_readlane_b32 s2, v101, 18
	v_readlane_b32 s3, v101, 22
	v_exp_f32_e32 v73, v56
	v_mov_b32_e32 v57, s2
	v_mov_b32_e32 v56, s3
	v_cndmask_b32_e32 v56, v56, v57, vcc
	v_sub_f32_e32 v56, v101, v56
	v_mul_f32_e32 v56, 0x3fb8aa3b, v56
	v_readlane_b32 s2, v101, 19
	v_readlane_b32 s3, v101, 23
	v_exp_f32_e32 v70, v56
	v_mov_b32_e32 v57, s2
	v_mov_b32_e32 v56, s3
	v_cndmask_b32_e32 v56, v56, v57, vcc
	v_sub_f32_e32 v56, v101, v56
	v_mul_f32_e32 v56, 0x3fb8aa3b, v56
	v_readlane_b32 s2, v101, 24
	v_readlane_b32 s3, v101, 28
	v_exp_f32_e32 v71, v56
	v_mov_b32_e32 v57, s2
	v_mov_b32_e32 v56, s3
	v_cndmask_b32_e32 v56, v56, v57, vcc
	v_sub_f32_e32 v56, v101, v56
	v_mul_f32_e32 v56, 0x3fb8aa3b, v56
	v_readlane_b32 s2, v101, 25
	v_readlane_b32 s3, v101, 29
	v_exp_f32_e32 v68, v56
	v_mov_b32_e32 v57, s2
	v_mov_b32_e32 v56, s3
	v_cndmask_b32_e32 v56, v56, v57, vcc
	v_sub_f32_e32 v56, v101, v56
	v_mul_f32_e32 v56, 0x3fb8aa3b, v56
	v_readlane_b32 s2, v101, 26
	v_readlane_b32 s3, v101, 30
	v_exp_f32_e32 v69, v56
	v_mov_b32_e32 v57, s2
	v_mov_b32_e32 v56, s3
	v_cndmask_b32_e32 v56, v56, v57, vcc
	v_sub_f32_e32 v56, v101, v56
	v_mul_f32_e32 v56, 0x3fb8aa3b, v56
	v_readlane_b32 s2, v101, 27
	v_readlane_b32 s3, v101, 31
	v_pk_mul_f32 v[2:3], v[2:3], v[64:65]
	v_exp_f32_e32 v66, v56
	v_mov_b32_e32 v56, s3
	v_mov_b32_e32 v57, s2
	v_cndmask_b32_e32 v56, v56, v57, vcc
	v_cvt_pk_bf16_f32 v2, v2, v3
	v_cmp_lt_i32_e32 vcc, -1, v128
	v_pk_mul_f32 v[4:5], v[4:5], v[62:63]
	v_pk_mul_f32 v[6:7], v[6:7], v[60:61]
	v_cndmask_b32_e32 v3, 0, v2, vcc
	v_lshrrev_b32_e32 v2, 16, v2
	v_cmp_lt_i32_e32 vcc, 0, v128
	v_pk_mul_f32 v[8:9], v[8:9], v[58:59]
	v_sub_f32_e32 v56, v101, v56
	v_cndmask_b32_e32 v2, 0, v2, vcc
	v_perm_b32 v2, v2, v3, s15
	v_cvt_pk_bf16_f32 v3, v4, v5
	v_cmp_lt_i32_e32 vcc, 1, v128
	v_mul_f32_e32 v56, 0x3fb8aa3b, v56
	v_exp_f32_e32 v67, v56
	v_cndmask_b32_e32 v4, 0, v3, vcc
	v_lshrrev_b32_e32 v3, 16, v3
	v_cmp_lt_i32_e32 vcc, 2, v128
	s_add_u32 s2, s0, 0x2000
	v_lshlrev_b32_e32 v56, 4, v22
	v_cndmask_b32_e32 v3, 0, v3, vcc
	v_perm_b32 v3, v3, v4, s15
	v_cvt_pk_bf16_f32 v4, v6, v7
	v_cmp_lt_i32_e32 vcc, 7, v128
	s_addc_u32 s3, s1, 0
	v_ashrrev_i32_e32 v57, 31, v56
	v_cndmask_b32_e32 v5, 0, v4, vcc
	v_lshrrev_b32_e32 v4, 16, v4
	v_cmp_lt_i32_e32 vcc, 8, v128
	v_pk_mul_f32 v[10:11], v[10:11], v[72:73]
	v_pk_mul_f32 v[12:13], v[12:13], v[70:71]
	v_cndmask_b32_e32 v4, 0, v4, vcc
	v_perm_b32 v4, v4, v5, s15
	v_cvt_pk_bf16_f32 v5, v8, v9
	v_cmp_lt_i32_e32 vcc, 9, v128
	v_pk_mul_f32 v[14:15], v[14:15], v[68:69]
	v_pk_mul_f32 v[16:17], v[16:17], v[66:67]
	v_cndmask_b32_e32 v6, 0, v5, vcc
	v_lshrrev_b32_e32 v5, 16, v5
	v_cmp_lt_i32_e32 vcc, 10, v128
	v_lshl_add_u32 v101, v96, 7, s51
	v_lshl_add_u32 v8, v109, 3, v101
	v_cndmask_b32_e32 v5, 0, v5, vcc
	v_perm_b32 v5, v5, v6, s15
	v_lshl_add_u64 v[6:7], s[2:3], 0, v[56:57]
	flat_store_dwordx4 v[6:7], v[2:5]
	v_cmp_lt_i32_e32 vcc, 15, v128
	v_lshlrev_b32_e32 v9, 4, v127
	v_cvt_pk_bf16_f32 v2, v10, v11
	v_cndmask_b32_e32 v3, 0, v2, vcc
	v_lshrrev_b32_e32 v2, 16, v2
	v_cmp_lt_i32_e32 vcc, 16, v128
	v_lshlrev_b32_e32 v109, 9, v109
	s_nop 0
	v_cndmask_b32_e32 v2, 0, v2, vcc
	v_perm_b32 v2, v2, v3, s15
	v_cvt_pk_bf16_f32 v3, v12, v13
	v_cmp_lt_i32_e32 vcc, 17, v128
	s_nop 1
	v_cndmask_b32_e32 v4, 0, v3, vcc
	v_lshrrev_b32_e32 v3, 16, v3
	v_cmp_lt_i32_e32 vcc, 18, v128
	s_nop 1
	v_cndmask_b32_e32 v3, 0, v3, vcc
	v_perm_b32 v3, v3, v4, s15
	v_cvt_pk_bf16_f32 v4, v14, v15
	v_cmp_lt_i32_e32 vcc, 23, v128
	s_nop 1
	v_cndmask_b32_e32 v5, 0, v4, vcc
	v_lshrrev_b32_e32 v4, 16, v4
	v_cmp_lt_i32_e32 vcc, 24, v128
	s_nop 1
	v_cndmask_b32_e32 v4, 0, v4, vcc
	v_perm_b32 v4, v4, v5, s15
	v_cvt_pk_bf16_f32 v5, v16, v17
	v_cmp_lt_i32_e32 vcc, 25, v128
	s_nop 1
	v_cndmask_b32_e32 v6, 0, v5, vcc
	v_lshrrev_b32_e32 v5, 16, v5
	v_cmp_lt_i32_e32 vcc, 26, v128
	s_nop 1
	v_cndmask_b32_e32 v5, 0, v5, vcc
	v_perm_b32 v5, v5, v6, s15
	v_add_u32_e32 v6, 0x400, v56
	v_ashrrev_i32_e32 v7, 31, v6
	v_lshl_add_u64 v[6:7], s[2:3], 0, v[6:7]
	flat_store_dwordx4 v[6:7], v[2:5]
	s_add_u32 s2, s0, 0x1000
	v_or_b32_e32 v6, v109, v108
	v_add_u32_e32 v2, v8, v9
	v_xad_u32 v4, v9, 16, v8
	ds_read_b64 v[2:3], v2
	ds_read_b64 v[4:5], v4
	s_addc_u32 s3, s1, 0
	v_ashrrev_i32_e32 v7, 31, v6
	v_lshl_add_u64 v[6:7], s[2:3], 0, v[6:7]
	v_cmp_gt_i32_e32 vcc, v96, v115
	s_waitcnt lgkmcnt(0)
	flat_store_dwordx4 v[6:7], v[2:5]
	v_lshl_or_b32 v6, v117, 9, v108
	v_ashrrev_i32_e32 v7, 31, v6
	v_xad_u32 v2, v9, 32, v8
	v_xad_u32 v4, v9, 48, v8
	ds_read_b64 v[2:3], v2
	ds_read_b64 v[4:5], v4
	v_lshl_add_u64 v[6:7], s[2:3], 0, v[6:7]
	s_waitcnt lgkmcnt(0)
	flat_store_dwordx4 v[6:7], v[2:5]
	s_nop 1
	v_xad_u32 v2, v9, 64, v8
	v_xad_u32 v4, v9, s4, v8
	ds_read_b64 v[2:3], v2
	ds_read_b64 v[4:5], v4
	v_lshl_or_b32 v6, v119, 9, v108
	v_ashrrev_i32_e32 v7, 31, v6
	v_lshl_add_u64 v[6:7], s[2:3], 0, v[6:7]
	s_movk_i32 s4, 0x60
	s_waitcnt lgkmcnt(0)
	flat_store_dwordx4 v[6:7], v[2:5]
	v_lshl_or_b32 v6, v125, 9, v108
	v_ashrrev_i32_e32 v7, 31, v6
	v_xad_u32 v2, v9, s4, v8
	s_movk_i32 s4, 0x70
	v_xad_u32 v4, v9, s4, v8
	ds_read_b64 v[2:3], v2
	ds_read_b64 v[4:5], v4
	v_lshl_add_u64 v[6:7], s[2:3], 0, v[6:7]
	s_movk_i32 s2, 0xff84
	v_mad_i32_i24 v101, v96, s2, v101
	s_add_u32 s2, s0, 0x3800
	s_waitcnt lgkmcnt(0)
	flat_store_dwordx4 v[6:7], v[2:5]
	ds_read_b128 v[2:5], v116 offset:4096
	ds_read_b128 v[116:119], v118 offset:4096
	s_waitcnt lgkmcnt(0)
	v_mfma_f32_32x32x16_bf16 v[2:17], v[2:5], v[2:5], 0
	s_addc_u32 s3, s1, 0
	v_mfma_f32_32x32x16_bf16 v[2:17], v[116:119], v[116:119], v[2:17]
	ds_read_b128 v[116:119], v124 offset:4096
	ds_read_b128 v[124:127], v126 offset:4096
	s_waitcnt lgkmcnt(0)
	v_mfma_f32_32x32x16_bf16 v[2:17], v[116:119], v[116:119], v[2:17]
	v_mfma_f32_32x32x16_bf16 v[2:17], v[124:127], v[124:127], v[2:17]
	s_nop 11
	v_mul_f32_e32 v2, v102, v2
	v_mul_f32_e32 v2, v2, v64
	v_cndmask_b32_e32 v2, 0, v2, vcc
	v_add_u32_e32 v64, v101, v109
	ds_write_b32 v64, v2 offset:8192
	v_or_b32_e32 v2, 1, v115
	v_mul_f32_e32 v3, v102, v3
	v_mul_f32_e32 v3, v3, v65
	v_cmp_gt_i32_e32 vcc, v96, v2
	v_lshl_add_u32 v2, v2, 7, v101
	s_nop 0
	v_cndmask_b32_e32 v3, 0, v3, vcc
	ds_write_b32 v2, v3 offset:8192
	v_or_b32_e32 v2, 2, v115
	v_mul_f32_e32 v3, v102, v4
	v_mul_f32_e32 v3, v3, v62
	v_cmp_gt_i32_e32 vcc, v96, v2
	v_lshl_add_u32 v2, v2, 7, v101
	s_nop 0
	v_cndmask_b32_e32 v3, 0, v3, vcc
	ds_write_b32 v2, v3 offset:8192
	v_or_b32_e32 v2, 3, v115
	v_mul_f32_e32 v3, v102, v5
	v_mul_f32_e32 v3, v3, v63
	v_cmp_gt_i32_e32 vcc, v96, v2
	v_lshl_add_u32 v2, v2, 7, v101
	s_nop 0
	v_cndmask_b32_e32 v3, 0, v3, vcc
	ds_write_b32 v2, v3 offset:8192
	v_add_u32_e32 v2, 8, v115
	v_mul_f32_e32 v3, v102, v6
	v_mul_f32_e32 v3, v3, v60
	v_cmp_gt_i32_e32 vcc, v96, v2
	v_lshl_add_u32 v2, v2, 7, v101
	s_nop 0
	v_cndmask_b32_e32 v3, 0, v3, vcc
	ds_write_b32 v2, v3 offset:8192
	v_add_u32_e32 v2, 9, v115
	v_mul_f32_e32 v3, v102, v7
	v_mul_f32_e32 v3, v3, v61
	v_cmp_gt_i32_e32 vcc, v96, v2
	v_lshl_add_u32 v2, v2, 7, v101
	s_nop 0
	v_cndmask_b32_e32 v3, 0, v3, vcc
	ds_write_b32 v2, v3 offset:8192
	v_add_u32_e32 v2, 10, v115
	v_mul_f32_e32 v3, v102, v8
	v_mul_f32_e32 v3, v3, v58
	v_cmp_gt_i32_e32 vcc, v96, v2
	v_lshl_add_u32 v2, v2, 7, v101
	v_mov_b32_e32 v58, 0
	v_cndmask_b32_e32 v3, 0, v3, vcc
	ds_write_b32 v2, v3 offset:8192
	v_add_u32_e32 v2, 11, v115
	v_mul_f32_e32 v3, v102, v9
	v_mul_f32_e32 v3, v3, v59
	v_cmp_gt_i32_e32 vcc, v96, v2
	v_lshl_add_u32 v2, v2, 7, v101
	s_nop 0
	v_cndmask_b32_e32 v3, 0, v3, vcc
	ds_write_b32 v2, v3 offset:8192
	v_add_u32_e32 v2, 16, v115
	v_mul_f32_e32 v3, v102, v10
	v_mul_f32_e32 v3, v3, v72
	v_cmp_gt_i32_e32 vcc, v96, v2
	v_lshl_add_u32 v2, v2, 7, v101
	s_nop 0
	v_cndmask_b32_e32 v3, 0, v3, vcc
	ds_write_b32 v2, v3 offset:8192
	v_add_u32_e32 v2, 17, v115
	v_mul_f32_e32 v3, v102, v11
	v_mul_f32_e32 v3, v3, v73
	v_cmp_gt_i32_e32 vcc, v96, v2
	v_lshl_add_u32 v2, v2, 7, v101
	s_nop 0
	v_cndmask_b32_e32 v3, 0, v3, vcc
	ds_write_b32 v2, v3 offset:8192
	v_add_u32_e32 v2, 18, v115
	v_mul_f32_e32 v3, v102, v12
	v_mul_f32_e32 v3, v3, v70
	v_cmp_gt_i32_e32 vcc, v96, v2
	v_lshl_add_u32 v2, v2, 7, v101
	s_nop 0
	v_cndmask_b32_e32 v3, 0, v3, vcc
	ds_write_b32 v2, v3 offset:8192
	v_add_u32_e32 v2, 19, v115
	v_mul_f32_e32 v3, v102, v13
	v_mul_f32_e32 v3, v3, v71
	v_cmp_gt_i32_e32 vcc, v96, v2
	v_lshl_add_u32 v2, v2, 7, v101
	s_nop 0
	v_cndmask_b32_e32 v3, 0, v3, vcc
	ds_write_b32 v2, v3 offset:8192
	v_add_u32_e32 v2, 24, v115
	v_mul_f32_e32 v3, v102, v14
	v_mul_f32_e32 v3, v3, v68
	v_cmp_gt_i32_e32 vcc, v96, v2
	v_lshl_add_u32 v2, v2, 7, v101
	s_nop 0
	v_cndmask_b32_e32 v3, 0, v3, vcc
	ds_write_b32 v2, v3 offset:8192
	v_add_u32_e32 v2, 25, v115
	v_mul_f32_e32 v3, v102, v15
	v_mul_f32_e32 v3, v3, v69
	v_cmp_gt_i32_e32 vcc, v96, v2
	v_lshl_add_u32 v2, v2, 7, v101
	s_nop 0
	v_cndmask_b32_e32 v3, 0, v3, vcc
	ds_write_b32 v2, v3 offset:8192
	v_add_u32_e32 v2, 26, v115
	v_mul_f32_e32 v3, v102, v16
	v_mul_f32_e32 v3, v3, v66
	v_cmp_gt_i32_e32 vcc, v96, v2
	v_lshl_add_u32 v2, v2, 7, v101
	s_nop 0
	v_cndmask_b32_e32 v3, 0, v3, vcc
	ds_write_b32 v2, v3 offset:8192
	v_add_u32_e32 v2, 27, v115
	v_mul_f32_e32 v3, v102, v17
	v_mul_f32_e32 v3, v3, v67
	v_cmp_gt_i32_e32 vcc, v96, v2
	v_lshl_add_u32 v2, v2, 7, v101
	s_nop 0
	v_cndmask_b32_e32 v3, 0, v3, vcc
	ds_write_b32 v2, v3 offset:8192
	s_waitcnt lgkmcnt(0)
	s_nop 0
	v_add_u32_e32 v14, s51, v58
	ds_read_b128 v[2:5], v14 offset:8192
	ds_read_b128 v[6:9], v14 offset:8208
	ds_read_b128 v[10:13], v14 offset:8224
	ds_read_b128 v[14:17], v14 offset:8240
	s_waitcnt lgkmcnt(0)
	v_fma_f32 v36, -v14, v24, v36
	v_fma_f32 v104, -v14, v88, v104
	v_fma_f32 v39, -v17, v24, v39
	v_fma_f32 v25, -v3, v24, v25
	v_fma_f32 v90, -v3, v88, v90
	v_fma_f32 v26, -v4, v24, v26
	v_fma_f32 v89, -v4, v88, v89
	v_fma_f32 v27, -v5, v24, v27
	s_nop 0
	v_fma_f32 v91, -v5, v88, v91
	v_fma_f32 v28, -v6, v24, v28
	v_fma_f32 v92, -v6, v88, v92
	v_fma_f32 v29, -v7, v24, v29
	v_fma_f32 v93, -v7, v88, v93
	s_nop 0
	v_add_u32_e32 v14, s51, v58
	v_fma_f32 v30, -v8, v24, v30
	v_fma_f32 v94, -v8, v88, v94
	v_fma_f32 v31, -v9, v24, v31
	v_fma_f32 v95, -v9, v88, v95
	v_fma_f32 v32, -v10, v24, v32
	v_fma_f32 v98, -v10, v88, v98
	v_fma_f32 v33, -v11, v24, v33
	v_fma_f32 v97, -v11, v88, v97
	v_fma_f32 v34, -v12, v24, v34
	v_fma_f32 v100, -v12, v88, v100
	v_fma_f32 v35, -v13, v24, v35
	v_fma_f32 v99, -v13, v88, v99
	v_fma_f32 v37, -v15, v24, v37
	v_fma_f32 v103, -v15, v88, v103
	v_fma_f32 v38, -v16, v24, v38
	v_fma_f32 v107, -v16, v88, v107
	ds_read_b128 v[2:5], v14 offset:8256
	v_fma_f32 v106, -v17, v88, v106
	ds_read_b128 v[6:9], v14 offset:8272
	ds_read_b128 v[10:13], v14 offset:8288
	ds_read_b128 v[14:17], v14 offset:8304
	v_mov_b32_e32 v58, 0x80
	s_waitcnt lgkmcnt(0)
	v_fma_f32 v52, -v14, v24, v52
	v_fma_f32 v78, -v14, v88, v78
	v_fma_f32 v40, -v2, v24, v40
	v_fma_f32 v111, -v2, v88, v111
	v_fma_f32 v41, -v3, v24, v41
	v_fma_f32 v110, -v3, v88, v110
	v_fma_f32 v42, -v4, v24, v42
	s_nop 0
	v_add_u32_e32 v14, s51, v58
	v_fma_f32 v113, -v4, v88, v113
	v_fma_f32 v43, -v5, v24, v43
	v_fma_f32 v112, -v5, v88, v112
	v_fma_f32 v46, -v6, v24, v46
	v_fma_f32 v121, -v6, v88, v121
	v_fma_f32 v47, -v7, v24, v47
	v_fma_f32 v120, -v7, v88, v120
	v_fma_f32 v48, -v8, v24, v48
	v_fma_f32 v123, -v8, v88, v123
	v_fma_f32 v49, -v9, v24, v49
	v_fma_f32 v122, -v9, v88, v122
	v_fma_f32 v44, -v10, v24, v44
	v_fma_f32 v74, -v10, v88, v74
	v_fma_f32 v45, -v11, v24, v45
	v_fma_f32 v75, -v11, v88, v75
	v_fma_f32 v50, -v12, v24, v50
	v_fma_f32 v76, -v12, v88, v76
	v_fma_f32 v51, -v13, v24, v51
	v_fma_f32 v77, -v13, v88, v77
	v_fma_f32 v53, -v15, v24, v53
	v_fma_f32 v79, -v15, v88, v79
	v_fma_f32 v54, -v16, v24, v54
	v_fma_f32 v105, -v16, v88, v105
	v_fma_f32 v55, -v17, v24, v55
	ds_read_b128 v[2:5], v14 offset:8192
	v_fma_f32 v114, -v17, v88, v114
	ds_read_b128 v[6:9], v14 offset:8208
	ds_read_b128 v[10:13], v14 offset:8224
	ds_read_b128 v[14:17], v14 offset:8240
	s_waitcnt lgkmcnt(0)
	v_fma_f32 v36, -v14, v25, v36
	v_fma_f32 v104, -v14, v90, v104
	v_fma_f32 v39, -v17, v25, v39
	v_fma_f32 v26, -v4, v25, v26
	v_fma_f32 v89, -v4, v90, v89
	v_fma_f32 v27, -v5, v25, v27
	v_fma_f32 v91, -v5, v90, v91
	v_fma_f32 v28, -v6, v25, v28
	s_nop 0
	v_fma_f32 v92, -v6, v90, v92
	v_fma_f32 v29, -v7, v25, v29
	v_fma_f32 v93, -v7, v90, v93
	v_fma_f32 v30, -v8, v25, v30
	v_fma_f32 v94, -v8, v90, v94
	s_nop 0
	v_add_u32_e32 v14, s51, v58
	v_fma_f32 v31, -v9, v25, v31
	v_fma_f32 v95, -v9, v90, v95
	v_fma_f32 v32, -v10, v25, v32
	v_fma_f32 v98, -v10, v90, v98
	v_fma_f32 v33, -v11, v25, v33
	v_fma_f32 v97, -v11, v90, v97
	v_fma_f32 v34, -v12, v25, v34
	v_fma_f32 v100, -v12, v90, v100
	v_fma_f32 v35, -v13, v25, v35
	v_fma_f32 v99, -v13, v90, v99
	v_fma_f32 v37, -v15, v25, v37
	v_fma_f32 v103, -v15, v90, v103
	v_fma_f32 v38, -v16, v25, v38
	v_fma_f32 v107, -v16, v90, v107
	ds_read_b128 v[2:5], v14 offset:8256
	v_fma_f32 v106, -v17, v90, v106
	ds_read_b128 v[6:9], v14 offset:8272
	ds_read_b128 v[10:13], v14 offset:8288
	ds_read_b128 v[14:17], v14 offset:8304
	v_mov_b32_e32 v58, 0x100
	s_waitcnt lgkmcnt(0)
	v_fma_f32 v52, -v14, v25, v52
	v_fma_f32 v78, -v14, v90, v78
	v_fma_f32 v40, -v2, v25, v40
	v_fma_f32 v111, -v2, v90, v111
	v_fma_f32 v41, -v3, v25, v41
	v_fma_f32 v110, -v3, v90, v110
	v_fma_f32 v42, -v4, v25, v42
	s_nop 0
	v_add_u32_e32 v14, s51, v58
	v_fma_f32 v113, -v4, v90, v113
	v_fma_f32 v43, -v5, v25, v43
	v_fma_f32 v112, -v5, v90, v112
	v_fma_f32 v46, -v6, v25, v46
	v_fma_f32 v121, -v6, v90, v121
	v_fma_f32 v47, -v7, v25, v47
	v_fma_f32 v120, -v7, v90, v120
	v_fma_f32 v48, -v8, v25, v48
	v_fma_f32 v123, -v8, v90, v123
	v_fma_f32 v49, -v9, v25, v49
	v_fma_f32 v122, -v9, v90, v122
	v_fma_f32 v44, -v10, v25, v44
	v_fma_f32 v74, -v10, v90, v74
	v_fma_f32 v45, -v11, v25, v45
	v_fma_f32 v75, -v11, v90, v75
	v_fma_f32 v50, -v12, v25, v50
	v_fma_f32 v76, -v12, v90, v76
	v_fma_f32 v51, -v13, v25, v51
	v_fma_f32 v77, -v13, v90, v77
	v_fma_f32 v53, -v15, v25, v53
	v_fma_f32 v79, -v15, v90, v79
	v_fma_f32 v54, -v16, v25, v54
	v_fma_f32 v105, -v16, v90, v105
	v_fma_f32 v55, -v17, v25, v55
	ds_read_b128 v[2:5], v14 offset:8192
	v_fma_f32 v114, -v17, v90, v114
	ds_read_b128 v[6:9], v14 offset:8208
	ds_read_b128 v[10:13], v14 offset:8224
	ds_read_b128 v[14:17], v14 offset:8240
	s_waitcnt lgkmcnt(0)
	v_fma_f32 v36, -v14, v26, v36
	v_fma_f32 v104, -v14, v89, v104
	v_fma_f32 v39, -v17, v26, v39
	v_fma_f32 v27, -v5, v26, v27
	v_fma_f32 v91, -v5, v89, v91
	v_fma_f32 v28, -v6, v26, v28
	v_fma_f32 v92, -v6, v89, v92
	v_fma_f32 v29, -v7, v26, v29
	s_nop 0
	v_fma_f32 v93, -v7, v89, v93
	v_fma_f32 v30, -v8, v26, v30
	v_fma_f32 v94, -v8, v89, v94
	v_fma_f32 v31, -v9, v26, v31
	v_fma_f32 v95, -v9, v89, v95
	s_nop 0
	v_add_u32_e32 v14, s51, v58
	v_fma_f32 v32, -v10, v26, v32
	v_fma_f32 v98, -v10, v89, v98
	v_fma_f32 v33, -v11, v26, v33
	v_fma_f32 v97, -v11, v89, v97
	v_fma_f32 v34, -v12, v26, v34
	v_fma_f32 v100, -v12, v89, v100
	v_fma_f32 v35, -v13, v26, v35
	v_fma_f32 v99, -v13, v89, v99
	v_fma_f32 v37, -v15, v26, v37
	v_fma_f32 v103, -v15, v89, v103
	v_fma_f32 v38, -v16, v26, v38
	v_fma_f32 v107, -v16, v89, v107
	ds_read_b128 v[2:5], v14 offset:8256
	v_fma_f32 v106, -v17, v89, v106
	ds_read_b128 v[6:9], v14 offset:8272
	ds_read_b128 v[10:13], v14 offset:8288
	ds_read_b128 v[14:17], v14 offset:8304
	v_mov_b32_e32 v58, 0x180
	s_waitcnt lgkmcnt(0)
	v_fma_f32 v52, -v14, v26, v52
	v_fma_f32 v78, -v14, v89, v78
	v_fma_f32 v40, -v2, v26, v40
	v_fma_f32 v111, -v2, v89, v111
	v_fma_f32 v41, -v3, v26, v41
	v_fma_f32 v110, -v3, v89, v110
	v_fma_f32 v42, -v4, v26, v42
	s_nop 0
	v_add_u32_e32 v14, s51, v58
	v_fma_f32 v113, -v4, v89, v113
	v_fma_f32 v43, -v5, v26, v43
	v_fma_f32 v112, -v5, v89, v112
	v_fma_f32 v46, -v6, v26, v46
	v_fma_f32 v121, -v6, v89, v121
	v_fma_f32 v47, -v7, v26, v47
	v_fma_f32 v120, -v7, v89, v120
	v_fma_f32 v48, -v8, v26, v48
	v_fma_f32 v123, -v8, v89, v123
	v_fma_f32 v49, -v9, v26, v49
	v_fma_f32 v122, -v9, v89, v122
	v_fma_f32 v44, -v10, v26, v44
	v_fma_f32 v74, -v10, v89, v74
	v_fma_f32 v45, -v11, v26, v45
	v_fma_f32 v75, -v11, v89, v75
	v_fma_f32 v50, -v12, v26, v50
	v_fma_f32 v76, -v12, v89, v76
	v_fma_f32 v51, -v13, v26, v51
	v_fma_f32 v77, -v13, v89, v77
	v_fma_f32 v53, -v15, v26, v53
	v_fma_f32 v79, -v15, v89, v79
	v_fma_f32 v54, -v16, v26, v54
	v_fma_f32 v105, -v16, v89, v105
	v_fma_f32 v55, -v17, v26, v55
	ds_read_b128 v[2:5], v14 offset:8208
	v_fma_f32 v114, -v17, v89, v114
	ds_read_b128 v[6:9], v14 offset:8224
	ds_read_b128 v[10:13], v14 offset:8240
	ds_read_b128 v[14:17], v14 offset:8256
	s_waitcnt lgkmcnt(0)
	v_fma_f32 v36, -v10, v27, v36
	v_fma_f32 v104, -v10, v91, v104
	v_fma_f32 v43, -v17, v27, v43
	v_fma_f32 v28, -v2, v27, v28
	v_fma_f32 v92, -v2, v91, v92
	v_fma_f32 v29, -v3, v27, v29
	v_fma_f32 v93, -v3, v91, v93
	v_fma_f32 v30, -v4, v27, v30
	s_nop 0
	v_fma_f32 v94, -v4, v91, v94
	v_fma_f32 v31, -v5, v27, v31
	v_fma_f32 v95, -v5, v91, v95
	v_fma_f32 v32, -v6, v27, v32
	v_fma_f32 v98, -v6, v91, v98
	s_nop 0
	v_add_u32_e32 v10, s51, v58
	v_fma_f32 v33, -v7, v27, v33
	v_fma_f32 v97, -v7, v91, v97
	v_fma_f32 v34, -v8, v27, v34
	v_fma_f32 v100, -v8, v91, v100
	v_fma_f32 v35, -v9, v27, v35
	v_fma_f32 v99, -v9, v91, v99
	v_fma_f32 v37, -v11, v27, v37
	v_fma_f32 v103, -v11, v91, v103
	v_fma_f32 v38, -v12, v27, v38
	v_fma_f32 v107, -v12, v91, v107
	v_fma_f32 v39, -v13, v27, v39
	v_fma_f32 v106, -v13, v91, v106
	ds_read_b128 v[2:5], v10 offset:8272
	ds_read_b128 v[6:9], v10 offset:8288
	ds_read_b128 v[10:13], v10 offset:8304
	v_mov_b32_e32 v58, 0x200
	v_fma_f32 v40, -v14, v27, v40
	v_fma_f32 v111, -v14, v91, v111
	v_fma_f32 v41, -v15, v27, v41
	v_fma_f32 v110, -v15, v91, v110
	v_fma_f32 v42, -v16, v27, v42
	v_fma_f32 v113, -v16, v91, v113
	v_fma_f32 v112, -v17, v91, v112
	s_nop 0
	v_add_u32_e32 v14, s51, v58
	s_waitcnt lgkmcnt(0)
	v_fma_f32 v46, -v2, v27, v46
	v_fma_f32 v121, -v2, v91, v121
	v_fma_f32 v47, -v3, v27, v47
	v_fma_f32 v120, -v3, v91, v120
	v_fma_f32 v48, -v4, v27, v48
	v_fma_f32 v123, -v4, v91, v123
	v_fma_f32 v49, -v5, v27, v49
	v_fma_f32 v122, -v5, v91, v122
	v_fma_f32 v44, -v6, v27, v44
	v_fma_f32 v74, -v6, v91, v74
	v_fma_f32 v45, -v7, v27, v45
	v_fma_f32 v75, -v7, v91, v75
	v_fma_f32 v50, -v8, v27, v50
	v_fma_f32 v76, -v8, v91, v76
	v_fma_f32 v51, -v9, v27, v51
	v_fma_f32 v77, -v9, v91, v77
	v_fma_f32 v52, -v10, v27, v52
	v_fma_f32 v78, -v10, v91, v78
	v_fma_f32 v53, -v11, v27, v53
	v_fma_f32 v79, -v11, v91, v79
	v_fma_f32 v54, -v12, v27, v54
	v_fma_f32 v105, -v12, v91, v105
	v_fma_f32 v55, -v13, v27, v55
	ds_read_b128 v[2:5], v14 offset:8208
	v_fma_f32 v114, -v13, v91, v114
	ds_read_b128 v[6:9], v14 offset:8224
	ds_read_b128 v[10:13], v14 offset:8240
	ds_read_b128 v[14:17], v14 offset:8256
	s_waitcnt lgkmcnt(0)
	v_fma_f32 v36, -v10, v28, v36
	v_fma_f32 v104, -v10, v92, v104
	v_fma_f32 v43, -v17, v28, v43
	v_fma_f32 v29, -v3, v28, v29
	v_fma_f32 v93, -v3, v92, v93
	v_fma_f32 v30, -v4, v28, v30
	v_fma_f32 v94, -v4, v92, v94
	v_fma_f32 v31, -v5, v28, v31
	s_nop 0
	v_fma_f32 v95, -v5, v92, v95
	v_fma_f32 v32, -v6, v28, v32
	v_fma_f32 v98, -v6, v92, v98
	v_fma_f32 v33, -v7, v28, v33
	v_fma_f32 v97, -v7, v92, v97
	s_nop 0
	v_add_u32_e32 v10, s51, v58
	v_fma_f32 v34, -v8, v28, v34
	v_fma_f32 v100, -v8, v92, v100
	v_fma_f32 v35, -v9, v28, v35
	v_fma_f32 v99, -v9, v92, v99
	v_fma_f32 v37, -v11, v28, v37
	v_fma_f32 v103, -v11, v92, v103
	v_fma_f32 v38, -v12, v28, v38
	v_fma_f32 v107, -v12, v92, v107
	v_fma_f32 v39, -v13, v28, v39
	v_fma_f32 v106, -v13, v92, v106
	ds_read_b128 v[2:5], v10 offset:8272
	ds_read_b128 v[6:9], v10 offset:8288
	ds_read_b128 v[10:13], v10 offset:8304
	v_mov_b32_e32 v58, 0x280
	v_fma_f32 v40, -v14, v28, v40
	v_fma_f32 v111, -v14, v92, v111
	v_fma_f32 v41, -v15, v28, v41
	v_fma_f32 v110, -v15, v92, v110
	v_fma_f32 v42, -v16, v28, v42
	v_fma_f32 v113, -v16, v92, v113
	v_fma_f32 v112, -v17, v92, v112
	s_nop 0
	v_add_u32_e32 v14, s51, v58
	s_waitcnt lgkmcnt(0)
	v_fma_f32 v46, -v2, v28, v46
	v_fma_f32 v121, -v2, v92, v121
	v_fma_f32 v47, -v3, v28, v47
	v_fma_f32 v120, -v3, v92, v120
	v_fma_f32 v48, -v4, v28, v48
	v_fma_f32 v123, -v4, v92, v123
	v_fma_f32 v49, -v5, v28, v49
	v_fma_f32 v122, -v5, v92, v122
	v_fma_f32 v44, -v6, v28, v44
	v_fma_f32 v74, -v6, v92, v74
	v_fma_f32 v45, -v7, v28, v45
	v_fma_f32 v75, -v7, v92, v75
	v_fma_f32 v50, -v8, v28, v50
	v_fma_f32 v76, -v8, v92, v76
	v_fma_f32 v51, -v9, v28, v51
	v_fma_f32 v77, -v9, v92, v77
	v_fma_f32 v52, -v10, v28, v52
	v_fma_f32 v78, -v10, v92, v78
	v_fma_f32 v53, -v11, v28, v53
	v_fma_f32 v79, -v11, v92, v79
	v_fma_f32 v54, -v12, v28, v54
	v_fma_f32 v105, -v12, v92, v105
	v_fma_f32 v55, -v13, v28, v55
	ds_read_b128 v[2:5], v14 offset:8208
	v_fma_f32 v114, -v13, v92, v114
	ds_read_b128 v[6:9], v14 offset:8224
	ds_read_b128 v[10:13], v14 offset:8240
	ds_read_b128 v[14:17], v14 offset:8256
	s_waitcnt lgkmcnt(0)
	v_fma_f32 v36, -v10, v29, v36
	v_fma_f32 v104, -v10, v93, v104
	v_fma_f32 v43, -v17, v29, v43
	v_fma_f32 v30, -v4, v29, v30
	v_fma_f32 v94, -v4, v93, v94
	v_fma_f32 v31, -v5, v29, v31
	v_fma_f32 v95, -v5, v93, v95
	v_fma_f32 v32, -v6, v29, v32
	s_nop 0
	v_fma_f32 v98, -v6, v93, v98
	v_fma_f32 v33, -v7, v29, v33
	v_fma_f32 v97, -v7, v93, v97
	v_fma_f32 v34, -v8, v29, v34
	v_fma_f32 v100, -v8, v93, v100
	s_nop 0
	v_add_u32_e32 v10, s51, v58
	v_fma_f32 v35, -v9, v29, v35
	v_fma_f32 v99, -v9, v93, v99
	v_fma_f32 v37, -v11, v29, v37
	v_fma_f32 v103, -v11, v93, v103
	v_fma_f32 v38, -v12, v29, v38
	v_fma_f32 v107, -v12, v93, v107
	v_fma_f32 v39, -v13, v29, v39
	v_fma_f32 v106, -v13, v93, v106
	ds_read_b128 v[2:5], v10 offset:8272
	ds_read_b128 v[6:9], v10 offset:8288
	ds_read_b128 v[10:13], v10 offset:8304
	v_mov_b32_e32 v58, 0x300
	v_fma_f32 v40, -v14, v29, v40
	v_fma_f32 v111, -v14, v93, v111
	v_fma_f32 v41, -v15, v29, v41
	v_fma_f32 v110, -v15, v93, v110
	v_fma_f32 v42, -v16, v29, v42
	v_fma_f32 v113, -v16, v93, v113
	v_fma_f32 v112, -v17, v93, v112
	s_nop 0
	v_add_u32_e32 v14, s51, v58
	s_waitcnt lgkmcnt(0)
	v_fma_f32 v46, -v2, v29, v46
	v_fma_f32 v121, -v2, v93, v121
	v_fma_f32 v47, -v3, v29, v47
	v_fma_f32 v120, -v3, v93, v120
	v_fma_f32 v48, -v4, v29, v48
	v_fma_f32 v123, -v4, v93, v123
	v_fma_f32 v49, -v5, v29, v49
	v_fma_f32 v122, -v5, v93, v122
	v_fma_f32 v44, -v6, v29, v44
	v_fma_f32 v74, -v6, v93, v74
	v_fma_f32 v45, -v7, v29, v45
	v_fma_f32 v75, -v7, v93, v75
	v_fma_f32 v50, -v8, v29, v50
	v_fma_f32 v76, -v8, v93, v76
	v_fma_f32 v51, -v9, v29, v51
	v_fma_f32 v77, -v9, v93, v77
	v_fma_f32 v52, -v10, v29, v52
	v_fma_f32 v78, -v10, v93, v78
	v_fma_f32 v53, -v11, v29, v53
	v_fma_f32 v79, -v11, v93, v79
	v_fma_f32 v54, -v12, v29, v54
	v_fma_f32 v105, -v12, v93, v105
	v_fma_f32 v55, -v13, v29, v55
	ds_read_b128 v[2:5], v14 offset:8208
	v_fma_f32 v114, -v13, v93, v114
	ds_read_b128 v[6:9], v14 offset:8224
	ds_read_b128 v[10:13], v14 offset:8240
	ds_read_b128 v[14:17], v14 offset:8256
	s_waitcnt lgkmcnt(0)
	v_fma_f32 v36, -v10, v30, v36
	v_fma_f32 v104, -v10, v94, v104
	v_fma_f32 v43, -v17, v30, v43
	v_fma_f32 v31, -v5, v30, v31
	v_fma_f32 v95, -v5, v94, v95
	v_fma_f32 v32, -v6, v30, v32
	v_fma_f32 v98, -v6, v94, v98
	v_fma_f32 v33, -v7, v30, v33
	s_nop 0
	v_fma_f32 v97, -v7, v94, v97
	v_fma_f32 v34, -v8, v30, v34
	v_fma_f32 v100, -v8, v94, v100
	v_fma_f32 v35, -v9, v30, v35
	v_fma_f32 v99, -v9, v94, v99
	s_nop 0
	v_add_u32_e32 v10, s51, v58
	v_fma_f32 v37, -v11, v30, v37
	v_fma_f32 v103, -v11, v94, v103
	v_fma_f32 v38, -v12, v30, v38
	v_fma_f32 v107, -v12, v94, v107
	v_fma_f32 v39, -v13, v30, v39
	v_fma_f32 v106, -v13, v94, v106
	ds_read_b128 v[2:5], v10 offset:8272
	ds_read_b128 v[6:9], v10 offset:8288
	ds_read_b128 v[10:13], v10 offset:8304
	v_mov_b32_e32 v58, 0x380
	v_fma_f32 v40, -v14, v30, v40
	v_fma_f32 v111, -v14, v94, v111
	v_fma_f32 v41, -v15, v30, v41
	v_fma_f32 v110, -v15, v94, v110
	v_fma_f32 v42, -v16, v30, v42
	v_fma_f32 v113, -v16, v94, v113
	v_fma_f32 v112, -v17, v94, v112
	s_nop 0
	v_add_u32_e32 v14, s51, v58
	s_waitcnt lgkmcnt(0)
	v_fma_f32 v46, -v2, v30, v46
	v_fma_f32 v121, -v2, v94, v121
	v_fma_f32 v47, -v3, v30, v47
	v_fma_f32 v120, -v3, v94, v120
	v_fma_f32 v48, -v4, v30, v48
	v_fma_f32 v123, -v4, v94, v123
	v_fma_f32 v49, -v5, v30, v49
	v_fma_f32 v122, -v5, v94, v122
	v_fma_f32 v44, -v6, v30, v44
	v_fma_f32 v74, -v6, v94, v74
	v_fma_f32 v45, -v7, v30, v45
	v_fma_f32 v75, -v7, v94, v75
	v_fma_f32 v50, -v8, v30, v50
	v_fma_f32 v76, -v8, v94, v76
	v_fma_f32 v51, -v9, v30, v51
	v_fma_f32 v77, -v9, v94, v77
	v_fma_f32 v52, -v10, v30, v52
	v_fma_f32 v78, -v10, v94, v78
	v_fma_f32 v53, -v11, v30, v53
	v_fma_f32 v79, -v11, v94, v79
	v_fma_f32 v54, -v12, v30, v54
	v_fma_f32 v105, -v12, v94, v105
	v_fma_f32 v55, -v13, v30, v55
	ds_read_b128 v[2:5], v14 offset:8224
	v_fma_f32 v114, -v13, v94, v114
	ds_read_b128 v[6:9], v14 offset:8240
	ds_read_b128 v[10:13], v14 offset:8256
	ds_read_b128 v[14:17], v14 offset:8272
	s_waitcnt lgkmcnt(0)
	v_fma_f32 v49, -v17, v31, v49
	s_nop 0
	v_fma_f32 v36, -v6, v31, v36
	v_fma_f32 v104, -v6, v95, v104
	v_fma_f32 v32, -v2, v31, v32
	v_fma_f32 v98, -v2, v95, v98
	v_fma_f32 v33, -v3, v31, v33
	s_nop 0
	v_add_u32_e32 v6, s51, v58
	v_mov_b32_e32 v58, 0x400
	v_fma_f32 v97, -v3, v95, v97
	v_fma_f32 v34, -v4, v31, v34
	v_fma_f32 v100, -v4, v95, v100
	v_fma_f32 v35, -v5, v31, v35
	v_fma_f32 v99, -v5, v95, v99
	v_fma_f32 v37, -v7, v31, v37
	v_fma_f32 v103, -v7, v95, v103
	v_fma_f32 v38, -v8, v31, v38
	v_fma_f32 v107, -v8, v95, v107
	v_fma_f32 v39, -v9, v31, v39
	v_fma_f32 v106, -v9, v95, v106
	v_fma_f32 v46, -v14, v31, v46
	v_fma_f32 v121, -v14, v95, v121
	ds_read_b128 v[2:5], v6 offset:8288
	ds_read_b128 v[6:9], v6 offset:8304
	v_fma_f32 v40, -v10, v31, v40
	v_fma_f32 v111, -v10, v95, v111
	v_fma_f32 v41, -v11, v31, v41
	v_fma_f32 v110, -v11, v95, v110
	v_fma_f32 v42, -v12, v31, v42
	s_nop 0
	v_add_u32_e32 v14, s51, v58
	v_fma_f32 v113, -v12, v95, v113
	v_fma_f32 v43, -v13, v31, v43
	v_fma_f32 v112, -v13, v95, v112
	v_fma_f32 v47, -v15, v31, v47
	v_fma_f32 v120, -v15, v95, v120
	v_fma_f32 v48, -v16, v31, v48
	v_fma_f32 v123, -v16, v95, v123
	v_fma_f32 v122, -v17, v95, v122
	s_waitcnt lgkmcnt(0)
	v_fma_f32 v44, -v2, v31, v44
	v_fma_f32 v74, -v2, v95, v74
	v_fma_f32 v45, -v3, v31, v45
	v_fma_f32 v75, -v3, v95, v75
	v_fma_f32 v50, -v4, v31, v50
	v_fma_f32 v76, -v4, v95, v76
	v_fma_f32 v51, -v5, v31, v51
	v_fma_f32 v77, -v5, v95, v77
	v_fma_f32 v52, -v6, v31, v52
	v_fma_f32 v78, -v6, v95, v78
	v_fma_f32 v53, -v7, v31, v53
	v_fma_f32 v79, -v7, v95, v79
	v_fma_f32 v54, -v8, v31, v54
	v_fma_f32 v105, -v8, v95, v105
	v_fma_f32 v55, -v9, v31, v55
	ds_read_b128 v[2:5], v14 offset:8224
	v_fma_f32 v114, -v9, v95, v114
	ds_read_b128 v[6:9], v14 offset:8240
	ds_read_b128 v[10:13], v14 offset:8256
	ds_read_b128 v[14:17], v14 offset:8272
	s_waitcnt lgkmcnt(0)
	v_fma_f32 v49, -v17, v32, v49
	s_nop 0
	v_fma_f32 v36, -v6, v32, v36
	v_fma_f32 v104, -v6, v98, v104
	v_fma_f32 v33, -v3, v32, v33
	v_fma_f32 v97, -v3, v98, v97
	v_fma_f32 v34, -v4, v32, v34
	s_nop 0
	v_add_u32_e32 v6, s51, v58
	v_mov_b32_e32 v58, 0x480
	v_fma_f32 v100, -v4, v98, v100
	v_fma_f32 v35, -v5, v32, v35
	v_fma_f32 v99, -v5, v98, v99
	v_fma_f32 v37, -v7, v32, v37
	v_fma_f32 v103, -v7, v98, v103
	v_fma_f32 v38, -v8, v32, v38
	v_fma_f32 v107, -v8, v98, v107
	v_fma_f32 v39, -v9, v32, v39
	v_fma_f32 v106, -v9, v98, v106
	v_fma_f32 v46, -v14, v32, v46
	v_fma_f32 v121, -v14, v98, v121
	ds_read_b128 v[2:5], v6 offset:8288
	ds_read_b128 v[6:9], v6 offset:8304
	v_fma_f32 v40, -v10, v32, v40
	v_fma_f32 v111, -v10, v98, v111
	v_fma_f32 v41, -v11, v32, v41
	v_fma_f32 v110, -v11, v98, v110
	v_fma_f32 v42, -v12, v32, v42
	s_nop 0
	v_add_u32_e32 v14, s51, v58
	v_fma_f32 v113, -v12, v98, v113
	v_fma_f32 v43, -v13, v32, v43
	v_fma_f32 v112, -v13, v98, v112
	v_fma_f32 v47, -v15, v32, v47
	v_fma_f32 v120, -v15, v98, v120
	v_fma_f32 v48, -v16, v32, v48
	v_fma_f32 v123, -v16, v98, v123
	v_fma_f32 v122, -v17, v98, v122
	s_waitcnt lgkmcnt(0)
	v_fma_f32 v44, -v2, v32, v44
	v_fma_f32 v74, -v2, v98, v74
	v_fma_f32 v45, -v3, v32, v45
	v_fma_f32 v75, -v3, v98, v75
	v_fma_f32 v50, -v4, v32, v50
	v_fma_f32 v76, -v4, v98, v76
	v_fma_f32 v51, -v5, v32, v51
	v_fma_f32 v77, -v5, v98, v77
	v_fma_f32 v52, -v6, v32, v52
	v_fma_f32 v78, -v6, v98, v78
	v_fma_f32 v53, -v7, v32, v53
	v_fma_f32 v79, -v7, v98, v79
	v_fma_f32 v54, -v8, v32, v54
	v_fma_f32 v105, -v8, v98, v105
	v_fma_f32 v55, -v9, v32, v55
	ds_read_b128 v[2:5], v14 offset:8224
	v_fma_f32 v114, -v9, v98, v114
	ds_read_b128 v[6:9], v14 offset:8240
	ds_read_b128 v[10:13], v14 offset:8256
	ds_read_b128 v[14:17], v14 offset:8272
	s_waitcnt lgkmcnt(0)
	v_fma_f32 v49, -v17, v33, v49
	s_nop 0
	v_fma_f32 v36, -v6, v33, v36
	v_fma_f32 v104, -v6, v97, v104
	v_fma_f32 v34, -v4, v33, v34
	v_fma_f32 v100, -v4, v97, v100
	v_fma_f32 v35, -v5, v33, v35
	s_nop 0
	v_add_u32_e32 v6, s51, v58
	v_mov_b32_e32 v58, 0x500
	v_fma_f32 v99, -v5, v97, v99
	v_fma_f32 v37, -v7, v33, v37
	v_fma_f32 v103, -v7, v97, v103
	v_fma_f32 v38, -v8, v33, v38
	v_fma_f32 v107, -v8, v97, v107
	v_fma_f32 v39, -v9, v33, v39
	v_fma_f32 v106, -v9, v97, v106
	v_fma_f32 v46, -v14, v33, v46
	v_fma_f32 v121, -v14, v97, v121
	ds_read_b128 v[2:5], v6 offset:8288
	ds_read_b128 v[6:9], v6 offset:8304
	v_fma_f32 v40, -v10, v33, v40
	v_fma_f32 v111, -v10, v97, v111
	v_fma_f32 v41, -v11, v33, v41
	v_fma_f32 v110, -v11, v97, v110
	v_fma_f32 v42, -v12, v33, v42
	s_nop 0
	v_add_u32_e32 v14, s51, v58
	v_fma_f32 v113, -v12, v97, v113
	v_fma_f32 v43, -v13, v33, v43
	v_fma_f32 v112, -v13, v97, v112
	v_fma_f32 v47, -v15, v33, v47
	v_fma_f32 v120, -v15, v97, v120
	v_fma_f32 v48, -v16, v33, v48
	v_fma_f32 v123, -v16, v97, v123
	v_fma_f32 v122, -v17, v97, v122
	s_waitcnt lgkmcnt(0)
	v_fma_f32 v44, -v2, v33, v44
	v_fma_f32 v74, -v2, v97, v74
	v_fma_f32 v45, -v3, v33, v45
	v_fma_f32 v75, -v3, v97, v75
	v_fma_f32 v50, -v4, v33, v50
	v_fma_f32 v76, -v4, v97, v76
	v_fma_f32 v51, -v5, v33, v51
	v_fma_f32 v77, -v5, v97, v77
	v_fma_f32 v52, -v6, v33, v52
	v_fma_f32 v78, -v6, v97, v78
	v_fma_f32 v53, -v7, v33, v53
	v_fma_f32 v79, -v7, v97, v79
	v_fma_f32 v54, -v8, v33, v54
	v_fma_f32 v105, -v8, v97, v105
	v_fma_f32 v55, -v9, v33, v55
	ds_read_b128 v[2:5], v14 offset:8224
	v_fma_f32 v114, -v9, v97, v114
	ds_read_b128 v[6:9], v14 offset:8240
	ds_read_b128 v[10:13], v14 offset:8256
	ds_read_b128 v[14:17], v14 offset:8272
	s_waitcnt lgkmcnt(0)
	v_fma_f32 v49, -v17, v34, v49
	s_nop 0
	v_fma_f32 v36, -v6, v34, v36
	v_fma_f32 v104, -v6, v100, v104
	v_fma_f32 v35, -v5, v34, v35
	v_fma_f32 v99, -v5, v100, v99
	v_fma_f32 v37, -v7, v34, v37
	s_nop 0
	v_add_u32_e32 v6, s51, v58
	v_mov_b32_e32 v58, 0x580
	v_fma_f32 v103, -v7, v100, v103
	v_fma_f32 v38, -v8, v34, v38
	v_fma_f32 v107, -v8, v100, v107
	v_fma_f32 v39, -v9, v34, v39
	v_fma_f32 v106, -v9, v100, v106
	v_fma_f32 v46, -v14, v34, v46
	v_fma_f32 v121, -v14, v100, v121
	ds_read_b128 v[2:5], v6 offset:8288
	ds_read_b128 v[6:9], v6 offset:8304
	v_fma_f32 v40, -v10, v34, v40
	v_fma_f32 v111, -v10, v100, v111
	v_fma_f32 v41, -v11, v34, v41
	v_fma_f32 v110, -v11, v100, v110
	v_fma_f32 v42, -v12, v34, v42
	s_nop 0
	v_add_u32_e32 v14, s51, v58
	v_fma_f32 v113, -v12, v100, v113
	v_fma_f32 v43, -v13, v34, v43
	v_fma_f32 v112, -v13, v100, v112
	v_fma_f32 v47, -v15, v34, v47
	v_fma_f32 v120, -v15, v100, v120
	v_fma_f32 v48, -v16, v34, v48
	v_fma_f32 v123, -v16, v100, v123
	v_fma_f32 v122, -v17, v100, v122
	s_waitcnt lgkmcnt(0)
	v_fma_f32 v44, -v2, v34, v44
	v_fma_f32 v74, -v2, v100, v74
	v_fma_f32 v45, -v3, v34, v45
	v_fma_f32 v75, -v3, v100, v75
	v_fma_f32 v50, -v4, v34, v50
	v_fma_f32 v76, -v4, v100, v76
	v_fma_f32 v51, -v5, v34, v51
	v_fma_f32 v77, -v5, v100, v77
	v_fma_f32 v52, -v6, v34, v52
	v_fma_f32 v78, -v6, v100, v78
	v_fma_f32 v53, -v7, v34, v53
	v_fma_f32 v79, -v7, v100, v79
	v_fma_f32 v54, -v8, v34, v54
	v_fma_f32 v105, -v8, v100, v105
	v_fma_f32 v55, -v9, v34, v55
	ds_read_b128 v[2:5], v14 offset:8240
	v_fma_f32 v114, -v9, v100, v114
	ds_read_b128 v[6:9], v14 offset:8256
	ds_read_b128 v[10:13], v14 offset:8272
	ds_read_b128 v[14:17], v14 offset:8288
	s_waitcnt lgkmcnt(0)
	v_fma_f32 v51, -v17, v35, v51
	s_nop 0
	v_fma_f32 v36, -v2, v35, v36
	v_fma_f32 v104, -v2, v99, v104
	v_fma_f32 v37, -v3, v35, v37
	v_fma_f32 v103, -v3, v99, v103
	v_fma_f32 v38, -v4, v35, v38
	s_nop 0
	v_add_u32_e32 v2, s51, v58
	v_mov_b32_e32 v58, 0x600
	v_fma_f32 v107, -v4, v99, v107
	v_fma_f32 v39, -v5, v35, v39
	v_fma_f32 v106, -v5, v99, v106
	v_fma_f32 v44, -v14, v35, v44
	v_fma_f32 v74, -v14, v99, v74
	ds_read_b128 v[2:5], v2 offset:8304
	v_fma_f32 v40, -v6, v35, v40
	v_fma_f32 v111, -v6, v99, v111
	v_fma_f32 v41, -v7, v35, v41
	v_fma_f32 v110, -v7, v99, v110
	v_fma_f32 v42, -v8, v35, v42
	s_nop 0
	v_add_u32_e32 v14, s51, v58
	v_fma_f32 v113, -v8, v99, v113
	v_fma_f32 v43, -v9, v35, v43
	v_fma_f32 v112, -v9, v99, v112
	v_fma_f32 v46, -v10, v35, v46
	v_fma_f32 v121, -v10, v99, v121
	v_fma_f32 v47, -v11, v35, v47
	v_fma_f32 v120, -v11, v99, v120
	v_fma_f32 v48, -v12, v35, v48
	v_fma_f32 v123, -v12, v99, v123
	v_fma_f32 v49, -v13, v35, v49
	v_fma_f32 v122, -v13, v99, v122
	v_fma_f32 v45, -v15, v35, v45
	v_fma_f32 v75, -v15, v99, v75
	v_fma_f32 v50, -v16, v35, v50
	v_fma_f32 v76, -v16, v99, v76
	v_fma_f32 v77, -v17, v99, v77
	s_waitcnt lgkmcnt(0)
	v_fma_f32 v52, -v2, v35, v52
	v_fma_f32 v78, -v2, v99, v78
	v_fma_f32 v53, -v3, v35, v53
	v_fma_f32 v79, -v3, v99, v79
	v_fma_f32 v54, -v4, v35, v54
	v_fma_f32 v105, -v4, v99, v105
	v_fma_f32 v55, -v5, v35, v55
	ds_read_b128 v[6:9], v14 offset:8240
	v_fma_f32 v114, -v5, v99, v114
	ds_read_b128 v[2:5], v14 offset:8256
	ds_read_b128 v[10:13], v14 offset:8272
	ds_read_b128 v[14:17], v14 offset:8288
	s_waitcnt lgkmcnt(0)
	v_fma_f32 v51, -v17, v36, v51
	s_nop 0
	v_fma_f32 v40, -v2, v36, v40
	v_fma_f32 v111, -v2, v104, v111
	v_fma_f32 v37, -v7, v36, v37
	v_fma_f32 v103, -v7, v104, v103
	v_fma_f32 v41, -v3, v36, v41
	s_nop 0
	v_add_u32_e32 v2, s51, v58
	v_mov_b32_e32 v58, 0x680
	v_fma_f32 v110, -v3, v104, v110
	v_fma_f32 v42, -v4, v36, v42
	v_fma_f32 v113, -v4, v104, v113
	v_fma_f32 v43, -v5, v36, v43
	v_fma_f32 v112, -v5, v104, v112
	v_fma_f32 v44, -v14, v36, v44
	v_fma_f32 v74, -v14, v104, v74
	ds_read_b128 v[2:5], v2 offset:8304
	v_fma_f32 v38, -v8, v36, v38
	v_fma_f32 v107, -v8, v104, v107
	v_fma_f32 v39, -v9, v36, v39
	v_fma_f32 v106, -v9, v104, v106
	v_fma_f32 v46, -v10, v36, v46
	s_nop 0
	v_add_u32_e32 v14, s51, v58
	v_fma_f32 v121, -v10, v104, v121
	v_fma_f32 v47, -v11, v36, v47
	v_fma_f32 v120, -v11, v104, v120
	v_fma_f32 v48, -v12, v36, v48
	v_fma_f32 v123, -v12, v104, v123
	v_fma_f32 v49, -v13, v36, v49
	v_fma_f32 v122, -v13, v104, v122
	v_fma_f32 v45, -v15, v36, v45
	v_fma_f32 v75, -v15, v104, v75
	v_fma_f32 v50, -v16, v36, v50
	v_fma_f32 v76, -v16, v104, v76
	v_fma_f32 v77, -v17, v104, v77
	s_waitcnt lgkmcnt(0)
	v_fma_f32 v52, -v2, v36, v52
	v_fma_f32 v78, -v2, v104, v78
	v_fma_f32 v53, -v3, v36, v53
	v_fma_f32 v79, -v3, v104, v79
	v_fma_f32 v54, -v4, v36, v54
	v_fma_f32 v105, -v4, v104, v105
	v_fma_f32 v55, -v5, v36, v55
	ds_read_b128 v[6:9], v14 offset:8240
	v_fma_f32 v114, -v5, v104, v114
	ds_read_b128 v[2:5], v14 offset:8256
	ds_read_b128 v[10:13], v14 offset:8272
	ds_read_b128 v[14:17], v14 offset:8288
	s_waitcnt lgkmcnt(0)
	v_fma_f32 v51, -v17, v37, v51
	s_nop 0
	v_fma_f32 v40, -v2, v37, v40
	v_fma_f32 v111, -v2, v103, v111
	v_fma_f32 v38, -v8, v37, v38
	v_fma_f32 v107, -v8, v103, v107
	v_fma_f32 v41, -v3, v37, v41
	s_nop 0
	v_add_u32_e32 v2, s51, v58
	v_mov_b32_e32 v58, 0x700
	v_fma_f32 v110, -v3, v103, v110
	v_fma_f32 v42, -v4, v37, v42
	v_fma_f32 v113, -v4, v103, v113
	v_fma_f32 v43, -v5, v37, v43
	v_fma_f32 v112, -v5, v103, v112
	v_fma_f32 v44, -v14, v37, v44
	v_fma_f32 v74, -v14, v103, v74
	ds_read_b128 v[2:5], v2 offset:8304
	v_fma_f32 v39, -v9, v37, v39
	v_fma_f32 v106, -v9, v103, v106
	v_fma_f32 v46, -v10, v37, v46
	v_fma_f32 v121, -v10, v103, v121
	v_fma_f32 v47, -v11, v37, v47
	s_nop 0
	v_add_u32_e32 v14, s51, v58
	v_fma_f32 v120, -v11, v103, v120
	v_fma_f32 v48, -v12, v37, v48
	v_fma_f32 v123, -v12, v103, v123
	v_fma_f32 v49, -v13, v37, v49
	v_fma_f32 v122, -v13, v103, v122
	v_fma_f32 v45, -v15, v37, v45
	v_fma_f32 v75, -v15, v103, v75
	v_fma_f32 v50, -v16, v37, v50
	v_fma_f32 v76, -v16, v103, v76
	v_fma_f32 v77, -v17, v103, v77
	s_waitcnt lgkmcnt(0)
	v_fma_f32 v52, -v2, v37, v52
	v_fma_f32 v78, -v2, v103, v78
	v_fma_f32 v53, -v3, v37, v53
	v_fma_f32 v79, -v3, v103, v79
	v_fma_f32 v54, -v4, v37, v54
	v_fma_f32 v105, -v4, v103, v105
	v_fma_f32 v55, -v5, v37, v55
	ds_read_b128 v[6:9], v14 offset:8240
	v_fma_f32 v114, -v5, v103, v114
	ds_read_b128 v[2:5], v14 offset:8256
	ds_read_b128 v[10:13], v14 offset:8272
	ds_read_b128 v[14:17], v14 offset:8288
	s_waitcnt lgkmcnt(0)
	v_fma_f32 v40, -v2, v38, v40
	v_fma_f32 v111, -v2, v107, v111
	v_fma_f32 v51, -v17, v38, v51
	v_fma_f32 v41, -v3, v38, v41
	v_fma_f32 v110, -v3, v107, v110
	v_fma_f32 v42, -v4, v38, v42
	v_fma_f32 v113, -v4, v107, v113
	v_fma_f32 v43, -v5, v38, v43
	s_nop 0
	v_fma_f32 v112, -v5, v107, v112
	v_fma_f32 v39, -v9, v38, v39
	v_fma_f32 v106, -v9, v107, v106
	v_fma_f32 v44, -v14, v38, v44
	v_fma_f32 v74, -v14, v107, v74
	s_nop 0
	v_add_u32_e32 v2, s51, v58
	ds_read_b128 v[2:5], v2 offset:8304
	s_waitcnt lgkmcnt(0)
	v_fma_f32 v52, -v2, v38, v52
	v_fma_f32 v78, -v2, v107, v78
	v_mov_b32_e32 v2, 0x780
	v_fma_f32 v46, -v10, v38, v46
	v_fma_f32 v121, -v10, v107, v121
	v_fma_f32 v47, -v11, v38, v47
	v_fma_f32 v120, -v11, v107, v120
	v_fma_f32 v48, -v12, v38, v48
	s_nop 0
	v_add_u32_e32 v14, s51, v2
	v_fma_f32 v123, -v12, v107, v123
	v_fma_f32 v49, -v13, v38, v49
	v_fma_f32 v122, -v13, v107, v122
	v_fma_f32 v45, -v15, v38, v45
	v_fma_f32 v75, -v15, v107, v75
	v_fma_f32 v50, -v16, v38, v50
	v_fma_f32 v76, -v16, v107, v76
	v_fma_f32 v77, -v17, v107, v77
	v_fma_f32 v53, -v3, v38, v53
	v_fma_f32 v79, -v3, v107, v79
	v_fma_f32 v54, -v4, v38, v54
	v_fma_f32 v105, -v4, v107, v105
	v_fma_f32 v55, -v5, v38, v55
	ds_read_b128 v[6:9], v14 offset:8256
	v_fma_f32 v114, -v5, v107, v114
	ds_read_b128 v[2:5], v14 offset:8272
	ds_read_b128 v[10:13], v14 offset:8288
	ds_read_b128 v[14:17], v14 offset:8304
	s_waitcnt lgkmcnt(0)
	v_fma_f32 v46, -v2, v39, v46
	v_fma_f32 v121, -v2, v106, v121
	v_mov_b32_e32 v2, 0x800
	v_fma_f32 v40, -v6, v39, v40
	v_fma_f32 v111, -v6, v106, v111
	v_fma_f32 v52, -v14, v39, v52
	v_fma_f32 v78, -v14, v106, v78
	v_fma_f32 v41, -v7, v39, v41
	v_fma_f32 v110, -v7, v106, v110
	v_fma_f32 v42, -v8, v39, v42
	s_nop 0
	v_fma_f32 v113, -v8, v106, v113
	v_fma_f32 v43, -v9, v39, v43
	v_fma_f32 v112, -v9, v106, v112
	v_fma_f32 v47, -v3, v39, v47
	v_fma_f32 v120, -v3, v106, v120
	s_nop 0
	v_add_u32_e32 v14, s51, v2
	v_fma_f32 v48, -v4, v39, v48
	v_fma_f32 v123, -v4, v106, v123
	v_fma_f32 v49, -v5, v39, v49
	v_fma_f32 v122, -v5, v106, v122
	v_fma_f32 v44, -v10, v39, v44
	v_fma_f32 v74, -v10, v106, v74
	v_fma_f32 v45, -v11, v39, v45
	v_fma_f32 v75, -v11, v106, v75
	v_fma_f32 v50, -v12, v39, v50
	v_fma_f32 v76, -v12, v106, v76
	v_fma_f32 v51, -v13, v39, v51
	v_fma_f32 v77, -v13, v106, v77
	v_fma_f32 v53, -v15, v39, v53
	v_fma_f32 v79, -v15, v106, v79
	v_fma_f32 v54, -v16, v39, v54
	v_fma_f32 v105, -v16, v106, v105
	v_fma_f32 v55, -v17, v39, v55
	ds_read_b128 v[2:5], v14 offset:8256
	v_fma_f32 v114, -v17, v106, v114
	ds_read_b128 v[6:9], v14 offset:8272
	ds_read_b128 v[10:13], v14 offset:8288
	ds_read_b128 v[14:17], v14 offset:8304
	s_waitcnt lgkmcnt(0)
	v_mov_b32_e32 v2, 0x880
	v_fma_f32 v41, -v3, v40, v41
	v_fma_f32 v110, -v3, v111, v110
	v_fma_f32 v52, -v14, v40, v52
	v_fma_f32 v78, -v14, v111, v78
	s_nop 0
	v_fma_f32 v42, -v4, v40, v42
	v_fma_f32 v113, -v4, v111, v113
	v_fma_f32 v43, -v5, v40, v43
	v_fma_f32 v112, -v5, v111, v112
	v_fma_f32 v46, -v6, v40, v46
	s_nop 0
	v_add_u32_e32 v14, s51, v2
	v_fma_f32 v121, -v6, v111, v121
	v_fma_f32 v47, -v7, v40, v47
	v_fma_f32 v120, -v7, v111, v120
	v_fma_f32 v48, -v8, v40, v48
	v_fma_f32 v123, -v8, v111, v123
	v_fma_f32 v49, -v9, v40, v49
	v_fma_f32 v122, -v9, v111, v122
	v_fma_f32 v44, -v10, v40, v44
	v_fma_f32 v74, -v10, v111, v74
	v_fma_f32 v45, -v11, v40, v45
	v_fma_f32 v75, -v11, v111, v75
	v_fma_f32 v50, -v12, v40, v50
	v_fma_f32 v76, -v12, v111, v76
	v_fma_f32 v51, -v13, v40, v51
	v_fma_f32 v77, -v13, v111, v77
	v_fma_f32 v53, -v15, v40, v53
	v_fma_f32 v79, -v15, v111, v79
	v_fma_f32 v54, -v16, v40, v54
	v_fma_f32 v105, -v16, v111, v105
	v_fma_f32 v55, -v17, v40, v55
	ds_read_b128 v[2:5], v14 offset:8256
	v_fma_f32 v114, -v17, v111, v114
	ds_read_b128 v[6:9], v14 offset:8272
	ds_read_b128 v[10:13], v14 offset:8288
	ds_read_b128 v[14:17], v14 offset:8304
	s_waitcnt lgkmcnt(0)
	v_mov_b32_e32 v2, 0x900
	v_fma_f32 v42, -v4, v41, v42
	v_fma_f32 v113, -v4, v110, v113
	v_fma_f32 v52, -v14, v41, v52
	v_fma_f32 v78, -v14, v110, v78
	s_nop 0
	v_fma_f32 v43, -v5, v41, v43
	v_fma_f32 v112, -v5, v110, v112
	v_fma_f32 v46, -v6, v41, v46
	v_fma_f32 v121, -v6, v110, v121
	v_fma_f32 v47, -v7, v41, v47
	s_nop 0
	v_add_u32_e32 v14, s51, v2
	v_fma_f32 v120, -v7, v110, v120
	v_fma_f32 v48, -v8, v41, v48
	v_fma_f32 v123, -v8, v110, v123
	v_fma_f32 v49, -v9, v41, v49
	v_fma_f32 v122, -v9, v110, v122
	v_fma_f32 v44, -v10, v41, v44
	v_fma_f32 v74, -v10, v110, v74
	v_fma_f32 v45, -v11, v41, v45
	v_fma_f32 v75, -v11, v110, v75
	v_fma_f32 v50, -v12, v41, v50
	v_fma_f32 v76, -v12, v110, v76
	v_fma_f32 v51, -v13, v41, v51
	v_fma_f32 v77, -v13, v110, v77
	v_fma_f32 v53, -v15, v41, v53
	v_fma_f32 v79, -v15, v110, v79
	v_fma_f32 v54, -v16, v41, v54
	v_fma_f32 v105, -v16, v110, v105
	v_fma_f32 v55, -v17, v41, v55
	ds_read_b128 v[2:5], v14 offset:8256
	v_fma_f32 v114, -v17, v110, v114
	ds_read_b128 v[6:9], v14 offset:8272
	ds_read_b128 v[10:13], v14 offset:8288
	ds_read_b128 v[14:17], v14 offset:8304
	s_waitcnt lgkmcnt(0)
	v_mov_b32_e32 v2, 0x980
	v_fma_f32 v43, -v5, v42, v43
	v_fma_f32 v112, -v5, v113, v112
	v_fma_f32 v44, -v10, v42, v44
	v_fma_f32 v74, -v10, v113, v74
	v_fma_f32 v46, -v6, v42, v46
	v_fma_f32 v121, -v6, v113, v121
	v_fma_f32 v47, -v7, v42, v47
	s_nop 0
	v_fma_f32 v120, -v7, v113, v120
	v_fma_f32 v48, -v8, v42, v48
	v_fma_f32 v123, -v8, v113, v123
	v_fma_f32 v49, -v9, v42, v49
	v_fma_f32 v122, -v9, v113, v122
	s_nop 0
	v_add_u32_e32 v10, s51, v2
	v_fma_f32 v45, -v11, v42, v45
	v_fma_f32 v75, -v11, v113, v75
	v_fma_f32 v50, -v12, v42, v50
	v_fma_f32 v76, -v12, v113, v76
	v_fma_f32 v51, -v13, v42, v51
	v_fma_f32 v77, -v13, v113, v77
	ds_read_b128 v[2:5], v10 offset:8272
	ds_read_b128 v[6:9], v10 offset:8288
	ds_read_b128 v[10:13], v10 offset:8304
	v_fma_f32 v52, -v14, v42, v52
	v_fma_f32 v78, -v14, v113, v78
	s_waitcnt lgkmcnt(0)
	v_fma_f32 v46, -v2, v43, v46
	v_fma_f32 v121, -v2, v112, v121
	v_mov_b32_e32 v2, 0xa00
	v_fma_f32 v53, -v15, v42, v53
	v_fma_f32 v79, -v15, v113, v79
	v_fma_f32 v54, -v16, v42, v54
	v_fma_f32 v105, -v16, v113, v105
	v_fma_f32 v55, -v17, v42, v55
	v_fma_f32 v114, -v17, v113, v114
	v_fma_f32 v52, -v10, v43, v52
	v_fma_f32 v78, -v10, v112, v78
	v_fma_f32 v47, -v3, v43, v47
	v_fma_f32 v120, -v3, v112, v120
	v_fma_f32 v48, -v4, v43, v48
	v_fma_f32 v123, -v4, v112, v123
	v_fma_f32 v49, -v5, v43, v49
	s_nop 0
	v_add_u32_e32 v10, s51, v2
	v_fma_f32 v122, -v5, v112, v122
	v_fma_f32 v44, -v6, v43, v44
	v_fma_f32 v74, -v6, v112, v74
	v_fma_f32 v45, -v7, v43, v45
	v_fma_f32 v75, -v7, v112, v75
	v_fma_f32 v50, -v8, v43, v50
	v_fma_f32 v76, -v8, v112, v76
	v_fma_f32 v51, -v9, v43, v51
	v_fma_f32 v77, -v9, v112, v77
	v_fma_f32 v53, -v11, v43, v53
	v_fma_f32 v79, -v11, v112, v79
	v_fma_f32 v54, -v12, v43, v54
	v_fma_f32 v105, -v12, v112, v105
	ds_read_b128 v[2:5], v10 offset:8272
	v_fma_f32 v55, -v13, v43, v55
	v_fma_f32 v114, -v13, v112, v114
	ds_read_b128 v[6:9], v10 offset:8288
	ds_read_b128 v[10:13], v10 offset:8304
	s_waitcnt lgkmcnt(0)
	v_mov_b32_e32 v2, 0xa80
	v_fma_f32 v47, -v3, v46, v47
	v_fma_f32 v120, -v3, v121, v120
	v_fma_f32 v52, -v10, v46, v52
	v_fma_f32 v78, -v10, v121, v78
	s_nop 0
	v_fma_f32 v48, -v4, v46, v48
	v_fma_f32 v123, -v4, v121, v123
	v_fma_f32 v49, -v5, v46, v49
	v_fma_f32 v122, -v5, v121, v122
	v_fma_f32 v44, -v6, v46, v44
	s_nop 0
	v_add_u32_e32 v10, s51, v2
	v_fma_f32 v74, -v6, v121, v74
	v_fma_f32 v45, -v7, v46, v45
	v_fma_f32 v75, -v7, v121, v75
	v_fma_f32 v50, -v8, v46, v50
	v_fma_f32 v76, -v8, v121, v76
	v_fma_f32 v51, -v9, v46, v51
	v_fma_f32 v77, -v9, v121, v77
	v_fma_f32 v53, -v11, v46, v53
	v_fma_f32 v79, -v11, v121, v79
	v_fma_f32 v54, -v12, v46, v54
	v_fma_f32 v105, -v12, v121, v105
	ds_read_b128 v[2:5], v10 offset:8272
	v_fma_f32 v55, -v13, v46, v55
	v_fma_f32 v114, -v13, v121, v114
	ds_read_b128 v[6:9], v10 offset:8288
	ds_read_b128 v[10:13], v10 offset:8304
	s_waitcnt lgkmcnt(0)
	v_mov_b32_e32 v2, 0xb00
	v_fma_f32 v48, -v4, v47, v48
	v_fma_f32 v123, -v4, v120, v123
	v_fma_f32 v52, -v10, v47, v52
	v_fma_f32 v78, -v10, v120, v78
	s_nop 0
	v_fma_f32 v49, -v5, v47, v49
	v_fma_f32 v122, -v5, v120, v122
	v_fma_f32 v44, -v6, v47, v44
	v_fma_f32 v74, -v6, v120, v74
	v_fma_f32 v45, -v7, v47, v45
	s_nop 0
	v_add_u32_e32 v10, s51, v2
	ds_read_b128 v[2:5], v10 offset:8272
	v_fma_f32 v75, -v7, v120, v75
	v_fma_f32 v50, -v8, v47, v50
	v_fma_f32 v76, -v8, v120, v76
	v_fma_f32 v51, -v9, v47, v51
	v_fma_f32 v77, -v9, v120, v77
	ds_read_b128 v[6:9], v10 offset:8288
	s_waitcnt lgkmcnt(0)
	v_mov_b32_e32 v2, 0xb80
	v_fma_f32 v53, -v11, v47, v53
	v_fma_f32 v79, -v11, v120, v79
	v_fma_f32 v54, -v12, v47, v54
	v_fma_f32 v105, -v12, v120, v105
	v_fma_f32 v55, -v13, v47, v55
	v_fma_f32 v114, -v13, v120, v114
	ds_read_b128 v[10:13], v10 offset:8304
	v_fma_f32 v49, -v5, v48, v49
	v_fma_f32 v122, -v5, v123, v122
	v_fma_f32 v44, -v6, v48, v44
	v_fma_f32 v74, -v6, v123, v74
	v_fma_f32 v45, -v7, v48, v45
	v_fma_f32 v75, -v7, v123, v75
	v_fma_f32 v50, -v8, v48, v50
	s_nop 0
	v_fma_f32 v76, -v8, v123, v76
	v_fma_f32 v51, -v9, v48, v51
	v_fma_f32 v77, -v9, v123, v77
	s_waitcnt lgkmcnt(0)
	v_fma_f32 v52, -v10, v48, v52
	v_fma_f32 v78, -v10, v123, v78
	v_add_u32_e32 v6, s51, v2
	ds_read_b128 v[2:5], v6 offset:8288
	ds_read_b128 v[6:9], v6 offset:8304
	s_waitcnt lgkmcnt(0)
	v_fma_f32 v44, -v2, v49, v44
	v_fma_f32 v74, -v2, v122, v74
	v_mov_b32_e32 v2, 0xc00
	v_fma_f32 v52, -v6, v49, v52
	v_fma_f32 v78, -v6, v122, v78
	v_fma_f32 v53, -v11, v48, v53
	v_fma_f32 v79, -v11, v123, v79
	v_fma_f32 v54, -v12, v48, v54
	v_fma_f32 v105, -v12, v123, v105
	v_fma_f32 v55, -v13, v48, v55
	s_nop 0
	v_add_u32_e32 v6, s51, v2
	v_fma_f32 v114, -v13, v123, v114
	v_fma_f32 v45, -v3, v49, v45
	v_fma_f32 v75, -v3, v122, v75
	v_fma_f32 v50, -v4, v49, v50
	v_fma_f32 v76, -v4, v122, v76
	v_fma_f32 v51, -v5, v49, v51
	v_fma_f32 v77, -v5, v122, v77
	ds_read_b128 v[2:5], v6 offset:8288
	v_fma_f32 v53, -v7, v49, v53
	v_fma_f32 v79, -v7, v122, v79
	v_fma_f32 v54, -v8, v49, v54
	v_fma_f32 v105, -v8, v122, v105
	v_fma_f32 v55, -v9, v49, v55
	v_fma_f32 v114, -v9, v122, v114
	ds_read_b128 v[6:9], v6 offset:8304
	s_waitcnt lgkmcnt(0)
	v_mov_b32_e32 v2, 0xc80
	v_fma_f32 v45, -v3, v44, v45
	v_fma_f32 v75, -v3, v74, v75
	v_fma_f32 v52, -v6, v44, v52
	v_fma_f32 v78, -v6, v74, v78
	v_fma_f32 v50, -v4, v44, v50
	v_fma_f32 v76, -v4, v74, v76
	v_fma_f32 v51, -v5, v44, v51
	s_nop 0
	v_fma_f32 v77, -v5, v74, v77
	v_fma_f32 v53, -v7, v44, v53
	v_fma_f32 v79, -v7, v74, v79
	v_fma_f32 v54, -v8, v44, v54
	v_fma_f32 v105, -v8, v74, v105
	s_nop 0
	v_add_u32_e32 v6, s51, v2
	ds_read_b128 v[2:5], v6 offset:8288
	v_fma_f32 v55, -v9, v44, v55
	v_fma_f32 v114, -v9, v74, v114
	ds_read_b128 v[6:9], v6 offset:8304
	s_waitcnt lgkmcnt(0)
	v_mov_b32_e32 v2, 0xd00
	v_fma_f32 v50, -v4, v45, v50
	v_fma_f32 v76, -v4, v75, v76
	v_fma_f32 v52, -v6, v45, v52
	v_fma_f32 v78, -v6, v75, v78
	v_fma_f32 v51, -v5, v45, v51
	v_fma_f32 v77, -v5, v75, v77
	v_fma_f32 v53, -v7, v45, v53
	s_nop 0
	v_fma_f32 v79, -v7, v75, v79
	v_fma_f32 v54, -v8, v45, v54
	v_fma_f32 v105, -v8, v75, v105
	v_fma_f32 v55, -v9, v45, v55
	v_fma_f32 v114, -v9, v75, v114
	s_nop 0
	v_add_u32_e32 v6, s51, v2
	ds_read_b128 v[2:5], v6 offset:8288
	ds_read_b128 v[10:13], v6 offset:8304
	s_waitcnt lgkmcnt(0)
	v_mov_b32_e32 v2, 0xd80
	v_fma_f32 v51, -v5, v50, v51
	v_fma_f32 v77, -v5, v76, v77
	v_fma_f32 v52, -v10, v50, v52
	v_fma_f32 v78, -v10, v76, v78
	v_fma_f32 v53, -v11, v50, v53
	v_fma_f32 v79, -v11, v76, v79
	v_fma_f32 v54, -v12, v50, v54
	s_nop 0
	v_fma_f32 v105, -v12, v76, v105
	v_fma_f32 v55, -v13, v50, v55
	v_fma_f32 v114, -v13, v76, v114
	s_nop 0
	v_add_u32_e32 v2, s51, v2
	ds_read_b128 v[2:5], v2 offset:8304
	s_waitcnt lgkmcnt(0)
	v_fma_f32 v52, -v2, v51, v52
	v_fma_f32 v78, -v2, v77, v78
	v_mov_b32_e32 v2, 0xe00
	v_fma_f32 v53, -v3, v51, v53
	v_fma_f32 v79, -v3, v77, v79
	v_fma_f32 v54, -v4, v51, v54
	v_fma_f32 v105, -v4, v77, v105
	v_fma_f32 v55, -v5, v51, v55
	s_nop 0
	v_add_u32_e32 v2, s51, v2
	ds_read_b128 v[6:9], v2 offset:8304
	v_mov_b32_e32 v2, 0xe80
	s_waitcnt lgkmcnt(0)
	v_fma_f32 v53, -v7, v52, v53
	v_fma_f32 v79, -v7, v78, v79
	v_fma_f32 v54, -v8, v52, v54
	v_fma_f32 v105, -v8, v78, v105
	v_fma_f32 v114, -v5, v77, v114
	v_fma_f32 v55, -v9, v52, v55
	v_add_u32_e32 v8, s51, v56
	v_fma_f32 v114, -v9, v78, v114
	s_nop 0
	v_add_u32_e32 v2, s51, v2
	ds_read_b128 v[10:13], v2 offset:8304
	v_mov_b32_e32 v2, 0xf00
	s_waitcnt lgkmcnt(0)
	v_fma_f32 v54, -v12, v53, v54
	v_fma_f32 v105, -v12, v79, v105
	v_fma_f32 v55, -v13, v53, v55
	v_fma_f32 v114, -v13, v79, v114
	s_nop 0
	s_nop 0
	v_add_u32_e32 v2, s51, v2
	ds_read_b128 v[2:5], v2 offset:8304
	s_waitcnt lgkmcnt(0)
	v_lshlrev_b64 v[2:3], 2, v[22:23]
	v_fma_f32 v55, -v5, v54, v55
	v_fma_f32 v114, -v5, v105, v114
	v_lshl_add_u64 v[4:5], s[2:3], 0, v[2:3]
	flat_store_dword v[4:5], v24
	v_lshlrev_b64 v[4:5], 2, v[22:23]
	v_lshl_add_u64 v[6:7], s[2:3], 0, v[4:5]
	s_add_u32 s2, s0, 0x4800
	s_addc_u32 s3, s1, 0
	v_lshl_add_u64 v[2:3], s[2:3], 0, v[2:3]
	flat_store_dword v[6:7], v25 offset:256
	flat_store_dword v[6:7], v26 offset:512
	flat_store_dword v[6:7], v27 offset:768
	flat_store_dword v[6:7], v28 offset:1024
	flat_store_dword v[6:7], v29 offset:1280
	flat_store_dword v[6:7], v30 offset:1536
	flat_store_dword v[6:7], v31 offset:1792
	flat_store_dword v[6:7], v32 offset:2048
	flat_store_dword v[6:7], v33 offset:2304
	flat_store_dword v[6:7], v34 offset:2560
	flat_store_dword v[6:7], v35 offset:2816
	flat_store_dword v[6:7], v36 offset:3072
	flat_store_dword v[6:7], v37 offset:3328
	flat_store_dword v[6:7], v38 offset:3584
	flat_store_dword v[6:7], v39 offset:3840
	flat_store_dword v[2:3], v40
	v_lshl_add_u64 v[2:3], s[2:3], 0, v[4:5]
	flat_store_dword v[2:3], v41 offset:256
	flat_store_dword v[2:3], v42 offset:512
	flat_store_dword v[2:3], v43 offset:768
	flat_store_dword v[2:3], v46 offset:1024
	flat_store_dword v[2:3], v47 offset:1280
	flat_store_dword v[2:3], v48 offset:1536
	flat_store_dword v[2:3], v49 offset:1792
	flat_store_dword v[2:3], v44 offset:2048
	flat_store_dword v[2:3], v45 offset:2304
	flat_store_dword v[2:3], v50 offset:2560
	flat_store_dword v[2:3], v51 offset:2816
	flat_store_dword v[2:3], v52 offset:3072
	flat_store_dword v[2:3], v53 offset:3328
	flat_store_dword v[2:3], v54 offset:3584
	flat_store_dword v[2:3], v55 offset:3840
	v_bfe_u32 v2, v22, 2, 1
	s_mov_b32 s2, 0x7ffffe
	v_and_or_b32 v2, v21, s2, v2
	v_and_b32_e32 v3, 6, v87
	v_and_b32_e32 v4, 8, v22
	v_lshl_add_u32 v2, v2, 9, s51
	v_add3_u32 v2, v2, v4, v3
	v_cvt_pk_bf16_f32 v3, -v88, s0
	s_waitcnt lgkmcnt(0)
	ds_write_b16 v2, v3
	v_cvt_pk_bf16_f32 v3, -v90, s0
	ds_write_b16 v2, v3 offset:16
	v_cvt_pk_bf16_f32 v3, -v89, s0
	ds_write_b16 v2, v3 offset:32
	v_cvt_pk_bf16_f32 v3, -v91, s0
	ds_write_b16 v2, v3 offset:48
	v_cvt_pk_bf16_f32 v3, -v92, s0
	ds_write_b16 v2, v3 offset:64
	v_cvt_pk_bf16_f32 v3, -v93, s0
	ds_write_b16 v2, v3 offset:80
	v_cvt_pk_bf16_f32 v3, -v94, s0
	ds_write_b16 v2, v3 offset:96
	v_cvt_pk_bf16_f32 v3, -v95, s0
	ds_write_b16 v2, v3 offset:112
	v_cvt_pk_bf16_f32 v3, -v98, s0
	ds_write_b16 v2, v3 offset:128
	v_cvt_pk_bf16_f32 v3, -v97, s0
	ds_write_b16 v2, v3 offset:144
	v_cvt_pk_bf16_f32 v3, -v100, s0
	ds_write_b16 v2, v3 offset:160
	v_cvt_pk_bf16_f32 v3, -v99, s0
	ds_write_b16 v2, v3 offset:176
	v_cvt_pk_bf16_f32 v3, -v104, s0
	ds_write_b16 v2, v3 offset:192
	v_cvt_pk_bf16_f32 v3, -v103, s0
	ds_write_b16 v2, v3 offset:208
	v_cvt_pk_bf16_f32 v3, -v107, s0
	ds_write_b16 v2, v3 offset:224
	v_cvt_pk_bf16_f32 v3, -v106, s0
	ds_write_b16 v2, v3 offset:240
	v_cvt_pk_bf16_f32 v3, -v111, s0
	ds_write_b16 v2, v3 offset:256
	v_cvt_pk_bf16_f32 v3, -v110, s0
	ds_write_b16 v2, v3 offset:272
	v_cvt_pk_bf16_f32 v3, -v113, s0
	ds_write_b16 v2, v3 offset:288
	v_cvt_pk_bf16_f32 v3, -v112, s0
	ds_write_b16 v2, v3 offset:304
	v_cvt_pk_bf16_f32 v3, -v121, s0
	ds_write_b16 v2, v3 offset:320
	v_cvt_pk_bf16_f32 v3, -v120, s0
	ds_write_b16 v2, v3 offset:336
	v_cvt_pk_bf16_f32 v3, -v123, s0
	ds_write_b16 v2, v3 offset:352
	v_cvt_pk_bf16_f32 v3, -v122, s0
	ds_write_b16 v2, v3 offset:368
	v_cvt_pk_bf16_f32 v3, -v74, s0
	ds_write_b16 v2, v3 offset:384
	v_cvt_pk_bf16_f32 v3, -v75, s0
	ds_write_b16 v2, v3 offset:400
	v_cvt_pk_bf16_f32 v3, -v76, s0
	ds_write_b16 v2, v3 offset:416
	v_cvt_pk_bf16_f32 v3, -v77, s0
	ds_write_b16 v2, v3 offset:432
	v_cvt_pk_bf16_f32 v3, -v78, s0
	ds_write_b16 v2, v3 offset:448
	v_cvt_pk_bf16_f32 v3, -v79, s0
	ds_write_b16 v2, v3 offset:464
	v_cvt_pk_bf16_f32 v3, -v105, s0
	ds_write_b16 v2, v3 offset:480
	v_cvt_pk_bf16_f32 v3, -v114, s0
	ds_write_b16 v2, v3 offset:496
	s_waitcnt lgkmcnt(0)
	ds_read_b128 v[2:5], v8
	v_lshl_add_u64 v[6:7], s[0:1], 0, v[56:57]
	v_readlane_b32 s3, v245, 63
	s_add_i32 s76, s76, s3
	s_add_i32 s10, s10, s11
	s_waitcnt lgkmcnt(0)
	flat_store_dwordx4 v[6:7], v[2:5]
	ds_read_b128 v[2:5], v8 offset:1024
	s_mul_i32 s2, s3, 0x5a00
	s_add_u32 s0, s0, s2
	s_mul_hi_i32 s2, s3, 0x5a00
	s_addc_u32 s1, s1, s2
	s_waitcnt lgkmcnt(0)
	flat_store_dwordx4 v[6:7], v[2:5] offset:1024
	ds_read_b128 v[2:5], v8 offset:2048
	s_cmpk_gt_i32 s76, 0xfff
	s_waitcnt lgkmcnt(0)
	flat_store_dwordx4 v[6:7], v[2:5] offset:2048
	ds_read_b128 v[2:5], v8 offset:3072
	s_waitcnt lgkmcnt(0)
	flat_store_dwordx4 v[6:7], v[2:5] offset:3072
	s_waitcnt lgkmcnt(0)
	s_cbranch_scc1 .LBB0_1077
.LBB0_1067:
	s_and_b32 s8, s76, 63
	v_mov_b32_e32 v22, v196
	s_and_b32 s2, s10, 0xfffff800
	s_lshl_b32 s3, s8, 5
	s_or_b32 s6, s2, s3
	v_and_b32_e32 v96, 31, v22
	s_bfe_u32 s9, s76, 0x30006
	v_or_b32_e32 v2, s6, v96
	s_movk_i32 s2, 0x3c00
	v_mad_i64_i32 v[2:3], s[2:3], v2, s2, v[18:19]
	s_lshl_b32 s4, s9, 2
	v_lshl_add_u64 v[2:3], v[2:3], 0, s[4:5]
	v_readlane_b32 s16, v245, 39
	v_add_co_u32_e32 v2, vcc, 0x3000, v2
	v_mov_b32_e32 v4, s4
	v_readlane_b32 s17, v245, 40
	v_addc_co_u32_e32 v3, vcc, 0, v3, vcc
	s_nop 3
	global_load_dword v4, v4, s[16:17] nt
	s_nop 0
	global_load_dword v5, v[2:3], off offset:2080 nt
	global_load_dword v14, v[2:3], off offset:2048 nt
	s_mov_b32 s2, 0x41a00000
	v_readlane_b32 s18, v245, 41
	v_readlane_b32 s19, v245, 42
	v_readlane_b32 s20, v245, 43
	v_readlane_b32 s21, v245, 44
	v_readlane_b32 s22, v245, 45
	v_readlane_b32 s23, v245, 46
	v_readlane_b32 s24, v245, 47
	v_readlane_b32 s25, v245, 48
	v_readlane_b32 s26, v245, 49
	v_readlane_b32 s27, v245, 50
	v_readlane_b32 s28, v245, 51
	v_readlane_b32 s29, v245, 52
	v_readlane_b32 s30, v245, 53
	v_readlane_b32 s31, v245, 54
	s_waitcnt vmcnt(0)
	v_add_f32_e32 v2, v5, v4
	v_cmp_nlt_f32_e32 vcc, s2, v2
	s_and_saveexec_b64 s[2:3], vcc
	s_cbranch_execz .LBB0_1069
	v_mul_f32_e32 v2, 0x3fb8aa3b, v2
	v_exp_f32_e32 v15, v2
	s_mov_b32 s7, 0x3f2aaaab
	v_add_f32_e32 v4, 1.0, v15
	v_frexp_mant_f32_e32 v6, v4
	v_cvt_f64_f32_e32 v[2:3], v4
	v_frexp_exp_i32_f64_e32 v2, v[2:3]
	v_cmp_gt_f32_e32 vcc, s7, v6
	v_add_f32_e32 v5, -1.0, v4
	v_sub_f32_e32 v7, v5, v4
	v_subbrev_co_u32_e32 v10, vcc, 0, v2, vcc
	v_sub_u32_e32 v2, 0, v10
	v_sub_f32_e32 v5, v15, v5
	v_add_f32_e32 v7, 1.0, v7
	v_ldexp_f32 v3, v4, v2
	v_add_f32_e32 v5, v5, v7
	v_add_f32_e32 v4, -1.0, v3
	v_add_f32_e32 v6, 1.0, v3
	v_ldexp_f32 v2, v5, v2
	v_add_f32_e32 v5, 1.0, v4
	v_add_f32_e32 v7, -1.0, v6
	v_sub_f32_e32 v5, v3, v5
	v_sub_f32_e32 v3, v3, v7
	v_add_f32_e32 v5, v2, v5
	v_add_f32_e32 v2, v2, v3
	v_add_f32_e32 v11, v6, v2
	v_rcp_f32_e32 v13, v11
	v_sub_f32_e32 v3, v11, v6
	v_sub_f32_e32 v12, v2, v3
	v_add_f32_e32 v3, v4, v5
	v_mul_f32_e32 v17, v3, v13
	v_sub_f32_e32 v2, v3, v4
	v_mul_f32_e32 v4, v11, v17
	v_fma_f32 v6, v17, v11, -v4
	v_fmac_f32_e32 v6, v17, v12
	v_sub_f32_e32 v16, v5, v2
	v_add_f32_e32 v2, v4, v6
	v_sub_f32_e32 v5, v3, v2
	v_pk_add_f32 v[8:9], v[2:3], v[4:5] neg_lo:[0,1] neg_hi:[0,1]
	v_mov_b32_e32 v7, v2
	v_pk_add_f32 v[2:3], v[8:9], v[6:7] neg_lo:[0,1] neg_hi:[0,1]
	s_mov_b32 s7, 0x3f317218
	v_add_f32_e32 v3, v16, v3
	v_add_f32_e32 v2, v2, v3
	v_add_f32_e32 v3, v5, v2
	v_mul_f32_e32 v16, v13, v3
	v_mul_f32_e32 v4, v11, v16
	v_fma_f32 v6, v16, v11, -v4
	v_fmac_f32_e32 v6, v16, v12
	v_sub_f32_e32 v5, v5, v3
	v_add_f32_e32 v11, v2, v5
	v_add_f32_e32 v2, v4, v6
	v_sub_f32_e32 v5, v3, v2
	v_pk_add_f32 v[8:9], v[2:3], v[4:5] neg_lo:[0,1] neg_hi:[0,1]
	v_mov_b32_e32 v7, v2
	v_pk_add_f32 v[2:3], v[8:9], v[6:7] neg_lo:[0,1] neg_hi:[0,1]
	s_nop 0
	v_add_f32_e32 v3, v11, v3
	v_add_f32_e32 v2, v2, v3
	v_add_f32_e32 v3, v17, v16
	v_add_f32_e32 v2, v5, v2
	v_sub_f32_e32 v4, v3, v17
	v_mul_f32_e32 v2, v13, v2
	v_sub_f32_e32 v4, v16, v4
	v_add_f32_e32 v4, v4, v2
	v_add_f32_e32 v6, v3, v4
	v_mul_f32_e32 v7, v6, v6
	v_fmamk_f32 v2, v7, 0x3e9b6dac, v80
	v_fmaak_f32 v21, v7, v2, 0x3f2aaada
	v_cvt_f32_i32_e32 v2, v10
	v_sub_f32_e32 v3, v6, v3
	v_sub_f32_e32 v3, v4, v3
	v_ldexp_f32 v8, v3, 1
	v_mul_f32_e32 v3, v6, v7
	v_ldexp_f32 v5, v6, 1
	v_pk_mul_f32 v[6:7], v[2:3], v[20:21]
	s_nop 0
	v_fma_f32 v4, v2, s7, -v6
	v_fmac_f32_e32 v4, 0xb102e308, v2
	v_pk_add_f32 v[2:3], v[6:7], v[4:5]
	s_mov_b32 s7, 0x7f800000
	v_sub_f32_e32 v5, v3, v5
	v_sub_f32_e32 v5, v7, v5
	v_add_f32_e32 v9, v8, v5
	v_mov_b32_e32 v8, v6
	v_pk_add_f32 v[6:7], v[2:3], v[6:7] neg_lo:[0,1] neg_hi:[0,1]
	v_pk_add_f32 v[10:11], v[2:3], v[8:9]
	v_mov_b32_e32 v5, v2
	v_mov_b32_e32 v7, v11
	v_pk_add_f32 v[12:13], v[4:5], v[6:7] neg_lo:[0,1] neg_hi:[0,1]
	v_pk_add_f32 v[4:5], v[4:5], v[6:7]
	v_mov_b32_e32 v8, v9
	v_pk_add_f32 v[6:7], v[4:5], v[2:3] op_sel:[1,0] op_sel_hi:[0,1] neg_lo:[0,1] neg_hi:[0,1]
	v_pk_add_f32 v[16:17], v[10:11], v[6:7] op_sel_hi:[1,0] neg_lo:[0,1] neg_hi:[0,1]
	v_mov_b32_e32 v10, v11
	v_mov_b32_e32 v11, v5
	v_pk_mov_b32 v[6:7], v[2:3], v[6:7] op_sel:[1,0]
	v_mov_b32_e32 v9, v2
	v_pk_add_f32 v[6:7], v[10:11], v[6:7] neg_lo:[0,1] neg_hi:[0,1]
	v_mov_b32_e32 v16, v12
	v_pk_add_f32 v[2:3], v[8:9], v[6:7] neg_lo:[0,1] neg_hi:[0,1]
	v_mov_b32_e32 v13, v5
	v_pk_add_f32 v[6:7], v[16:17], v[2:3]
	v_cmp_neq_f32_e32 vcc, s7, v15
	v_pk_add_f32 v[8:9], v[6:7], v[6:7] op_sel:[0,1] op_sel_hi:[1,0]
	s_mov_b32 s7, 0x33800000
	v_pk_add_f32 v[4:5], v[4:5], v[8:9] op_sel:[1,0] op_sel_hi:[0,1]
	v_mov_b32_e32 v7, v4
	v_pk_add_f32 v[10:11], v[6:7], v[12:13] neg_lo:[0,1] neg_hi:[0,1]
	v_mov_b32_e32 v3, v8
	v_sub_f32_e32 v5, v6, v10
	v_pk_add_f32 v[2:3], v[2:3], v[10:11] neg_lo:[0,1] neg_hi:[0,1]
	v_sub_f32_e32 v5, v12, v5
	v_add_f32_e32 v2, v2, v5
	v_add_f32_e32 v2, v2, v3
	v_add_f32_e32 v2, v4, v2
	v_cndmask_b32_e32 v2, v81, v2, vcc
	v_cmp_ngt_f32_e32 vcc, -1.0, v15
	s_nop 1
	v_cndmask_b32_e32 v2, v82, v2, vcc
	v_cmp_neq_f32_e32 vcc, -1.0, v15
	s_nop 1
	v_cndmask_b32_e32 v2, v83, v2, vcc
	v_cmp_lt_f32_e64 vcc, |v15|, s7
	s_nop 1
	v_cndmask_b32_e32 v2, v2, v15, vcc
.LBB0_1069:
	s_or_b64 exec, exec, s[2:3]
	v_readlane_b32 s16, v245, 21
	v_mov_b32_e32 v3, s4
	v_readlane_b32 s30, v245, 35
	v_readlane_b32 s31, v245, 36
	v_and_b32_e32 v4, 0x60, v84
	v_add_u32_e32 v5, -1, v84
	v_cmp_lt_i32_e32 vcc, v5, v4
	v_add_u32_e32 v7, -2, v84
	v_ashrrev_i32_e32 v23, 31, v22
	global_load_dword v3, v3, s[30:31] nt
	v_cndmask_b32_e32 v5, v5, v84, vcc
	v_lshlrev_b32_e32 v5, 2, v5
	v_cmp_lt_i32_e32 vcc, v7, v4
	v_readlane_b32 s17, v245, 22
	v_readlane_b32 s18, v245, 23
	v_cndmask_b32_e32 v7, v7, v84, vcc
	v_cmp_eq_u32_e32 vcc, 0, v96
	v_lshlrev_b32_e32 v7, 2, v7
	v_readlane_b32 s19, v245, 24
	v_readlane_b32 s20, v245, 25
	v_readlane_b32 s21, v245, 26
	v_readlane_b32 s22, v245, 27
	v_readlane_b32 s23, v245, 28
	v_readlane_b32 s24, v245, 29
	v_readlane_b32 s25, v245, 30
	v_readlane_b32 s26, v245, 31
	v_readlane_b32 s27, v245, 32
	v_readlane_b32 s28, v245, 33
	v_readlane_b32 s29, v245, 34
	s_waitcnt vmcnt(0)
	v_mul_f32_e32 v3, 0x3fb8aa3b, v3
	v_exp_f32_e32 v3, v3
	s_nop 0
	v_mul_f32_e64 v6, v2, -v3
	ds_bpermute_b32 v5, v5, v6
	s_waitcnt lgkmcnt(0)
	v_fma_f32 v2, v2, -v3, v5
	v_cndmask_b32_e32 v2, v2, v6, vcc
	ds_bpermute_b32 v3, v7, v2
	v_add_u32_e32 v5, -4, v84
	v_cmp_lt_i32_e32 vcc, v5, v4
	s_waitcnt lgkmcnt(0)
	v_add_f32_e32 v3, v2, v3
	v_cndmask_b32_e32 v5, v5, v84, vcc
	v_cmp_gt_u32_e32 vcc, 2, v96
	v_lshlrev_b32_e32 v5, 2, v5
	s_nop 0
	v_cndmask_b32_e32 v2, v3, v2, vcc
	ds_bpermute_b32 v3, v5, v2
	v_add_u32_e32 v5, -8, v84
	v_cmp_lt_i32_e32 vcc, v5, v4
	s_waitcnt lgkmcnt(0)
	v_add_f32_e32 v3, v2, v3
	v_cndmask_b32_e32 v5, v5, v84, vcc
	v_cmp_gt_u32_e32 vcc, 4, v96
	v_lshlrev_b32_e32 v5, 2, v5
	s_nop 0
	v_cndmask_b32_e32 v2, v3, v2, vcc
	ds_bpermute_b32 v3, v5, v2
	v_add_u32_e32 v5, -16, v84
	v_cmp_lt_i32_e32 vcc, v5, v4
	s_waitcnt lgkmcnt(0)
	v_add_f32_e32 v3, v2, v3
	v_cndmask_b32_e32 v4, v5, v84, vcc
	v_cmp_gt_u32_e32 vcc, 8, v96
	v_lshlrev_b32_e32 v4, 2, v4
	s_nop 0
	v_cndmask_b32_e32 v2, v3, v2, vcc
	ds_bpermute_b32 v3, v4, v2
	v_cmp_gt_u32_e32 vcc, 16, v96
	s_waitcnt lgkmcnt(0)
	v_add_f32_e32 v3, v2, v3
	v_cndmask_b32_e32 v101, v3, v2, vcc
	v_mul_f32_e32 v2, 0x3fb8aa3b, v101
	v_exp_f32_e32 v3, v2
	v_readlane_b32 s4, v101, 31
	v_cmp_gt_i32_e32 vcc, 32, v22
	s_and_saveexec_b64 s[2:3], vcc
	s_cbranch_execz .LBB0_1071
	v_sub_f32_e32 v2, s4, v101
	v_mul_f32_e32 v2, 0x3fb8aa3b, v2
	v_exp_f32_e32 v2, v2
	v_lshl_add_u64 v[4:5], v[22:23], 2, s[0:1]
	s_mov_b64 s[16:17], 0x5800
	v_lshl_add_u64 v[6:7], v[4:5], 0, s[16:17]
	v_add_co_u32_e32 v4, vcc, 0x5000, v4
	s_nop 1
	v_addc_co_u32_e32 v5, vcc, 0, v5, vcc
	flat_store_dword v[4:5], v3 offset:2048
	flat_store_dword v[6:7], v2 offset:128

.LBB0_1073:
	s_or_b64 exec, exec, s[2:3]
	v_lshl_add_u32 v6, s9, 6, v22
	v_readlane_b32 s16, v245, 21
	v_add_u32_e32 v4, 0x400, v6
	v_readlane_b32 s20, v245, 25
	v_readlane_b32 s21, v245, 26
	v_readlane_b32 s22, v245, 27
	v_readlane_b32 s23, v245, 28
	v_readlane_b32 s28, v245, 33
	v_readlane_b32 s29, v245, 34
	v_readlane_b32 s30, v245, 35
	v_readlane_b32 s31, v245, 36
	s_mov_b64 s[20:21], s[28:29]
	v_ashrrev_i32_e32 v5, 31, v4
	v_lshl_add_u64 v[8:9], v[4:5], 2, s[20:21]
	v_add_u32_e32 v4, 0x800, v6
	v_ashrrev_i32_e32 v7, 31, v6
	v_ashrrev_i32_e32 v5, 31, v4
	v_lshl_add_u64 v[16:17], v[6:7], 2, s[20:21]
	v_lshl_add_u64 v[24:25], v[4:5], 2, s[20:21]
	v_add_u32_e32 v4, 0xa00, v6
	v_add_co_u32_e32 v10, vcc, 0x1000, v16
	v_ashrrev_i32_e32 v5, 31, v4
	s_nop 0
	v_addc_co_u32_e32 v11, vcc, 0, v17, vcc
	v_lshl_add_u64 v[26:27], v[4:5], 2, s[20:21]
	v_add_u32_e32 v4, 0xe00, v6
	v_add_co_u32_e32 v28, vcc, s12, v16
	v_ashrrev_i32_e32 v5, 31, v4
	s_nop 0
	v_addc_co_u32_e32 v29, vcc, 0, v17, vcc
	v_lshl_add_u64 v[30:31], v[4:5], 2, s[20:21]
	global_load_dword v5, v[16:17], off nt
	global_load_dword v13, v[16:17], off offset:2048 nt
	global_load_dword v2, v[8:9], off nt
	s_nop 0
	global_load_dword v9, v[10:11], off offset:2048 nt
	global_load_dword v12, v[24:25], off nt
	global_load_dword v4, v[26:27], off nt
	global_load_dword v7, v[28:29], off nt
	s_nop 0
	global_load_dword v10, v[30:31], off nt
	v_add_u32_e32 v24, 0x1000, v6
	v_ashrrev_i32_e32 v25, 31, v24
	v_add_u32_e32 v26, 0x1400, v6
	v_add_u32_e32 v28, 0x1600, v6
	v_lshl_add_u64 v[24:25], v[24:25], 2, s[20:21]
	v_add_co_u32_e32 v16, vcc, s13, v16
	v_ashrrev_i32_e32 v27, 31, v26
	v_ashrrev_i32_e32 v29, 31, v28
	v_addc_co_u32_e32 v17, vcc, 0, v17, vcc
	v_lshl_add_u64 v[26:27], v[26:27], 2, s[20:21]
	v_lshl_add_u64 v[28:29], v[28:29], 2, s[20:21]
	global_load_dword v6, v[24:25], off nt
	global_load_dword v105, v[16:17], off offset:2048 nt
	global_load_dword v11, v[26:27], off nt
	global_load_dword v8, v[28:29], off nt
	s_ashr_i32 s7, s6, 31
	s_lshl_b64 s[2:3], s[6:7], 12
	s_add_u32 s2, s64, s2
	s_addc_u32 s3, s65, s3
	s_lshl_b32 s4, s9, 7
	s_add_u32 s2, s2, s4
	s_addc_u32 s3, s3, 0
	s_add_u32 s6, s2, 0x400
	s_addc_u32 s7, s3, 0
	s_cmp_lg_u32 s8, 0
	v_readlane_b32 s17, v245, 22
	v_readlane_b32 s18, v245, 23
	v_readlane_b32 s19, v245, 24
	v_readlane_b32 s24, v245, 29
	v_readlane_b32 s25, v245, 30
	v_readlane_b32 s26, v245, 31
	v_readlane_b32 s27, v245, 32
	s_mov_b64 s[22:23], s[30:31]
	s_cbranch_scc0 .LBB0_1075
	s_add_u32 s2, s6, 0xffffd000
	s_addc_u32 s3, s7, -1
	s_add_u32 s8, s6, 0xffffe000
	s_addc_u32 s9, s7, -1
	s_movk_i32 s18, 0xfc00
	s_add_u32 s16, s6, 0xfffff000
	v_lshlrev_b64 v[16:17], 1, v[22:23]
	s_mov_b32 s19, -1
	s_addc_u32 s17, s7, -1
	v_lshl_add_u64 v[24:25], v[16:17], 0, s[18:19]
	v_lshl_add_u64 v[26:27], s[2:3], 0, v[24:25]
	v_lshl_add_u64 v[28:29], s[2:3], 0, v[16:17]
	v_lshl_add_u64 v[30:31], s[8:9], 0, v[24:25]
	v_lshl_add_u64 v[32:33], s[8:9], 0, v[16:17]
	v_lshl_add_u64 v[24:25], s[16:17], 0, v[24:25]
	v_lshl_add_u64 v[16:17], s[16:17], 0, v[16:17]
	flat_load_ushort v21, v[30:31] nt
	flat_load_ushort v15, v[26:27] nt
	s_nop 0
	flat_load_ushort v26, v[28:29] nt
	s_nop 0
	flat_load_ushort v24, v[24:25] nt
	s_nop 0
	flat_load_ushort v25, v[32:33] nt
	flat_load_ushort v27, v[16:17] nt
	flat_load_ushort v30, v[32:33] offset:1024 nt
	flat_load_ushort v31, v[28:29] offset:1024 nt
	s_nop 0
	flat_load_ushort v17, v[16:17] offset:1024 nt
	s_waitcnt vmcnt(0) lgkmcnt(0)
	v_lshlrev_b32_e32 v70, 16, v21
	v_lshlrev_b32_e32 v16, 16, v15
	v_lshlrev_b32_e32 v15, 16, v26
	v_lshlrev_b32_e32 v46, 16, v24
	v_lshlrev_b32_e32 v28, 16, v25
	v_lshlrev_b32_e32 v29, 16, v27
	v_lshlrev_b32_e32 v27, 16, v30
	v_lshlrev_b32_e32 v26, 16, v31
	v_lshlrev_b32_e32 v25, 16, v17
	v_mov_b32_e32 v24, v27
	s_cbranch_execnz .LBB0_1066
	s_branch .LBB0_1076

; #define GAS __attribute__((address_space(1)))
; #define LAS __attribute__((address_space(3)))
; #define LDS_WAIT() asm volatile("s_waitcnt lgkmcnt(0)" ::: "memory")
; __device__ __forceinline__ unsigned pk2(float lo, float hi) { f32x2_p v = {lo, hi}; bf16x2_p b = __builtin_convertvector(v, bf16x2_p); return __builtin_bit_cast(unsigned, b); }
; __device__ __forceinline__ void p0_transpose_item(const float* W0, const float* W1, int K, int Nsrc, int Nd, int mode, bf16* WT, LAS float* scr, int item, int lane) {
;     const int nblk = Nd / 32, kb = item / nblk, nb = item % nblk, k0 = 64 * kb, n0 = 32 * nb;
;     const float* src = W0; int c0 = n0;
;     if (mode == 1) { const int t = n0 / 256, w = n0 % 256; src = (w < 128) ? W0 : W1; c0 = t * 128 + (w & 127); }
;     const bool okc = (c0 + (lane & 31)) < Nsrc; const int cc = okc ? c0 + (lane & 31) : Nsrc - 1;
;     float tv[32];
; #pragma unroll
;     for (int i = 0; i < 32; ++i) { const int kk = 2 * i + (lane >> 5); tv[i] = src[(size_t)(k0 + kk) * Nsrc + cc]; }
; #pragma unroll
;     for (int i = 0; i < 32; ++i) { const int kk = 2 * i + (lane >> 5); scr[kk * 33 + (lane & 31)] = okc ? tv[i] : 0.f; }
;     LDS_WAIT(); asm volatile("" ::: "memory");
;     const int c = lane & 7;
; #pragma unroll
;     for (int j = 0; j < 4; ++j) { const int n = (lane >> 3) + 8 * j; const LAS float* s = scr + (8 * c) * 33 + n;
;         v4u o; o.x = pk2(s[0 * 33], s[1 * 33]); o.y = pk2(s[2 * 33], s[3 * 33]); o.z = pk2(s[4 * 33], s[5 * 33]); o.w = pk2(s[6 * 33], s[7 * 33]);
;         *(GAS v4u*)(WT + (size_t)(n0 + n) * K + k0 + 8 * c) = o; }
;     LDS_WAIT(); asm volatile("" ::: "memory");
; }
.LBB0_1223:
	s_ashr_i32 s0, s6, 31
	s_lshr_b32 s0, s0, 27
	s_add_i32 s0, s6, s0
	s_ashr_i32 s1, s0, 5
	s_lshl_b32 s0, s1, 6
	s_lshl_b32 s1, s1, 10
	s_sub_i32 s7, s4, s1
	v_or_b32_e32 v16, s0, v169
	v_add_u32_e32 v4, s7, v168
	v_or_b32_e32 v24, 8, v16
	v_or_b32_e32 v26, 10, v16
	v_or_b32_e32 v28, 12, v16
	v_or_b32_e32 v30, 14, v16
	v_or_b32_e32 v38, 22, v16
	v_or_b32_e32 v40, 24, v16
	v_or_b32_e32 v42, 26, v16
	v_or_b32_e32 v44, 28, v16
	v_or_b32_e32 v46, 30, v16
	v_or_b32_e32 v48, 32, v16
	v_or_b32_e32 v50, 34, v16
	v_or_b32_e32 v52, 36, v16
	v_or_b32_e32 v54, 38, v16
	v_or_b32_e32 v56, 40, v16
	v_ashrrev_i32_e32 v17, 31, v16
	v_or_b32_e32 v18, 2, v16
	v_or_b32_e32 v20, 4, v16
	v_or_b32_e32 v22, 6, v16
	v_or_b32_e32 v32, 16, v16
	v_or_b32_e32 v34, 18, v16
	v_or_b32_e32 v36, 20, v16
	v_or_b32_e32 v58, 42, v16
	v_or_b32_e32 v60, 44, v16
	v_or_b32_e32 v62, 46, v16
	v_or_b32_e32 v64, 48, v16
	v_or_b32_e32 v66, 50, v16
	v_or_b32_e32 v68, 52, v16
	v_or_b32_e32 v70, 54, v16
	v_or_b32_e32 v72, 56, v16
	v_or_b32_e32 v74, 58, v16
	v_or_b32_e32 v76, 60, v16
	v_or_b32_e32 v78, 62, v16
	v_ashrrev_i32_e32 v5, 31, v4
	v_ashrrev_i32_e32 v25, 31, v24
	v_ashrrev_i32_e32 v27, 31, v26
	v_ashrrev_i32_e32 v29, 31, v28
	v_ashrrev_i32_e32 v31, 31, v30
	v_ashrrev_i32_e32 v39, 31, v38
	v_ashrrev_i32_e32 v41, 31, v40
	v_ashrrev_i32_e32 v43, 31, v42
	v_ashrrev_i32_e32 v45, 31, v44
	v_ashrrev_i32_e32 v47, 31, v46
	v_ashrrev_i32_e32 v49, 31, v48
	v_ashrrev_i32_e32 v51, 31, v50
	v_ashrrev_i32_e32 v53, 31, v52
	v_ashrrev_i32_e32 v55, 31, v54
	v_ashrrev_i32_e32 v57, 31, v56
	v_lshlrev_b64 v[16:17], 12, v[16:17]
	v_ashrrev_i32_e32 v19, 31, v18
	v_ashrrev_i32_e32 v21, 31, v20
	v_ashrrev_i32_e32 v23, 31, v22
	v_ashrrev_i32_e32 v33, 31, v32
	v_ashrrev_i32_e32 v35, 31, v34
	v_ashrrev_i32_e32 v37, 31, v36
	v_ashrrev_i32_e32 v59, 31, v58
	v_ashrrev_i32_e32 v61, 31, v60
	v_ashrrev_i32_e32 v63, 31, v62
	v_ashrrev_i32_e32 v65, 31, v64
	v_ashrrev_i32_e32 v67, 31, v66
	v_ashrrev_i32_e32 v69, 31, v68
	v_ashrrev_i32_e32 v71, 31, v70
	v_ashrrev_i32_e32 v73, 31, v72
	v_ashrrev_i32_e32 v75, 31, v74
	v_ashrrev_i32_e32 v77, 31, v76
	v_ashrrev_i32_e32 v79, 31, v78
	v_lshl_add_u64 v[4:5], v[4:5], 2, s[10:11]
	v_lshlrev_b64 v[24:25], 12, v[24:25]
	v_lshlrev_b64 v[26:27], 12, v[26:27]
	v_lshlrev_b64 v[28:29], 12, v[28:29]
	v_lshlrev_b64 v[30:31], 12, v[30:31]
	v_lshlrev_b64 v[38:39], 12, v[38:39]
	v_lshlrev_b64 v[40:41], 12, v[40:41]
	v_lshlrev_b64 v[42:43], 12, v[42:43]
	v_lshlrev_b64 v[44:45], 12, v[44:45]
	v_lshlrev_b64 v[46:47], 12, v[46:47]
	v_lshlrev_b64 v[48:49], 12, v[48:49]
	v_lshlrev_b64 v[50:51], 12, v[50:51]
	v_lshlrev_b64 v[52:53], 12, v[52:53]
	v_lshlrev_b64 v[54:55], 12, v[54:55]
	v_lshlrev_b64 v[56:57], 12, v[56:57]
	v_lshlrev_b64 v[18:19], 12, v[18:19]
	v_lshlrev_b64 v[20:21], 12, v[20:21]
	v_lshlrev_b64 v[22:23], 12, v[22:23]
	v_lshlrev_b64 v[32:33], 12, v[32:33]
	v_lshlrev_b64 v[34:35], 12, v[34:35]
	v_lshlrev_b64 v[36:37], 12, v[36:37]
	v_lshlrev_b64 v[58:59], 12, v[58:59]
	v_lshlrev_b64 v[60:61], 12, v[60:61]
	v_lshlrev_b64 v[62:63], 12, v[62:63]
	v_lshlrev_b64 v[64:65], 12, v[64:65]
	v_lshlrev_b64 v[66:67], 12, v[66:67]
	v_lshlrev_b64 v[68:69], 12, v[68:69]
	v_lshlrev_b64 v[70:71], 12, v[70:71]
	v_lshlrev_b64 v[72:73], 12, v[72:73]
	v_lshlrev_b64 v[74:75], 12, v[74:75]
	v_lshlrev_b64 v[76:77], 12, v[76:77]
	v_lshlrev_b64 v[78:79], 12, v[78:79]
	v_lshl_add_u64 v[16:17], v[4:5], 0, v[16:17]
	v_lshl_add_u64 v[24:25], v[4:5], 0, v[24:25]
	v_lshl_add_u64 v[26:27], v[4:5], 0, v[26:27]
	v_lshl_add_u64 v[28:29], v[4:5], 0, v[28:29]
	v_lshl_add_u64 v[30:31], v[4:5], 0, v[30:31]
	v_lshl_add_u64 v[38:39], v[4:5], 0, v[38:39]
	v_lshl_add_u64 v[40:41], v[4:5], 0, v[40:41]
	v_lshl_add_u64 v[42:43], v[4:5], 0, v[42:43]
	v_lshl_add_u64 v[44:45], v[4:5], 0, v[44:45]
	v_lshl_add_u64 v[46:47], v[4:5], 0, v[46:47]
	v_lshl_add_u64 v[48:49], v[4:5], 0, v[48:49]
	v_lshl_add_u64 v[50:51], v[4:5], 0, v[50:51]
	v_lshl_add_u64 v[52:53], v[4:5], 0, v[52:53]
	v_lshl_add_u64 v[54:55], v[4:5], 0, v[54:55]
	v_lshl_add_u64 v[56:57], v[4:5], 0, v[56:57]
	v_lshl_add_u64 v[18:19], v[4:5], 0, v[18:19]
	v_lshl_add_u64 v[20:21], v[4:5], 0, v[20:21]
	v_lshl_add_u64 v[22:23], v[4:5], 0, v[22:23]
	v_lshl_add_u64 v[32:33], v[4:5], 0, v[32:33]
	v_lshl_add_u64 v[34:35], v[4:5], 0, v[34:35]
	v_lshl_add_u64 v[36:37], v[4:5], 0, v[36:37]
	v_lshl_add_u64 v[58:59], v[4:5], 0, v[58:59]
	v_lshl_add_u64 v[60:61], v[4:5], 0, v[60:61]
	v_lshl_add_u64 v[62:63], v[4:5], 0, v[62:63]
	v_lshl_add_u64 v[64:65], v[4:5], 0, v[64:65]
	v_lshl_add_u64 v[66:67], v[4:5], 0, v[66:67]
	v_lshl_add_u64 v[68:69], v[4:5], 0, v[68:69]
	v_lshl_add_u64 v[70:71], v[4:5], 0, v[70:71]
	v_lshl_add_u64 v[72:73], v[4:5], 0, v[72:73]
	v_lshl_add_u64 v[74:75], v[4:5], 0, v[74:75]
	v_lshl_add_u64 v[76:77], v[4:5], 0, v[76:77]
	v_lshl_add_u64 v[4:5], v[4:5], 0, v[78:79]
	global_load_dword v15, v[16:17], off nt
	global_load_dword v78, v[18:19], off nt
	global_load_dword v79, v[20:21], off nt
	global_load_dword v80, v[22:23], off nt
	s_nop 0
	global_load_dword v24, v[24:25], off nt
	s_nop 0
	global_load_dword v25, v[26:27], off nt
	s_nop 0
	global_load_dword v26, v[28:29], off nt
	global_load_dword v27, v[30:31], off nt
	s_nop 0
	global_load_dword v28, v[32:33], off nt
	global_load_dword v29, v[34:35], off nt
	global_load_dword v30, v[36:37], off nt
	global_load_dword v31, v[38:39], off nt
	s_nop 0
	global_load_dword v38, v[40:41], off nt
	global_load_dword v39, v[42:43], off nt
	s_nop 0
	global_load_dword v40, v[44:45], off nt
	global_load_dword v41, v[46:47], off nt
	global_load_dword v42, v[48:49], off nt
	global_load_dword v43, v[50:51], off nt
	s_nop 0
	global_load_dword v44, v[52:53], off nt
	global_load_dword v45, v[54:55], off nt
	global_load_dword v46, v[56:57], off nt
	global_load_dword v47, v[58:59], off nt
	global_load_dword v48, v[60:61], off nt
	global_load_dword v49, v[62:63], off nt
	global_load_dword v50, v[64:65], off nt
	global_load_dword v51, v[66:67], off nt
	global_load_dword v52, v[68:69], off nt
	global_load_dword v53, v[70:71], off nt
	global_load_dword v54, v[72:73], off nt
	global_load_dword v55, v[74:75], off nt
	global_load_dword v56, v[76:77], off nt
	global_load_dword v57, v[4:5], off nt
	v_add_u32_e32 v16, s7, v170
	s_ashr_i32 s1, s0, 31
	v_ashrrev_i32_e32 v17, 31, v16
	v_add_u32_e32 v18, 8, v16
	v_add_u32_e32 v20, 16, v16
	v_add_u32_e32 v22, 24, v16
	s_waitcnt vmcnt(0)
; #define GAS __attribute__((address_space(1)))
; #define LAS __attribute__((address_space(3)))
; #define LDS_WAIT() asm volatile("s_waitcnt lgkmcnt(0)" ::: "memory")
; __device__ __forceinline__ unsigned pk2(float lo, float hi) { f32x2_p v = {lo, hi}; bf16x2_p b = __builtin_convertvector(v, bf16x2_p); return __builtin_bit_cast(unsigned, b); }
; __device__ __forceinline__ void p0_transpose_item(const float* W0, const float* W1, int K, int Nsrc, int Nd, int mode, bf16* WT, LAS float* scr, int item, int lane) {
;     const int nblk = Nd / 32, kb = item / nblk, nb = item % nblk, k0 = 64 * kb, n0 = 32 * nb;
;     const float* src = W0; int c0 = n0;
;     if (mode == 1) { const int t = n0 / 256, w = n0 % 256; src = (w < 128) ? W0 : W1; c0 = t * 128 + (w & 127); }
;     const bool okc = (c0 + (lane & 31)) < Nsrc; const int cc = okc ? c0 + (lane & 31) : Nsrc - 1;
;     float tv[32];
; #pragma unroll
;     for (int i = 0; i < 32; ++i) { const int kk = 2 * i + (lane >> 5); tv[i] = src[(size_t)(k0 + kk) * Nsrc + cc]; }
; #pragma unroll
;     for (int i = 0; i < 32; ++i) { const int kk = 2 * i + (lane >> 5); scr[kk * 33 + (lane & 31)] = okc ? tv[i] : 0.f; }
;     LDS_WAIT(); asm volatile("" ::: "memory");
;     const int c = lane & 7;
; #pragma unroll
;     for (int j = 0; j < 4; ++j) { const int n = (lane >> 3) + 8 * j; const LAS float* s = scr + (8 * c) * 33 + n;
;         v4u o; o.x = pk2(s[0 * 33], s[1 * 33]); o.y = pk2(s[2 * 33], s[3 * 33]); o.z = pk2(s[4 * 33], s[5 * 33]); o.w = pk2(s[6 * 33], s[7 * 33]);
;         *(GAS v4u*)(WT + (size_t)(n0 + n) * K + k0 + 8 * c) = o; }
;     LDS_WAIT(); asm volatile("" ::: "memory");
; }
	ds_write2_b32 v7, v15, v78 offset1:66
	ds_write2_b32 v7, v79, v80 offset0:132 offset1:198
	ds_write2_b32 v8, v24, v25 offset0:8 offset1:74
	ds_write2_b32 v8, v26, v27 offset0:140 offset1:206
	ds_write2_b32 v9, v28, v29 offset0:16 offset1:82
	ds_write2_b32 v9, v30, v31 offset0:148 offset1:214
	ds_write2_b32 v10, v38, v39 offset0:24 offset1:90
	ds_write2_b32 v10, v40, v41 offset0:156 offset1:222
	ds_write2_b32 v11, v42, v43 offset0:32 offset1:98
	ds_write2_b32 v11, v44, v45 offset0:164 offset1:230
	ds_write2_b32 v12, v46, v47 offset0:40 offset1:106
	ds_write2_b32 v12, v48, v49 offset0:172 offset1:238
	ds_write2_b32 v13, v50, v51 offset0:48 offset1:114
	ds_write2_b32 v13, v52, v53 offset0:180 offset1:246
	ds_write2_b32 v14, v54, v55 offset0:56 offset1:122
	ds_write2_b32 v14, v56, v57 offset0:188 offset1:254
	v_lshl_add_u64 v[4:5], s[0:1], 1, v[2:3]
	v_lshlrev_b64 v[16:17], 11, v[16:17]
	v_ashrrev_i32_e32 v19, 31, v18
	v_ashrrev_i32_e32 v21, 31, v20
	v_ashrrev_i32_e32 v23, 31, v22
	s_waitcnt lgkmcnt(0)
	v_lshl_add_u64 v[32:33], v[4:5], 0, v[16:17]
	v_lshlrev_b64 v[16:17], 11, v[18:19]
	v_lshlrev_b64 v[18:19], 11, v[20:21]
	v_lshlrev_b64 v[20:21], 11, v[22:23]
	v_lshl_add_u64 v[34:35], v[4:5], 0, v[16:17]
	v_lshl_add_u64 v[36:37], v[4:5], 0, v[18:19]
	v_lshl_add_u64 v[4:5], v[4:5], 0, v[20:21]
	ds_read2_b32 v[20:21], v6 offset0:33 offset1:41
	ds_read2_b32 v[22:23], v6 offset1:8
	ds_read2_b32 v[24:25], v6 offset0:66 offset1:74
	ds_read2_b32 v[26:27], v6 offset0:99 offset1:107
	ds_read2_b32 v[28:29], v6 offset0:132 offset1:140
	ds_read2_b32 v[30:31], v6 offset0:165 offset1:173
	ds_read2_b32 v[38:39], v6 offset0:198 offset1:206
	ds_read2_b32 v[40:41], v6 offset0:231 offset1:239
	ds_read2_b32 v[42:43], v6 offset0:49 offset1:57
	ds_read2_b32 v[44:45], v6 offset0:16 offset1:24
	ds_read2_b32 v[46:47], v6 offset0:82 offset1:90
	ds_read2_b32 v[48:49], v6 offset0:115 offset1:123
	ds_read2_b32 v[50:51], v6 offset0:148 offset1:156
	ds_read2_b32 v[52:53], v6 offset0:181 offset1:189
	ds_read2_b32 v[54:55], v6 offset0:214 offset1:222
	ds_read2_b32 v[56:57], v6 offset0:247 offset1:255
	s_waitcnt lgkmcnt(14)
	v_cvt_pk_bf16_f32 v16, v22, v20
	s_waitcnt lgkmcnt(12)
	v_cvt_pk_bf16_f32 v17, v24, v26
	s_waitcnt lgkmcnt(10)
	v_cvt_pk_bf16_f32 v18, v28, v30
	s_waitcnt lgkmcnt(8)
	v_cvt_pk_bf16_f32 v19, v38, v40
	v_cvt_pk_bf16_f32 v20, v23, v21
	v_cvt_pk_bf16_f32 v21, v25, v27
	v_cvt_pk_bf16_f32 v22, v29, v31
	v_cvt_pk_bf16_f32 v23, v39, v41
	s_waitcnt lgkmcnt(6)
	v_cvt_pk_bf16_f32 v24, v44, v42
	s_waitcnt lgkmcnt(4)
	v_cvt_pk_bf16_f32 v25, v46, v48
	s_waitcnt lgkmcnt(2)
	v_cvt_pk_bf16_f32 v26, v50, v52
	s_waitcnt lgkmcnt(0)
	v_cvt_pk_bf16_f32 v27, v54, v56
	v_cvt_pk_bf16_f32 v28, v45, v43
	v_cvt_pk_bf16_f32 v29, v47, v49
	v_cvt_pk_bf16_f32 v30, v51, v53
	v_cvt_pk_bf16_f32 v31, v55, v57
	global_store_dwordx4 v[32:33], v[16:19], off
	global_store_dwordx4 v[34:35], v[20:23], off
	global_store_dwordx4 v[36:37], v[24:27], off
	global_store_dwordx4 v[4:5], v[28:31], off
	s_waitcnt lgkmcnt(0)
	s_add_i32 s6, s6, s3
	s_add_i32 s4, s4, s5
	s_cmpk_lt_i32 s6, 0x200
	s_cbranch_scc1 .LBB0_1223

; #define GAS __attribute__((address_space(1)))
; #define LAS __attribute__((address_space(3)))
; #define LDS_WAIT() asm volatile("s_waitcnt lgkmcnt(0)" ::: "memory")
; __device__ __forceinline__ unsigned pk2(float lo, float hi) { f32x2_p v = {lo, hi}; bf16x2_p b = __builtin_convertvector(v, bf16x2_p); return __builtin_bit_cast(unsigned, b); }
; __device__ __forceinline__ void p0_transpose_item(const float* W0, const float* W1, int K, int Nsrc, int Nd, int mode, bf16* WT, LAS float* scr, int item, int lane) {
;     const int nblk = Nd / 32, kb = item / nblk, nb = item % nblk, k0 = 64 * kb, n0 = 32 * nb;
;     const float* src = W0; int c0 = n0;
;     if (mode == 1) { const int t = n0 / 256, w = n0 % 256; src = (w < 128) ? W0 : W1; c0 = t * 128 + (w & 127); }
;     const bool okc = (c0 + (lane & 31)) < Nsrc; const int cc = okc ? c0 + (lane & 31) : Nsrc - 1;
;     float tv[32];
; #pragma unroll
;     for (int i = 0; i < 32; ++i) { const int kk = 2 * i + (lane >> 5); tv[i] = src[(size_t)(k0 + kk) * Nsrc + cc]; }
; #pragma unroll
;     for (int i = 0; i < 32; ++i) { const int kk = 2 * i + (lane >> 5); scr[kk * 33 + (lane & 31)] = okc ? tv[i] : 0.f; }
;     LDS_WAIT(); asm volatile("" ::: "memory");
;     const int c = lane & 7;
; #pragma unroll
;     for (int j = 0; j < 4; ++j) { const int n = (lane >> 3) + 8 * j; const LAS float* s = scr + (8 * c) * 33 + n;
;         v4u o; o.x = pk2(s[0 * 33], s[1 * 33]); o.y = pk2(s[2 * 33], s[3 * 33]); o.z = pk2(s[4 * 33], s[5 * 33]); o.w = pk2(s[6 * 33], s[7 * 33]);
;         *(GAS v4u*)(WT + (size_t)(n0 + n) * K + k0 + 8 * c) = o; }
;     LDS_WAIT(); asm volatile("" ::: "memory");
; }
.LBB0_1226:
	s_mul_hi_i32 s6, s2, 0x2e8ba2e9
	s_lshr_b32 s7, s6, 31
	s_ashr_i32 s6, s6, 5
	s_add_i32 s6, s6, s7
	s_mul_i32 s7, s6, 0xffffff50
	s_mul_i32 s8, s6, 0xffffea00
	s_add_i32 s9, s2, s7
	s_add_i32 s7, s0, s8
	s_bfe_u32 s8, s9, 0x3001c
	s_lshr_b32 s10, s7, 23
	s_add_i32 s9, s9, s8
	s_and_b32 s8, s10, 0xff
	s_add_i32 s8, s7, s8
	s_and_b32 s8, s8, 0xff00
	v_add_u32_e32 v14, s7, v170
	s_sub_i32 s7, s7, s8
	s_sext_i32_i16 s8, s7
	s_sext_i32_i16 s9, s9
	s_cmpk_lt_i32 s8, 0x80
	s_cselect_b32 s8, s13, s15
	s_cselect_b32 s10, s12, s14
	s_lshl_b32 s9, s9, 4
	s_and_b32 s11, s7, 0x60
	s_lshl_b32 s6, s6, 6
	v_mov_b32_e32 v23, s8
	s_and_b32 s8, s9, 0xffffff80
	v_ashrrev_i32_e32 v15, 31, v14
	s_ashr_i32 s7, s6, 31
	s_or_b32 s8, s8, s11
	v_add_u32_e32 v16, 8, v14
	v_add_u32_e32 v18, 16, v14
	v_add_u32_e32 v20, 24, v14
	v_lshlrev_b64 v[14:15], 11, v[14:15]
	v_lshl_add_u64 v[24:25], s[6:7], 1, v[2:3]
	v_or_b32_e32 v89, s8, v168
	v_lshl_add_u64 v[30:31], v[24:25], 0, v[14:15]
	v_min_i32_e32 v14, 0xaff, v89
	v_mov_b32_e32 v22, s10
	v_or_b32_e32 v13, s6, v169
	v_ashrrev_i32_e32 v15, 31, v14
	v_or_b32_e32 v26, 2, v13
	v_or_b32_e32 v28, 4, v13
	v_or_b32_e32 v32, 6, v13
	v_or_b32_e32 v34, 8, v13
	v_or_b32_e32 v36, 10, v13
	v_or_b32_e32 v38, 12, v13
	v_or_b32_e32 v40, 14, v13
	v_or_b32_e32 v42, 16, v13
	v_or_b32_e32 v44, 18, v13
	v_or_b32_e32 v46, 20, v13
	v_or_b32_e32 v48, 22, v13
	v_or_b32_e32 v50, 24, v13
	v_or_b32_e32 v52, 26, v13
	v_or_b32_e32 v54, 28, v13
	v_or_b32_e32 v56, 30, v13
	v_or_b32_e32 v58, 32, v13
	v_or_b32_e32 v60, 34, v13
	v_or_b32_e32 v62, 36, v13
	v_or_b32_e32 v64, 38, v13
	v_or_b32_e32 v66, 40, v13
	v_or_b32_e32 v68, 42, v13
	v_or_b32_e32 v70, 44, v13
	v_or_b32_e32 v72, 46, v13
	v_or_b32_e32 v74, 48, v13
	v_or_b32_e32 v76, 50, v13
	v_or_b32_e32 v78, 52, v13
	v_or_b32_e32 v80, 54, v13
	v_or_b32_e32 v82, 56, v13
	v_or_b32_e32 v84, 58, v13
	v_or_b32_e32 v86, 60, v13
	v_or_b32_e32 v88, 62, v13
	v_lshl_add_u64 v[14:15], v[14:15], 2, v[22:23]
	v_mad_i64_i32 v[22:23], s[6:7], v13, s4, v[14:15]
	v_mad_i64_i32 v[26:27], s[6:7], v26, s4, v[14:15]
	v_mad_i64_i32 v[28:29], s[6:7], v28, s4, v[14:15]
	v_mad_i64_i32 v[32:33], s[6:7], v32, s4, v[14:15]
	v_mad_i64_i32 v[34:35], s[6:7], v34, s4, v[14:15]
	v_mad_i64_i32 v[36:37], s[6:7], v36, s4, v[14:15]
	v_mad_i64_i32 v[38:39], s[6:7], v38, s4, v[14:15]
	v_mad_i64_i32 v[40:41], s[6:7], v40, s4, v[14:15]
	v_mad_i64_i32 v[42:43], s[6:7], v42, s4, v[14:15]
	v_mad_i64_i32 v[44:45], s[6:7], v44, s4, v[14:15]
	v_mad_i64_i32 v[46:47], s[6:7], v46, s4, v[14:15]
	v_mad_i64_i32 v[48:49], s[6:7], v48, s4, v[14:15]
	v_mad_i64_i32 v[50:51], s[6:7], v50, s4, v[14:15]
	v_mad_i64_i32 v[52:53], s[6:7], v52, s4, v[14:15]
	v_mad_i64_i32 v[54:55], s[6:7], v54, s4, v[14:15]
	v_mad_i64_i32 v[56:57], s[6:7], v56, s4, v[14:15]
	v_mad_i64_i32 v[58:59], s[6:7], v58, s4, v[14:15]
	v_mad_i64_i32 v[60:61], s[6:7], v60, s4, v[14:15]
	v_mad_i64_i32 v[62:63], s[6:7], v62, s4, v[14:15]
	v_mad_i64_i32 v[64:65], s[6:7], v64, s4, v[14:15]
	v_mad_i64_i32 v[66:67], s[6:7], v66, s4, v[14:15]
	v_mad_i64_i32 v[68:69], s[6:7], v68, s4, v[14:15]
	v_mad_i64_i32 v[70:71], s[6:7], v70, s4, v[14:15]
	v_mad_i64_i32 v[72:73], s[6:7], v72, s4, v[14:15]
	v_mad_i64_i32 v[74:75], s[6:7], v74, s4, v[14:15]
	v_mad_i64_i32 v[76:77], s[6:7], v76, s4, v[14:15]
	v_mad_i64_i32 v[78:79], s[6:7], v78, s4, v[14:15]
	v_mad_i64_i32 v[80:81], s[6:7], v80, s4, v[14:15]
	v_mad_i64_i32 v[82:83], s[6:7], v82, s4, v[14:15]
	v_mad_i64_i32 v[84:85], s[6:7], v84, s4, v[14:15]
	v_mad_i64_i32 v[86:87], s[6:7], v86, s4, v[14:15]
	v_mad_i64_i32 v[14:15], s[6:7], v88, s4, v[14:15]
	global_load_dword v13, v[22:23], off nt
	s_nop 0
	global_load_dword v22, v[26:27], off nt
	global_load_dword v23, v[28:29], off nt
	s_nop 0
	global_load_dword v26, v[32:33], off nt
	global_load_dword v27, v[34:35], off nt
	global_load_dword v28, v[36:37], off nt
	global_load_dword v29, v[38:39], off nt
	s_nop 0
	global_load_dword v38, v[40:41], off nt
	global_load_dword v39, v[42:43], off nt
	s_nop 0
	global_load_dword v40, v[44:45], off nt
	global_load_dword v41, v[46:47], off nt
	global_load_dword v42, v[48:49], off nt
	global_load_dword v43, v[50:51], off nt
	s_nop 0
	global_load_dword v44, v[52:53], off nt
	global_load_dword v45, v[54:55], off nt
	global_load_dword v46, v[56:57], off nt
	global_load_dword v47, v[58:59], off nt
	global_load_dword v48, v[60:61], off nt
	global_load_dword v49, v[62:63], off nt
	global_load_dword v50, v[64:65], off nt
	global_load_dword v51, v[66:67], off nt
	global_load_dword v52, v[68:69], off nt
	global_load_dword v53, v[70:71], off nt
	global_load_dword v54, v[72:73], off nt
	global_load_dword v55, v[74:75], off nt
	global_load_dword v56, v[76:77], off nt
	global_load_dword v57, v[78:79], off nt
	global_load_dword v58, v[80:81], off nt
	global_load_dword v59, v[82:83], off nt
	global_load_dword v60, v[84:85], off nt
	global_load_dword v61, v[86:87], off nt
	s_nop 0
	global_load_dword v14, v[14:15], off nt
	v_ashrrev_i32_e32 v17, 31, v16
	v_ashrrev_i32_e32 v19, 31, v18
	v_ashrrev_i32_e32 v21, 31, v20
	v_cmp_gt_i32_e32 vcc, s5, v89
	v_lshlrev_b64 v[16:17], 11, v[16:17]
	v_lshlrev_b64 v[18:19], 11, v[18:19]
	v_lshlrev_b64 v[20:21], 11, v[20:21]
	v_lshl_add_u64 v[32:33], v[24:25], 0, v[16:17]
	v_lshl_add_u64 v[34:35], v[24:25], 0, v[18:19]
	v_lshl_add_u64 v[36:37], v[24:25], 0, v[20:21]
	s_add_i32 s2, s2, s3
	s_add_i32 s0, s0, s1
	s_cmpk_lt_i32 s2, 0xb00
	s_waitcnt vmcnt(0)
; #define GAS __attribute__((address_space(1)))
; #define LAS __attribute__((address_space(3)))
; #define LDS_WAIT() asm volatile("s_waitcnt lgkmcnt(0)" ::: "memory")
; __device__ __forceinline__ unsigned pk2(float lo, float hi) { f32x2_p v = {lo, hi}; bf16x2_p b = __builtin_convertvector(v, bf16x2_p); return __builtin_bit_cast(unsigned, b); }
; __device__ __forceinline__ void p0_transpose_item(const float* W0, const float* W1, int K, int Nsrc, int Nd, int mode, bf16* WT, LAS float* scr, int item, int lane) {
;     const int nblk = Nd / 32, kb = item / nblk, nb = item % nblk, k0 = 64 * kb, n0 = 32 * nb;
;     const float* src = W0; int c0 = n0;
;     if (mode == 1) { const int t = n0 / 256, w = n0 % 256; src = (w < 128) ? W0 : W1; c0 = t * 128 + (w & 127); }
;     const bool okc = (c0 + (lane & 31)) < Nsrc; const int cc = okc ? c0 + (lane & 31) : Nsrc - 1;
;     float tv[32];
; #pragma unroll
;     for (int i = 0; i < 32; ++i) { const int kk = 2 * i + (lane >> 5); tv[i] = src[(size_t)(k0 + kk) * Nsrc + cc]; }
; #pragma unroll
;     for (int i = 0; i < 32; ++i) { const int kk = 2 * i + (lane >> 5); scr[kk * 33 + (lane & 31)] = okc ? tv[i] : 0.f; }
;     LDS_WAIT(); asm volatile("" ::: "memory");
;     const int c = lane & 7;
; #pragma unroll
;     for (int j = 0; j < 4; ++j) { const int n = (lane >> 3) + 8 * j; const LAS float* s = scr + (8 * c) * 33 + n;
;         v4u o; o.x = pk2(s[0 * 33], s[1 * 33]); o.y = pk2(s[2 * 33], s[3 * 33]); o.z = pk2(s[4 * 33], s[5 * 33]); o.w = pk2(s[6 * 33], s[7 * 33]);
;         *(GAS v4u*)(WT + (size_t)(n0 + n) * K + k0 + 8 * c) = o; }
;     LDS_WAIT(); asm volatile("" ::: "memory");
; }
	v_cndmask_b32_e32 v13, 0, v13, vcc
	v_cndmask_b32_e32 v15, 0, v22, vcc
	v_cndmask_b32_e32 v16, 0, v23, vcc
	v_cndmask_b32_e32 v17, 0, v26, vcc
	v_cndmask_b32_e32 v18, 0, v27, vcc
	v_cndmask_b32_e32 v19, 0, v28, vcc
	v_cndmask_b32_e32 v20, 0, v29, vcc
	v_cndmask_b32_e32 v21, 0, v38, vcc
	v_cndmask_b32_e32 v22, 0, v39, vcc
	v_cndmask_b32_e32 v23, 0, v40, vcc
	v_cndmask_b32_e32 v24, 0, v41, vcc
	v_cndmask_b32_e32 v25, 0, v42, vcc
	v_cndmask_b32_e32 v26, 0, v43, vcc
	v_cndmask_b32_e32 v27, 0, v44, vcc
	v_cndmask_b32_e32 v28, 0, v45, vcc
	v_cndmask_b32_e32 v29, 0, v46, vcc
	v_cndmask_b32_e32 v38, 0, v47, vcc
	v_cndmask_b32_e32 v39, 0, v48, vcc
	v_cndmask_b32_e32 v40, 0, v49, vcc
	v_cndmask_b32_e32 v41, 0, v50, vcc
	v_cndmask_b32_e32 v42, 0, v51, vcc
	v_cndmask_b32_e32 v43, 0, v52, vcc
	v_cndmask_b32_e32 v44, 0, v53, vcc
	v_cndmask_b32_e32 v45, 0, v54, vcc
	v_cndmask_b32_e32 v46, 0, v55, vcc
	v_cndmask_b32_e32 v47, 0, v56, vcc
	v_cndmask_b32_e32 v48, 0, v57, vcc
	v_cndmask_b32_e32 v49, 0, v58, vcc
	v_cndmask_b32_e32 v50, 0, v59, vcc
	v_cndmask_b32_e32 v51, 0, v60, vcc
	v_cndmask_b32_e32 v52, 0, v61, vcc
	v_cndmask_b32_e32 v14, 0, v14, vcc
	ds_write2_b32 v5, v13, v15 offset1:66
	ds_write2_b32 v5, v16, v17 offset0:132 offset1:198
	ds_write2_b32 v6, v18, v19 offset0:8 offset1:74
	ds_write2_b32 v6, v20, v21 offset0:140 offset1:206
	ds_write2_b32 v7, v22, v23 offset0:16 offset1:82
	ds_write2_b32 v7, v24, v25 offset0:148 offset1:214
	ds_write2_b32 v8, v26, v27 offset0:24 offset1:90
	ds_write2_b32 v8, v28, v29 offset0:156 offset1:222
	ds_write2_b32 v9, v38, v39 offset0:32 offset1:98
	ds_write2_b32 v9, v40, v41 offset0:164 offset1:230
	ds_write2_b32 v10, v42, v43 offset0:40 offset1:106
	ds_write2_b32 v10, v44, v45 offset0:172 offset1:238
	ds_write2_b32 v11, v46, v47 offset0:48 offset1:114
	ds_write2_b32 v11, v48, v49 offset0:180 offset1:246
	ds_write2_b32 v12, v50, v51 offset0:56 offset1:122
	ds_write2_b32 v12, v52, v14 offset0:188 offset1:254
	s_waitcnt lgkmcnt(0)
	ds_read2_b32 v[18:19], v4 offset0:33 offset1:41
	ds_read2_b32 v[20:21], v4 offset1:8
	ds_read2_b32 v[22:23], v4 offset0:66 offset1:74
	ds_read2_b32 v[24:25], v4 offset0:99 offset1:107
	ds_read2_b32 v[26:27], v4 offset0:132 offset1:140
	ds_read2_b32 v[28:29], v4 offset0:165 offset1:173
	ds_read2_b32 v[38:39], v4 offset0:198 offset1:206
	ds_read2_b32 v[40:41], v4 offset0:231 offset1:239
	ds_read2_b32 v[42:43], v4 offset0:49 offset1:57
	ds_read2_b32 v[44:45], v4 offset0:16 offset1:24
	ds_read2_b32 v[46:47], v4 offset0:82 offset1:90
	ds_read2_b32 v[48:49], v4 offset0:115 offset1:123
	ds_read2_b32 v[50:51], v4 offset0:148 offset1:156
	ds_read2_b32 v[52:53], v4 offset0:181 offset1:189
	ds_read2_b32 v[54:55], v4 offset0:214 offset1:222
	ds_read2_b32 v[56:57], v4 offset0:247 offset1:255
	s_waitcnt lgkmcnt(14)
	v_cvt_pk_bf16_f32 v14, v20, v18
	s_waitcnt lgkmcnt(12)
	v_cvt_pk_bf16_f32 v15, v22, v24
	s_waitcnt lgkmcnt(10)
	v_cvt_pk_bf16_f32 v16, v26, v28
	s_waitcnt lgkmcnt(8)
	v_cvt_pk_bf16_f32 v17, v38, v40
	v_cvt_pk_bf16_f32 v18, v21, v19
	v_cvt_pk_bf16_f32 v19, v23, v25
	v_cvt_pk_bf16_f32 v20, v27, v29
	v_cvt_pk_bf16_f32 v21, v39, v41
	s_waitcnt lgkmcnt(6)
	v_cvt_pk_bf16_f32 v22, v44, v42
	s_waitcnt lgkmcnt(4)
	v_cvt_pk_bf16_f32 v23, v46, v48
	s_waitcnt lgkmcnt(2)
	v_cvt_pk_bf16_f32 v24, v50, v52
	s_waitcnt lgkmcnt(0)
	v_cvt_pk_bf16_f32 v25, v54, v56
	v_cvt_pk_bf16_f32 v26, v45, v43
	v_cvt_pk_bf16_f32 v27, v47, v49
	v_cvt_pk_bf16_f32 v28, v51, v53
	v_cvt_pk_bf16_f32 v29, v55, v57
	global_store_dwordx4 v[30:31], v[14:17], off
	global_store_dwordx4 v[32:33], v[18:21], off
	global_store_dwordx4 v[34:35], v[22:25], off
	global_store_dwordx4 v[36:37], v[26:29], off
	s_waitcnt lgkmcnt(0)
	s_cbranch_scc1 .LBB0_1226

; __device__ __forceinline__ void gdn_scan_task(int task, const float* GQ, const float* GK, const float* GV, const float* GG, const float* GB, const float* s0, const float* P, const float* nw, bf16* heads, float* out, int lane) {
;     const int seq = task / NH, h = task % NH;
;     float S[64]; int row0, L; float* sdst;
;     if (seq < NB) { row0 = seq * SEQ; L = SEQ; sdst = out + O_SGP + ((size_t)seq * NH + h) * 4096;
; #pragma unroll
;         for (int d = 0; d < 64; ++d) S[d] = 0.f; }
;     else { const int b = seq - NB; row0 = MP + b * DS; L = DS; sdst = out + O_SGS + ((size_t)b * NH + h) * 4096; const float* sp = s0 + ((size_t)b * NH + h) * 4096;
; #pragma unroll
;         for (int d = 0; d < 64; ++d) S[d] = sp[d * 64 + lane]; }
;     const float nwl = nw[lane];
;     size_t o = (size_t)row0 * GW + h * 64 + lane;
;     float qn = GQ[o], kn = GK[o], vn = GV[o], gn = GG[(size_t)row0 * NH + h], bn = GB[(size_t)row0 * NH + h], zn = P[(size_t)row0 * NINP + C_Z + h * 64 + lane];
.LBB0_1230:
	s_ashr_i32 s0, s33, 31
	s_lshr_b32 s0, s0, 29
	s_add_i32 s0, s33, s0
	s_ashr_i32 s10, s0, 3
	s_and_b32 s0, s0, -8
	s_sub_i32 s6, s33, s0
	s_cmp_gt_i32 s33, 63
	s_mov_b64 s[2:3], -1
	s_cbranch_scc0 .LBB0_1232
	s_add_i32 s4, s10, -8
	s_lshl_b32 s0, s6, 12
	s_mov_b32 s1, s5
	s_lshl_b64 s[0:1], s[0:1], 2
	s_lshl_b64 s[2:3], s[4:5], 17
	s_or_b64 s[2:3], s[2:3], s[0:1]
	v_lshl_add_u64 v[16:17], v[4:5], 0, s[2:3]
	s_movk_i32 s0, 0x1000
	v_add_co_u32_e32 v18, vcc, s0, v16
	s_movk_i32 s0, 0x2000
	s_nop 0
	v_addc_co_u32_e32 v19, vcc, 0, v17, vcc
	v_add_co_u32_e32 v22, vcc, s0, v16
	global_load_dword v10, v[16:17], off nt
	global_load_dword v14, v[16:17], off offset:256 nt
	global_load_dword v11, v[16:17], off offset:512 nt
	global_load_dword v15, v[16:17], off offset:768 nt
	global_load_dword v12, v[16:17], off offset:1024 nt
	global_load_dword v42, v[16:17], off offset:1280 nt
	global_load_dword v13, v[16:17], off offset:1536 nt
	global_load_dword v43, v[16:17], off offset:1792 nt
	global_load_dword v28, v[16:17], off offset:2048 nt
	global_load_dword v54, v[16:17], off offset:2304 nt
	global_load_dword v29, v[16:17], off offset:2560 nt
	global_load_dword v55, v[16:17], off offset:2816 nt
	global_load_dword v52, v[16:17], off offset:3072 nt
	global_load_dword v70, v[16:17], off offset:3328 nt
	global_load_dword v53, v[16:17], off offset:3584 nt
	global_load_dword v71, v[16:17], off offset:3840 nt
	v_addc_co_u32_e32 v23, vcc, 0, v17, vcc
	v_add_co_u32_e32 v74, vcc, s48, v16
	global_load_dword v72, v[18:19], off offset:256 nt
	global_load_dword v67, v[18:19], off offset:512 nt
	global_load_dword v73, v[18:19], off offset:768 nt
	global_load_dword v58, v[18:19], off offset:1024 nt
	global_load_dword v60, v[18:19], off offset:1280 nt
	global_load_dword v59, v[18:19], off offset:1536 nt
	global_load_dword v61, v[18:19], off offset:1792 nt
	global_load_dword v56, v[18:19], off offset:2048 nt
	global_load_dword v48, v[22:23], off nt
	global_load_dword v50, v[22:23], off offset:256 nt
	global_load_dword v49, v[22:23], off offset:512 nt
	global_load_dword v51, v[22:23], off offset:768 nt
	global_load_dword v46, v[22:23], off offset:1024 nt
	global_load_dword v44, v[22:23], off offset:1280 nt
	global_load_dword v47, v[22:23], off offset:1536 nt
	global_load_dword v45, v[22:23], off offset:1792 nt
	global_load_dword v38, v[22:23], off offset:2048 nt
	global_load_dword v40, v[22:23], off offset:2304 nt
	global_load_dword v39, v[22:23], off offset:2560 nt
	global_load_dword v41, v[22:23], off offset:2816 nt
	global_load_dword v30, v[22:23], off offset:3072 nt
	global_load_dword v32, v[22:23], off offset:3328 nt
	global_load_dword v31, v[22:23], off offset:3584 nt
	global_load_dword v33, v[22:23], off offset:3840 nt
	v_addc_co_u32_e32 v75, vcc, 0, v17, vcc
	global_load_dword v68, v[18:19], off offset:2304 nt
	global_load_dword v57, v[18:19], off offset:2560 nt
	global_load_dword v69, v[18:19], off offset:2816 nt
	global_load_dword v64, v[18:19], off offset:3072 nt
	global_load_dword v62, v[18:19], off offset:3328 nt
	global_load_dword v65, v[18:19], off offset:3584 nt
	global_load_dword v63, v[18:19], off offset:3840 nt
	global_load_dword v34, v[74:75], off nt
	global_load_dword v36, v[74:75], off offset:256 nt
	global_load_dword v35, v[74:75], off offset:512 nt
	global_load_dword v37, v[74:75], off offset:768 nt
	global_load_dword v24, v[74:75], off offset:1024 nt
	global_load_dword v26, v[74:75], off offset:1280 nt
	global_load_dword v25, v[74:75], off offset:1536 nt
	global_load_dword v27, v[74:75], off offset:1792 nt
	global_load_dword v20, v[74:75], off offset:2048 nt
	global_load_dword v66, v[22:23], off offset:-4096 nt
	s_nop 0
	global_load_dword v22, v[74:75], off offset:2304 nt
	global_load_dword v21, v[74:75], off offset:2560 nt
	global_load_dword v23, v[74:75], off offset:2816 nt
	global_load_dword v18, v[74:75], off offset:3072 nt
	global_load_dword v16, v[74:75], off offset:3328 nt
	global_load_dword v19, v[74:75], off offset:3584 nt
	global_load_dword v17, v[74:75], off offset:3840 nt
	s_lshl_b32 s0, s4, 2
	s_addk_i32 s0, 0x4000
	v_readlane_b32 s1, v244, 43
	s_add_u32 s8, s1, s2
	v_readlane_b32 s1, v244, 44
	s_addc_u32 s9, s1, s3
	s_mov_b32 s7, s5
	s_mov_b64 s[2:3], 0

; __device__ __forceinline__ void gdn_scan_task(int task, const float* GQ, const float* GK, const float* GV, const float* GG, const float* GB, const float* s0, const float* P, const float* nw, bf16* heads, float* out, int lane) {
;     ...
;     const float nwl = nw[lane];
;     size_t o = (size_t)row0 * GW + h * 64 + lane;
;     float qn = GQ[o], kn = GK[o], vn = GV[o], gn = GG[(size_t)row0 * NH + h], bn = GB[(size_t)row0 * NH + h], zn = P[(size_t)row0 * NINP + C_Z + h * 64 + lane];
;     for (int t = 0; t < L; ++t) {
;         const float qv = qn, kv = kn, vv = vn, eg = __expf(gn), beta = bn, z = zn; const int m = row0 + t;
;         if (t + 1 < L) { o += GW; qn = GQ[o]; kn = GK[o]; vn = GV[o]; gn = GG[(size_t)(m + 1) * NH + h]; bn = GB[(size_t)(m + 1) * NH + h]; zn = P[(size_t)(m + 1) * NINP + C_Z + h * 64 + lane]; }
.LBB0_1234:
	s_ashr_i32 s1, s0, 31
	s_lshl_b32 s12, s6, 6
	s_lshl_b64 s[2:3], s[0:1], 9
	s_ashr_i32 s13, s12, 31
	s_add_u32 s2, s2, s12
	s_addc_u32 s3, s3, s13
	v_mov_b32_e32 v75, s3
	v_or_b32_e32 v74, s2, v196
	v_readlane_b32 s2, v244, 31
	v_lshlrev_b64 v[76:77], 2, v[74:75]
	v_readlane_b32 s3, v244, 32
	v_readlane_b32 s10, v244, 35
	s_mul_i32 s11, s0, 0x3c00
	v_lshl_add_u64 v[80:81], s[2:3], 0, v[76:77]
	v_readlane_b32 s2, v244, 33
	v_readlane_b32 s3, v244, 34
	v_lshlrev_b32_e32 v2, 2, v196
	global_load_dword v99, v[6:7], off nt
	v_lshl_add_u64 v[82:83], s[2:3], 0, v[76:77]
	s_lshl_b64 s[2:3], s[0:1], 3
	s_add_u32 s2, s2, s6
	s_addc_u32 s3, s3, s7
	s_lshl_b64 s[2:3], s[2:3], 2
	s_add_u32 s14, s10, s2
	v_readlane_b32 s10, v244, 36
	s_addc_u32 s15, s10, s3
	v_readlane_b32 s10, v244, 37
	s_add_u32 s2, s10, s2
	v_readlane_b32 s10, v244, 38
	s_addc_u32 s3, s10, s3
	s_mul_hi_i32 s10, s0, 0x3c00
	s_add_u32 s16, s88, s11
	s_addc_u32 s17, s89, s10
	s_lshl_b64 s[10:11], s[12:13], 2
	s_add_u32 s16, s16, s10
	s_addc_u32 s17, s17, s11
	v_lshl_add_u64 v[84:85], s[16:17], 0, v[2:3]
	v_add_co_u32_e32 v84, vcc, s48, v84
	v_lshl_add_u64 v[76:77], s[68:69], 0, v[76:77]
	s_nop 0
	v_addc_co_u32_e32 v85, vcc, 0, v85, vcc
	global_load_dword v101, v[80:81], off nt
	s_nop 0
	global_load_dword v80, v[82:83], off nt
	global_load_dword v108, v[76:77], off nt
	global_load_dword v78, v3, s[14:15] nt
	global_load_dword v109, v3, s[2:3] nt
	global_load_dword v100, v[84:85], off nt
	s_add_i32 s49, s0, 1
	s_lshl_b64 s[0:1], s[0:1], 11
	s_lshl_b64 s[12:13], s[12:13], 1
	s_add_u32 s0, s0, s12
	s_addc_u32 s1, s1, s13
	s_mov_b32 s2, 0
	v_lshl_add_u64 v[76:77], v[8:9], 0, s[0:1]
	s_add_i32 s66, s2, 1
	s_cmp_ge_u32 s66, s4
	s_cbranch_scc1 .LBB0_1236
.LBB0_1235:
	s_mov_b64 s[0:1], 0x200
	v_lshl_add_u64 v[74:75], v[74:75], 0, s[0:1]
	v_readlane_b32 s0, v244, 31
	v_lshlrev_b64 v[82:83], 2, v[74:75]
	v_readlane_b32 s1, v244, 32
	s_nop 1
	v_lshl_add_u64 v[84:85], s[0:1], 0, v[82:83]
	v_readlane_b32 s0, v244, 33
	v_readlane_b32 s1, v244, 34
	s_nop 1
	v_lshl_add_u64 v[86:87], s[0:1], 0, v[82:83]
	s_add_i32 s0, s49, s2
	s_ashr_i32 s1, s0, 31
	s_lshl_b64 s[2:3], s[0:1], 3
	s_add_u32 s2, s2, s6
	s_addc_u32 s3, s3, s7
	s_lshl_b64 s[2:3], s[2:3], 2
	v_readlane_b32 s1, v244, 35
	s_add_u32 s12, s1, s2
	v_readlane_b32 s1, v244, 36
	s_addc_u32 s13, s1, s3
	v_readlane_b32 s1, v244, 37
	s_add_u32 s2, s1, s2
	v_readlane_b32 s1, v244, 38
	s_addc_u32 s3, s1, s3
	s_mul_hi_i32 s1, s0, 0x3c00
	s_mulk_i32 s0, 0x3c00
	s_add_u32 s0, s88, s0
	s_addc_u32 s1, s89, s1
	s_add_u32 s0, s0, s10
	s_addc_u32 s1, s1, s11
	v_lshl_add_u64 v[88:89], s[0:1], 0, v[2:3]
	v_add_co_u32_e32 v88, vcc, 0x3000, v88
	v_lshl_add_u64 v[82:83], s[68:69], 0, v[82:83]
	s_nop 0
	v_addc_co_u32_e32 v89, vcc, 0, v89, vcc
	global_load_dword v106, v[84:85], off nt
	global_load_dword v105, v[86:87], off nt
	global_load_dword v104, v[82:83], off nt
	global_load_dword v103, v3, s[12:13] nt
	global_load_dword v102, v3, s[2:3] nt
	global_load_dword v107, v[88:89], off nt
	s_branch .LBB0_1237
